# PEER V phase work queue: 8-token groups instead of 16 (finer end-of-phase balance)
# baseline (speedup 1.0000x reference)
.LBB0_1199:
	s_or_b64 exec, exec, s[0:1]
	s_mov_b64 s[0:1], 0
	v_readlane_b32 s4, v250, 0
	s_waitcnt lgkmcnt(0)
	s_barrier
	v_readlane_b32 s6, v250, 2
	v_readlane_b32 s7, v250, 3
	s_add_u32 s0, s6, s0
	s_addc_u32 s1, s7, s1
	s_mov_b64 s[6:7], 0
	s_mov_b64 s[6:7], 0
	s_mov_b64 s[18:19], 0
	s_mov_b64 s[16:17], 0
	s_mov_b64 s[10:11], 0
	s_mov_b64 s[6:7], 0
	s_mov_b64 s[14:15], 0
	s_mov_b64 s[12:13], 0
	s_mov_b64 s[8:9], 0
	v_mov_b32_e32 v2, v0
	s_add_u32 s0, s0, 0x4800
	s_getreg_b32 s2, hwreg(HW_REG_XCC_ID, 0, 4)
	v_and_b32_e32 v3, 63, v2
	s_addc_u32 s1, s1, 0
	s_and_b32 s26, s2, 7
	v_mov_b32_e32 v216, 0
	v_cmp_eq_u32_e64 s[6:7], 0, v3
	v_readlane_b32 s5, v250, 1
	s_and_saveexec_b64 s[20:21], s[6:7]
	s_cbranch_execz .LBB0_1203
	s_mov_b64 s[24:25], exec
	v_mbcnt_lo_u32_b32 v4, s24, 0
	v_mbcnt_hi_u32_b32 v4, s25, v4
	v_cmp_eq_u32_e32 vcc, 0, v4
	s_and_saveexec_b64 s[22:23], vcc
	s_cbranch_execz .LBB0_1202
	s_bcnt1_i32_b64 s24, s[24:25]
	s_lshl_b32 s27, s26, 8
	s_lshl_b32 s24, s24, 3
	v_mov_b32_e32 v5, s27
	v_mov_b32_e32 v6, s24
	global_atomic_add v5, v5, v6, s[0:1] sc0
.LBB0_1202:
	s_or_b64 exec, exec, s[22:23]
	s_waitcnt vmcnt(0)
	v_readfirstlane_b32 s22, v5
	s_nop 1
	v_lshl_add_u32 v216, v4, 3, s22
.LBB0_1203:
	s_or_b64 exec, exec, s[20:21]
	v_readlane_b32 s28, v250, 0
	v_readlane_b32 s30, v250, 2
	v_readlane_b32 s31, v250, 3
	s_add_u32 s20, s30, s16
	s_addc_u32 s21, s31, s17
	s_add_u32 s22, s30, s10
	s_addc_u32 s23, s31, s11
	s_add_u32 s10, s30, s14
	s_addc_u32 s11, s31, s15
	s_add_u32 s10, s10, 0x3cd06000
	s_addc_u32 s11, s11, 0
	s_add_u32 s12, s30, s12
	s_addc_u32 s13, s31, s13
	s_add_u32 s33, s12, 0x1e6000
	s_addc_u32 s34, s13, 0
	s_add_u32 s8, s30, s8
	s_addc_u32 s9, s31, s9
	s_add_u32 s12, s8, 0x4c618000
	s_addc_u32 s13, s9, 0
	s_add_u32 s8, s30, s18
	s_addc_u32 s9, s31, s19
	s_add_u32 s14, s8, 0x50e18000
	v_readlane_b32 s40, v250, 4
	s_addc_u32 s15, s9, 0
	v_readlane_b32 s41, v250, 5
	v_readlane_b32 s44, v250, 8
	s_cmp_eq_u64 s[40:41], 0
	v_readlane_b32 s45, v250, 9
	s_cselect_b64 s[16:17], -1, 0
	s_add_u32 s35, s44, 0xf8000000
	s_addc_u32 s36, s45, -1
	v_lshlrev_b32_e32 v217, 2, v3
	v_lshlrev_b32_e32 v4, 4, v3
	v_lshlrev_b32_e32 v3, 3, v3
	s_waitcnt vmcnt(0)
	v_and_b32_e32 v190, 0x1c0, v3
	v_mov_b32_e32 v191, 0
	v_and_b32_e32 v3, 56, v2
	s_add_u32 s18, s30, s18
	v_and_b32_e32 v218, 0x70, v4
	v_lshl_add_u64 v[4:5], s[20:21], 0, v[190:191]
	s_mov_b64 s[8:9], 0x2ade6000
	v_lshlrev_b32_e32 v190, 2, v3
	s_addc_u32 s19, s31, s19
	v_lshl_add_u64 v[192:193], v[4:5], 0, s[8:9]
	v_lshl_add_u64 v[4:5], s[22:23], 0, v[190:191]
	s_mov_b64 s[8:9], 0x4c198000
	v_and_b32_e32 v2, 8, v2
	s_add_u32 s37, s18, 0x50e18000
	v_lshl_add_u64 v[194:195], v[4:5], 0, s[8:9]
	s_mov_b32 s40, 0
	v_cmp_eq_u32_e64 s[8:9], 0, v2
	s_addc_u32 s38, s19, 0
	v_mov_b32_e32 v220, s26
	v_mov_b32_e32 v219, 8
	s_mov_b32 s39, 0xa000
	s_mov_b64 s[18:19], 0x2000
	v_readlane_b32 s29, v250, 1
	v_readlane_b32 s42, v250, 6
	v_readlane_b32 s43, v250, 7
	v_readlane_b32 s46, v250, 10
	v_readlane_b32 s47, v250, 11
	v_readlane_b32 s48, v250, 12
	v_readlane_b32 s49, v250, 13
	v_readlane_b32 s50, v250, 14
	v_readlane_b32 s51, v250, 15
	v_readlane_b32 s52, v250, 16
	v_readlane_b32 s53, v250, 17
	v_readlane_b32 s54, v250, 18
	v_readlane_b32 s55, v250, 19
	s_branch .LBB0_1206

.LBB0_1210:
	s_add_i32 s21, s20, s41
	s_add_i32 s23, s21, 2
	s_add_i32 s22, s21, 1
	s_add_i32 s25, s21, 3
	s_cmp_lt_u32 s41, 6
	s_cselect_b32 s24, s23, s21
	s_cselect_b32 s26, s25, s22
	s_ashr_i32 s25, s24, 31
	s_ashr_i32 s23, s22, 31
	s_lshl_b64 s[28:29], s[24:25], 9
	s_lshl_b64 s[30:31], s[22:23], 8
	s_lshl_b64 s[44:45], s[22:23], 13
	s_add_i32 s24, s41, 1
	s_cmp_lt_u32 s24, 7
	s_cselect_b64 s[46:47], -1, 0
	s_ashr_i32 s27, s26, 31
	s_lshl_b64 s[24:25], s[26:27], 9
	s_cmp_lg_u64 s[46:47], 0
	v_lshl_add_u64 v[14:15], v[192:193], 0, s[28:29]
	s_addc_u32 s26, s21, 1
	s_lshl_b64 s[22:23], s[22:23], 12
	global_load_dwordx4 v[174:177], v[14:15], off offset:48
	global_load_dwordx4 v[178:181], v[14:15], off offset:32
	global_load_dwordx4 v[182:185], v[14:15], off offset:16
	global_load_dwordx4 v[186:189], v[14:15], off
	v_lshl_add_u64 v[14:15], v[194:195], 0, s[30:31]
	global_load_dwordx4 v[30:33], v[14:15], off offset:16
	global_load_dwordx4 v[106:109], v[14:15], off
	v_lshl_add_u64 v[14:15], v[196:197], 0, s[44:45]
	v_lshl_add_u64 v[38:39], v[198:199], 0, s[22:23]
	global_load_dwordx4 v[14:17], v[14:15], off
	s_ashr_i32 s27, s26, 31
	global_load_dwordx2 v[206:207], v[38:39], off
	s_waitcnt vmcnt(29)
	v_lshl_add_u32 v38, v146, 7, v221
	v_lshl_add_u32 v39, v147, 7, v221
	global_load_dwordx4 v[170:173], v38, s[10:11]
	global_load_dwordx4 v[166:169], v39, s[10:11]
	v_lshl_add_u32 v38, v148, 7, v221
	v_lshl_add_u32 v39, v149, 7, v221
	global_load_dwordx4 v[162:165], v38, s[10:11]
	global_load_dwordx4 v[158:161], v39, s[10:11]
	v_lshl_add_u32 v38, v142, 7, v221
	v_lshl_add_u32 v39, v143, 7, v221
	global_load_dwordx4 v[154:157], v38, s[10:11]
	global_load_dwordx4 v[138:141], v39, s[10:11]
	v_lshl_add_u32 v38, v144, 7, v221
	v_lshl_add_u32 v39, v145, 7, v221
	global_load_dwordx4 v[122:125], v38, s[10:11]
	global_load_dwordx4 v[114:117], v39, s[10:11]
	v_lshl_add_u32 v38, v130, 7, v221
	v_lshl_add_u32 v39, v131, 7, v221
	global_load_dwordx4 v[102:105], v38, s[10:11]
	global_load_dwordx4 v[94:97], v39, s[10:11]
	v_lshl_add_u32 v38, v132, 7, v221
	v_lshl_add_u32 v39, v133, 7, v221
	global_load_dwordx4 v[82:85], v38, s[10:11]
	global_load_dwordx4 v[74:77], v39, s[10:11]
	s_waitcnt vmcnt(39)
	v_lshl_add_u32 v38, v126, 7, v221
	v_lshl_add_u32 v39, v127, 7, v221
	global_load_dwordx4 v[66:69], v38, s[10:11]
	global_load_dwordx4 v[58:61], v39, s[10:11]
	v_lshl_add_u32 v38, v128, 7, v221
	v_lshl_add_u32 v39, v129, 7, v221
	global_load_dwordx4 v[46:49], v38, s[10:11]
	s_nop 0
	global_load_dwordx4 v[38:41], v39, s[10:11]
	s_lshl_b64 s[30:31], s[26:27], 8
	s_lshl_b64 s[28:29], s[26:27], 13
	s_lshl_b64 s[26:27], s[26:27], 12
	s_add_i32 s21, s41, 2
	s_cmp_gt_u32 s41, 5
	s_waitcnt vmcnt(39)
	v_cvt_scalef32_pk_f16_fp4 v126, v150, 1.0
	v_pk_fma_f16 v126, v50, v126, 0 op_sel_hi:[0,1,1]
	v_cvt_scalef32_pk_f16_fp4 v127, v150, 1.0 op_sel:[1,0,0]
	v_cvt_scalef32_pk_f16_fp4 v128, v150, 1.0 op_sel:[0,1,0]
	v_cvt_scalef32_pk_f16_fp4 v129, v150, 1.0 op_sel:[1,1,0]
	s_waitcnt vmcnt(38)
	v_cvt_scalef32_pk_f16_fp4 v150, v134, 1.0
	v_pk_fma_f16 v127, v50, v127, 0 op_sel_hi:[0,1,1]
	v_pk_fma_f16 v126, v50, v150, v126 op_sel:[1,0,0]
	v_cvt_scalef32_pk_f16_fp4 v150, v134, 1.0 op_sel:[1,0,0]
	v_pk_fma_f16 v129, v50, v129, 0 op_sel_hi:[0,1,1]
	v_cvt_scalef32_pk_f16_fp4 v130, v151, 1.0
	v_pk_fma_f16 v127, v50, v150, v127 op_sel:[1,0,0]
	v_cvt_scalef32_pk_f16_fp4 v150, v134, 1.0 op_sel:[0,1,0]
	v_cvt_scalef32_pk_f16_fp4 v134, v134, 1.0 op_sel:[1,1,0]
	v_pk_fma_f16 v130, v50, v130, 0 op_sel_hi:[0,1,1]
	v_cvt_scalef32_pk_f16_fp4 v131, v151, 1.0 op_sel:[1,0,0]
	v_pk_fma_f16 v129, v50, v134, v129 op_sel:[1,0,0]
	v_cvt_scalef32_pk_f16_fp4 v134, v135, 1.0
	v_pk_fma_f16 v131, v50, v131, 0 op_sel_hi:[0,1,1]
	v_cvt_scalef32_pk_f16_fp4 v132, v151, 1.0 op_sel:[0,1,0]
	v_pk_fma_f16 v130, v50, v134, v130 op_sel:[1,0,0]
	v_cvt_scalef32_pk_f16_fp4 v134, v135, 1.0 op_sel:[1,0,0]
	v_pk_fma_f16 v132, v50, v132, 0 op_sel_hi:[0,1,1]
	v_cvt_scalef32_pk_f16_fp4 v133, v151, 1.0 op_sel:[1,1,0]
	v_pk_fma_f16 v131, v50, v134, v131 op_sel:[1,0,0]
	v_cvt_scalef32_pk_f16_fp4 v134, v135, 1.0 op_sel:[0,1,0]
	v_pk_fma_f16 v133, v50, v133, 0 op_sel_hi:[0,1,1]
	v_cvt_scalef32_pk_f16_fp4 v142, v152, 1.0
	v_pk_fma_f16 v132, v50, v134, v132 op_sel:[1,0,0]
	v_cvt_scalef32_pk_f16_fp4 v134, v135, 1.0 op_sel:[1,1,0]
	v_pk_fma_f16 v142, v50, v142, 0 op_sel_hi:[0,1,1]
	v_cvt_scalef32_pk_f16_fp4 v143, v152, 1.0 op_sel:[1,0,0]
	v_cvt_scalef32_pk_f16_fp4 v144, v152, 1.0 op_sel:[0,1,0]
	v_cvt_scalef32_pk_f16_fp4 v145, v152, 1.0 op_sel:[1,1,0]
	v_pk_fma_f16 v133, v50, v134, v133 op_sel:[1,0,0]
	v_cvt_scalef32_pk_f16_fp4 v134, v136, 1.0
	v_pk_fma_f16 v143, v50, v143, 0 op_sel_hi:[0,1,1]
	v_pk_fma_f16 v144, v50, v144, 0 op_sel_hi:[0,1,1]
	v_pk_fma_f16 v145, v50, v145, 0 op_sel_hi:[0,1,1]
	v_cvt_scalef32_pk_f16_fp4 v146, v153, 1.0
	v_cvt_scalef32_pk_f16_fp4 v147, v153, 1.0 op_sel:[1,0,0]
	v_cvt_scalef32_pk_f16_fp4 v148, v153, 1.0 op_sel:[0,1,0]
	v_cvt_scalef32_pk_f16_fp4 v149, v153, 1.0 op_sel:[1,1,0]
	v_pk_fma_f16 v134, v50, v134, v142 op_sel:[1,0,0]
	v_cvt_scalef32_pk_f16_fp4 v135, v136, 1.0 op_sel:[1,0,0]
	v_cvt_scalef32_pk_f16_fp4 v142, v136, 1.0 op_sel:[0,1,0]
	v_cvt_scalef32_pk_f16_fp4 v136, v136, 1.0 op_sel:[1,1,0]
	v_pk_fma_f16 v128, v50, v128, 0 op_sel_hi:[0,1,1]
	v_pk_fma_f16 v146, v50, v146, 0 op_sel_hi:[0,1,1]
	v_pk_fma_f16 v147, v50, v147, 0 op_sel_hi:[0,1,1]
	v_pk_fma_f16 v148, v50, v148, 0 op_sel_hi:[0,1,1]
	v_pk_fma_f16 v149, v50, v149, 0 op_sel_hi:[0,1,1]
	v_pk_fma_f16 v135, v50, v135, v143 op_sel:[1,0,0]
	v_pk_fma_f16 v142, v50, v142, v144 op_sel:[1,0,0]
	v_pk_fma_f16 v136, v50, v136, v145 op_sel:[1,0,0]
	v_cvt_scalef32_pk_f16_fp4 v143, v137, 1.0
	v_cvt_scalef32_pk_f16_fp4 v144, v137, 1.0 op_sel:[1,0,0]
	v_cvt_scalef32_pk_f16_fp4 v145, v137, 1.0 op_sel:[0,1,0]
	v_cvt_scalef32_pk_f16_fp4 v137, v137, 1.0 op_sel:[1,1,0]
	v_pk_fma_f16 v128, v50, v150, v128 op_sel:[1,0,0]
	v_pk_fma_f16 v143, v50, v143, v146 op_sel:[1,0,0]
	v_pk_fma_f16 v144, v50, v144, v147 op_sel:[1,0,0]
	v_pk_fma_f16 v145, v50, v145, v148 op_sel:[1,0,0]
	v_pk_fma_f16 v50, v50, v137, v149 op_sel:[1,0,0]
	s_waitcnt vmcnt(37)
	v_cvt_scalef32_pk_f16_fp4 v137, v118, 1.0
	v_pk_fma_f16 v126, v51, v137, v126 op_sel_hi:[0,1,1]
	v_cvt_scalef32_pk_f16_fp4 v137, v118, 1.0 op_sel:[1,0,0]
	v_pk_fma_f16 v127, v51, v137, v127 op_sel_hi:[0,1,1]
	v_cvt_scalef32_pk_f16_fp4 v137, v118, 1.0 op_sel:[0,1,0]
	v_cvt_scalef32_pk_f16_fp4 v118, v118, 1.0 op_sel:[1,1,0]
	v_pk_fma_f16 v118, v51, v118, v129 op_sel_hi:[0,1,1]
	v_cvt_scalef32_pk_f16_fp4 v129, v119, 1.0
	v_pk_fma_f16 v129, v51, v129, v130 op_sel_hi:[0,1,1]
	v_cvt_scalef32_pk_f16_fp4 v130, v119, 1.0 op_sel:[1,0,0]
	v_pk_fma_f16 v130, v51, v130, v131 op_sel_hi:[0,1,1]
	v_cvt_scalef32_pk_f16_fp4 v131, v119, 1.0 op_sel:[0,1,0]
	v_pk_fma_f16 v131, v51, v131, v132 op_sel_hi:[0,1,1]
	v_cvt_scalef32_pk_f16_fp4 v119, v119, 1.0 op_sel:[1,1,0]
	v_cvt_scalef32_pk_f16_fp4 v132, v120, 1.0
	v_pk_fma_f16 v119, v51, v119, v133 op_sel_hi:[0,1,1]
	v_pk_fma_f16 v132, v51, v132, v134 op_sel_hi:[0,1,1]
	v_cvt_scalef32_pk_f16_fp4 v133, v120, 1.0 op_sel:[1,0,0]
	v_cvt_scalef32_pk_f16_fp4 v134, v120, 1.0 op_sel:[0,1,0]
	v_cvt_scalef32_pk_f16_fp4 v120, v120, 1.0 op_sel:[1,1,0]
	v_pk_fma_f16 v128, v51, v137, v128 op_sel_hi:[0,1,1]
	v_pk_fma_f16 v133, v51, v133, v135 op_sel_hi:[0,1,1]
	v_pk_fma_f16 v120, v51, v120, v136 op_sel_hi:[0,1,1]
	v_cvt_scalef32_pk_f16_fp4 v135, v121, 1.0
	v_cvt_scalef32_pk_f16_fp4 v136, v121, 1.0 op_sel:[1,0,0]
	v_cvt_scalef32_pk_f16_fp4 v137, v121, 1.0 op_sel:[0,1,0]
	v_cvt_scalef32_pk_f16_fp4 v121, v121, 1.0 op_sel:[1,1,0]
	v_pk_fma_f16 v50, v51, v121, v50 op_sel_hi:[0,1,1]
	s_waitcnt vmcnt(36)
	v_cvt_scalef32_pk_f16_fp4 v121, v110, 1.0
	v_pk_fma_f16 v121, v51, v121, v126 op_sel:[1,0,0]
	v_cvt_scalef32_pk_f16_fp4 v126, v110, 1.0 op_sel:[1,0,0]
	v_pk_fma_f16 v126, v51, v126, v127 op_sel:[1,0,0]
	v_cvt_scalef32_pk_f16_fp4 v127, v110, 1.0 op_sel:[0,1,0]
	v_cvt_scalef32_pk_f16_fp4 v110, v110, 1.0 op_sel:[1,1,0]
	v_pk_fma_f16 v110, v51, v110, v118 op_sel:[1,0,0]
	v_cvt_scalef32_pk_f16_fp4 v118, v111, 1.0
	v_pk_fma_f16 v127, v51, v127, v128 op_sel:[1,0,0]
	v_pk_fma_f16 v118, v51, v118, v129 op_sel:[1,0,0]
	v_cvt_scalef32_pk_f16_fp4 v128, v111, 1.0 op_sel:[1,0,0]
	v_cvt_scalef32_pk_f16_fp4 v129, v111, 1.0 op_sel:[0,1,0]
	v_cvt_scalef32_pk_f16_fp4 v111, v111, 1.0 op_sel:[1,1,0]
	v_pk_fma_f16 v128, v51, v128, v130 op_sel:[1,0,0]
	v_pk_fma_f16 v129, v51, v129, v131 op_sel:[1,0,0]
	v_pk_fma_f16 v111, v51, v111, v119 op_sel:[1,0,0]
	v_cvt_scalef32_pk_f16_fp4 v119, v112, 1.0
	v_cvt_scalef32_pk_f16_fp4 v130, v112, 1.0 op_sel:[1,0,0]
	v_cvt_scalef32_pk_f16_fp4 v131, v112, 1.0 op_sel:[0,1,0]
	v_cvt_scalef32_pk_f16_fp4 v112, v112, 1.0 op_sel:[1,1,0]
	v_pk_fma_f16 v134, v51, v134, v142 op_sel_hi:[0,1,1]
	v_pk_fma_f16 v135, v51, v135, v143 op_sel_hi:[0,1,1]
	v_pk_fma_f16 v136, v51, v136, v144 op_sel_hi:[0,1,1]
	v_pk_fma_f16 v137, v51, v137, v145 op_sel_hi:[0,1,1]
	v_pk_fma_f16 v119, v51, v119, v132 op_sel:[1,0,0]
	v_pk_fma_f16 v130, v51, v130, v133 op_sel:[1,0,0]
	v_pk_fma_f16 v112, v51, v112, v120 op_sel:[1,0,0]
	v_cvt_scalef32_pk_f16_fp4 v120, v113, 1.0
	v_cvt_scalef32_pk_f16_fp4 v132, v113, 1.0 op_sel:[1,0,0]
	v_cvt_scalef32_pk_f16_fp4 v133, v113, 1.0 op_sel:[0,1,0]
	v_cvt_scalef32_pk_f16_fp4 v113, v113, 1.0 op_sel:[1,1,0]
	v_pk_fma_f16 v131, v51, v131, v134 op_sel:[1,0,0]
	v_pk_fma_f16 v120, v51, v120, v135 op_sel:[1,0,0]
	v_pk_fma_f16 v132, v51, v132, v136 op_sel:[1,0,0]
	v_pk_fma_f16 v133, v51, v133, v137 op_sel:[1,0,0]
	v_pk_fma_f16 v50, v51, v113, v50 op_sel:[1,0,0]
	s_waitcnt vmcnt(35)
	v_cvt_scalef32_pk_f16_fp4 v51, v98, 1.0
	v_pk_fma_f16 v51, v52, v51, v121 op_sel_hi:[0,1,1]
	v_cvt_scalef32_pk_f16_fp4 v113, v98, 1.0 op_sel:[1,0,0]
	v_cvt_scalef32_pk_f16_fp4 v121, v98, 1.0 op_sel:[0,1,0]
	v_cvt_scalef32_pk_f16_fp4 v98, v98, 1.0 op_sel:[1,1,0]
	v_pk_fma_f16 v98, v52, v98, v110 op_sel_hi:[0,1,1]
	v_cvt_scalef32_pk_f16_fp4 v110, v99, 1.0
	v_pk_fma_f16 v113, v52, v113, v126 op_sel_hi:[0,1,1]
	v_pk_fma_f16 v110, v52, v110, v118 op_sel_hi:[0,1,1]
	v_cvt_scalef32_pk_f16_fp4 v118, v99, 1.0 op_sel:[1,0,0]
	v_cvt_scalef32_pk_f16_fp4 v126, v99, 1.0 op_sel:[0,1,0]
	v_cvt_scalef32_pk_f16_fp4 v99, v99, 1.0 op_sel:[1,1,0]
	v_pk_fma_f16 v99, v52, v99, v111 op_sel_hi:[0,1,1]
	v_cvt_scalef32_pk_f16_fp4 v111, v100, 1.0
	v_pk_fma_f16 v121, v52, v121, v127 op_sel_hi:[0,1,1]
	v_pk_fma_f16 v111, v52, v111, v119 op_sel_hi:[0,1,1]
	v_cvt_scalef32_pk_f16_fp4 v119, v100, 1.0 op_sel:[1,0,0]
	v_cvt_scalef32_pk_f16_fp4 v127, v100, 1.0 op_sel:[0,1,0]
	v_cvt_scalef32_pk_f16_fp4 v100, v100, 1.0 op_sel:[1,1,0]
	v_pk_fma_f16 v100, v52, v100, v112 op_sel_hi:[0,1,1]
	v_cvt_scalef32_pk_f16_fp4 v112, v101, 1.0
	v_pk_fma_f16 v118, v52, v118, v128 op_sel_hi:[0,1,1]
	v_pk_fma_f16 v112, v52, v112, v120 op_sel_hi:[0,1,1]
	v_cvt_scalef32_pk_f16_fp4 v120, v101, 1.0 op_sel:[1,0,0]
	v_cvt_scalef32_pk_f16_fp4 v128, v101, 1.0 op_sel:[0,1,0]
	v_cvt_scalef32_pk_f16_fp4 v101, v101, 1.0 op_sel:[1,1,0]
	v_pk_fma_f16 v50, v52, v101, v50 op_sel_hi:[0,1,1]
	s_waitcnt vmcnt(34)
	v_cvt_scalef32_pk_f16_fp4 v101, v90, 1.0
	v_pk_fma_f16 v51, v52, v101, v51 op_sel:[1,0,0]
	v_cvt_scalef32_pk_f16_fp4 v101, v90, 1.0 op_sel:[1,0,0]
	v_pk_fma_f16 v101, v52, v101, v113 op_sel:[1,0,0]
	v_cvt_scalef32_pk_f16_fp4 v113, v90, 1.0 op_sel:[0,1,0]
	v_cvt_scalef32_pk_f16_fp4 v90, v90, 1.0 op_sel:[1,1,0]
	v_pk_fma_f16 v90, v52, v90, v98 op_sel:[1,0,0]
	v_cvt_scalef32_pk_f16_fp4 v98, v91, 1.0
	v_pk_fma_f16 v98, v52, v98, v110 op_sel:[1,0,0]
	v_cvt_scalef32_pk_f16_fp4 v110, v91, 1.0 op_sel:[1,0,0]
	v_pk_fma_f16 v110, v52, v110, v118 op_sel:[1,0,0]
	v_cvt_scalef32_pk_f16_fp4 v118, v91, 1.0 op_sel:[0,1,0]
	v_cvt_scalef32_pk_f16_fp4 v91, v91, 1.0 op_sel:[1,1,0]
	v_pk_fma_f16 v91, v52, v91, v99 op_sel:[1,0,0]
	v_cvt_scalef32_pk_f16_fp4 v99, v92, 1.0
	v_pk_fma_f16 v119, v52, v119, v130 op_sel_hi:[0,1,1]
	v_pk_fma_f16 v99, v52, v99, v111 op_sel:[1,0,0]
	v_cvt_scalef32_pk_f16_fp4 v111, v92, 1.0 op_sel:[1,0,0]
	v_pk_fma_f16 v111, v52, v111, v119 op_sel:[1,0,0]
	v_cvt_scalef32_pk_f16_fp4 v119, v92, 1.0 op_sel:[0,1,0]
	v_cvt_scalef32_pk_f16_fp4 v92, v92, 1.0 op_sel:[1,1,0]
	v_pk_fma_f16 v92, v52, v92, v100 op_sel:[1,0,0]
	v_cvt_scalef32_pk_f16_fp4 v100, v93, 1.0
	v_pk_fma_f16 v120, v52, v120, v132 op_sel_hi:[0,1,1]
	v_pk_fma_f16 v100, v52, v100, v112 op_sel:[1,0,0]
	v_cvt_scalef32_pk_f16_fp4 v112, v93, 1.0 op_sel:[1,0,0]
	v_pk_fma_f16 v126, v52, v126, v129 op_sel_hi:[0,1,1]
	v_pk_fma_f16 v127, v52, v127, v131 op_sel_hi:[0,1,1]
	v_pk_fma_f16 v128, v52, v128, v133 op_sel_hi:[0,1,1]
	v_pk_fma_f16 v112, v52, v112, v120 op_sel:[1,0,0]
	v_cvt_scalef32_pk_f16_fp4 v120, v93, 1.0 op_sel:[0,1,0]
	v_cvt_scalef32_pk_f16_fp4 v93, v93, 1.0 op_sel:[1,1,0]
	v_pk_fma_f16 v113, v52, v113, v121 op_sel:[1,0,0]
	v_pk_fma_f16 v118, v52, v118, v126 op_sel:[1,0,0]
	v_pk_fma_f16 v119, v52, v119, v127 op_sel:[1,0,0]
	v_pk_fma_f16 v120, v52, v120, v128 op_sel:[1,0,0]
	v_pk_fma_f16 v50, v52, v93, v50 op_sel:[1,0,0]
	s_waitcnt vmcnt(33)
	v_cvt_scalef32_pk_f16_fp4 v52, v86, 1.0
	v_pk_fma_f16 v51, v53, v52, v51 op_sel_hi:[0,1,1]
	v_cvt_scalef32_pk_f16_fp4 v52, v86, 1.0 op_sel:[1,0,0]
	v_cvt_scalef32_pk_f16_fp4 v93, v86, 1.0 op_sel:[0,1,0]
	v_cvt_scalef32_pk_f16_fp4 v86, v86, 1.0 op_sel:[1,1,0]
	v_pk_fma_f16 v86, v53, v86, v90 op_sel_hi:[0,1,1]
	v_cvt_scalef32_pk_f16_fp4 v90, v87, 1.0
	v_pk_fma_f16 v52, v53, v52, v101 op_sel_hi:[0,1,1]
	v_pk_fma_f16 v90, v53, v90, v98 op_sel_hi:[0,1,1]
	v_cvt_scalef32_pk_f16_fp4 v98, v87, 1.0 op_sel:[1,0,0]
	v_cvt_scalef32_pk_f16_fp4 v101, v87, 1.0 op_sel:[0,1,0]
	v_cvt_scalef32_pk_f16_fp4 v87, v87, 1.0 op_sel:[1,1,0]
	v_pk_fma_f16 v87, v53, v87, v91 op_sel_hi:[0,1,1]
	v_cvt_scalef32_pk_f16_fp4 v91, v88, 1.0
	v_pk_fma_f16 v98, v53, v98, v110 op_sel_hi:[0,1,1]
	v_pk_fma_f16 v91, v53, v91, v99 op_sel_hi:[0,1,1]
	v_cvt_scalef32_pk_f16_fp4 v99, v88, 1.0 op_sel:[1,0,0]
	v_cvt_scalef32_pk_f16_fp4 v110, v88, 1.0 op_sel:[0,1,0]
	v_cvt_scalef32_pk_f16_fp4 v88, v88, 1.0 op_sel:[1,1,0]
	v_pk_fma_f16 v88, v53, v88, v92 op_sel_hi:[0,1,1]
	v_cvt_scalef32_pk_f16_fp4 v92, v89, 1.0
	v_pk_fma_f16 v99, v53, v99, v111 op_sel_hi:[0,1,1]
	v_pk_fma_f16 v92, v53, v92, v100 op_sel_hi:[0,1,1]
	v_cvt_scalef32_pk_f16_fp4 v100, v89, 1.0 op_sel:[1,0,0]
	v_cvt_scalef32_pk_f16_fp4 v111, v89, 1.0 op_sel:[0,1,0]
	v_cvt_scalef32_pk_f16_fp4 v89, v89, 1.0 op_sel:[1,1,0]
	v_pk_fma_f16 v50, v53, v89, v50 op_sel_hi:[0,1,1]
	s_waitcnt vmcnt(32)
	v_cvt_scalef32_pk_f16_fp4 v89, v78, 1.0
	v_pk_fma_f16 v51, v53, v89, v51 op_sel:[1,0,0]
	v_cvt_scalef32_pk_f16_fp4 v89, v78, 1.0 op_sel:[1,0,0]
	v_pk_fma_f16 v52, v53, v89, v52 op_sel:[1,0,0]
	v_cvt_scalef32_pk_f16_fp4 v89, v78, 1.0 op_sel:[0,1,0]
	v_cvt_scalef32_pk_f16_fp4 v78, v78, 1.0 op_sel:[1,1,0]
	v_pk_fma_f16 v93, v53, v93, v113 op_sel_hi:[0,1,1]
	v_pk_fma_f16 v78, v53, v78, v86 op_sel:[1,0,0]
	v_cvt_scalef32_pk_f16_fp4 v86, v79, 1.0
	v_pk_fma_f16 v89, v53, v89, v93 op_sel:[1,0,0]
	v_pk_fma_f16 v86, v53, v86, v90 op_sel:[1,0,0]
	v_cvt_scalef32_pk_f16_fp4 v90, v79, 1.0 op_sel:[1,0,0]
	v_cvt_scalef32_pk_f16_fp4 v93, v79, 1.0 op_sel:[0,1,0]
	v_cvt_scalef32_pk_f16_fp4 v79, v79, 1.0 op_sel:[1,1,0]
	v_pk_fma_f16 v79, v53, v79, v87 op_sel:[1,0,0]
	v_cvt_scalef32_pk_f16_fp4 v87, v80, 1.0
	v_pk_fma_f16 v90, v53, v90, v98 op_sel:[1,0,0]
	v_pk_fma_f16 v87, v53, v87, v91 op_sel:[1,0,0]
	v_cvt_scalef32_pk_f16_fp4 v91, v80, 1.0 op_sel:[1,0,0]
	v_cvt_scalef32_pk_f16_fp4 v98, v80, 1.0 op_sel:[0,1,0]
	v_cvt_scalef32_pk_f16_fp4 v80, v80, 1.0 op_sel:[1,1,0]
	v_pk_fma_f16 v80, v53, v80, v88 op_sel:[1,0,0]
	v_cvt_scalef32_pk_f16_fp4 v88, v81, 1.0
	v_pk_fma_f16 v101, v53, v101, v118 op_sel_hi:[0,1,1]
	v_pk_fma_f16 v110, v53, v110, v119 op_sel_hi:[0,1,1]
	v_pk_fma_f16 v100, v53, v100, v112 op_sel_hi:[0,1,1]
	v_pk_fma_f16 v111, v53, v111, v120 op_sel_hi:[0,1,1]
	v_pk_fma_f16 v91, v53, v91, v99 op_sel:[1,0,0]
	v_pk_fma_f16 v88, v53, v88, v92 op_sel:[1,0,0]
	v_cvt_scalef32_pk_f16_fp4 v92, v81, 1.0 op_sel:[1,0,0]
	v_cvt_scalef32_pk_f16_fp4 v99, v81, 1.0 op_sel:[0,1,0]
	v_cvt_scalef32_pk_f16_fp4 v81, v81, 1.0 op_sel:[1,1,0]
	v_pk_fma_f16 v93, v53, v93, v101 op_sel:[1,0,0]
	v_pk_fma_f16 v98, v53, v98, v110 op_sel:[1,0,0]
	v_pk_fma_f16 v92, v53, v92, v100 op_sel:[1,0,0]
	v_pk_fma_f16 v99, v53, v99, v111 op_sel:[1,0,0]
	v_pk_fma_f16 v50, v53, v81, v50 op_sel:[1,0,0]
	s_waitcnt vmcnt(31)
	v_cvt_scalef32_pk_f16_fp4 v53, v70, 1.0
	v_pk_fma_f16 v51, v10, v53, v51 op_sel_hi:[0,1,1]
	v_cvt_scalef32_pk_f16_fp4 v53, v70, 1.0 op_sel:[1,0,0]
	v_pk_fma_f16 v52, v10, v53, v52 op_sel_hi:[0,1,1]
	v_cvt_scalef32_pk_f16_fp4 v53, v70, 1.0 op_sel:[0,1,0]
	v_cvt_scalef32_pk_f16_fp4 v70, v70, 1.0 op_sel:[1,1,0]
	v_pk_fma_f16 v70, v10, v70, v78 op_sel_hi:[0,1,1]
	v_cvt_scalef32_pk_f16_fp4 v78, v71, 1.0
	v_pk_fma_f16 v78, v10, v78, v86 op_sel_hi:[0,1,1]
	v_cvt_scalef32_pk_f16_fp4 v81, v71, 1.0 op_sel:[1,0,0]
	v_cvt_scalef32_pk_f16_fp4 v86, v71, 1.0 op_sel:[0,1,0]
	v_cvt_scalef32_pk_f16_fp4 v71, v71, 1.0 op_sel:[1,1,0]
	v_pk_fma_f16 v71, v10, v71, v79 op_sel_hi:[0,1,1]
	v_cvt_scalef32_pk_f16_fp4 v79, v72, 1.0
	v_pk_fma_f16 v53, v10, v53, v89 op_sel_hi:[0,1,1]
	v_pk_fma_f16 v79, v10, v79, v87 op_sel_hi:[0,1,1]
	v_cvt_scalef32_pk_f16_fp4 v87, v72, 1.0 op_sel:[1,0,0]
	v_cvt_scalef32_pk_f16_fp4 v89, v72, 1.0 op_sel:[0,1,0]
	v_cvt_scalef32_pk_f16_fp4 v72, v72, 1.0 op_sel:[1,1,0]
	v_pk_fma_f16 v72, v10, v72, v80 op_sel_hi:[0,1,1]
	v_cvt_scalef32_pk_f16_fp4 v80, v73, 1.0
	v_pk_fma_f16 v81, v10, v81, v90 op_sel_hi:[0,1,1]
	v_pk_fma_f16 v80, v10, v80, v88 op_sel_hi:[0,1,1]
	v_cvt_scalef32_pk_f16_fp4 v88, v73, 1.0 op_sel:[1,0,0]
	v_cvt_scalef32_pk_f16_fp4 v90, v73, 1.0 op_sel:[0,1,0]
	v_cvt_scalef32_pk_f16_fp4 v73, v73, 1.0 op_sel:[1,1,0]
	v_pk_fma_f16 v50, v10, v73, v50 op_sel_hi:[0,1,1]
	s_waitcnt vmcnt(30)
	v_cvt_scalef32_pk_f16_fp4 v73, v62, 1.0
	v_pk_fma_f16 v51, v10, v73, v51 op_sel:[1,0,0]
	v_cvt_scalef32_pk_f16_fp4 v73, v62, 1.0 op_sel:[1,0,0]
	v_pk_fma_f16 v52, v10, v73, v52 op_sel:[1,0,0]
	v_cvt_scalef32_pk_f16_fp4 v73, v62, 1.0 op_sel:[0,1,0]
	v_cvt_scalef32_pk_f16_fp4 v62, v62, 1.0 op_sel:[1,1,0]
	v_pk_fma_f16 v62, v10, v62, v70 op_sel:[1,0,0]
	v_cvt_scalef32_pk_f16_fp4 v70, v63, 1.0
	v_pk_fma_f16 v53, v10, v73, v53 op_sel:[1,0,0]
	v_pk_fma_f16 v70, v10, v70, v78 op_sel:[1,0,0]
	v_cvt_scalef32_pk_f16_fp4 v73, v63, 1.0 op_sel:[1,0,0]
	v_cvt_scalef32_pk_f16_fp4 v78, v63, 1.0 op_sel:[0,1,0]
	v_cvt_scalef32_pk_f16_fp4 v63, v63, 1.0 op_sel:[1,1,0]
	v_pk_fma_f16 v63, v10, v63, v71 op_sel:[1,0,0]
	v_cvt_scalef32_pk_f16_fp4 v71, v64, 1.0
	v_pk_fma_f16 v73, v10, v73, v81 op_sel:[1,0,0]
	v_pk_fma_f16 v71, v10, v71, v79 op_sel:[1,0,0]
	v_cvt_scalef32_pk_f16_fp4 v79, v64, 1.0 op_sel:[1,0,0]
	v_cvt_scalef32_pk_f16_fp4 v81, v64, 1.0 op_sel:[0,1,0]
	v_cvt_scalef32_pk_f16_fp4 v64, v64, 1.0 op_sel:[1,1,0]
	v_pk_fma_f16 v86, v10, v86, v93 op_sel_hi:[0,1,1]
	v_pk_fma_f16 v64, v10, v64, v72 op_sel:[1,0,0]
	v_cvt_scalef32_pk_f16_fp4 v72, v65, 1.0
	v_pk_fma_f16 v87, v10, v87, v91 op_sel_hi:[0,1,1]
	v_pk_fma_f16 v89, v10, v89, v98 op_sel_hi:[0,1,1]
	v_pk_fma_f16 v88, v10, v88, v92 op_sel_hi:[0,1,1]
	v_pk_fma_f16 v90, v10, v90, v99 op_sel_hi:[0,1,1]
	v_pk_fma_f16 v78, v10, v78, v86 op_sel:[1,0,0]
	v_pk_fma_f16 v72, v10, v72, v80 op_sel:[1,0,0]
	v_cvt_scalef32_pk_f16_fp4 v80, v65, 1.0 op_sel:[1,0,0]
	v_cvt_scalef32_pk_f16_fp4 v86, v65, 1.0 op_sel:[0,1,0]
	v_cvt_scalef32_pk_f16_fp4 v65, v65, 1.0 op_sel:[1,1,0]
	v_pk_fma_f16 v79, v10, v79, v87 op_sel:[1,0,0]
	v_pk_fma_f16 v81, v10, v81, v89 op_sel:[1,0,0]
	v_pk_fma_f16 v80, v10, v80, v88 op_sel:[1,0,0]
	v_pk_fma_f16 v86, v10, v86, v90 op_sel:[1,0,0]
	v_pk_fma_f16 v10, v10, v65, v50 op_sel:[1,0,0]
	s_waitcnt vmcnt(29)
	v_cvt_scalef32_pk_f16_fp4 v50, v54, 1.0
	v_pk_fma_f16 v50, v11, v50, v51 op_sel_hi:[0,1,1]
	v_cvt_scalef32_pk_f16_fp4 v51, v54, 1.0 op_sel:[1,0,0]
	v_pk_fma_f16 v51, v11, v51, v52 op_sel_hi:[0,1,1]
	v_cvt_scalef32_pk_f16_fp4 v52, v54, 1.0 op_sel:[0,1,0]
	v_pk_fma_f16 v52, v11, v52, v53 op_sel_hi:[0,1,1]
	v_cvt_scalef32_pk_f16_fp4 v53, v54, 1.0 op_sel:[1,1,0]
	v_pk_fma_f16 v53, v11, v53, v62 op_sel_hi:[0,1,1]
	v_cvt_scalef32_pk_f16_fp4 v54, v55, 1.0
	v_cvt_scalef32_pk_f16_fp4 v62, v55, 1.0 op_sel:[1,0,0]
	v_cvt_scalef32_pk_f16_fp4 v65, v55, 1.0 op_sel:[0,1,0]
	v_cvt_scalef32_pk_f16_fp4 v55, v55, 1.0 op_sel:[1,1,0]
	v_pk_fma_f16 v55, v11, v55, v63 op_sel_hi:[0,1,1]
	v_cvt_scalef32_pk_f16_fp4 v63, v56, 1.0
	v_pk_fma_f16 v54, v11, v54, v70 op_sel_hi:[0,1,1]
	v_pk_fma_f16 v63, v11, v63, v71 op_sel_hi:[0,1,1]
	v_cvt_scalef32_pk_f16_fp4 v70, v56, 1.0 op_sel:[1,0,0]
	v_cvt_scalef32_pk_f16_fp4 v71, v56, 1.0 op_sel:[0,1,0]
	v_cvt_scalef32_pk_f16_fp4 v56, v56, 1.0 op_sel:[1,1,0]
	v_pk_fma_f16 v56, v11, v56, v64 op_sel_hi:[0,1,1]
	v_cvt_scalef32_pk_f16_fp4 v64, v57, 1.0
	v_pk_fma_f16 v62, v11, v62, v73 op_sel_hi:[0,1,1]
	v_pk_fma_f16 v64, v11, v64, v72 op_sel_hi:[0,1,1]
	v_cvt_scalef32_pk_f16_fp4 v72, v57, 1.0 op_sel:[1,0,0]
	v_cvt_scalef32_pk_f16_fp4 v73, v57, 1.0 op_sel:[0,1,0]
	v_cvt_scalef32_pk_f16_fp4 v57, v57, 1.0 op_sel:[1,1,0]
	v_pk_fma_f16 v10, v11, v57, v10 op_sel_hi:[0,1,1]
	s_waitcnt vmcnt(28)
	v_cvt_scalef32_pk_f16_fp4 v57, v42, 1.0
	v_pk_fma_f16 v50, v11, v57, v50 op_sel:[1,0,0]
	v_cvt_scalef32_pk_f16_fp4 v57, v42, 1.0 op_sel:[1,0,0]
	v_pk_fma_f16 v51, v11, v57, v51 op_sel:[1,0,0]
	v_cvt_scalef32_pk_f16_fp4 v57, v42, 1.0 op_sel:[0,1,0]
	v_cvt_scalef32_pk_f16_fp4 v42, v42, 1.0 op_sel:[1,1,0]
	v_pk_fma_f16 v42, v11, v42, v53 op_sel:[1,0,0]
	v_cvt_scalef32_pk_f16_fp4 v53, v43, 1.0
	v_pk_fma_f16 v52, v11, v57, v52 op_sel:[1,0,0]
	v_pk_fma_f16 v53, v11, v53, v54 op_sel:[1,0,0]
	v_cvt_scalef32_pk_f16_fp4 v54, v43, 1.0 op_sel:[1,0,0]
	v_cvt_scalef32_pk_f16_fp4 v57, v43, 1.0 op_sel:[0,1,0]
	v_cvt_scalef32_pk_f16_fp4 v43, v43, 1.0 op_sel:[1,1,0]
	v_pk_fma_f16 v43, v11, v43, v55 op_sel:[1,0,0]
	v_cvt_scalef32_pk_f16_fp4 v55, v44, 1.0
	v_pk_fma_f16 v54, v11, v54, v62 op_sel:[1,0,0]
	v_pk_fma_f16 v55, v11, v55, v63 op_sel:[1,0,0]
	v_cvt_scalef32_pk_f16_fp4 v62, v44, 1.0 op_sel:[1,0,0]
	v_cvt_scalef32_pk_f16_fp4 v63, v44, 1.0 op_sel:[0,1,0]
	v_cvt_scalef32_pk_f16_fp4 v44, v44, 1.0 op_sel:[1,1,0]
	v_pk_fma_f16 v65, v11, v65, v78 op_sel_hi:[0,1,1]
	v_pk_fma_f16 v44, v11, v44, v56 op_sel:[1,0,0]
	v_cvt_scalef32_pk_f16_fp4 v56, v45, 1.0
	v_pk_fma_f16 v70, v11, v70, v79 op_sel_hi:[0,1,1]
	v_pk_fma_f16 v71, v11, v71, v81 op_sel_hi:[0,1,1]
	v_pk_fma_f16 v72, v11, v72, v80 op_sel_hi:[0,1,1]
	v_pk_fma_f16 v73, v11, v73, v86 op_sel_hi:[0,1,1]
	v_pk_fma_f16 v57, v11, v57, v65 op_sel:[1,0,0]
	v_pk_fma_f16 v56, v11, v56, v64 op_sel:[1,0,0]
	v_cvt_scalef32_pk_f16_fp4 v64, v45, 1.0 op_sel:[1,0,0]
	v_cvt_scalef32_pk_f16_fp4 v65, v45, 1.0 op_sel:[0,1,0]
	v_cvt_scalef32_pk_f16_fp4 v45, v45, 1.0 op_sel:[1,1,0]
	v_pk_fma_f16 v62, v11, v62, v70 op_sel:[1,0,0]
	v_pk_fma_f16 v63, v11, v63, v71 op_sel:[1,0,0]
	v_pk_fma_f16 v64, v11, v64, v72 op_sel:[1,0,0]
	v_pk_fma_f16 v65, v11, v65, v73 op_sel:[1,0,0]
	v_pk_fma_f16 v10, v11, v45, v10 op_sel:[1,0,0]
	s_waitcnt vmcnt(27)
	v_cvt_scalef32_pk_f16_fp4 v11, v34, 1.0
	v_pk_fma_f16 v11, v12, v11, v50 op_sel_hi:[0,1,1]
	v_cvt_scalef32_pk_f16_fp4 v45, v34, 1.0 op_sel:[1,0,0]
	v_cvt_scalef32_pk_f16_fp4 v50, v34, 1.0 op_sel:[0,1,0]
	v_cvt_scalef32_pk_f16_fp4 v34, v34, 1.0 op_sel:[1,1,0]
	v_pk_fma_f16 v45, v12, v45, v51 op_sel_hi:[0,1,1]
	v_pk_fma_f16 v50, v12, v50, v52 op_sel_hi:[0,1,1]
	v_pk_fma_f16 v34, v12, v34, v42 op_sel_hi:[0,1,1]
	v_cvt_scalef32_pk_f16_fp4 v42, v35, 1.0
	v_cvt_scalef32_pk_f16_fp4 v51, v35, 1.0 op_sel:[1,0,0]
	v_cvt_scalef32_pk_f16_fp4 v52, v35, 1.0 op_sel:[0,1,0]
	v_cvt_scalef32_pk_f16_fp4 v35, v35, 1.0 op_sel:[1,1,0]
	v_pk_fma_f16 v42, v12, v42, v53 op_sel_hi:[0,1,1]
	v_pk_fma_f16 v51, v12, v51, v54 op_sel_hi:[0,1,1]
	v_pk_fma_f16 v35, v12, v35, v43 op_sel_hi:[0,1,1]
	v_cvt_scalef32_pk_f16_fp4 v43, v36, 1.0
	v_cvt_scalef32_pk_f16_fp4 v53, v36, 1.0 op_sel:[1,0,0]
	v_cvt_scalef32_pk_f16_fp4 v54, v36, 1.0 op_sel:[0,1,0]
	v_cvt_scalef32_pk_f16_fp4 v36, v36, 1.0 op_sel:[1,1,0]
	v_pk_fma_f16 v36, v12, v36, v44 op_sel_hi:[0,1,1]
	v_cvt_scalef32_pk_f16_fp4 v44, v37, 1.0
	v_pk_fma_f16 v43, v12, v43, v55 op_sel_hi:[0,1,1]
	v_pk_fma_f16 v44, v12, v44, v56 op_sel_hi:[0,1,1]
	v_cvt_scalef32_pk_f16_fp4 v55, v37, 1.0 op_sel:[1,0,0]
	v_cvt_scalef32_pk_f16_fp4 v56, v37, 1.0 op_sel:[0,1,0]
	v_cvt_scalef32_pk_f16_fp4 v37, v37, 1.0 op_sel:[1,1,0]
	v_pk_fma_f16 v10, v12, v37, v10 op_sel_hi:[0,1,1]
	s_waitcnt vmcnt(26)
	v_cvt_scalef32_pk_f16_fp4 v37, v26, 1.0
	v_pk_fma_f16 v11, v12, v37, v11 op_sel:[1,0,0]
	v_cvt_scalef32_pk_f16_fp4 v37, v26, 1.0 op_sel:[1,0,0]
	v_pk_fma_f16 v37, v12, v37, v45 op_sel:[1,0,0]
	v_cvt_scalef32_pk_f16_fp4 v45, v26, 1.0 op_sel:[0,1,0]
	v_cvt_scalef32_pk_f16_fp4 v26, v26, 1.0 op_sel:[1,1,0]
	v_pk_fma_f16 v26, v12, v26, v34 op_sel:[1,0,0]
	v_cvt_scalef32_pk_f16_fp4 v34, v27, 1.0
	v_pk_fma_f16 v45, v12, v45, v50 op_sel:[1,0,0]
	v_pk_fma_f16 v34, v12, v34, v42 op_sel:[1,0,0]
	v_cvt_scalef32_pk_f16_fp4 v42, v27, 1.0 op_sel:[1,0,0]
	v_cvt_scalef32_pk_f16_fp4 v50, v27, 1.0 op_sel:[0,1,0]
	v_cvt_scalef32_pk_f16_fp4 v27, v27, 1.0 op_sel:[1,1,0]
	v_pk_fma_f16 v27, v12, v27, v35 op_sel:[1,0,0]
	v_cvt_scalef32_pk_f16_fp4 v35, v28, 1.0
	v_pk_fma_f16 v42, v12, v42, v51 op_sel:[1,0,0]
	v_pk_fma_f16 v35, v12, v35, v43 op_sel:[1,0,0]
	v_cvt_scalef32_pk_f16_fp4 v43, v28, 1.0 op_sel:[1,0,0]
	v_cvt_scalef32_pk_f16_fp4 v51, v28, 1.0 op_sel:[0,1,0]
	v_cvt_scalef32_pk_f16_fp4 v28, v28, 1.0 op_sel:[1,1,0]
	v_pk_fma_f16 v52, v12, v52, v57 op_sel_hi:[0,1,1]
	v_pk_fma_f16 v28, v12, v28, v36 op_sel:[1,0,0]
	v_cvt_scalef32_pk_f16_fp4 v36, v29, 1.0
	v_pk_fma_f16 v53, v12, v53, v62 op_sel_hi:[0,1,1]
	v_pk_fma_f16 v54, v12, v54, v63 op_sel_hi:[0,1,1]
	v_pk_fma_f16 v55, v12, v55, v64 op_sel_hi:[0,1,1]
	v_pk_fma_f16 v56, v12, v56, v65 op_sel_hi:[0,1,1]
	v_pk_fma_f16 v50, v12, v50, v52 op_sel:[1,0,0]
	v_pk_fma_f16 v36, v12, v36, v44 op_sel:[1,0,0]
	v_cvt_scalef32_pk_f16_fp4 v44, v29, 1.0 op_sel:[1,0,0]
	v_cvt_scalef32_pk_f16_fp4 v52, v29, 1.0 op_sel:[0,1,0]
	v_cvt_scalef32_pk_f16_fp4 v29, v29, 1.0 op_sel:[1,1,0]
	v_pk_fma_f16 v43, v12, v43, v53 op_sel:[1,0,0]
	v_pk_fma_f16 v51, v12, v51, v54 op_sel:[1,0,0]
	v_pk_fma_f16 v44, v12, v44, v55 op_sel:[1,0,0]
	v_pk_fma_f16 v52, v12, v52, v56 op_sel:[1,0,0]
	v_pk_fma_f16 v10, v12, v29, v10 op_sel:[1,0,0]
	s_waitcnt vmcnt(25)
	v_cvt_scalef32_pk_f16_fp4 v12, v22, 1.0
	v_pk_fma_f16 v11, v13, v12, v11 op_sel_hi:[0,1,1]
	v_cvt_scalef32_pk_f16_fp4 v12, v22, 1.0 op_sel:[1,0,0]
	v_cvt_scalef32_pk_f16_fp4 v29, v22, 1.0 op_sel:[0,1,0]
	v_cvt_scalef32_pk_f16_fp4 v22, v22, 1.0 op_sel:[1,1,0]
	v_pk_fma_f16 v22, v13, v22, v26 op_sel_hi:[0,1,1]
	v_cvt_scalef32_pk_f16_fp4 v26, v23, 1.0
	v_pk_fma_f16 v12, v13, v12, v37 op_sel_hi:[0,1,1]
	v_pk_fma_f16 v26, v13, v26, v34 op_sel_hi:[0,1,1]
	v_cvt_scalef32_pk_f16_fp4 v34, v23, 1.0 op_sel:[1,0,0]
	v_cvt_scalef32_pk_f16_fp4 v37, v23, 1.0 op_sel:[0,1,0]
	v_cvt_scalef32_pk_f16_fp4 v23, v23, 1.0 op_sel:[1,1,0]
	v_pk_fma_f16 v23, v13, v23, v27 op_sel_hi:[0,1,1]
	v_cvt_scalef32_pk_f16_fp4 v27, v24, 1.0
	v_pk_fma_f16 v34, v13, v34, v42 op_sel_hi:[0,1,1]
	v_pk_fma_f16 v27, v13, v27, v35 op_sel_hi:[0,1,1]
	v_cvt_scalef32_pk_f16_fp4 v35, v24, 1.0 op_sel:[1,0,0]
	v_cvt_scalef32_pk_f16_fp4 v42, v24, 1.0 op_sel:[0,1,0]
	v_cvt_scalef32_pk_f16_fp4 v24, v24, 1.0 op_sel:[1,1,0]
	v_pk_fma_f16 v24, v13, v24, v28 op_sel_hi:[0,1,1]
	v_cvt_scalef32_pk_f16_fp4 v28, v25, 1.0
	v_pk_fma_f16 v35, v13, v35, v43 op_sel_hi:[0,1,1]
	v_pk_fma_f16 v28, v13, v28, v36 op_sel_hi:[0,1,1]
	v_cvt_scalef32_pk_f16_fp4 v36, v25, 1.0 op_sel:[1,0,0]
	v_cvt_scalef32_pk_f16_fp4 v43, v25, 1.0 op_sel:[0,1,0]
	v_cvt_scalef32_pk_f16_fp4 v25, v25, 1.0 op_sel:[1,1,0]
	v_pk_fma_f16 v10, v13, v25, v10 op_sel_hi:[0,1,1]
	s_waitcnt vmcnt(24)
	v_cvt_scalef32_pk_f16_fp4 v25, v18, 1.0
	v_pk_fma_f16 v11, v13, v25, v11 op_sel:[1,0,0]
	v_cvt_scalef32_pk_f16_fp4 v25, v18, 1.0 op_sel:[1,0,0]
	v_pk_fma_f16 v12, v13, v25, v12 op_sel:[1,0,0]
	v_cvt_scalef32_pk_f16_fp4 v25, v18, 1.0 op_sel:[0,1,0]
	v_cvt_scalef32_pk_f16_fp4 v18, v18, 1.0 op_sel:[1,1,0]
	v_pk_fma_f16 v29, v13, v29, v45 op_sel_hi:[0,1,1]
	v_pk_fma_f16 v18, v13, v18, v22 op_sel:[1,0,0]
	v_cvt_scalef32_pk_f16_fp4 v22, v19, 1.0
	v_pk_fma_f16 v25, v13, v25, v29 op_sel:[1,0,0]
	v_pk_fma_f16 v22, v13, v22, v26 op_sel:[1,0,0]
	v_cvt_scalef32_pk_f16_fp4 v26, v19, 1.0 op_sel:[1,0,0]
	v_cvt_scalef32_pk_f16_fp4 v29, v19, 1.0 op_sel:[0,1,0]
	v_cvt_scalef32_pk_f16_fp4 v19, v19, 1.0 op_sel:[1,1,0]
	v_pk_fma_f16 v19, v13, v19, v23 op_sel:[1,0,0]
	v_cvt_scalef32_pk_f16_fp4 v23, v20, 1.0
	v_pk_fma_f16 v26, v13, v26, v34 op_sel:[1,0,0]
	v_pk_fma_f16 v23, v13, v23, v27 op_sel:[1,0,0]
	v_cvt_scalef32_pk_f16_fp4 v27, v20, 1.0 op_sel:[1,0,0]
	v_cvt_scalef32_pk_f16_fp4 v34, v20, 1.0 op_sel:[0,1,0]
	v_cvt_scalef32_pk_f16_fp4 v20, v20, 1.0 op_sel:[1,1,0]
	v_pk_fma_f16 v37, v13, v37, v50 op_sel_hi:[0,1,1]
	v_pk_fma_f16 v42, v13, v42, v51 op_sel_hi:[0,1,1]
	v_pk_fma_f16 v43, v13, v43, v52 op_sel_hi:[0,1,1]
	v_pk_fma_f16 v27, v13, v27, v35 op_sel:[1,0,0]
	v_pk_fma_f16 v20, v13, v20, v24 op_sel:[1,0,0]
	v_cvt_scalef32_pk_f16_fp4 v24, v21, 1.0
	v_cvt_scalef32_pk_f16_fp4 v35, v21, 1.0 op_sel:[0,1,0]
	v_pk_fma_f16 v29, v13, v29, v37 op_sel:[1,0,0]
	v_pk_fma_f16 v34, v13, v34, v42 op_sel:[1,0,0]
	v_pk_fma_f16 v24, v13, v24, v28 op_sel:[1,0,0]
	v_cvt_scalef32_pk_f16_fp4 v28, v21, 1.0 op_sel:[1,0,0]
	v_pk_fma_f16 v35, v13, v35, v43 op_sel:[1,0,0]
	v_cvt_scalef32_pk_f16_fp4 v21, v21, 1.0 op_sel:[1,1,0]
	v_pk_fma_f16 v36, v13, v36, v44 op_sel_hi:[0,1,1]
	v_pk_fma_f16 v10, v13, v21, v10 op_sel:[1,0,0]
	v_permlane32_swap_b32_e32 v11, v23
	v_permlane32_swap_b32_e32 v25, v34
	v_permlane32_swap_b32_e32 v18, v20
	v_permlane32_swap_b32_e32 v22, v24
	v_permlane32_swap_b32_e32 v29, v35
	v_pk_fma_f16 v28, v13, v28, v36 op_sel:[1,0,0]
	v_pk_add_f16 v11, v11, v23
	v_pk_add_f16 v13, v25, v34
	v_pk_add_f16 v18, v18, v20
	v_pk_add_f16 v20, v22, v24
	v_pk_add_f16 v22, v29, v35
	v_permlane32_swap_b32_e32 v19, v10
	v_permlane32_swap_b32_e32 v12, v27
	v_permlane32_swap_b32_e32 v26, v28
	v_pk_add_f16 v10, v19, v10
	v_permlane16_swap_b32_e32 v11, v20
	v_permlane16_swap_b32_e32 v13, v22
	v_pk_add_f16 v12, v12, v27
	v_pk_add_f16 v21, v26, v28
	v_pk_add_f16 v11, v11, v20
	v_pk_add_f16 v13, v13, v22
	v_permlane16_swap_b32_e32 v18, v10
	v_permlane16_swap_b32_e32 v12, v21
	v_pk_add_f16 v10, v18, v10
	v_cndmask_b32_e64 v18, v13, v11, s[8:9]
	v_cndmask_b32_e64 v11, v11, v13, s[8:9]
	v_pk_add_f16 v12, v12, v21
	v_cvt_f32_f16_sdwa v19, v203 dst_sel:DWORD dst_unused:UNUSED_PAD src0_sel:WORD_1
	v_mov_b32_dpp v11, v11 row_ror:8 row_mask:0xf bank_mask:0xf bound_ctrl:1
	v_pk_add_f16 v13, v18, v11
	v_cndmask_b32_e64 v11, v10, v12, s[8:9]
	v_cndmask_b32_e64 v10, v12, v10, s[8:9]
	v_cvt_f32_f16_e32 v12, v13
	v_cvt_f32_f16_sdwa v13, v13 dst_sel:DWORD dst_unused:UNUSED_PAD src0_sel:WORD_1
	v_mov_b32_dpp v10, v10 row_ror:8 row_mask:0xf bank_mask:0xf bound_ctrl:1
	v_pk_add_f16 v21, v11, v10
	v_cvt_f32_f16_sdwa v11, v202 dst_sel:DWORD dst_unused:UNUSED_PAD src0_sel:WORD_1
	v_cvt_f32_f16_e32 v10, v202
	v_cvt_f32_f16_e32 v18, v203
	v_cvt_f32_f16_e32 v20, v21
	v_cvt_f32_f16_sdwa v21, v21 dst_sel:DWORD dst_unused:UNUSED_PAD src0_sel:WORD_1
	v_pk_fma_f32 v[10:11], v[2:3], v[12:13], v[10:11]
	s_nop 0
	v_pk_add_f32 v[6:7], v[6:7], v[10:11]
	v_pk_fma_f32 v[10:11], v[4:5], v[20:21], v[18:19]
	v_cvt_pk_f16_f32 v6, v6, v7
	v_pk_add_f32 v[8:9], v[8:9], v[10:11]
	s_nop 0
	v_cvt_pk_f16_f32 v7, v8, v9
	global_store_dwordx2 v[204:205], v[6:7], off
	v_lshl_add_u64 v[6:7], v[192:193], 0, s[24:25]
	global_load_dwordx4 v[126:129], v[6:7], off offset:48
	global_load_dwordx4 v[130:133], v[6:7], off offset:32
	global_load_dwordx4 v[142:145], v[6:7], off offset:16
	global_load_dwordx4 v[146:149], v[6:7], off
	v_lshl_add_u64 v[6:7], v[194:195], 0, s[30:31]
	global_load_dwordx4 v[10:13], v[6:7], off offset:16
	global_load_dwordx4 v[50:53], v[6:7], off
	v_lshl_add_u64 v[6:7], v[196:197], 0, s[28:29]
	v_lshl_add_u64 v[18:19], v[198:199], 0, s[26:27]
	global_load_dwordx4 v[6:9], v[6:7], off
	s_nop 0
	global_load_dwordx2 v[202:203], v[18:19], off
	s_waitcnt vmcnt(29)
	v_lshl_add_u32 v18, v186, 7, v221
	v_lshl_add_u32 v19, v187, 7, v221
	global_load_dwordx4 v[150:153], v18, s[10:11]
	global_load_dwordx4 v[134:137], v19, s[10:11]
	v_lshl_add_u32 v18, v188, 7, v221
	v_lshl_add_u32 v19, v189, 7, v221
	global_load_dwordx4 v[118:121], v18, s[10:11]
	global_load_dwordx4 v[110:113], v19, s[10:11]
	v_lshl_add_u32 v18, v182, 7, v221
	v_lshl_add_u32 v19, v183, 7, v221
	global_load_dwordx4 v[98:101], v18, s[10:11]
	global_load_dwordx4 v[90:93], v19, s[10:11]
	v_lshl_add_u32 v18, v184, 7, v221
	v_lshl_add_u32 v19, v185, 7, v221
	global_load_dwordx4 v[86:89], v18, s[10:11]
	global_load_dwordx4 v[78:81], v19, s[10:11]
	v_lshl_add_u32 v18, v178, 7, v221
	v_lshl_add_u32 v19, v179, 7, v221
	global_load_dwordx4 v[70:73], v18, s[10:11]
	global_load_dwordx4 v[62:65], v19, s[10:11]
	v_lshl_add_u32 v18, v180, 7, v221
	v_lshl_add_u32 v19, v181, 7, v221
	global_load_dwordx4 v[54:57], v18, s[10:11]
	global_load_dwordx4 v[42:45], v19, s[10:11]
	v_lshl_add_u32 v18, v174, 7, v221
	v_lshl_add_u32 v19, v175, 7, v221
	global_load_dwordx4 v[34:37], v18, s[10:11]
	global_load_dwordx4 v[26:29], v19, s[10:11]
	v_lshl_add_u32 v18, v176, 7, v221
	v_lshl_add_u32 v19, v177, 7, v221
	global_load_dwordx4 v[22:25], v18, s[10:11]
	s_nop 0
	global_load_dwordx4 v[18:21], v19, s[10:11]
	s_waitcnt vmcnt(40)
	v_cvt_scalef32_pk_f16_fp4 v174, v170, 1.0
	v_pk_fma_f16 v174, v106, v174, 0 op_sel_hi:[0,1,1]
	v_cvt_scalef32_pk_f16_fp4 v175, v170, 1.0 op_sel:[1,0,0]
	s_waitcnt vmcnt(39)
	v_cvt_scalef32_pk_f16_fp4 v186, v166, 1.0
	v_pk_fma_f16 v175, v106, v175, 0 op_sel_hi:[0,1,1]
	v_cvt_scalef32_pk_f16_fp4 v176, v170, 1.0 op_sel:[0,1,0]
	v_cvt_scalef32_pk_f16_fp4 v170, v170, 1.0 op_sel:[1,1,0]
	v_pk_fma_f16 v174, v106, v186, v174 op_sel:[1,0,0]
	v_cvt_scalef32_pk_f16_fp4 v186, v166, 1.0 op_sel:[1,0,0]
	v_pk_fma_f16 v170, v106, v170, 0 op_sel_hi:[0,1,1]
	v_cvt_scalef32_pk_f16_fp4 v177, v171, 1.0
	v_pk_fma_f16 v175, v106, v186, v175 op_sel:[1,0,0]
	v_cvt_scalef32_pk_f16_fp4 v186, v166, 1.0 op_sel:[0,1,0]
	v_cvt_scalef32_pk_f16_fp4 v166, v166, 1.0 op_sel:[1,1,0]
	v_pk_fma_f16 v177, v106, v177, 0 op_sel_hi:[0,1,1]
	v_cvt_scalef32_pk_f16_fp4 v178, v171, 1.0 op_sel:[1,0,0]
	v_pk_fma_f16 v166, v106, v166, v170 op_sel:[1,0,0]
	v_cvt_scalef32_pk_f16_fp4 v170, v167, 1.0
	v_pk_fma_f16 v178, v106, v178, 0 op_sel_hi:[0,1,1]
	v_cvt_scalef32_pk_f16_fp4 v179, v171, 1.0 op_sel:[0,1,0]
	v_cvt_scalef32_pk_f16_fp4 v171, v171, 1.0 op_sel:[1,1,0]
	v_pk_fma_f16 v170, v106, v170, v177 op_sel:[1,0,0]
	v_cvt_scalef32_pk_f16_fp4 v177, v167, 1.0 op_sel:[1,0,0]
	v_pk_fma_f16 v171, v106, v171, 0 op_sel_hi:[0,1,1]
	v_cvt_scalef32_pk_f16_fp4 v180, v172, 1.0
	v_pk_fma_f16 v177, v106, v177, v178 op_sel:[1,0,0]
	v_cvt_scalef32_pk_f16_fp4 v178, v167, 1.0 op_sel:[0,1,0]
	v_cvt_scalef32_pk_f16_fp4 v167, v167, 1.0 op_sel:[1,1,0]
	v_pk_fma_f16 v179, v106, v179, 0 op_sel_hi:[0,1,1]
	v_pk_fma_f16 v180, v106, v180, 0 op_sel_hi:[0,1,1]
	v_cvt_scalef32_pk_f16_fp4 v181, v172, 1.0 op_sel:[1,0,0]
	v_cvt_scalef32_pk_f16_fp4 v182, v172, 1.0 op_sel:[0,1,0]
	v_cvt_scalef32_pk_f16_fp4 v172, v172, 1.0 op_sel:[1,1,0]
	v_pk_fma_f16 v167, v106, v167, v171 op_sel:[1,0,0]
	v_cvt_scalef32_pk_f16_fp4 v171, v168, 1.0
	v_pk_fma_f16 v181, v106, v181, 0 op_sel_hi:[0,1,1]
	v_pk_fma_f16 v182, v106, v182, 0 op_sel_hi:[0,1,1]
	v_pk_fma_f16 v172, v106, v172, 0 op_sel_hi:[0,1,1]
	v_cvt_scalef32_pk_f16_fp4 v183, v173, 1.0
	v_cvt_scalef32_pk_f16_fp4 v184, v173, 1.0 op_sel:[1,0,0]
	v_cvt_scalef32_pk_f16_fp4 v185, v173, 1.0 op_sel:[0,1,0]
	v_cvt_scalef32_pk_f16_fp4 v173, v173, 1.0 op_sel:[1,1,0]
	v_pk_fma_f16 v178, v106, v178, v179 op_sel:[1,0,0]
	v_pk_fma_f16 v171, v106, v171, v180 op_sel:[1,0,0]
	v_cvt_scalef32_pk_f16_fp4 v179, v168, 1.0 op_sel:[1,0,0]
	v_cvt_scalef32_pk_f16_fp4 v180, v168, 1.0 op_sel:[0,1,0]
	v_cvt_scalef32_pk_f16_fp4 v168, v168, 1.0 op_sel:[1,1,0]
	v_pk_fma_f16 v176, v106, v176, 0 op_sel_hi:[0,1,1]
	v_pk_fma_f16 v183, v106, v183, 0 op_sel_hi:[0,1,1]
	v_pk_fma_f16 v184, v106, v184, 0 op_sel_hi:[0,1,1]
	v_pk_fma_f16 v185, v106, v185, 0 op_sel_hi:[0,1,1]
	v_pk_fma_f16 v173, v106, v173, 0 op_sel_hi:[0,1,1]
	v_pk_fma_f16 v179, v106, v179, v181 op_sel:[1,0,0]
	v_pk_fma_f16 v180, v106, v180, v182 op_sel:[1,0,0]
	v_pk_fma_f16 v168, v106, v168, v172 op_sel:[1,0,0]
	v_cvt_scalef32_pk_f16_fp4 v172, v169, 1.0
	v_cvt_scalef32_pk_f16_fp4 v181, v169, 1.0 op_sel:[1,0,0]
	v_cvt_scalef32_pk_f16_fp4 v182, v169, 1.0 op_sel:[0,1,0]
	v_cvt_scalef32_pk_f16_fp4 v169, v169, 1.0 op_sel:[1,1,0]
	v_pk_fma_f16 v176, v106, v186, v176 op_sel:[1,0,0]
	v_pk_fma_f16 v172, v106, v172, v183 op_sel:[1,0,0]
	v_pk_fma_f16 v181, v106, v181, v184 op_sel:[1,0,0]
	v_pk_fma_f16 v182, v106, v182, v185 op_sel:[1,0,0]
	v_pk_fma_f16 v106, v106, v169, v173 op_sel:[1,0,0]
	s_waitcnt vmcnt(38)
	v_cvt_scalef32_pk_f16_fp4 v169, v162, 1.0
	v_pk_fma_f16 v169, v107, v169, v174 op_sel_hi:[0,1,1]
	v_cvt_scalef32_pk_f16_fp4 v173, v162, 1.0 op_sel:[1,0,0]
	v_cvt_scalef32_pk_f16_fp4 v174, v162, 1.0 op_sel:[0,1,0]
	v_cvt_scalef32_pk_f16_fp4 v162, v162, 1.0 op_sel:[1,1,0]
	v_pk_fma_f16 v162, v107, v162, v166 op_sel_hi:[0,1,1]
	v_cvt_scalef32_pk_f16_fp4 v166, v163, 1.0
	v_pk_fma_f16 v173, v107, v173, v175 op_sel_hi:[0,1,1]
	v_pk_fma_f16 v166, v107, v166, v170 op_sel_hi:[0,1,1]
	v_cvt_scalef32_pk_f16_fp4 v170, v163, 1.0 op_sel:[1,0,0]
	v_cvt_scalef32_pk_f16_fp4 v175, v163, 1.0 op_sel:[0,1,0]
	v_cvt_scalef32_pk_f16_fp4 v163, v163, 1.0 op_sel:[1,1,0]
	v_pk_fma_f16 v163, v107, v163, v167 op_sel_hi:[0,1,1]
	v_cvt_scalef32_pk_f16_fp4 v167, v164, 1.0
	v_pk_fma_f16 v174, v107, v174, v176 op_sel_hi:[0,1,1]
	v_pk_fma_f16 v167, v107, v167, v171 op_sel_hi:[0,1,1]
	v_cvt_scalef32_pk_f16_fp4 v171, v164, 1.0 op_sel:[1,0,0]
	v_cvt_scalef32_pk_f16_fp4 v176, v164, 1.0 op_sel:[0,1,0]
	v_cvt_scalef32_pk_f16_fp4 v164, v164, 1.0 op_sel:[1,1,0]
	v_pk_fma_f16 v164, v107, v164, v168 op_sel_hi:[0,1,1]
	v_cvt_scalef32_pk_f16_fp4 v168, v165, 1.0
	v_pk_fma_f16 v170, v107, v170, v177 op_sel_hi:[0,1,1]
	v_pk_fma_f16 v168, v107, v168, v172 op_sel_hi:[0,1,1]
	v_cvt_scalef32_pk_f16_fp4 v172, v165, 1.0 op_sel:[1,0,0]
	v_cvt_scalef32_pk_f16_fp4 v177, v165, 1.0 op_sel:[0,1,0]
	v_cvt_scalef32_pk_f16_fp4 v165, v165, 1.0 op_sel:[1,1,0]
	v_pk_fma_f16 v106, v107, v165, v106 op_sel_hi:[0,1,1]
	s_waitcnt vmcnt(37)
	v_cvt_scalef32_pk_f16_fp4 v165, v158, 1.0
	v_pk_fma_f16 v165, v107, v165, v169 op_sel:[1,0,0]
	v_cvt_scalef32_pk_f16_fp4 v169, v158, 1.0 op_sel:[1,0,0]
	v_pk_fma_f16 v169, v107, v169, v173 op_sel:[1,0,0]
	v_cvt_scalef32_pk_f16_fp4 v173, v158, 1.0 op_sel:[0,1,0]
	v_cvt_scalef32_pk_f16_fp4 v158, v158, 1.0 op_sel:[1,1,0]
	v_pk_fma_f16 v158, v107, v158, v162 op_sel:[1,0,0]
	v_cvt_scalef32_pk_f16_fp4 v162, v159, 1.0
	v_pk_fma_f16 v162, v107, v162, v166 op_sel:[1,0,0]
	v_cvt_scalef32_pk_f16_fp4 v166, v159, 1.0 op_sel:[1,0,0]
	v_pk_fma_f16 v166, v107, v166, v170 op_sel:[1,0,0]
	v_cvt_scalef32_pk_f16_fp4 v170, v159, 1.0 op_sel:[0,1,0]
	v_cvt_scalef32_pk_f16_fp4 v159, v159, 1.0 op_sel:[1,1,0]
	v_pk_fma_f16 v159, v107, v159, v163 op_sel:[1,0,0]
	v_cvt_scalef32_pk_f16_fp4 v163, v160, 1.0
	v_pk_fma_f16 v171, v107, v171, v179 op_sel_hi:[0,1,1]
	v_pk_fma_f16 v163, v107, v163, v167 op_sel:[1,0,0]
	v_cvt_scalef32_pk_f16_fp4 v167, v160, 1.0 op_sel:[1,0,0]
	v_pk_fma_f16 v167, v107, v167, v171 op_sel:[1,0,0]
	v_cvt_scalef32_pk_f16_fp4 v171, v160, 1.0 op_sel:[0,1,0]
	v_cvt_scalef32_pk_f16_fp4 v160, v160, 1.0 op_sel:[1,1,0]
	v_pk_fma_f16 v160, v107, v160, v164 op_sel:[1,0,0]
	v_cvt_scalef32_pk_f16_fp4 v164, v161, 1.0
	v_pk_fma_f16 v172, v107, v172, v181 op_sel_hi:[0,1,1]
	v_pk_fma_f16 v164, v107, v164, v168 op_sel:[1,0,0]
	v_cvt_scalef32_pk_f16_fp4 v168, v161, 1.0 op_sel:[1,0,0]
	v_pk_fma_f16 v175, v107, v175, v178 op_sel_hi:[0,1,1]
	v_pk_fma_f16 v176, v107, v176, v180 op_sel_hi:[0,1,1]
	v_pk_fma_f16 v177, v107, v177, v182 op_sel_hi:[0,1,1]
	v_pk_fma_f16 v168, v107, v168, v172 op_sel:[1,0,0]
	v_cvt_scalef32_pk_f16_fp4 v172, v161, 1.0 op_sel:[0,1,0]
	v_cvt_scalef32_pk_f16_fp4 v161, v161, 1.0 op_sel:[1,1,0]
	v_pk_fma_f16 v173, v107, v173, v174 op_sel:[1,0,0]
	v_pk_fma_f16 v170, v107, v170, v175 op_sel:[1,0,0]
	v_pk_fma_f16 v171, v107, v171, v176 op_sel:[1,0,0]
	v_pk_fma_f16 v172, v107, v172, v177 op_sel:[1,0,0]
	v_pk_fma_f16 v106, v107, v161, v106 op_sel:[1,0,0]
	s_waitcnt vmcnt(36)
	v_cvt_scalef32_pk_f16_fp4 v107, v154, 1.0
	v_pk_fma_f16 v107, v108, v107, v165 op_sel_hi:[0,1,1]
	v_cvt_scalef32_pk_f16_fp4 v161, v154, 1.0 op_sel:[1,0,0]
	v_cvt_scalef32_pk_f16_fp4 v165, v154, 1.0 op_sel:[0,1,0]
	v_cvt_scalef32_pk_f16_fp4 v154, v154, 1.0 op_sel:[1,1,0]
	v_pk_fma_f16 v154, v108, v154, v158 op_sel_hi:[0,1,1]
	v_cvt_scalef32_pk_f16_fp4 v158, v155, 1.0
	v_pk_fma_f16 v158, v108, v158, v162 op_sel_hi:[0,1,1]
	v_cvt_scalef32_pk_f16_fp4 v162, v155, 1.0 op_sel:[1,0,0]
	v_pk_fma_f16 v162, v108, v162, v166 op_sel_hi:[0,1,1]
	v_cvt_scalef32_pk_f16_fp4 v166, v155, 1.0 op_sel:[0,1,0]
	v_cvt_scalef32_pk_f16_fp4 v155, v155, 1.0 op_sel:[1,1,0]
	v_pk_fma_f16 v155, v108, v155, v159 op_sel_hi:[0,1,1]
	v_cvt_scalef32_pk_f16_fp4 v159, v156, 1.0
	v_pk_fma_f16 v159, v108, v159, v163 op_sel_hi:[0,1,1]
	v_cvt_scalef32_pk_f16_fp4 v163, v156, 1.0 op_sel:[1,0,0]
	v_pk_fma_f16 v163, v108, v163, v167 op_sel_hi:[0,1,1]
	v_cvt_scalef32_pk_f16_fp4 v167, v156, 1.0 op_sel:[0,1,0]
	v_cvt_scalef32_pk_f16_fp4 v156, v156, 1.0 op_sel:[1,1,0]
	v_pk_fma_f16 v156, v108, v156, v160 op_sel_hi:[0,1,1]
	v_cvt_scalef32_pk_f16_fp4 v160, v157, 1.0
	v_pk_fma_f16 v160, v108, v160, v164 op_sel_hi:[0,1,1]
	v_cvt_scalef32_pk_f16_fp4 v164, v157, 1.0 op_sel:[1,0,0]
	v_pk_fma_f16 v164, v108, v164, v168 op_sel_hi:[0,1,1]
	v_cvt_scalef32_pk_f16_fp4 v168, v157, 1.0 op_sel:[0,1,0]
	v_cvt_scalef32_pk_f16_fp4 v157, v157, 1.0 op_sel:[1,1,0]
	v_pk_fma_f16 v106, v108, v157, v106 op_sel_hi:[0,1,1]
	s_waitcnt vmcnt(35)
	v_cvt_scalef32_pk_f16_fp4 v157, v138, 1.0
	v_pk_fma_f16 v161, v108, v161, v169 op_sel_hi:[0,1,1]
	v_pk_fma_f16 v107, v108, v157, v107 op_sel:[1,0,0]
	v_cvt_scalef32_pk_f16_fp4 v157, v138, 1.0 op_sel:[1,0,0]
	v_pk_fma_f16 v157, v108, v157, v161 op_sel:[1,0,0]
	v_cvt_scalef32_pk_f16_fp4 v161, v138, 1.0 op_sel:[0,1,0]
	v_cvt_scalef32_pk_f16_fp4 v138, v138, 1.0 op_sel:[1,1,0]
	v_pk_fma_f16 v138, v108, v138, v154 op_sel:[1,0,0]
	v_cvt_scalef32_pk_f16_fp4 v154, v139, 1.0
	v_pk_fma_f16 v154, v108, v154, v158 op_sel:[1,0,0]
	v_cvt_scalef32_pk_f16_fp4 v158, v139, 1.0 op_sel:[1,0,0]
	v_pk_fma_f16 v158, v108, v158, v162 op_sel:[1,0,0]
	v_cvt_scalef32_pk_f16_fp4 v162, v139, 1.0 op_sel:[0,1,0]
	v_cvt_scalef32_pk_f16_fp4 v139, v139, 1.0 op_sel:[1,1,0]
	v_pk_fma_f16 v139, v108, v139, v155 op_sel:[1,0,0]
	v_cvt_scalef32_pk_f16_fp4 v155, v140, 1.0
	v_pk_fma_f16 v155, v108, v155, v159 op_sel:[1,0,0]
	v_cvt_scalef32_pk_f16_fp4 v159, v140, 1.0 op_sel:[1,0,0]
	v_pk_fma_f16 v159, v108, v159, v163 op_sel:[1,0,0]
	v_cvt_scalef32_pk_f16_fp4 v163, v140, 1.0 op_sel:[0,1,0]
	v_cvt_scalef32_pk_f16_fp4 v140, v140, 1.0 op_sel:[1,1,0]
	v_pk_fma_f16 v140, v108, v140, v156 op_sel:[1,0,0]
	v_cvt_scalef32_pk_f16_fp4 v156, v141, 1.0
	v_pk_fma_f16 v156, v108, v156, v160 op_sel:[1,0,0]
	v_cvt_scalef32_pk_f16_fp4 v160, v141, 1.0 op_sel:[1,0,0]
	v_pk_fma_f16 v165, v108, v165, v173 op_sel_hi:[0,1,1]
	v_pk_fma_f16 v166, v108, v166, v170 op_sel_hi:[0,1,1]
	v_pk_fma_f16 v167, v108, v167, v171 op_sel_hi:[0,1,1]
	v_pk_fma_f16 v168, v108, v168, v172 op_sel_hi:[0,1,1]
	v_pk_fma_f16 v160, v108, v160, v164 op_sel:[1,0,0]
	v_cvt_scalef32_pk_f16_fp4 v164, v141, 1.0 op_sel:[0,1,0]
	v_cvt_scalef32_pk_f16_fp4 v141, v141, 1.0 op_sel:[1,1,0]
	v_pk_fma_f16 v161, v108, v161, v165 op_sel:[1,0,0]
	v_pk_fma_f16 v162, v108, v162, v166 op_sel:[1,0,0]
	v_pk_fma_f16 v163, v108, v163, v167 op_sel:[1,0,0]
	v_pk_fma_f16 v164, v108, v164, v168 op_sel:[1,0,0]
	v_pk_fma_f16 v106, v108, v141, v106 op_sel:[1,0,0]
	s_waitcnt vmcnt(34)
	v_cvt_scalef32_pk_f16_fp4 v108, v122, 1.0
	v_pk_fma_f16 v107, v109, v108, v107 op_sel_hi:[0,1,1]
	v_cvt_scalef32_pk_f16_fp4 v108, v122, 1.0 op_sel:[1,0,0]
	v_cvt_scalef32_pk_f16_fp4 v141, v122, 1.0 op_sel:[0,1,0]
	v_cvt_scalef32_pk_f16_fp4 v122, v122, 1.0 op_sel:[1,1,0]
	v_pk_fma_f16 v122, v109, v122, v138 op_sel_hi:[0,1,1]
	v_cvt_scalef32_pk_f16_fp4 v138, v123, 1.0
	v_pk_fma_f16 v108, v109, v108, v157 op_sel_hi:[0,1,1]
	v_pk_fma_f16 v138, v109, v138, v154 op_sel_hi:[0,1,1]
	v_cvt_scalef32_pk_f16_fp4 v154, v123, 1.0 op_sel:[1,0,0]
	v_cvt_scalef32_pk_f16_fp4 v157, v123, 1.0 op_sel:[0,1,0]
	v_cvt_scalef32_pk_f16_fp4 v123, v123, 1.0 op_sel:[1,1,0]
	v_pk_fma_f16 v123, v109, v123, v139 op_sel_hi:[0,1,1]
	v_cvt_scalef32_pk_f16_fp4 v139, v124, 1.0
	v_pk_fma_f16 v154, v109, v154, v158 op_sel_hi:[0,1,1]
	v_pk_fma_f16 v139, v109, v139, v155 op_sel_hi:[0,1,1]
	v_cvt_scalef32_pk_f16_fp4 v155, v124, 1.0 op_sel:[1,0,0]
	v_cvt_scalef32_pk_f16_fp4 v158, v124, 1.0 op_sel:[0,1,0]
	v_cvt_scalef32_pk_f16_fp4 v124, v124, 1.0 op_sel:[1,1,0]
	v_pk_fma_f16 v124, v109, v124, v140 op_sel_hi:[0,1,1]
	v_cvt_scalef32_pk_f16_fp4 v140, v125, 1.0
	v_pk_fma_f16 v155, v109, v155, v159 op_sel_hi:[0,1,1]
	v_pk_fma_f16 v140, v109, v140, v156 op_sel_hi:[0,1,1]
	v_cvt_scalef32_pk_f16_fp4 v156, v125, 1.0 op_sel:[1,0,0]
	v_cvt_scalef32_pk_f16_fp4 v159, v125, 1.0 op_sel:[0,1,0]
	v_cvt_scalef32_pk_f16_fp4 v125, v125, 1.0 op_sel:[1,1,0]
	v_pk_fma_f16 v106, v109, v125, v106 op_sel_hi:[0,1,1]
	s_waitcnt vmcnt(33)
	v_cvt_scalef32_pk_f16_fp4 v125, v114, 1.0
	v_pk_fma_f16 v107, v109, v125, v107 op_sel:[1,0,0]
	v_cvt_scalef32_pk_f16_fp4 v125, v114, 1.0 op_sel:[1,0,0]
	v_pk_fma_f16 v108, v109, v125, v108 op_sel:[1,0,0]
	v_cvt_scalef32_pk_f16_fp4 v125, v114, 1.0 op_sel:[0,1,0]
	v_cvt_scalef32_pk_f16_fp4 v114, v114, 1.0 op_sel:[1,1,0]
	v_pk_fma_f16 v141, v109, v141, v161 op_sel_hi:[0,1,1]
	v_pk_fma_f16 v114, v109, v114, v122 op_sel:[1,0,0]
	v_cvt_scalef32_pk_f16_fp4 v122, v115, 1.0
	v_pk_fma_f16 v125, v109, v125, v141 op_sel:[1,0,0]
	v_pk_fma_f16 v122, v109, v122, v138 op_sel:[1,0,0]
	v_cvt_scalef32_pk_f16_fp4 v138, v115, 1.0 op_sel:[1,0,0]
	v_cvt_scalef32_pk_f16_fp4 v141, v115, 1.0 op_sel:[0,1,0]
	v_cvt_scalef32_pk_f16_fp4 v115, v115, 1.0 op_sel:[1,1,0]
	v_pk_fma_f16 v115, v109, v115, v123 op_sel:[1,0,0]
	v_cvt_scalef32_pk_f16_fp4 v123, v116, 1.0
	v_pk_fma_f16 v138, v109, v138, v154 op_sel:[1,0,0]
	v_pk_fma_f16 v123, v109, v123, v139 op_sel:[1,0,0]
	v_cvt_scalef32_pk_f16_fp4 v139, v116, 1.0 op_sel:[1,0,0]
	v_cvt_scalef32_pk_f16_fp4 v154, v116, 1.0 op_sel:[0,1,0]
	v_cvt_scalef32_pk_f16_fp4 v116, v116, 1.0 op_sel:[1,1,0]
	v_pk_fma_f16 v116, v109, v116, v124 op_sel:[1,0,0]
	v_cvt_scalef32_pk_f16_fp4 v124, v117, 1.0
	v_pk_fma_f16 v157, v109, v157, v162 op_sel_hi:[0,1,1]
	v_pk_fma_f16 v158, v109, v158, v163 op_sel_hi:[0,1,1]
	v_pk_fma_f16 v156, v109, v156, v160 op_sel_hi:[0,1,1]
	v_pk_fma_f16 v159, v109, v159, v164 op_sel_hi:[0,1,1]
	v_pk_fma_f16 v139, v109, v139, v155 op_sel:[1,0,0]
	v_pk_fma_f16 v124, v109, v124, v140 op_sel:[1,0,0]
	v_cvt_scalef32_pk_f16_fp4 v140, v117, 1.0 op_sel:[1,0,0]
	v_cvt_scalef32_pk_f16_fp4 v155, v117, 1.0 op_sel:[0,1,0]
	v_cvt_scalef32_pk_f16_fp4 v117, v117, 1.0 op_sel:[1,1,0]
	v_pk_fma_f16 v141, v109, v141, v157 op_sel:[1,0,0]
	v_pk_fma_f16 v154, v109, v154, v158 op_sel:[1,0,0]
	v_pk_fma_f16 v140, v109, v140, v156 op_sel:[1,0,0]
	v_pk_fma_f16 v155, v109, v155, v159 op_sel:[1,0,0]
	v_pk_fma_f16 v106, v109, v117, v106 op_sel:[1,0,0]
	s_waitcnt vmcnt(32)
	v_cvt_scalef32_pk_f16_fp4 v109, v102, 1.0
	v_pk_fma_f16 v107, v30, v109, v107 op_sel_hi:[0,1,1]
	v_cvt_scalef32_pk_f16_fp4 v109, v102, 1.0 op_sel:[1,0,0]
	v_pk_fma_f16 v108, v30, v109, v108 op_sel_hi:[0,1,1]
	v_cvt_scalef32_pk_f16_fp4 v109, v102, 1.0 op_sel:[0,1,0]
	v_cvt_scalef32_pk_f16_fp4 v102, v102, 1.0 op_sel:[1,1,0]
	v_pk_fma_f16 v102, v30, v102, v114 op_sel_hi:[0,1,1]
	v_cvt_scalef32_pk_f16_fp4 v114, v103, 1.0
	v_pk_fma_f16 v114, v30, v114, v122 op_sel_hi:[0,1,1]
	v_cvt_scalef32_pk_f16_fp4 v117, v103, 1.0 op_sel:[1,0,0]
	v_cvt_scalef32_pk_f16_fp4 v122, v103, 1.0 op_sel:[0,1,0]
	v_cvt_scalef32_pk_f16_fp4 v103, v103, 1.0 op_sel:[1,1,0]
	v_pk_fma_f16 v103, v30, v103, v115 op_sel_hi:[0,1,1]
	v_cvt_scalef32_pk_f16_fp4 v115, v104, 1.0
	v_pk_fma_f16 v109, v30, v109, v125 op_sel_hi:[0,1,1]
	v_pk_fma_f16 v115, v30, v115, v123 op_sel_hi:[0,1,1]
	v_cvt_scalef32_pk_f16_fp4 v123, v104, 1.0 op_sel:[1,0,0]
	v_cvt_scalef32_pk_f16_fp4 v125, v104, 1.0 op_sel:[0,1,0]
	v_cvt_scalef32_pk_f16_fp4 v104, v104, 1.0 op_sel:[1,1,0]
	v_pk_fma_f16 v104, v30, v104, v116 op_sel_hi:[0,1,1]
	v_cvt_scalef32_pk_f16_fp4 v116, v105, 1.0
	v_pk_fma_f16 v117, v30, v117, v138 op_sel_hi:[0,1,1]
	v_pk_fma_f16 v116, v30, v116, v124 op_sel_hi:[0,1,1]
	v_cvt_scalef32_pk_f16_fp4 v124, v105, 1.0 op_sel:[1,0,0]
	v_cvt_scalef32_pk_f16_fp4 v138, v105, 1.0 op_sel:[0,1,0]
	v_cvt_scalef32_pk_f16_fp4 v105, v105, 1.0 op_sel:[1,1,0]
	v_pk_fma_f16 v105, v30, v105, v106 op_sel_hi:[0,1,1]
	s_waitcnt vmcnt(31)
	v_cvt_scalef32_pk_f16_fp4 v106, v94, 1.0
	v_pk_fma_f16 v106, v30, v106, v107 op_sel:[1,0,0]
	v_cvt_scalef32_pk_f16_fp4 v107, v94, 1.0 op_sel:[1,0,0]
	v_pk_fma_f16 v107, v30, v107, v108 op_sel:[1,0,0]
	v_cvt_scalef32_pk_f16_fp4 v108, v94, 1.0 op_sel:[0,1,0]
	v_cvt_scalef32_pk_f16_fp4 v94, v94, 1.0 op_sel:[1,1,0]
	v_pk_fma_f16 v94, v30, v94, v102 op_sel:[1,0,0]
	v_cvt_scalef32_pk_f16_fp4 v102, v95, 1.0
	v_pk_fma_f16 v108, v30, v108, v109 op_sel:[1,0,0]
	v_pk_fma_f16 v102, v30, v102, v114 op_sel:[1,0,0]
	v_cvt_scalef32_pk_f16_fp4 v109, v95, 1.0 op_sel:[1,0,0]
	v_cvt_scalef32_pk_f16_fp4 v114, v95, 1.0 op_sel:[0,1,0]
	v_cvt_scalef32_pk_f16_fp4 v95, v95, 1.0 op_sel:[1,1,0]
	v_pk_fma_f16 v95, v30, v95, v103 op_sel:[1,0,0]
	v_cvt_scalef32_pk_f16_fp4 v103, v96, 1.0
	v_pk_fma_f16 v109, v30, v109, v117 op_sel:[1,0,0]
	v_pk_fma_f16 v103, v30, v103, v115 op_sel:[1,0,0]
	v_cvt_scalef32_pk_f16_fp4 v115, v96, 1.0 op_sel:[1,0,0]
	v_cvt_scalef32_pk_f16_fp4 v117, v96, 1.0 op_sel:[0,1,0]
	v_cvt_scalef32_pk_f16_fp4 v96, v96, 1.0 op_sel:[1,1,0]
	v_pk_fma_f16 v122, v30, v122, v141 op_sel_hi:[0,1,1]
	v_pk_fma_f16 v96, v30, v96, v104 op_sel:[1,0,0]
	v_cvt_scalef32_pk_f16_fp4 v104, v97, 1.0
	v_pk_fma_f16 v123, v30, v123, v139 op_sel_hi:[0,1,1]
	v_pk_fma_f16 v125, v30, v125, v154 op_sel_hi:[0,1,1]
	v_pk_fma_f16 v124, v30, v124, v140 op_sel_hi:[0,1,1]
	v_pk_fma_f16 v138, v30, v138, v155 op_sel_hi:[0,1,1]
	v_pk_fma_f16 v114, v30, v114, v122 op_sel:[1,0,0]
	v_pk_fma_f16 v104, v30, v104, v116 op_sel:[1,0,0]
	v_cvt_scalef32_pk_f16_fp4 v116, v97, 1.0 op_sel:[1,0,0]
	v_cvt_scalef32_pk_f16_fp4 v122, v97, 1.0 op_sel:[0,1,0]
	v_cvt_scalef32_pk_f16_fp4 v97, v97, 1.0 op_sel:[1,1,0]
	v_pk_fma_f16 v115, v30, v115, v123 op_sel:[1,0,0]
	v_pk_fma_f16 v117, v30, v117, v125 op_sel:[1,0,0]
	v_pk_fma_f16 v116, v30, v116, v124 op_sel:[1,0,0]
	v_pk_fma_f16 v122, v30, v122, v138 op_sel:[1,0,0]
	v_pk_fma_f16 v30, v30, v97, v105 op_sel:[1,0,0]
	s_waitcnt vmcnt(30)
	v_cvt_scalef32_pk_f16_fp4 v97, v82, 1.0
	v_pk_fma_f16 v97, v31, v97, v106 op_sel_hi:[0,1,1]
	v_cvt_scalef32_pk_f16_fp4 v105, v82, 1.0 op_sel:[1,0,0]
	v_cvt_scalef32_pk_f16_fp4 v106, v82, 1.0 op_sel:[0,1,0]
	v_cvt_scalef32_pk_f16_fp4 v82, v82, 1.0 op_sel:[1,1,0]
	v_pk_fma_f16 v82, v31, v82, v94 op_sel_hi:[0,1,1]
	v_cvt_scalef32_pk_f16_fp4 v94, v83, 1.0
	v_pk_fma_f16 v105, v31, v105, v107 op_sel_hi:[0,1,1]
	v_pk_fma_f16 v94, v31, v94, v102 op_sel_hi:[0,1,1]
	v_cvt_scalef32_pk_f16_fp4 v102, v83, 1.0 op_sel:[1,0,0]
	v_cvt_scalef32_pk_f16_fp4 v107, v83, 1.0 op_sel:[0,1,0]
	v_cvt_scalef32_pk_f16_fp4 v83, v83, 1.0 op_sel:[1,1,0]
	v_pk_fma_f16 v83, v31, v83, v95 op_sel_hi:[0,1,1]
	v_cvt_scalef32_pk_f16_fp4 v95, v84, 1.0
	v_pk_fma_f16 v106, v31, v106, v108 op_sel_hi:[0,1,1]
	v_pk_fma_f16 v95, v31, v95, v103 op_sel_hi:[0,1,1]
	v_cvt_scalef32_pk_f16_fp4 v103, v84, 1.0 op_sel:[1,0,0]
	v_cvt_scalef32_pk_f16_fp4 v108, v84, 1.0 op_sel:[0,1,0]
	v_cvt_scalef32_pk_f16_fp4 v84, v84, 1.0 op_sel:[1,1,0]
	v_pk_fma_f16 v84, v31, v84, v96 op_sel_hi:[0,1,1]
	v_cvt_scalef32_pk_f16_fp4 v96, v85, 1.0
	v_pk_fma_f16 v102, v31, v102, v109 op_sel_hi:[0,1,1]
	v_pk_fma_f16 v96, v31, v96, v104 op_sel_hi:[0,1,1]
	v_cvt_scalef32_pk_f16_fp4 v104, v85, 1.0 op_sel:[1,0,0]
	v_cvt_scalef32_pk_f16_fp4 v109, v85, 1.0 op_sel:[0,1,0]
	v_cvt_scalef32_pk_f16_fp4 v85, v85, 1.0 op_sel:[1,1,0]
	v_pk_fma_f16 v30, v31, v85, v30 op_sel_hi:[0,1,1]
	s_waitcnt vmcnt(29)
	v_cvt_scalef32_pk_f16_fp4 v85, v74, 1.0
	v_pk_fma_f16 v85, v31, v85, v97 op_sel:[1,0,0]
	v_cvt_scalef32_pk_f16_fp4 v97, v74, 1.0 op_sel:[1,0,0]
	v_pk_fma_f16 v97, v31, v97, v105 op_sel:[1,0,0]
	v_cvt_scalef32_pk_f16_fp4 v105, v74, 1.0 op_sel:[0,1,0]
	v_cvt_scalef32_pk_f16_fp4 v74, v74, 1.0 op_sel:[1,1,0]
	v_pk_fma_f16 v74, v31, v74, v82 op_sel:[1,0,0]
	v_cvt_scalef32_pk_f16_fp4 v82, v75, 1.0
	v_pk_fma_f16 v82, v31, v82, v94 op_sel:[1,0,0]
	v_cvt_scalef32_pk_f16_fp4 v94, v75, 1.0 op_sel:[1,0,0]
	v_pk_fma_f16 v94, v31, v94, v102 op_sel:[1,0,0]
	v_cvt_scalef32_pk_f16_fp4 v102, v75, 1.0 op_sel:[0,1,0]
	v_cvt_scalef32_pk_f16_fp4 v75, v75, 1.0 op_sel:[1,1,0]
	v_pk_fma_f16 v75, v31, v75, v83 op_sel:[1,0,0]
	v_cvt_scalef32_pk_f16_fp4 v83, v76, 1.0
	v_pk_fma_f16 v103, v31, v103, v115 op_sel_hi:[0,1,1]
	v_pk_fma_f16 v83, v31, v83, v95 op_sel:[1,0,0]
	v_cvt_scalef32_pk_f16_fp4 v95, v76, 1.0 op_sel:[1,0,0]
	v_pk_fma_f16 v95, v31, v95, v103 op_sel:[1,0,0]
	v_cvt_scalef32_pk_f16_fp4 v103, v76, 1.0 op_sel:[0,1,0]
	v_cvt_scalef32_pk_f16_fp4 v76, v76, 1.0 op_sel:[1,1,0]
	v_pk_fma_f16 v76, v31, v76, v84 op_sel:[1,0,0]
	v_cvt_scalef32_pk_f16_fp4 v84, v77, 1.0
	v_pk_fma_f16 v104, v31, v104, v116 op_sel_hi:[0,1,1]
	v_pk_fma_f16 v84, v31, v84, v96 op_sel:[1,0,0]
	v_cvt_scalef32_pk_f16_fp4 v96, v77, 1.0 op_sel:[1,0,0]
	v_pk_fma_f16 v107, v31, v107, v114 op_sel_hi:[0,1,1]
	v_pk_fma_f16 v108, v31, v108, v117 op_sel_hi:[0,1,1]
	v_pk_fma_f16 v109, v31, v109, v122 op_sel_hi:[0,1,1]
	v_pk_fma_f16 v96, v31, v96, v104 op_sel:[1,0,0]
	v_cvt_scalef32_pk_f16_fp4 v104, v77, 1.0 op_sel:[0,1,0]
	v_cvt_scalef32_pk_f16_fp4 v77, v77, 1.0 op_sel:[1,1,0]
	v_pk_fma_f16 v105, v31, v105, v106 op_sel:[1,0,0]
	v_pk_fma_f16 v102, v31, v102, v107 op_sel:[1,0,0]
	v_pk_fma_f16 v103, v31, v103, v108 op_sel:[1,0,0]
	v_pk_fma_f16 v104, v31, v104, v109 op_sel:[1,0,0]
	v_pk_fma_f16 v30, v31, v77, v30 op_sel:[1,0,0]
	s_waitcnt vmcnt(28)
	v_cvt_scalef32_pk_f16_fp4 v31, v66, 1.0
	v_pk_fma_f16 v31, v32, v31, v85 op_sel_hi:[0,1,1]
	v_cvt_scalef32_pk_f16_fp4 v77, v66, 1.0 op_sel:[1,0,0]
	v_cvt_scalef32_pk_f16_fp4 v85, v66, 1.0 op_sel:[0,1,0]
	v_cvt_scalef32_pk_f16_fp4 v66, v66, 1.0 op_sel:[1,1,0]
	v_pk_fma_f16 v66, v32, v66, v74 op_sel_hi:[0,1,1]
	v_cvt_scalef32_pk_f16_fp4 v74, v67, 1.0
	v_pk_fma_f16 v74, v32, v74, v82 op_sel_hi:[0,1,1]
	v_cvt_scalef32_pk_f16_fp4 v82, v67, 1.0 op_sel:[1,0,0]
	v_pk_fma_f16 v82, v32, v82, v94 op_sel_hi:[0,1,1]
	v_cvt_scalef32_pk_f16_fp4 v94, v67, 1.0 op_sel:[0,1,0]
	v_cvt_scalef32_pk_f16_fp4 v67, v67, 1.0 op_sel:[1,1,0]
	v_pk_fma_f16 v67, v32, v67, v75 op_sel_hi:[0,1,1]
	v_cvt_scalef32_pk_f16_fp4 v75, v68, 1.0
	v_pk_fma_f16 v75, v32, v75, v83 op_sel_hi:[0,1,1]
	v_cvt_scalef32_pk_f16_fp4 v83, v68, 1.0 op_sel:[1,0,0]
	v_pk_fma_f16 v83, v32, v83, v95 op_sel_hi:[0,1,1]
	v_cvt_scalef32_pk_f16_fp4 v95, v68, 1.0 op_sel:[0,1,0]
	v_cvt_scalef32_pk_f16_fp4 v68, v68, 1.0 op_sel:[1,1,0]
	v_pk_fma_f16 v68, v32, v68, v76 op_sel_hi:[0,1,1]
	v_cvt_scalef32_pk_f16_fp4 v76, v69, 1.0
	v_pk_fma_f16 v76, v32, v76, v84 op_sel_hi:[0,1,1]
	v_cvt_scalef32_pk_f16_fp4 v84, v69, 1.0 op_sel:[1,0,0]
	v_pk_fma_f16 v84, v32, v84, v96 op_sel_hi:[0,1,1]
	v_cvt_scalef32_pk_f16_fp4 v96, v69, 1.0 op_sel:[0,1,0]
	v_cvt_scalef32_pk_f16_fp4 v69, v69, 1.0 op_sel:[1,1,0]
	v_pk_fma_f16 v30, v32, v69, v30 op_sel_hi:[0,1,1]
	s_waitcnt vmcnt(27)
	v_cvt_scalef32_pk_f16_fp4 v69, v58, 1.0
	v_pk_fma_f16 v77, v32, v77, v97 op_sel_hi:[0,1,1]
	v_pk_fma_f16 v31, v32, v69, v31 op_sel:[1,0,0]
	v_cvt_scalef32_pk_f16_fp4 v69, v58, 1.0 op_sel:[1,0,0]
	v_pk_fma_f16 v69, v32, v69, v77 op_sel:[1,0,0]
	v_cvt_scalef32_pk_f16_fp4 v77, v58, 1.0 op_sel:[0,1,0]
	v_cvt_scalef32_pk_f16_fp4 v58, v58, 1.0 op_sel:[1,1,0]
	v_pk_fma_f16 v58, v32, v58, v66 op_sel:[1,0,0]
	v_cvt_scalef32_pk_f16_fp4 v66, v59, 1.0
	v_pk_fma_f16 v66, v32, v66, v74 op_sel:[1,0,0]
	v_cvt_scalef32_pk_f16_fp4 v74, v59, 1.0 op_sel:[1,0,0]
	v_pk_fma_f16 v74, v32, v74, v82 op_sel:[1,0,0]
	v_cvt_scalef32_pk_f16_fp4 v82, v59, 1.0 op_sel:[0,1,0]
	v_cvt_scalef32_pk_f16_fp4 v59, v59, 1.0 op_sel:[1,1,0]
	v_pk_fma_f16 v59, v32, v59, v67 op_sel:[1,0,0]
	v_cvt_scalef32_pk_f16_fp4 v67, v60, 1.0
	v_pk_fma_f16 v67, v32, v67, v75 op_sel:[1,0,0]
	v_cvt_scalef32_pk_f16_fp4 v75, v60, 1.0 op_sel:[1,0,0]
	v_pk_fma_f16 v75, v32, v75, v83 op_sel:[1,0,0]
	v_cvt_scalef32_pk_f16_fp4 v83, v60, 1.0 op_sel:[0,1,0]
	v_cvt_scalef32_pk_f16_fp4 v60, v60, 1.0 op_sel:[1,1,0]
	v_pk_fma_f16 v60, v32, v60, v68 op_sel:[1,0,0]
	v_cvt_scalef32_pk_f16_fp4 v68, v61, 1.0
	v_pk_fma_f16 v68, v32, v68, v76 op_sel:[1,0,0]
	v_cvt_scalef32_pk_f16_fp4 v76, v61, 1.0 op_sel:[1,0,0]
	v_pk_fma_f16 v85, v32, v85, v105 op_sel_hi:[0,1,1]
	v_pk_fma_f16 v94, v32, v94, v102 op_sel_hi:[0,1,1]
	v_pk_fma_f16 v95, v32, v95, v103 op_sel_hi:[0,1,1]
	v_pk_fma_f16 v96, v32, v96, v104 op_sel_hi:[0,1,1]
	v_pk_fma_f16 v76, v32, v76, v84 op_sel:[1,0,0]
	v_cvt_scalef32_pk_f16_fp4 v84, v61, 1.0 op_sel:[0,1,0]
	v_cvt_scalef32_pk_f16_fp4 v61, v61, 1.0 op_sel:[1,1,0]
	v_pk_fma_f16 v77, v32, v77, v85 op_sel:[1,0,0]
	v_pk_fma_f16 v82, v32, v82, v94 op_sel:[1,0,0]
	v_pk_fma_f16 v83, v32, v83, v95 op_sel:[1,0,0]
	v_pk_fma_f16 v84, v32, v84, v96 op_sel:[1,0,0]
	v_pk_fma_f16 v30, v32, v61, v30 op_sel:[1,0,0]
	s_waitcnt vmcnt(26)
	v_cvt_scalef32_pk_f16_fp4 v32, v46, 1.0
	v_pk_fma_f16 v31, v33, v32, v31 op_sel_hi:[0,1,1]
	v_cvt_scalef32_pk_f16_fp4 v32, v46, 1.0 op_sel:[1,0,0]
	v_cvt_scalef32_pk_f16_fp4 v61, v46, 1.0 op_sel:[0,1,0]
	v_cvt_scalef32_pk_f16_fp4 v46, v46, 1.0 op_sel:[1,1,0]
	v_pk_fma_f16 v46, v33, v46, v58 op_sel_hi:[0,1,1]
	v_cvt_scalef32_pk_f16_fp4 v58, v47, 1.0
	v_pk_fma_f16 v32, v33, v32, v69 op_sel_hi:[0,1,1]
	v_pk_fma_f16 v58, v33, v58, v66 op_sel_hi:[0,1,1]
	v_cvt_scalef32_pk_f16_fp4 v66, v47, 1.0 op_sel:[1,0,0]
	v_cvt_scalef32_pk_f16_fp4 v69, v47, 1.0 op_sel:[0,1,0]
	v_cvt_scalef32_pk_f16_fp4 v47, v47, 1.0 op_sel:[1,1,0]
	v_pk_fma_f16 v47, v33, v47, v59 op_sel_hi:[0,1,1]
	v_cvt_scalef32_pk_f16_fp4 v59, v48, 1.0
	v_pk_fma_f16 v66, v33, v66, v74 op_sel_hi:[0,1,1]
	v_pk_fma_f16 v59, v33, v59, v67 op_sel_hi:[0,1,1]
	v_cvt_scalef32_pk_f16_fp4 v67, v48, 1.0 op_sel:[1,0,0]
	v_cvt_scalef32_pk_f16_fp4 v74, v48, 1.0 op_sel:[0,1,0]
	v_cvt_scalef32_pk_f16_fp4 v48, v48, 1.0 op_sel:[1,1,0]
	v_pk_fma_f16 v48, v33, v48, v60 op_sel_hi:[0,1,1]
	v_cvt_scalef32_pk_f16_fp4 v60, v49, 1.0
	v_pk_fma_f16 v67, v33, v67, v75 op_sel_hi:[0,1,1]
	v_pk_fma_f16 v60, v33, v60, v68 op_sel_hi:[0,1,1]
	v_cvt_scalef32_pk_f16_fp4 v68, v49, 1.0 op_sel:[1,0,0]
	v_cvt_scalef32_pk_f16_fp4 v75, v49, 1.0 op_sel:[0,1,0]
	v_cvt_scalef32_pk_f16_fp4 v49, v49, 1.0 op_sel:[1,1,0]
	v_pk_fma_f16 v30, v33, v49, v30 op_sel_hi:[0,1,1]
	s_waitcnt vmcnt(25)
	v_cvt_scalef32_pk_f16_fp4 v49, v38, 1.0
	v_pk_fma_f16 v31, v33, v49, v31 op_sel:[1,0,0]
	v_cvt_scalef32_pk_f16_fp4 v49, v38, 1.0 op_sel:[1,0,0]
	v_pk_fma_f16 v32, v33, v49, v32 op_sel:[1,0,0]
	v_cvt_scalef32_pk_f16_fp4 v49, v38, 1.0 op_sel:[0,1,0]
	v_cvt_scalef32_pk_f16_fp4 v38, v38, 1.0 op_sel:[1,1,0]
	v_pk_fma_f16 v61, v33, v61, v77 op_sel_hi:[0,1,1]
	v_pk_fma_f16 v38, v33, v38, v46 op_sel:[1,0,0]
	v_cvt_scalef32_pk_f16_fp4 v46, v39, 1.0
	v_pk_fma_f16 v49, v33, v49, v61 op_sel:[1,0,0]
	v_pk_fma_f16 v46, v33, v46, v58 op_sel:[1,0,0]
	v_cvt_scalef32_pk_f16_fp4 v58, v39, 1.0 op_sel:[1,0,0]
	v_cvt_scalef32_pk_f16_fp4 v61, v39, 1.0 op_sel:[0,1,0]
	v_cvt_scalef32_pk_f16_fp4 v39, v39, 1.0 op_sel:[1,1,0]
	v_pk_fma_f16 v39, v33, v39, v47 op_sel:[1,0,0]
	v_cvt_scalef32_pk_f16_fp4 v47, v40, 1.0
	v_pk_fma_f16 v58, v33, v58, v66 op_sel:[1,0,0]
	v_pk_fma_f16 v47, v33, v47, v59 op_sel:[1,0,0]
	v_cvt_scalef32_pk_f16_fp4 v59, v40, 1.0 op_sel:[1,0,0]
	v_cvt_scalef32_pk_f16_fp4 v66, v40, 1.0 op_sel:[0,1,0]
	v_cvt_scalef32_pk_f16_fp4 v40, v40, 1.0 op_sel:[1,1,0]
	v_pk_fma_f16 v69, v33, v69, v82 op_sel_hi:[0,1,1]
	v_pk_fma_f16 v74, v33, v74, v83 op_sel_hi:[0,1,1]
	v_pk_fma_f16 v75, v33, v75, v84 op_sel_hi:[0,1,1]
	v_pk_fma_f16 v59, v33, v59, v67 op_sel:[1,0,0]
	v_pk_fma_f16 v40, v33, v40, v48 op_sel:[1,0,0]
	v_cvt_scalef32_pk_f16_fp4 v48, v41, 1.0
	v_cvt_scalef32_pk_f16_fp4 v67, v41, 1.0 op_sel:[0,1,0]
	v_pk_fma_f16 v61, v33, v61, v69 op_sel:[1,0,0]
	v_pk_fma_f16 v66, v33, v66, v74 op_sel:[1,0,0]
	v_pk_fma_f16 v48, v33, v48, v60 op_sel:[1,0,0]
	v_cvt_scalef32_pk_f16_fp4 v60, v41, 1.0 op_sel:[1,0,0]
	v_pk_fma_f16 v67, v33, v67, v75 op_sel:[1,0,0]
	v_cvt_scalef32_pk_f16_fp4 v41, v41, 1.0 op_sel:[1,1,0]
	v_pk_fma_f16 v68, v33, v68, v76 op_sel_hi:[0,1,1]
	v_pk_fma_f16 v30, v33, v41, v30 op_sel:[1,0,0]
	v_permlane32_swap_b32_e32 v31, v47
	v_permlane32_swap_b32_e32 v49, v66
	v_permlane32_swap_b32_e32 v38, v40
	v_permlane32_swap_b32_e32 v46, v48
	v_permlane32_swap_b32_e32 v61, v67
	v_pk_fma_f16 v60, v33, v60, v68 op_sel:[1,0,0]
	v_pk_add_f16 v31, v31, v47
	v_pk_add_f16 v33, v49, v66
	v_pk_add_f16 v38, v38, v40
	v_pk_add_f16 v40, v46, v48
	v_pk_add_f16 v46, v61, v67
	v_permlane32_swap_b32_e32 v39, v30
	v_permlane32_swap_b32_e32 v32, v59
	v_permlane32_swap_b32_e32 v58, v60
	v_pk_add_f16 v30, v39, v30
	v_permlane16_swap_b32_e32 v31, v40
	v_permlane16_swap_b32_e32 v33, v46
	v_pk_add_f16 v32, v32, v59
	v_pk_add_f16 v41, v58, v60
	v_pk_add_f16 v31, v31, v40
	v_pk_add_f16 v33, v33, v46
	v_permlane16_swap_b32_e32 v38, v30
	v_permlane16_swap_b32_e32 v32, v41
	v_pk_add_f16 v30, v38, v30
	v_cndmask_b32_e64 v38, v33, v31, s[8:9]
	v_cndmask_b32_e64 v31, v31, v33, s[8:9]
	v_pk_add_f16 v32, v32, v41
	v_cvt_f32_f16_sdwa v39, v207 dst_sel:DWORD dst_unused:UNUSED_PAD src0_sel:WORD_1
	v_mov_b32_dpp v31, v31 row_ror:8 row_mask:0xf bank_mask:0xf bound_ctrl:1
	v_pk_add_f16 v33, v38, v31
	v_cndmask_b32_e64 v31, v30, v32, s[8:9]
	v_cndmask_b32_e64 v30, v32, v30, s[8:9]
	v_cvt_f32_f16_e32 v32, v33
	v_cvt_f32_f16_sdwa v33, v33 dst_sel:DWORD dst_unused:UNUSED_PAD src0_sel:WORD_1
	v_mov_b32_dpp v30, v30 row_ror:8 row_mask:0xf bank_mask:0xf bound_ctrl:1
	v_pk_add_f16 v41, v31, v30
	v_cvt_f32_f16_e32 v30, v206
	v_cvt_f32_f16_sdwa v31, v206 dst_sel:DWORD dst_unused:UNUSED_PAD src0_sel:WORD_1
	v_cvt_f32_f16_e32 v38, v207
	v_cvt_f32_f16_e32 v40, v41
	v_cvt_f32_f16_sdwa v41, v41 dst_sel:DWORD dst_unused:UNUSED_PAD src0_sel:WORD_1
	v_pk_fma_f32 v[30:31], v[2:3], v[32:33], v[30:31]
	s_nop 0
	v_pk_add_f32 v[14:15], v[14:15], v[30:31]
	v_pk_fma_f32 v[30:31], v[4:5], v[40:41], v[38:39]
	v_cvt_pk_f16_f32 v14, v14, v15
	v_pk_add_f32 v[16:17], v[16:17], v[30:31]
	s_nop 0
	v_cvt_pk_f16_f32 v15, v16, v17
	v_lshl_add_u64 v[16:17], v[200:201], 0, s[22:23]
	global_store_dwordx2 v[16:17], v[14:15], off
	v_lshl_add_u64 v[204:205], v[204:205], 0, s[18:19]
	s_mov_b32 s41, s21
	s_cbranch_scc0 .LBB0_1210
	s_mov_b64 s[22:23], 0

.LBB0_2232:
	s_or_b64 exec, exec, s[0:1]
	s_mov_b64 s[0:1], 0
	s_mov_b64 s[6:7], 0
	s_waitcnt lgkmcnt(0)
	s_barrier
	s_mov_b64 s[6:7], 0
	v_readlane_b32 s12, v250, 0
	v_readlane_b32 s14, v250, 2
	s_mov_b64 s[16:17], 0
	s_mov_b64 s[10:11], 0
	s_mov_b64 s[6:7], 0
	v_readlane_b32 s13, v250, 1
	v_readlane_b32 s15, v250, 3
	s_add_u32 s0, s14, s0
	s_mov_b64 s[8:9], 0
	s_addc_u32 s1, s15, s1
	s_mov_b64 s[14:15], 0
	s_mov_b64 s[6:7], 0
	s_mov_b64 s[12:13], 0
	v_mov_b32_e32 v2, v0
	s_add_u32 s0, s0, 0x5800
	s_getreg_b32 s2, hwreg(HW_REG_XCC_ID, 0, 4)
	v_and_b32_e32 v3, 63, v2
	s_addc_u32 s1, s1, 0
	s_and_b32 s24, s2, 7
	v_mov_b32_e32 v202, 0
	v_cmp_eq_u32_e64 s[6:7], 0, v3
	s_and_saveexec_b64 s[18:19], s[6:7]
	s_cbranch_execz .LBB0_2236
	s_mov_b64 s[22:23], exec
	v_mbcnt_lo_u32_b32 v4, s22, 0
	v_mbcnt_hi_u32_b32 v4, s23, v4
	v_cmp_eq_u32_e32 vcc, 0, v4
	s_and_saveexec_b64 s[20:21], vcc
	s_cbranch_execz .LBB0_2235
	s_bcnt1_i32_b64 s22, s[22:23]
	s_lshl_b32 s25, s24, 8
	s_lshl_b32 s22, s22, 3
	v_mov_b32_e32 v5, s25
	v_mov_b32_e32 v6, s22
	global_atomic_add v5, v5, v6, s[0:1] sc0
.LBB0_2235:
	s_or_b64 exec, exec, s[20:21]
	s_waitcnt vmcnt(0)
	v_readfirstlane_b32 s20, v5
	s_nop 1
	v_lshl_add_u32 v202, v4, 3, s20
.LBB0_2236:
	s_or_b64 exec, exec, s[18:19]
	v_readlane_b32 s20, v250, 0
	v_readlane_b32 s22, v250, 2
	v_readlane_b32 s23, v250, 3
	s_add_u32 s16, s22, s16
	s_addc_u32 s17, s23, s17
	s_add_u32 s18, s22, s10
	s_addc_u32 s19, s23, s11
	s_add_u32 s10, s22, s14
	s_addc_u32 s11, s23, s15
	s_add_u32 s10, s10, 0x3dd06000
	s_addc_u32 s11, s11, 0
	s_add_u32 s12, s22, s12
	s_addc_u32 s13, s23, s13
	s_add_u32 s12, s12, 0x4c618000
	s_addc_u32 s13, s13, 0
	s_add_u32 s8, s22, s8
	s_addc_u32 s9, s23, s9
	v_lshlrev_b32_e32 v203, 2, v3
	v_lshlrev_b32_e32 v4, 4, v3
	v_lshlrev_b32_e32 v3, 3, v3
	s_add_u32 s14, s8, 0x50e18000
	v_and_b32_e32 v182, 0x1c0, v3
	v_mov_b32_e32 v183, 0
	v_and_b32_e32 v3, 56, v2
	s_addc_u32 s15, s9, 0
	v_and_b32_e32 v204, 0x70, v4
	v_lshl_add_u64 v[4:5], s[16:17], 0, v[182:183]
	s_mov_b64 s[8:9], 0x2ade6000
	v_lshlrev_b32_e32 v182, 2, v3
	v_lshl_add_u64 v[184:185], v[4:5], 0, s[8:9]
	v_lshl_add_u64 v[4:5], s[18:19], 0, v[182:183]
	s_mov_b64 s[8:9], 0x4c198000
	v_and_b32_e32 v2, 8, v2
	v_lshl_add_u64 v[186:187], v[4:5], 0, s[8:9]
	s_mov_b32 s27, 0
	v_cmp_eq_u32_e64 s[8:9], 0, v2
	v_mov_b32_e32 v206, s24
	v_mov_b32_e32 v205, 8
	s_mov_b32 s26, 0xa000
	v_readlane_b32 s21, v250, 1
	s_branch .LBB0_2239

.LBB0_2243:
	s_add_i32 s22, s16, s28
	s_add_i32 s17, s22, 2
	s_add_i32 s24, s22, 1
	s_add_i32 s19, s22, 3
	s_cmp_lt_u32 s28, 6
	s_cselect_b32 s18, s17, s22
	s_cselect_b32 s20, s19, s24
	s_ashr_i32 s19, s18, 31
	s_ashr_i32 s25, s24, 31
	s_ashr_i32 s23, s22, 31
	s_lshl_b64 s[30:31], s[18:19], 9
	s_lshl_b64 s[34:35], s[24:25], 8
	s_lshl_b64 s[18:19], s[22:23], 12
	s_add_i32 s17, s28, 1
	s_cmp_lt_u32 s17, 7
	s_cselect_b64 s[36:37], -1, 0
	s_ashr_i32 s21, s20, 31
	s_lshl_b64 s[20:21], s[20:21], 9
	s_cmp_lg_u64 s[36:37], 0
	s_addc_u32 s22, s22, 1
	s_lshl_b64 s[24:25], s[24:25], 12
	v_lshl_add_u64 v[18:19], v[184:185], 0, s[30:31]
	v_lshl_add_u64 v[30:31], v[186:187], 0, s[34:35]
	global_load_dwordx4 v[166:169], v[18:19], off offset:48
	global_load_dwordx4 v[170:173], v[18:19], off offset:32
	global_load_dwordx4 v[174:177], v[18:19], off offset:16
	global_load_dwordx4 v[178:181], v[18:19], off
	s_nop 0
	global_load_dwordx4 v[18:21], v[30:31], off offset:16
	global_load_dwordx4 v[90:93], v[30:31], off
	v_lshl_add_u64 v[196:197], v[190:191], 0, s[24:25]
	v_lshl_add_u64 v[30:31], v[192:193], 0, s[24:25]
	global_load_dwordx2 v[198:199], v[196:197], off
	global_load_dwordx2 v[200:201], v[30:31], off
	s_waitcnt vmcnt(29)
	v_lshl_add_u32 v30, v138, 7, v207
	v_lshl_add_u32 v31, v139, 7, v207
	global_load_dwordx4 v[162:165], v30, s[10:11]
	global_load_dwordx4 v[158:161], v31, s[10:11]
	v_lshl_add_u32 v30, v140, 7, v207
	v_lshl_add_u32 v31, v141, 7, v207
	global_load_dwordx4 v[154:157], v30, s[10:11]
	global_load_dwordx4 v[150:153], v31, s[10:11]
	v_lshl_add_u32 v30, v130, 7, v207
	v_lshl_add_u32 v31, v131, 7, v207
	global_load_dwordx4 v[142:145], v30, s[10:11]
	global_load_dwordx4 v[126:129], v31, s[10:11]
	v_lshl_add_u32 v30, v132, 7, v207
	v_lshl_add_u32 v31, v133, 7, v207
	global_load_dwordx4 v[110:113], v30, s[10:11]
	global_load_dwordx4 v[102:105], v31, s[10:11]
	v_lshl_add_u32 v30, v122, 7, v207
	v_lshl_add_u32 v31, v123, 7, v207
	global_load_dwordx4 v[94:97], v30, s[10:11]
	global_load_dwordx4 v[86:89], v31, s[10:11]
	v_lshl_add_u32 v30, v124, 7, v207
	v_lshl_add_u32 v31, v125, 7, v207
	global_load_dwordx4 v[78:81], v30, s[10:11]
	global_load_dwordx4 v[70:73], v31, s[10:11]
	s_waitcnt vmcnt(40)
	v_lshl_add_u32 v30, v118, 7, v207
	v_lshl_add_u32 v31, v119, 7, v207
	global_load_dwordx4 v[58:61], v30, s[10:11]
	global_load_dwordx4 v[50:53], v31, s[10:11]
	v_lshl_add_u32 v30, v120, 7, v207
	v_lshl_add_u32 v31, v121, 7, v207
	global_load_dwordx4 v[38:41], v30, s[10:11]
	s_nop 0
	global_load_dwordx4 v[30:33], v31, s[10:11]
	s_ashr_i32 s23, s22, 31
	s_lshl_b64 s[24:25], s[22:23], 8
	s_lshl_b64 s[22:23], s[22:23], 12
	s_add_i32 s17, s28, 2
	s_cmp_gt_u32 s28, 5
	s_waitcnt vmcnt(36)
	v_cvt_scalef32_pk_f16_fp4 v118, v146, 1.0
	v_pk_fma_f16 v118, v42, v118, 0 op_sel_hi:[0,1,1]
	v_cvt_scalef32_pk_f16_fp4 v119, v146, 1.0 op_sel:[1,0,0]
	v_cvt_scalef32_pk_f16_fp4 v120, v146, 1.0 op_sel:[0,1,0]
	v_cvt_scalef32_pk_f16_fp4 v121, v146, 1.0 op_sel:[1,1,0]
	s_waitcnt vmcnt(35)
	v_cvt_scalef32_pk_f16_fp4 v146, v134, 1.0
	v_pk_fma_f16 v119, v42, v119, 0 op_sel_hi:[0,1,1]
	v_pk_fma_f16 v118, v42, v146, v118 op_sel:[1,0,0]
	v_cvt_scalef32_pk_f16_fp4 v146, v134, 1.0 op_sel:[1,0,0]
	v_pk_fma_f16 v121, v42, v121, 0 op_sel_hi:[0,1,1]
	v_cvt_scalef32_pk_f16_fp4 v122, v147, 1.0
	v_pk_fma_f16 v119, v42, v146, v119 op_sel:[1,0,0]
	v_cvt_scalef32_pk_f16_fp4 v146, v134, 1.0 op_sel:[0,1,0]
	v_cvt_scalef32_pk_f16_fp4 v134, v134, 1.0 op_sel:[1,1,0]
	v_pk_fma_f16 v122, v42, v122, 0 op_sel_hi:[0,1,1]
	v_cvt_scalef32_pk_f16_fp4 v123, v147, 1.0 op_sel:[1,0,0]
	v_pk_fma_f16 v121, v42, v134, v121 op_sel:[1,0,0]
	v_cvt_scalef32_pk_f16_fp4 v134, v135, 1.0
	v_pk_fma_f16 v123, v42, v123, 0 op_sel_hi:[0,1,1]
	v_cvt_scalef32_pk_f16_fp4 v124, v147, 1.0 op_sel:[0,1,0]
	v_pk_fma_f16 v122, v42, v134, v122 op_sel:[1,0,0]
	v_cvt_scalef32_pk_f16_fp4 v134, v135, 1.0 op_sel:[1,0,0]
	v_pk_fma_f16 v124, v42, v124, 0 op_sel_hi:[0,1,1]
	v_cvt_scalef32_pk_f16_fp4 v125, v147, 1.0 op_sel:[1,1,0]
	v_pk_fma_f16 v123, v42, v134, v123 op_sel:[1,0,0]
	v_cvt_scalef32_pk_f16_fp4 v134, v135, 1.0 op_sel:[0,1,0]
	v_pk_fma_f16 v125, v42, v125, 0 op_sel_hi:[0,1,1]
	v_cvt_scalef32_pk_f16_fp4 v130, v148, 1.0
	v_pk_fma_f16 v124, v42, v134, v124 op_sel:[1,0,0]
	v_cvt_scalef32_pk_f16_fp4 v134, v135, 1.0 op_sel:[1,1,0]
	v_pk_fma_f16 v130, v42, v130, 0 op_sel_hi:[0,1,1]
	v_cvt_scalef32_pk_f16_fp4 v131, v148, 1.0 op_sel:[1,0,0]
	v_pk_fma_f16 v125, v42, v134, v125 op_sel:[1,0,0]
	v_cvt_scalef32_pk_f16_fp4 v134, v136, 1.0
	v_pk_fma_f16 v131, v42, v131, 0 op_sel_hi:[0,1,1]
	v_cvt_scalef32_pk_f16_fp4 v132, v148, 1.0 op_sel:[0,1,0]
	v_pk_fma_f16 v130, v42, v134, v130 op_sel:[1,0,0]
	v_cvt_scalef32_pk_f16_fp4 v134, v136, 1.0 op_sel:[1,0,0]
	v_pk_fma_f16 v132, v42, v132, 0 op_sel_hi:[0,1,1]
	v_cvt_scalef32_pk_f16_fp4 v133, v148, 1.0 op_sel:[1,1,0]
	v_pk_fma_f16 v131, v42, v134, v131 op_sel:[1,0,0]
	v_cvt_scalef32_pk_f16_fp4 v134, v136, 1.0 op_sel:[0,1,0]
	v_pk_fma_f16 v133, v42, v133, 0 op_sel_hi:[0,1,1]
	v_cvt_scalef32_pk_f16_fp4 v138, v149, 1.0
	v_cvt_scalef32_pk_f16_fp4 v139, v149, 1.0 op_sel:[1,0,0]
	v_cvt_scalef32_pk_f16_fp4 v140, v149, 1.0 op_sel:[0,1,0]
	v_cvt_scalef32_pk_f16_fp4 v141, v149, 1.0 op_sel:[1,1,0]
	v_pk_fma_f16 v132, v42, v134, v132 op_sel:[1,0,0]
	v_cvt_scalef32_pk_f16_fp4 v134, v136, 1.0 op_sel:[1,1,0]
	v_pk_fma_f16 v120, v42, v120, 0 op_sel_hi:[0,1,1]
	v_pk_fma_f16 v138, v42, v138, 0 op_sel_hi:[0,1,1]
	v_pk_fma_f16 v139, v42, v139, 0 op_sel_hi:[0,1,1]
	v_pk_fma_f16 v140, v42, v140, 0 op_sel_hi:[0,1,1]
	v_pk_fma_f16 v141, v42, v141, 0 op_sel_hi:[0,1,1]
	v_pk_fma_f16 v133, v42, v134, v133 op_sel:[1,0,0]
	v_cvt_scalef32_pk_f16_fp4 v134, v137, 1.0
	v_cvt_scalef32_pk_f16_fp4 v135, v137, 1.0 op_sel:[1,0,0]
	v_cvt_scalef32_pk_f16_fp4 v136, v137, 1.0 op_sel:[0,1,0]
	v_cvt_scalef32_pk_f16_fp4 v137, v137, 1.0 op_sel:[1,1,0]
	v_pk_fma_f16 v120, v42, v146, v120 op_sel:[1,0,0]
	v_pk_fma_f16 v134, v42, v134, v138 op_sel:[1,0,0]
	v_pk_fma_f16 v135, v42, v135, v139 op_sel:[1,0,0]
	v_pk_fma_f16 v136, v42, v136, v140 op_sel:[1,0,0]
	v_pk_fma_f16 v42, v42, v137, v141 op_sel:[1,0,0]
	s_waitcnt vmcnt(34)
	v_cvt_scalef32_pk_f16_fp4 v137, v114, 1.0
	v_pk_fma_f16 v118, v43, v137, v118 op_sel_hi:[0,1,1]
	v_cvt_scalef32_pk_f16_fp4 v137, v114, 1.0 op_sel:[1,0,0]
	v_pk_fma_f16 v119, v43, v137, v119 op_sel_hi:[0,1,1]
	v_cvt_scalef32_pk_f16_fp4 v137, v114, 1.0 op_sel:[0,1,0]
	v_cvt_scalef32_pk_f16_fp4 v114, v114, 1.0 op_sel:[1,1,0]
	v_pk_fma_f16 v114, v43, v114, v121 op_sel_hi:[0,1,1]
	v_cvt_scalef32_pk_f16_fp4 v121, v115, 1.0
	v_pk_fma_f16 v121, v43, v121, v122 op_sel_hi:[0,1,1]
	v_cvt_scalef32_pk_f16_fp4 v122, v115, 1.0 op_sel:[1,0,0]
	v_pk_fma_f16 v122, v43, v122, v123 op_sel_hi:[0,1,1]
	v_cvt_scalef32_pk_f16_fp4 v123, v115, 1.0 op_sel:[0,1,0]
	v_pk_fma_f16 v123, v43, v123, v124 op_sel_hi:[0,1,1]
	v_cvt_scalef32_pk_f16_fp4 v115, v115, 1.0 op_sel:[1,1,0]
	v_cvt_scalef32_pk_f16_fp4 v124, v116, 1.0
	v_pk_fma_f16 v115, v43, v115, v125 op_sel_hi:[0,1,1]
	v_pk_fma_f16 v124, v43, v124, v130 op_sel_hi:[0,1,1]
	v_cvt_scalef32_pk_f16_fp4 v125, v116, 1.0 op_sel:[1,0,0]
	v_cvt_scalef32_pk_f16_fp4 v130, v116, 1.0 op_sel:[0,1,0]
	v_cvt_scalef32_pk_f16_fp4 v116, v116, 1.0 op_sel:[1,1,0]
	v_pk_fma_f16 v125, v43, v125, v131 op_sel_hi:[0,1,1]
	v_pk_fma_f16 v130, v43, v130, v132 op_sel_hi:[0,1,1]
	v_pk_fma_f16 v116, v43, v116, v133 op_sel_hi:[0,1,1]
	v_cvt_scalef32_pk_f16_fp4 v131, v117, 1.0
	v_cvt_scalef32_pk_f16_fp4 v132, v117, 1.0 op_sel:[1,0,0]
	v_cvt_scalef32_pk_f16_fp4 v133, v117, 1.0 op_sel:[0,1,0]
	v_cvt_scalef32_pk_f16_fp4 v117, v117, 1.0 op_sel:[1,1,0]
	v_pk_fma_f16 v42, v43, v117, v42 op_sel_hi:[0,1,1]
	s_waitcnt vmcnt(33)
	v_cvt_scalef32_pk_f16_fp4 v117, v106, 1.0
	v_pk_fma_f16 v117, v43, v117, v118 op_sel:[1,0,0]
	v_cvt_scalef32_pk_f16_fp4 v118, v106, 1.0 op_sel:[1,0,0]
	v_pk_fma_f16 v118, v43, v118, v119 op_sel:[1,0,0]
	v_cvt_scalef32_pk_f16_fp4 v119, v106, 1.0 op_sel:[0,1,0]
	v_cvt_scalef32_pk_f16_fp4 v106, v106, 1.0 op_sel:[1,1,0]
	v_pk_fma_f16 v120, v43, v137, v120 op_sel_hi:[0,1,1]
	v_pk_fma_f16 v106, v43, v106, v114 op_sel:[1,0,0]
	v_cvt_scalef32_pk_f16_fp4 v114, v107, 1.0
	v_pk_fma_f16 v119, v43, v119, v120 op_sel:[1,0,0]
	v_pk_fma_f16 v114, v43, v114, v121 op_sel:[1,0,0]
	v_cvt_scalef32_pk_f16_fp4 v120, v107, 1.0 op_sel:[1,0,0]
	v_cvt_scalef32_pk_f16_fp4 v121, v107, 1.0 op_sel:[0,1,0]
	v_cvt_scalef32_pk_f16_fp4 v107, v107, 1.0 op_sel:[1,1,0]
	v_pk_fma_f16 v120, v43, v120, v122 op_sel:[1,0,0]
	v_pk_fma_f16 v121, v43, v121, v123 op_sel:[1,0,0]
	v_pk_fma_f16 v107, v43, v107, v115 op_sel:[1,0,0]
	v_cvt_scalef32_pk_f16_fp4 v115, v108, 1.0
	v_cvt_scalef32_pk_f16_fp4 v122, v108, 1.0 op_sel:[1,0,0]
	v_cvt_scalef32_pk_f16_fp4 v123, v108, 1.0 op_sel:[0,1,0]
	v_cvt_scalef32_pk_f16_fp4 v108, v108, 1.0 op_sel:[1,1,0]
	v_pk_fma_f16 v131, v43, v131, v134 op_sel_hi:[0,1,1]
	v_pk_fma_f16 v132, v43, v132, v135 op_sel_hi:[0,1,1]
	v_pk_fma_f16 v133, v43, v133, v136 op_sel_hi:[0,1,1]
	v_pk_fma_f16 v115, v43, v115, v124 op_sel:[1,0,0]
	v_pk_fma_f16 v122, v43, v122, v125 op_sel:[1,0,0]
	v_pk_fma_f16 v108, v43, v108, v116 op_sel:[1,0,0]
	v_cvt_scalef32_pk_f16_fp4 v116, v109, 1.0
	v_cvt_scalef32_pk_f16_fp4 v124, v109, 1.0 op_sel:[1,0,0]
	v_cvt_scalef32_pk_f16_fp4 v125, v109, 1.0 op_sel:[0,1,0]
	v_cvt_scalef32_pk_f16_fp4 v109, v109, 1.0 op_sel:[1,1,0]
	v_pk_fma_f16 v123, v43, v123, v130 op_sel:[1,0,0]
	v_pk_fma_f16 v116, v43, v116, v131 op_sel:[1,0,0]
	v_pk_fma_f16 v124, v43, v124, v132 op_sel:[1,0,0]
	v_pk_fma_f16 v125, v43, v125, v133 op_sel:[1,0,0]
	v_pk_fma_f16 v42, v43, v109, v42 op_sel:[1,0,0]
	s_waitcnt vmcnt(32)
	v_cvt_scalef32_pk_f16_fp4 v43, v98, 1.0
	v_pk_fma_f16 v43, v44, v43, v117 op_sel_hi:[0,1,1]
	v_cvt_scalef32_pk_f16_fp4 v109, v98, 1.0 op_sel:[1,0,0]
	v_cvt_scalef32_pk_f16_fp4 v117, v98, 1.0 op_sel:[0,1,0]
	v_cvt_scalef32_pk_f16_fp4 v98, v98, 1.0 op_sel:[1,1,0]
	v_pk_fma_f16 v98, v44, v98, v106 op_sel_hi:[0,1,1]
	v_cvt_scalef32_pk_f16_fp4 v106, v99, 1.0
	v_pk_fma_f16 v109, v44, v109, v118 op_sel_hi:[0,1,1]
	v_pk_fma_f16 v106, v44, v106, v114 op_sel_hi:[0,1,1]
	v_cvt_scalef32_pk_f16_fp4 v114, v99, 1.0 op_sel:[1,0,0]
	v_cvt_scalef32_pk_f16_fp4 v118, v99, 1.0 op_sel:[0,1,0]
	v_cvt_scalef32_pk_f16_fp4 v99, v99, 1.0 op_sel:[1,1,0]
	v_pk_fma_f16 v99, v44, v99, v107 op_sel_hi:[0,1,1]
	v_cvt_scalef32_pk_f16_fp4 v107, v100, 1.0
	v_pk_fma_f16 v117, v44, v117, v119 op_sel_hi:[0,1,1]
	v_pk_fma_f16 v107, v44, v107, v115 op_sel_hi:[0,1,1]
	v_cvt_scalef32_pk_f16_fp4 v115, v100, 1.0 op_sel:[1,0,0]
	v_cvt_scalef32_pk_f16_fp4 v119, v100, 1.0 op_sel:[0,1,0]
	v_cvt_scalef32_pk_f16_fp4 v100, v100, 1.0 op_sel:[1,1,0]
	v_pk_fma_f16 v100, v44, v100, v108 op_sel_hi:[0,1,1]
	v_cvt_scalef32_pk_f16_fp4 v108, v101, 1.0
	v_pk_fma_f16 v114, v44, v114, v120 op_sel_hi:[0,1,1]
	v_pk_fma_f16 v108, v44, v108, v116 op_sel_hi:[0,1,1]
	v_cvt_scalef32_pk_f16_fp4 v116, v101, 1.0 op_sel:[1,0,0]
	v_cvt_scalef32_pk_f16_fp4 v120, v101, 1.0 op_sel:[0,1,0]
	v_cvt_scalef32_pk_f16_fp4 v101, v101, 1.0 op_sel:[1,1,0]
	v_pk_fma_f16 v42, v44, v101, v42 op_sel_hi:[0,1,1]
	v_cvt_scalef32_pk_f16_fp4 v101, v82, 1.0
	v_pk_fma_f16 v43, v44, v101, v43 op_sel:[1,0,0]
	v_cvt_scalef32_pk_f16_fp4 v101, v82, 1.0 op_sel:[1,0,0]
	v_pk_fma_f16 v101, v44, v101, v109 op_sel:[1,0,0]
	v_cvt_scalef32_pk_f16_fp4 v109, v82, 1.0 op_sel:[0,1,0]
	v_cvt_scalef32_pk_f16_fp4 v82, v82, 1.0 op_sel:[1,1,0]
	v_pk_fma_f16 v82, v44, v82, v98 op_sel:[1,0,0]
	v_cvt_scalef32_pk_f16_fp4 v98, v83, 1.0
	v_pk_fma_f16 v98, v44, v98, v106 op_sel:[1,0,0]
	v_cvt_scalef32_pk_f16_fp4 v106, v83, 1.0 op_sel:[1,0,0]
	v_pk_fma_f16 v106, v44, v106, v114 op_sel:[1,0,0]
	v_cvt_scalef32_pk_f16_fp4 v114, v83, 1.0 op_sel:[0,1,0]
	v_cvt_scalef32_pk_f16_fp4 v83, v83, 1.0 op_sel:[1,1,0]
	v_pk_fma_f16 v83, v44, v83, v99 op_sel:[1,0,0]
	v_cvt_scalef32_pk_f16_fp4 v99, v84, 1.0
	v_pk_fma_f16 v115, v44, v115, v122 op_sel_hi:[0,1,1]
	v_pk_fma_f16 v99, v44, v99, v107 op_sel:[1,0,0]
	v_cvt_scalef32_pk_f16_fp4 v107, v84, 1.0 op_sel:[1,0,0]
	v_pk_fma_f16 v107, v44, v107, v115 op_sel:[1,0,0]
	v_cvt_scalef32_pk_f16_fp4 v115, v84, 1.0 op_sel:[0,1,0]
	v_cvt_scalef32_pk_f16_fp4 v84, v84, 1.0 op_sel:[1,1,0]
	v_pk_fma_f16 v84, v44, v84, v100 op_sel:[1,0,0]
	v_cvt_scalef32_pk_f16_fp4 v100, v85, 1.0
	v_pk_fma_f16 v116, v44, v116, v124 op_sel_hi:[0,1,1]
	v_pk_fma_f16 v100, v44, v100, v108 op_sel:[1,0,0]
	v_cvt_scalef32_pk_f16_fp4 v108, v85, 1.0 op_sel:[1,0,0]
	v_pk_fma_f16 v118, v44, v118, v121 op_sel_hi:[0,1,1]
	v_pk_fma_f16 v119, v44, v119, v123 op_sel_hi:[0,1,1]
	v_pk_fma_f16 v120, v44, v120, v125 op_sel_hi:[0,1,1]
	v_pk_fma_f16 v108, v44, v108, v116 op_sel:[1,0,0]
	v_cvt_scalef32_pk_f16_fp4 v116, v85, 1.0 op_sel:[0,1,0]
	v_cvt_scalef32_pk_f16_fp4 v85, v85, 1.0 op_sel:[1,1,0]
	v_pk_fma_f16 v109, v44, v109, v117 op_sel:[1,0,0]
	v_pk_fma_f16 v114, v44, v114, v118 op_sel:[1,0,0]
	v_pk_fma_f16 v115, v44, v115, v119 op_sel:[1,0,0]
	v_pk_fma_f16 v116, v44, v116, v120 op_sel:[1,0,0]
	v_pk_fma_f16 v42, v44, v85, v42 op_sel:[1,0,0]
	v_cvt_scalef32_pk_f16_fp4 v44, v74, 1.0
	v_pk_fma_f16 v43, v45, v44, v43 op_sel_hi:[0,1,1]
	v_cvt_scalef32_pk_f16_fp4 v44, v74, 1.0 op_sel:[1,0,0]
	v_cvt_scalef32_pk_f16_fp4 v85, v74, 1.0 op_sel:[0,1,0]
	v_cvt_scalef32_pk_f16_fp4 v74, v74, 1.0 op_sel:[1,1,0]
	v_pk_fma_f16 v74, v45, v74, v82 op_sel_hi:[0,1,1]
	v_cvt_scalef32_pk_f16_fp4 v82, v75, 1.0
	v_pk_fma_f16 v44, v45, v44, v101 op_sel_hi:[0,1,1]
	v_pk_fma_f16 v82, v45, v82, v98 op_sel_hi:[0,1,1]
	v_cvt_scalef32_pk_f16_fp4 v98, v75, 1.0 op_sel:[1,0,0]
	v_cvt_scalef32_pk_f16_fp4 v101, v75, 1.0 op_sel:[0,1,0]
	v_cvt_scalef32_pk_f16_fp4 v75, v75, 1.0 op_sel:[1,1,0]
	v_pk_fma_f16 v75, v45, v75, v83 op_sel_hi:[0,1,1]
	v_cvt_scalef32_pk_f16_fp4 v83, v76, 1.0
	v_pk_fma_f16 v98, v45, v98, v106 op_sel_hi:[0,1,1]
	v_pk_fma_f16 v83, v45, v83, v99 op_sel_hi:[0,1,1]
	v_cvt_scalef32_pk_f16_fp4 v99, v76, 1.0 op_sel:[1,0,0]
	v_cvt_scalef32_pk_f16_fp4 v106, v76, 1.0 op_sel:[0,1,0]
	v_cvt_scalef32_pk_f16_fp4 v76, v76, 1.0 op_sel:[1,1,0]
	v_pk_fma_f16 v76, v45, v76, v84 op_sel_hi:[0,1,1]
	v_cvt_scalef32_pk_f16_fp4 v84, v77, 1.0
	v_pk_fma_f16 v99, v45, v99, v107 op_sel_hi:[0,1,1]
	v_pk_fma_f16 v84, v45, v84, v100 op_sel_hi:[0,1,1]
	v_cvt_scalef32_pk_f16_fp4 v100, v77, 1.0 op_sel:[1,0,0]
	v_cvt_scalef32_pk_f16_fp4 v107, v77, 1.0 op_sel:[0,1,0]
	v_cvt_scalef32_pk_f16_fp4 v77, v77, 1.0 op_sel:[1,1,0]
	v_pk_fma_f16 v42, v45, v77, v42 op_sel_hi:[0,1,1]
	v_cvt_scalef32_pk_f16_fp4 v77, v66, 1.0
	v_pk_fma_f16 v43, v45, v77, v43 op_sel:[1,0,0]
	v_cvt_scalef32_pk_f16_fp4 v77, v66, 1.0 op_sel:[1,0,0]
	v_pk_fma_f16 v44, v45, v77, v44 op_sel:[1,0,0]
	v_cvt_scalef32_pk_f16_fp4 v77, v66, 1.0 op_sel:[0,1,0]
	v_cvt_scalef32_pk_f16_fp4 v66, v66, 1.0 op_sel:[1,1,0]
	v_pk_fma_f16 v85, v45, v85, v109 op_sel_hi:[0,1,1]
	v_pk_fma_f16 v66, v45, v66, v74 op_sel:[1,0,0]
	v_cvt_scalef32_pk_f16_fp4 v74, v67, 1.0
	v_pk_fma_f16 v77, v45, v77, v85 op_sel:[1,0,0]
	v_pk_fma_f16 v74, v45, v74, v82 op_sel:[1,0,0]
	v_cvt_scalef32_pk_f16_fp4 v82, v67, 1.0 op_sel:[1,0,0]
	v_cvt_scalef32_pk_f16_fp4 v85, v67, 1.0 op_sel:[0,1,0]
	v_cvt_scalef32_pk_f16_fp4 v67, v67, 1.0 op_sel:[1,1,0]
	v_pk_fma_f16 v67, v45, v67, v75 op_sel:[1,0,0]
	v_cvt_scalef32_pk_f16_fp4 v75, v68, 1.0
	v_pk_fma_f16 v82, v45, v82, v98 op_sel:[1,0,0]
	v_pk_fma_f16 v75, v45, v75, v83 op_sel:[1,0,0]
	v_cvt_scalef32_pk_f16_fp4 v83, v68, 1.0 op_sel:[1,0,0]
	v_cvt_scalef32_pk_f16_fp4 v98, v68, 1.0 op_sel:[0,1,0]
	v_cvt_scalef32_pk_f16_fp4 v68, v68, 1.0 op_sel:[1,1,0]
	v_pk_fma_f16 v68, v45, v68, v76 op_sel:[1,0,0]
	v_cvt_scalef32_pk_f16_fp4 v76, v69, 1.0
	v_pk_fma_f16 v101, v45, v101, v114 op_sel_hi:[0,1,1]
	v_pk_fma_f16 v106, v45, v106, v115 op_sel_hi:[0,1,1]
	v_pk_fma_f16 v100, v45, v100, v108 op_sel_hi:[0,1,1]
	v_pk_fma_f16 v107, v45, v107, v116 op_sel_hi:[0,1,1]
	v_pk_fma_f16 v83, v45, v83, v99 op_sel:[1,0,0]
	v_pk_fma_f16 v76, v45, v76, v84 op_sel:[1,0,0]
	v_cvt_scalef32_pk_f16_fp4 v84, v69, 1.0 op_sel:[1,0,0]
	v_cvt_scalef32_pk_f16_fp4 v99, v69, 1.0 op_sel:[0,1,0]
	v_cvt_scalef32_pk_f16_fp4 v69, v69, 1.0 op_sel:[1,1,0]
	v_pk_fma_f16 v85, v45, v85, v101 op_sel:[1,0,0]
	v_pk_fma_f16 v98, v45, v98, v106 op_sel:[1,0,0]
	v_pk_fma_f16 v84, v45, v84, v100 op_sel:[1,0,0]
	v_pk_fma_f16 v99, v45, v99, v107 op_sel:[1,0,0]
	v_pk_fma_f16 v42, v45, v69, v42 op_sel:[1,0,0]
	s_waitcnt vmcnt(31)
	v_cvt_scalef32_pk_f16_fp4 v45, v62, 1.0
	v_pk_fma_f16 v43, v6, v45, v43 op_sel_hi:[0,1,1]
	v_cvt_scalef32_pk_f16_fp4 v45, v62, 1.0 op_sel:[1,0,0]
	v_pk_fma_f16 v44, v6, v45, v44 op_sel_hi:[0,1,1]
	v_cvt_scalef32_pk_f16_fp4 v45, v62, 1.0 op_sel:[0,1,0]
	v_cvt_scalef32_pk_f16_fp4 v62, v62, 1.0 op_sel:[1,1,0]
	v_pk_fma_f16 v62, v6, v62, v66 op_sel_hi:[0,1,1]
	v_cvt_scalef32_pk_f16_fp4 v66, v63, 1.0
	v_pk_fma_f16 v66, v6, v66, v74 op_sel_hi:[0,1,1]
	v_cvt_scalef32_pk_f16_fp4 v69, v63, 1.0 op_sel:[1,0,0]
	v_cvt_scalef32_pk_f16_fp4 v74, v63, 1.0 op_sel:[0,1,0]
	v_cvt_scalef32_pk_f16_fp4 v63, v63, 1.0 op_sel:[1,1,0]
	v_pk_fma_f16 v63, v6, v63, v67 op_sel_hi:[0,1,1]
	v_cvt_scalef32_pk_f16_fp4 v67, v64, 1.0
	v_pk_fma_f16 v45, v6, v45, v77 op_sel_hi:[0,1,1]
	v_pk_fma_f16 v67, v6, v67, v75 op_sel_hi:[0,1,1]
	v_cvt_scalef32_pk_f16_fp4 v75, v64, 1.0 op_sel:[1,0,0]
	v_cvt_scalef32_pk_f16_fp4 v77, v64, 1.0 op_sel:[0,1,0]
	v_cvt_scalef32_pk_f16_fp4 v64, v64, 1.0 op_sel:[1,1,0]
	v_pk_fma_f16 v64, v6, v64, v68 op_sel_hi:[0,1,1]
	v_cvt_scalef32_pk_f16_fp4 v68, v65, 1.0
	v_pk_fma_f16 v69, v6, v69, v82 op_sel_hi:[0,1,1]
	v_pk_fma_f16 v68, v6, v68, v76 op_sel_hi:[0,1,1]
	v_cvt_scalef32_pk_f16_fp4 v76, v65, 1.0 op_sel:[1,0,0]
	v_cvt_scalef32_pk_f16_fp4 v82, v65, 1.0 op_sel:[0,1,0]
	v_cvt_scalef32_pk_f16_fp4 v65, v65, 1.0 op_sel:[1,1,0]
	v_pk_fma_f16 v42, v6, v65, v42 op_sel_hi:[0,1,1]
	s_waitcnt vmcnt(30)
	v_cvt_scalef32_pk_f16_fp4 v65, v54, 1.0
	v_pk_fma_f16 v43, v6, v65, v43 op_sel:[1,0,0]
	v_cvt_scalef32_pk_f16_fp4 v65, v54, 1.0 op_sel:[1,0,0]
	v_pk_fma_f16 v44, v6, v65, v44 op_sel:[1,0,0]
	v_cvt_scalef32_pk_f16_fp4 v65, v54, 1.0 op_sel:[0,1,0]
	v_cvt_scalef32_pk_f16_fp4 v54, v54, 1.0 op_sel:[1,1,0]
	v_pk_fma_f16 v54, v6, v54, v62 op_sel:[1,0,0]
	v_cvt_scalef32_pk_f16_fp4 v62, v55, 1.0
	v_pk_fma_f16 v45, v6, v65, v45 op_sel:[1,0,0]
	v_pk_fma_f16 v62, v6, v62, v66 op_sel:[1,0,0]
	v_cvt_scalef32_pk_f16_fp4 v65, v55, 1.0 op_sel:[1,0,0]
	v_cvt_scalef32_pk_f16_fp4 v66, v55, 1.0 op_sel:[0,1,0]
	v_cvt_scalef32_pk_f16_fp4 v55, v55, 1.0 op_sel:[1,1,0]
	v_pk_fma_f16 v55, v6, v55, v63 op_sel:[1,0,0]
	v_cvt_scalef32_pk_f16_fp4 v63, v56, 1.0
	v_pk_fma_f16 v65, v6, v65, v69 op_sel:[1,0,0]
	v_pk_fma_f16 v63, v6, v63, v67 op_sel:[1,0,0]
	v_cvt_scalef32_pk_f16_fp4 v67, v56, 1.0 op_sel:[1,0,0]
	v_cvt_scalef32_pk_f16_fp4 v69, v56, 1.0 op_sel:[0,1,0]
	v_cvt_scalef32_pk_f16_fp4 v56, v56, 1.0 op_sel:[1,1,0]
	v_pk_fma_f16 v74, v6, v74, v85 op_sel_hi:[0,1,1]
	v_pk_fma_f16 v56, v6, v56, v64 op_sel:[1,0,0]
	v_cvt_scalef32_pk_f16_fp4 v64, v57, 1.0
	v_pk_fma_f16 v75, v6, v75, v83 op_sel_hi:[0,1,1]
	v_pk_fma_f16 v77, v6, v77, v98 op_sel_hi:[0,1,1]
	v_pk_fma_f16 v76, v6, v76, v84 op_sel_hi:[0,1,1]
	v_pk_fma_f16 v82, v6, v82, v99 op_sel_hi:[0,1,1]
	v_pk_fma_f16 v66, v6, v66, v74 op_sel:[1,0,0]
	v_pk_fma_f16 v64, v6, v64, v68 op_sel:[1,0,0]
	v_cvt_scalef32_pk_f16_fp4 v68, v57, 1.0 op_sel:[1,0,0]
	v_cvt_scalef32_pk_f16_fp4 v74, v57, 1.0 op_sel:[0,1,0]
	v_cvt_scalef32_pk_f16_fp4 v57, v57, 1.0 op_sel:[1,1,0]
	v_pk_fma_f16 v67, v6, v67, v75 op_sel:[1,0,0]
	v_pk_fma_f16 v69, v6, v69, v77 op_sel:[1,0,0]
	v_pk_fma_f16 v68, v6, v68, v76 op_sel:[1,0,0]
	v_pk_fma_f16 v74, v6, v74, v82 op_sel:[1,0,0]
	v_pk_fma_f16 v6, v6, v57, v42 op_sel:[1,0,0]
	s_waitcnt vmcnt(29)
	v_cvt_scalef32_pk_f16_fp4 v42, v46, 1.0
	v_pk_fma_f16 v42, v7, v42, v43 op_sel_hi:[0,1,1]
	v_cvt_scalef32_pk_f16_fp4 v43, v46, 1.0 op_sel:[1,0,0]
	v_pk_fma_f16 v43, v7, v43, v44 op_sel_hi:[0,1,1]
	v_cvt_scalef32_pk_f16_fp4 v44, v46, 1.0 op_sel:[0,1,0]
	v_pk_fma_f16 v44, v7, v44, v45 op_sel_hi:[0,1,1]
	v_cvt_scalef32_pk_f16_fp4 v45, v46, 1.0 op_sel:[1,1,0]
	v_pk_fma_f16 v45, v7, v45, v54 op_sel_hi:[0,1,1]
	v_cvt_scalef32_pk_f16_fp4 v46, v47, 1.0
	v_cvt_scalef32_pk_f16_fp4 v54, v47, 1.0 op_sel:[1,0,0]
	v_cvt_scalef32_pk_f16_fp4 v57, v47, 1.0 op_sel:[0,1,0]
	v_cvt_scalef32_pk_f16_fp4 v47, v47, 1.0 op_sel:[1,1,0]
	v_pk_fma_f16 v47, v7, v47, v55 op_sel_hi:[0,1,1]
	v_cvt_scalef32_pk_f16_fp4 v55, v48, 1.0
	v_pk_fma_f16 v46, v7, v46, v62 op_sel_hi:[0,1,1]
	v_pk_fma_f16 v55, v7, v55, v63 op_sel_hi:[0,1,1]
	v_cvt_scalef32_pk_f16_fp4 v62, v48, 1.0 op_sel:[1,0,0]
	v_cvt_scalef32_pk_f16_fp4 v63, v48, 1.0 op_sel:[0,1,0]
	v_cvt_scalef32_pk_f16_fp4 v48, v48, 1.0 op_sel:[1,1,0]
	v_pk_fma_f16 v48, v7, v48, v56 op_sel_hi:[0,1,1]
	v_cvt_scalef32_pk_f16_fp4 v56, v49, 1.0
	v_pk_fma_f16 v54, v7, v54, v65 op_sel_hi:[0,1,1]
	v_pk_fma_f16 v56, v7, v56, v64 op_sel_hi:[0,1,1]
	v_cvt_scalef32_pk_f16_fp4 v64, v49, 1.0 op_sel:[1,0,0]
	v_cvt_scalef32_pk_f16_fp4 v65, v49, 1.0 op_sel:[0,1,0]
	v_cvt_scalef32_pk_f16_fp4 v49, v49, 1.0 op_sel:[1,1,0]
	v_pk_fma_f16 v6, v7, v49, v6 op_sel_hi:[0,1,1]
	s_waitcnt vmcnt(28)
	v_cvt_scalef32_pk_f16_fp4 v49, v34, 1.0
	v_pk_fma_f16 v42, v7, v49, v42 op_sel:[1,0,0]
	v_cvt_scalef32_pk_f16_fp4 v49, v34, 1.0 op_sel:[1,0,0]
	v_pk_fma_f16 v43, v7, v49, v43 op_sel:[1,0,0]
	v_cvt_scalef32_pk_f16_fp4 v49, v34, 1.0 op_sel:[0,1,0]
	v_cvt_scalef32_pk_f16_fp4 v34, v34, 1.0 op_sel:[1,1,0]
	v_pk_fma_f16 v34, v7, v34, v45 op_sel:[1,0,0]
	v_cvt_scalef32_pk_f16_fp4 v45, v35, 1.0
	v_pk_fma_f16 v44, v7, v49, v44 op_sel:[1,0,0]
	v_pk_fma_f16 v45, v7, v45, v46 op_sel:[1,0,0]
	v_cvt_scalef32_pk_f16_fp4 v46, v35, 1.0 op_sel:[1,0,0]
	v_cvt_scalef32_pk_f16_fp4 v49, v35, 1.0 op_sel:[0,1,0]
	v_cvt_scalef32_pk_f16_fp4 v35, v35, 1.0 op_sel:[1,1,0]
	v_pk_fma_f16 v35, v7, v35, v47 op_sel:[1,0,0]
	v_cvt_scalef32_pk_f16_fp4 v47, v36, 1.0
	v_pk_fma_f16 v46, v7, v46, v54 op_sel:[1,0,0]
	v_pk_fma_f16 v47, v7, v47, v55 op_sel:[1,0,0]
	v_cvt_scalef32_pk_f16_fp4 v54, v36, 1.0 op_sel:[1,0,0]
	v_cvt_scalef32_pk_f16_fp4 v55, v36, 1.0 op_sel:[0,1,0]
	v_cvt_scalef32_pk_f16_fp4 v36, v36, 1.0 op_sel:[1,1,0]
	v_pk_fma_f16 v57, v7, v57, v66 op_sel_hi:[0,1,1]
	v_pk_fma_f16 v36, v7, v36, v48 op_sel:[1,0,0]
	v_cvt_scalef32_pk_f16_fp4 v48, v37, 1.0
	v_pk_fma_f16 v62, v7, v62, v67 op_sel_hi:[0,1,1]
	v_pk_fma_f16 v63, v7, v63, v69 op_sel_hi:[0,1,1]
	v_pk_fma_f16 v64, v7, v64, v68 op_sel_hi:[0,1,1]
	v_pk_fma_f16 v65, v7, v65, v74 op_sel_hi:[0,1,1]
	v_pk_fma_f16 v49, v7, v49, v57 op_sel:[1,0,0]
	v_pk_fma_f16 v48, v7, v48, v56 op_sel:[1,0,0]
	v_cvt_scalef32_pk_f16_fp4 v56, v37, 1.0 op_sel:[1,0,0]
	v_cvt_scalef32_pk_f16_fp4 v57, v37, 1.0 op_sel:[0,1,0]
	v_cvt_scalef32_pk_f16_fp4 v37, v37, 1.0 op_sel:[1,1,0]
	v_pk_fma_f16 v54, v7, v54, v62 op_sel:[1,0,0]
	v_pk_fma_f16 v55, v7, v55, v63 op_sel:[1,0,0]
	v_pk_fma_f16 v56, v7, v56, v64 op_sel:[1,0,0]
	v_pk_fma_f16 v57, v7, v57, v65 op_sel:[1,0,0]
	v_pk_fma_f16 v6, v7, v37, v6 op_sel:[1,0,0]
	s_waitcnt vmcnt(27)
	v_cvt_scalef32_pk_f16_fp4 v7, v26, 1.0
	v_pk_fma_f16 v7, v8, v7, v42 op_sel_hi:[0,1,1]
	v_cvt_scalef32_pk_f16_fp4 v37, v26, 1.0 op_sel:[1,0,0]
	v_cvt_scalef32_pk_f16_fp4 v42, v26, 1.0 op_sel:[0,1,0]
	v_cvt_scalef32_pk_f16_fp4 v26, v26, 1.0 op_sel:[1,1,0]
	v_pk_fma_f16 v37, v8, v37, v43 op_sel_hi:[0,1,1]
	v_pk_fma_f16 v42, v8, v42, v44 op_sel_hi:[0,1,1]
	v_pk_fma_f16 v26, v8, v26, v34 op_sel_hi:[0,1,1]
	v_cvt_scalef32_pk_f16_fp4 v34, v27, 1.0
	v_cvt_scalef32_pk_f16_fp4 v43, v27, 1.0 op_sel:[1,0,0]
	v_cvt_scalef32_pk_f16_fp4 v44, v27, 1.0 op_sel:[0,1,0]
	v_cvt_scalef32_pk_f16_fp4 v27, v27, 1.0 op_sel:[1,1,0]
	v_pk_fma_f16 v34, v8, v34, v45 op_sel_hi:[0,1,1]
	v_pk_fma_f16 v43, v8, v43, v46 op_sel_hi:[0,1,1]
	v_pk_fma_f16 v27, v8, v27, v35 op_sel_hi:[0,1,1]
	v_cvt_scalef32_pk_f16_fp4 v35, v28, 1.0
	v_cvt_scalef32_pk_f16_fp4 v45, v28, 1.0 op_sel:[1,0,0]
	v_cvt_scalef32_pk_f16_fp4 v46, v28, 1.0 op_sel:[0,1,0]
	v_cvt_scalef32_pk_f16_fp4 v28, v28, 1.0 op_sel:[1,1,0]
	v_pk_fma_f16 v28, v8, v28, v36 op_sel_hi:[0,1,1]
	v_cvt_scalef32_pk_f16_fp4 v36, v29, 1.0
	v_pk_fma_f16 v35, v8, v35, v47 op_sel_hi:[0,1,1]
	v_pk_fma_f16 v36, v8, v36, v48 op_sel_hi:[0,1,1]
	v_cvt_scalef32_pk_f16_fp4 v47, v29, 1.0 op_sel:[1,0,0]
	v_cvt_scalef32_pk_f16_fp4 v48, v29, 1.0 op_sel:[0,1,0]
	v_cvt_scalef32_pk_f16_fp4 v29, v29, 1.0 op_sel:[1,1,0]
	v_pk_fma_f16 v6, v8, v29, v6 op_sel_hi:[0,1,1]
	s_waitcnt vmcnt(26)
	v_cvt_scalef32_pk_f16_fp4 v29, v22, 1.0
	v_pk_fma_f16 v7, v8, v29, v7 op_sel:[1,0,0]
	v_cvt_scalef32_pk_f16_fp4 v29, v22, 1.0 op_sel:[1,0,0]
	v_pk_fma_f16 v29, v8, v29, v37 op_sel:[1,0,0]
	v_cvt_scalef32_pk_f16_fp4 v37, v22, 1.0 op_sel:[0,1,0]
	v_cvt_scalef32_pk_f16_fp4 v22, v22, 1.0 op_sel:[1,1,0]
	v_pk_fma_f16 v22, v8, v22, v26 op_sel:[1,0,0]
	v_cvt_scalef32_pk_f16_fp4 v26, v23, 1.0
	v_pk_fma_f16 v37, v8, v37, v42 op_sel:[1,0,0]
	v_pk_fma_f16 v26, v8, v26, v34 op_sel:[1,0,0]
	v_cvt_scalef32_pk_f16_fp4 v34, v23, 1.0 op_sel:[1,0,0]
	v_cvt_scalef32_pk_f16_fp4 v42, v23, 1.0 op_sel:[0,1,0]
	v_cvt_scalef32_pk_f16_fp4 v23, v23, 1.0 op_sel:[1,1,0]
	v_pk_fma_f16 v23, v8, v23, v27 op_sel:[1,0,0]
	v_cvt_scalef32_pk_f16_fp4 v27, v24, 1.0
	v_pk_fma_f16 v34, v8, v34, v43 op_sel:[1,0,0]
	v_pk_fma_f16 v27, v8, v27, v35 op_sel:[1,0,0]
	v_cvt_scalef32_pk_f16_fp4 v35, v24, 1.0 op_sel:[1,0,0]
	v_cvt_scalef32_pk_f16_fp4 v43, v24, 1.0 op_sel:[0,1,0]
	v_cvt_scalef32_pk_f16_fp4 v24, v24, 1.0 op_sel:[1,1,0]
	v_pk_fma_f16 v44, v8, v44, v49 op_sel_hi:[0,1,1]
	v_pk_fma_f16 v24, v8, v24, v28 op_sel:[1,0,0]
	v_cvt_scalef32_pk_f16_fp4 v28, v25, 1.0
	v_pk_fma_f16 v45, v8, v45, v54 op_sel_hi:[0,1,1]
	v_pk_fma_f16 v46, v8, v46, v55 op_sel_hi:[0,1,1]
	v_pk_fma_f16 v47, v8, v47, v56 op_sel_hi:[0,1,1]
	v_pk_fma_f16 v48, v8, v48, v57 op_sel_hi:[0,1,1]
	v_pk_fma_f16 v42, v8, v42, v44 op_sel:[1,0,0]
	v_pk_fma_f16 v28, v8, v28, v36 op_sel:[1,0,0]
	v_cvt_scalef32_pk_f16_fp4 v36, v25, 1.0 op_sel:[1,0,0]
	v_cvt_scalef32_pk_f16_fp4 v44, v25, 1.0 op_sel:[0,1,0]
	v_cvt_scalef32_pk_f16_fp4 v25, v25, 1.0 op_sel:[1,1,0]
	v_pk_fma_f16 v35, v8, v35, v45 op_sel:[1,0,0]
	v_pk_fma_f16 v43, v8, v43, v46 op_sel:[1,0,0]
	v_pk_fma_f16 v36, v8, v36, v47 op_sel:[1,0,0]
	v_pk_fma_f16 v44, v8, v44, v48 op_sel:[1,0,0]
	v_pk_fma_f16 v6, v8, v25, v6 op_sel:[1,0,0]
	s_waitcnt vmcnt(25)
	v_cvt_scalef32_pk_f16_fp4 v8, v14, 1.0
	v_pk_fma_f16 v7, v9, v8, v7 op_sel_hi:[0,1,1]
	v_cvt_scalef32_pk_f16_fp4 v8, v14, 1.0 op_sel:[1,0,0]
	v_cvt_scalef32_pk_f16_fp4 v25, v14, 1.0 op_sel:[0,1,0]
	v_cvt_scalef32_pk_f16_fp4 v14, v14, 1.0 op_sel:[1,1,0]
	v_pk_fma_f16 v14, v9, v14, v22 op_sel_hi:[0,1,1]
	v_cvt_scalef32_pk_f16_fp4 v22, v15, 1.0
	v_pk_fma_f16 v8, v9, v8, v29 op_sel_hi:[0,1,1]
	v_pk_fma_f16 v22, v9, v22, v26 op_sel_hi:[0,1,1]
	v_cvt_scalef32_pk_f16_fp4 v26, v15, 1.0 op_sel:[1,0,0]
	v_cvt_scalef32_pk_f16_fp4 v29, v15, 1.0 op_sel:[0,1,0]
	v_cvt_scalef32_pk_f16_fp4 v15, v15, 1.0 op_sel:[1,1,0]
	v_pk_fma_f16 v15, v9, v15, v23 op_sel_hi:[0,1,1]
	v_cvt_scalef32_pk_f16_fp4 v23, v16, 1.0
	v_pk_fma_f16 v26, v9, v26, v34 op_sel_hi:[0,1,1]
	v_pk_fma_f16 v23, v9, v23, v27 op_sel_hi:[0,1,1]
	v_cvt_scalef32_pk_f16_fp4 v27, v16, 1.0 op_sel:[1,0,0]
	v_cvt_scalef32_pk_f16_fp4 v34, v16, 1.0 op_sel:[0,1,0]
	v_cvt_scalef32_pk_f16_fp4 v16, v16, 1.0 op_sel:[1,1,0]
	v_pk_fma_f16 v16, v9, v16, v24 op_sel_hi:[0,1,1]
	v_cvt_scalef32_pk_f16_fp4 v24, v17, 1.0
	v_pk_fma_f16 v27, v9, v27, v35 op_sel_hi:[0,1,1]
	v_pk_fma_f16 v24, v9, v24, v28 op_sel_hi:[0,1,1]
	v_cvt_scalef32_pk_f16_fp4 v28, v17, 1.0 op_sel:[1,0,0]
	v_cvt_scalef32_pk_f16_fp4 v35, v17, 1.0 op_sel:[0,1,0]
	v_cvt_scalef32_pk_f16_fp4 v17, v17, 1.0 op_sel:[1,1,0]
	v_pk_fma_f16 v6, v9, v17, v6 op_sel_hi:[0,1,1]
	s_waitcnt vmcnt(24)
	v_cvt_scalef32_pk_f16_fp4 v17, v10, 1.0
	v_pk_fma_f16 v7, v9, v17, v7 op_sel:[1,0,0]
	v_cvt_scalef32_pk_f16_fp4 v17, v10, 1.0 op_sel:[1,0,0]
	v_pk_fma_f16 v8, v9, v17, v8 op_sel:[1,0,0]
	v_cvt_scalef32_pk_f16_fp4 v17, v10, 1.0 op_sel:[0,1,0]
	v_cvt_scalef32_pk_f16_fp4 v10, v10, 1.0 op_sel:[1,1,0]
	v_pk_fma_f16 v25, v9, v25, v37 op_sel_hi:[0,1,1]
	v_pk_fma_f16 v10, v9, v10, v14 op_sel:[1,0,0]
	v_cvt_scalef32_pk_f16_fp4 v14, v11, 1.0
	v_pk_fma_f16 v17, v9, v17, v25 op_sel:[1,0,0]
	v_pk_fma_f16 v14, v9, v14, v22 op_sel:[1,0,0]
	v_cvt_scalef32_pk_f16_fp4 v22, v11, 1.0 op_sel:[1,0,0]
	v_cvt_scalef32_pk_f16_fp4 v25, v11, 1.0 op_sel:[0,1,0]
	v_cvt_scalef32_pk_f16_fp4 v11, v11, 1.0 op_sel:[1,1,0]
	v_pk_fma_f16 v11, v9, v11, v15 op_sel:[1,0,0]
	v_cvt_scalef32_pk_f16_fp4 v15, v12, 1.0
	v_pk_fma_f16 v22, v9, v22, v26 op_sel:[1,0,0]
	v_pk_fma_f16 v15, v9, v15, v23 op_sel:[1,0,0]
	v_cvt_scalef32_pk_f16_fp4 v23, v12, 1.0 op_sel:[1,0,0]
	v_cvt_scalef32_pk_f16_fp4 v26, v12, 1.0 op_sel:[0,1,0]
	v_cvt_scalef32_pk_f16_fp4 v12, v12, 1.0 op_sel:[1,1,0]
	v_pk_fma_f16 v29, v9, v29, v42 op_sel_hi:[0,1,1]
	v_pk_fma_f16 v34, v9, v34, v43 op_sel_hi:[0,1,1]
	v_pk_fma_f16 v35, v9, v35, v44 op_sel_hi:[0,1,1]
	v_pk_fma_f16 v23, v9, v23, v27 op_sel:[1,0,0]
	v_pk_fma_f16 v12, v9, v12, v16 op_sel:[1,0,0]
	v_cvt_scalef32_pk_f16_fp4 v16, v13, 1.0
	v_cvt_scalef32_pk_f16_fp4 v27, v13, 1.0 op_sel:[0,1,0]
	v_pk_fma_f16 v25, v9, v25, v29 op_sel:[1,0,0]
	v_pk_fma_f16 v26, v9, v26, v34 op_sel:[1,0,0]
	v_pk_fma_f16 v16, v9, v16, v24 op_sel:[1,0,0]
	v_cvt_scalef32_pk_f16_fp4 v24, v13, 1.0 op_sel:[1,0,0]
	v_pk_fma_f16 v27, v9, v27, v35 op_sel:[1,0,0]
	v_cvt_scalef32_pk_f16_fp4 v13, v13, 1.0 op_sel:[1,1,0]
	v_pk_fma_f16 v28, v9, v28, v36 op_sel_hi:[0,1,1]
	v_pk_fma_f16 v6, v9, v13, v6 op_sel:[1,0,0]
	v_permlane32_swap_b32_e32 v7, v15
	v_permlane32_swap_b32_e32 v17, v26
	v_permlane32_swap_b32_e32 v10, v12
	v_permlane32_swap_b32_e32 v14, v16
	v_permlane32_swap_b32_e32 v25, v27
	v_pk_fma_f16 v24, v9, v24, v28 op_sel:[1,0,0]
	v_pk_add_f16 v7, v7, v15
	v_pk_add_f16 v9, v17, v26
	v_pk_add_f16 v10, v10, v12
	v_pk_add_f16 v12, v14, v16
	v_pk_add_f16 v14, v25, v27
	v_permlane32_swap_b32_e32 v11, v6
	v_permlane32_swap_b32_e32 v8, v23
	v_permlane32_swap_b32_e32 v22, v24
	v_pk_add_f16 v6, v11, v6
	v_permlane16_swap_b32_e32 v7, v12
	v_permlane16_swap_b32_e32 v9, v14
	v_pk_add_f16 v8, v8, v23
	v_pk_add_f16 v13, v22, v24
	v_pk_add_f16 v7, v7, v12
	v_pk_add_f16 v9, v9, v14
	v_permlane16_swap_b32_e32 v10, v6
	v_permlane16_swap_b32_e32 v8, v13
	v_pk_add_f16 v6, v10, v6
	v_cndmask_b32_e64 v10, v9, v7, s[8:9]
	v_cndmask_b32_e64 v7, v7, v9, s[8:9]
	v_pk_add_f16 v8, v8, v13
	v_cvt_f32_f16_sdwa v13, v189 dst_sel:DWORD dst_unused:UNUSED_PAD src0_sel:WORD_1
	v_mov_b32_dpp v7, v7 row_ror:8 row_mask:0xf bank_mask:0xf bound_ctrl:1
	v_pk_add_f16 v9, v10, v7
	v_cndmask_b32_e64 v10, v6, v8, s[8:9]
	v_cndmask_b32_e64 v6, v8, v6, s[8:9]
	v_cvt_f32_f16_sdwa v7, v188 dst_sel:DWORD dst_unused:UNUSED_PAD src0_sel:WORD_1
	v_cvt_f32_f16_e32 v8, v9
	v_mov_b32_dpp v11, v6 row_ror:8 row_mask:0xf bank_mask:0xf bound_ctrl:1
	v_cvt_f32_f16_e32 v6, v188
	v_cvt_f32_f16_sdwa v9, v9 dst_sel:DWORD dst_unused:UNUSED_PAD src0_sel:WORD_1
	v_pk_add_f16 v15, v10, v11
	v_cvt_f32_f16_sdwa v11, v194 dst_sel:DWORD dst_unused:UNUSED_PAD src0_sel:WORD_1
	v_cvt_f32_f16_e32 v10, v194
	v_cvt_f32_f16_e32 v12, v189
	v_cvt_f32_f16_e32 v14, v15
	v_cvt_f32_f16_sdwa v15, v15 dst_sel:DWORD dst_unused:UNUSED_PAD src0_sel:WORD_1
	v_pk_fma_f32 v[6:7], v[2:3], v[8:9], v[6:7]
	v_cvt_f32_f16_sdwa v9, v195 dst_sel:DWORD dst_unused:UNUSED_PAD src0_sel:WORD_1
	v_cvt_f32_f16_e32 v8, v195
	v_pk_add_f32 v[6:7], v[6:7], v[10:11]
	v_pk_fma_f32 v[10:11], v[4:5], v[14:15], v[12:13]
	v_cvt_pk_f16_f32 v6, v6, v7
	v_pk_add_f32 v[8:9], v[10:11], v[8:9]
	s_nop 0
	v_cvt_pk_f16_f32 v7, v8, v9
	v_lshl_add_u64 v[8:9], v[190:191], 0, s[18:19]
	global_store_dwordx2 v[8:9], v[6:7], off
	v_lshl_add_u64 v[6:7], v[184:185], 0, s[20:21]
	v_lshl_add_u64 v[10:11], v[186:187], 0, s[24:25]
	global_load_dwordx4 v[118:121], v[6:7], off offset:48
	global_load_dwordx4 v[122:125], v[6:7], off offset:32
	global_load_dwordx4 v[130:133], v[6:7], off offset:16
	global_load_dwordx4 v[138:141], v[6:7], off
	s_nop 0
	global_load_dwordx4 v[6:9], v[10:11], off offset:16
	global_load_dwordx4 v[42:45], v[10:11], off
	v_lshl_add_u64 v[10:11], v[190:191], 0, s[22:23]
	v_lshl_add_u64 v[12:13], v[192:193], 0, s[22:23]
	global_load_dwordx2 v[194:195], v[10:11], off
	global_load_dwordx2 v[188:189], v[12:13], off
	s_waitcnt vmcnt(29)
	v_lshl_add_u32 v10, v178, 7, v207
	v_lshl_add_u32 v11, v179, 7, v207
	global_load_dwordx4 v[146:149], v10, s[10:11]
	global_load_dwordx4 v[134:137], v11, s[10:11]
	v_lshl_add_u32 v10, v180, 7, v207
	v_lshl_add_u32 v11, v181, 7, v207
	global_load_dwordx4 v[114:117], v10, s[10:11]
	global_load_dwordx4 v[106:109], v11, s[10:11]
	v_lshl_add_u32 v10, v174, 7, v207
	v_lshl_add_u32 v11, v175, 7, v207
	global_load_dwordx4 v[98:101], v10, s[10:11]
	global_load_dwordx4 v[82:85], v11, s[10:11]
	v_lshl_add_u32 v10, v176, 7, v207
	v_lshl_add_u32 v11, v177, 7, v207
	global_load_dwordx4 v[74:77], v10, s[10:11]
	global_load_dwordx4 v[66:69], v11, s[10:11]
	v_lshl_add_u32 v10, v170, 7, v207
	v_lshl_add_u32 v11, v171, 7, v207
	global_load_dwordx4 v[62:65], v10, s[10:11]
	global_load_dwordx4 v[54:57], v11, s[10:11]
	v_lshl_add_u32 v10, v172, 7, v207
	v_lshl_add_u32 v11, v173, 7, v207
	global_load_dwordx4 v[46:49], v10, s[10:11]
	global_load_dwordx4 v[34:37], v11, s[10:11]
	v_lshl_add_u32 v10, v166, 7, v207
	v_lshl_add_u32 v11, v167, 7, v207
	global_load_dwordx4 v[26:29], v10, s[10:11]
	global_load_dwordx4 v[22:25], v11, s[10:11]
	v_lshl_add_u32 v10, v168, 7, v207
	v_lshl_add_u32 v11, v169, 7, v207
	global_load_dwordx4 v[14:17], v10, s[10:11]
	s_nop 0
	global_load_dwordx4 v[10:13], v11, s[10:11]
	s_waitcnt vmcnt(40)
	v_cvt_scalef32_pk_f16_fp4 v166, v162, 1.0
	v_pk_fma_f16 v166, v90, v166, 0 op_sel_hi:[0,1,1]
	v_cvt_scalef32_pk_f16_fp4 v167, v162, 1.0 op_sel:[1,0,0]
	s_waitcnt vmcnt(39)
	v_cvt_scalef32_pk_f16_fp4 v178, v158, 1.0
	v_pk_fma_f16 v167, v90, v167, 0 op_sel_hi:[0,1,1]
	v_cvt_scalef32_pk_f16_fp4 v168, v162, 1.0 op_sel:[0,1,0]
	v_cvt_scalef32_pk_f16_fp4 v162, v162, 1.0 op_sel:[1,1,0]
	v_pk_fma_f16 v166, v90, v178, v166 op_sel:[1,0,0]
	v_cvt_scalef32_pk_f16_fp4 v178, v158, 1.0 op_sel:[1,0,0]
	v_pk_fma_f16 v162, v90, v162, 0 op_sel_hi:[0,1,1]
	v_cvt_scalef32_pk_f16_fp4 v169, v163, 1.0
	v_pk_fma_f16 v167, v90, v178, v167 op_sel:[1,0,0]
	v_cvt_scalef32_pk_f16_fp4 v178, v158, 1.0 op_sel:[0,1,0]
	v_cvt_scalef32_pk_f16_fp4 v158, v158, 1.0 op_sel:[1,1,0]
	v_pk_fma_f16 v169, v90, v169, 0 op_sel_hi:[0,1,1]
	v_cvt_scalef32_pk_f16_fp4 v170, v163, 1.0 op_sel:[1,0,0]
	v_pk_fma_f16 v158, v90, v158, v162 op_sel:[1,0,0]
	v_cvt_scalef32_pk_f16_fp4 v162, v159, 1.0
	v_pk_fma_f16 v170, v90, v170, 0 op_sel_hi:[0,1,1]
	v_cvt_scalef32_pk_f16_fp4 v171, v163, 1.0 op_sel:[0,1,0]
	v_cvt_scalef32_pk_f16_fp4 v163, v163, 1.0 op_sel:[1,1,0]
	v_pk_fma_f16 v162, v90, v162, v169 op_sel:[1,0,0]
	v_cvt_scalef32_pk_f16_fp4 v169, v159, 1.0 op_sel:[1,0,0]
	v_pk_fma_f16 v163, v90, v163, 0 op_sel_hi:[0,1,1]
	v_cvt_scalef32_pk_f16_fp4 v172, v164, 1.0
	v_pk_fma_f16 v169, v90, v169, v170 op_sel:[1,0,0]
	v_cvt_scalef32_pk_f16_fp4 v170, v159, 1.0 op_sel:[0,1,0]
	v_cvt_scalef32_pk_f16_fp4 v159, v159, 1.0 op_sel:[1,1,0]
	v_pk_fma_f16 v171, v90, v171, 0 op_sel_hi:[0,1,1]
	v_pk_fma_f16 v172, v90, v172, 0 op_sel_hi:[0,1,1]
	v_cvt_scalef32_pk_f16_fp4 v173, v164, 1.0 op_sel:[1,0,0]
	v_cvt_scalef32_pk_f16_fp4 v174, v164, 1.0 op_sel:[0,1,0]
	v_cvt_scalef32_pk_f16_fp4 v164, v164, 1.0 op_sel:[1,1,0]
	v_pk_fma_f16 v159, v90, v159, v163 op_sel:[1,0,0]
	v_cvt_scalef32_pk_f16_fp4 v163, v160, 1.0
	v_pk_fma_f16 v173, v90, v173, 0 op_sel_hi:[0,1,1]
	v_pk_fma_f16 v174, v90, v174, 0 op_sel_hi:[0,1,1]
	v_pk_fma_f16 v164, v90, v164, 0 op_sel_hi:[0,1,1]
	v_cvt_scalef32_pk_f16_fp4 v175, v165, 1.0
	v_cvt_scalef32_pk_f16_fp4 v176, v165, 1.0 op_sel:[1,0,0]
	v_cvt_scalef32_pk_f16_fp4 v177, v165, 1.0 op_sel:[0,1,0]
	v_cvt_scalef32_pk_f16_fp4 v165, v165, 1.0 op_sel:[1,1,0]
	v_pk_fma_f16 v170, v90, v170, v171 op_sel:[1,0,0]
	v_pk_fma_f16 v163, v90, v163, v172 op_sel:[1,0,0]
	v_cvt_scalef32_pk_f16_fp4 v171, v160, 1.0 op_sel:[1,0,0]
	v_cvt_scalef32_pk_f16_fp4 v172, v160, 1.0 op_sel:[0,1,0]
	v_cvt_scalef32_pk_f16_fp4 v160, v160, 1.0 op_sel:[1,1,0]
	v_pk_fma_f16 v168, v90, v168, 0 op_sel_hi:[0,1,1]
	v_pk_fma_f16 v175, v90, v175, 0 op_sel_hi:[0,1,1]
	v_pk_fma_f16 v176, v90, v176, 0 op_sel_hi:[0,1,1]
	v_pk_fma_f16 v177, v90, v177, 0 op_sel_hi:[0,1,1]
	v_pk_fma_f16 v165, v90, v165, 0 op_sel_hi:[0,1,1]
	v_pk_fma_f16 v171, v90, v171, v173 op_sel:[1,0,0]
	v_pk_fma_f16 v172, v90, v172, v174 op_sel:[1,0,0]
	v_pk_fma_f16 v160, v90, v160, v164 op_sel:[1,0,0]
	v_cvt_scalef32_pk_f16_fp4 v164, v161, 1.0
	v_cvt_scalef32_pk_f16_fp4 v173, v161, 1.0 op_sel:[1,0,0]
	v_cvt_scalef32_pk_f16_fp4 v174, v161, 1.0 op_sel:[0,1,0]
	v_cvt_scalef32_pk_f16_fp4 v161, v161, 1.0 op_sel:[1,1,0]
	v_pk_fma_f16 v168, v90, v178, v168 op_sel:[1,0,0]
	v_pk_fma_f16 v164, v90, v164, v175 op_sel:[1,0,0]
	v_pk_fma_f16 v173, v90, v173, v176 op_sel:[1,0,0]
	v_pk_fma_f16 v174, v90, v174, v177 op_sel:[1,0,0]
	v_pk_fma_f16 v90, v90, v161, v165 op_sel:[1,0,0]
	s_waitcnt vmcnt(38)
	v_cvt_scalef32_pk_f16_fp4 v161, v154, 1.0
	v_pk_fma_f16 v161, v91, v161, v166 op_sel_hi:[0,1,1]
	v_cvt_scalef32_pk_f16_fp4 v165, v154, 1.0 op_sel:[1,0,0]
	v_cvt_scalef32_pk_f16_fp4 v166, v154, 1.0 op_sel:[0,1,0]
	v_cvt_scalef32_pk_f16_fp4 v154, v154, 1.0 op_sel:[1,1,0]
	v_pk_fma_f16 v154, v91, v154, v158 op_sel_hi:[0,1,1]
	v_cvt_scalef32_pk_f16_fp4 v158, v155, 1.0
	v_pk_fma_f16 v165, v91, v165, v167 op_sel_hi:[0,1,1]
	v_pk_fma_f16 v158, v91, v158, v162 op_sel_hi:[0,1,1]
	v_cvt_scalef32_pk_f16_fp4 v162, v155, 1.0 op_sel:[1,0,0]
	v_cvt_scalef32_pk_f16_fp4 v167, v155, 1.0 op_sel:[0,1,0]
	v_cvt_scalef32_pk_f16_fp4 v155, v155, 1.0 op_sel:[1,1,0]
	v_pk_fma_f16 v155, v91, v155, v159 op_sel_hi:[0,1,1]
	v_cvt_scalef32_pk_f16_fp4 v159, v156, 1.0
	v_pk_fma_f16 v166, v91, v166, v168 op_sel_hi:[0,1,1]
	v_pk_fma_f16 v159, v91, v159, v163 op_sel_hi:[0,1,1]
	v_cvt_scalef32_pk_f16_fp4 v163, v156, 1.0 op_sel:[1,0,0]
	v_cvt_scalef32_pk_f16_fp4 v168, v156, 1.0 op_sel:[0,1,0]
	v_cvt_scalef32_pk_f16_fp4 v156, v156, 1.0 op_sel:[1,1,0]
	v_pk_fma_f16 v156, v91, v156, v160 op_sel_hi:[0,1,1]
	v_cvt_scalef32_pk_f16_fp4 v160, v157, 1.0
	v_pk_fma_f16 v162, v91, v162, v169 op_sel_hi:[0,1,1]
	v_pk_fma_f16 v160, v91, v160, v164 op_sel_hi:[0,1,1]
	v_cvt_scalef32_pk_f16_fp4 v164, v157, 1.0 op_sel:[1,0,0]
	v_cvt_scalef32_pk_f16_fp4 v169, v157, 1.0 op_sel:[0,1,0]
	v_cvt_scalef32_pk_f16_fp4 v157, v157, 1.0 op_sel:[1,1,0]
	v_pk_fma_f16 v90, v91, v157, v90 op_sel_hi:[0,1,1]
	s_waitcnt vmcnt(37)
	v_cvt_scalef32_pk_f16_fp4 v157, v150, 1.0
	v_pk_fma_f16 v157, v91, v157, v161 op_sel:[1,0,0]
	v_cvt_scalef32_pk_f16_fp4 v161, v150, 1.0 op_sel:[1,0,0]
	v_pk_fma_f16 v161, v91, v161, v165 op_sel:[1,0,0]
	v_cvt_scalef32_pk_f16_fp4 v165, v150, 1.0 op_sel:[0,1,0]
	v_cvt_scalef32_pk_f16_fp4 v150, v150, 1.0 op_sel:[1,1,0]
	v_pk_fma_f16 v150, v91, v150, v154 op_sel:[1,0,0]
	v_cvt_scalef32_pk_f16_fp4 v154, v151, 1.0
	v_pk_fma_f16 v154, v91, v154, v158 op_sel:[1,0,0]
	v_cvt_scalef32_pk_f16_fp4 v158, v151, 1.0 op_sel:[1,0,0]
	v_pk_fma_f16 v158, v91, v158, v162 op_sel:[1,0,0]
	v_cvt_scalef32_pk_f16_fp4 v162, v151, 1.0 op_sel:[0,1,0]
	v_cvt_scalef32_pk_f16_fp4 v151, v151, 1.0 op_sel:[1,1,0]
	v_pk_fma_f16 v151, v91, v151, v155 op_sel:[1,0,0]
	v_cvt_scalef32_pk_f16_fp4 v155, v152, 1.0
	v_pk_fma_f16 v163, v91, v163, v171 op_sel_hi:[0,1,1]
	v_pk_fma_f16 v155, v91, v155, v159 op_sel:[1,0,0]
	v_cvt_scalef32_pk_f16_fp4 v159, v152, 1.0 op_sel:[1,0,0]
	v_pk_fma_f16 v159, v91, v159, v163 op_sel:[1,0,0]
	v_cvt_scalef32_pk_f16_fp4 v163, v152, 1.0 op_sel:[0,1,0]
	v_cvt_scalef32_pk_f16_fp4 v152, v152, 1.0 op_sel:[1,1,0]
	v_pk_fma_f16 v152, v91, v152, v156 op_sel:[1,0,0]
	v_cvt_scalef32_pk_f16_fp4 v156, v153, 1.0
	v_pk_fma_f16 v164, v91, v164, v173 op_sel_hi:[0,1,1]
	v_pk_fma_f16 v156, v91, v156, v160 op_sel:[1,0,0]
	v_cvt_scalef32_pk_f16_fp4 v160, v153, 1.0 op_sel:[1,0,0]
	v_pk_fma_f16 v167, v91, v167, v170 op_sel_hi:[0,1,1]
	v_pk_fma_f16 v168, v91, v168, v172 op_sel_hi:[0,1,1]
	v_pk_fma_f16 v169, v91, v169, v174 op_sel_hi:[0,1,1]
	v_pk_fma_f16 v160, v91, v160, v164 op_sel:[1,0,0]
	v_cvt_scalef32_pk_f16_fp4 v164, v153, 1.0 op_sel:[0,1,0]
	v_cvt_scalef32_pk_f16_fp4 v153, v153, 1.0 op_sel:[1,1,0]
	v_pk_fma_f16 v165, v91, v165, v166 op_sel:[1,0,0]
	v_pk_fma_f16 v162, v91, v162, v167 op_sel:[1,0,0]
	v_pk_fma_f16 v163, v91, v163, v168 op_sel:[1,0,0]
	v_pk_fma_f16 v164, v91, v164, v169 op_sel:[1,0,0]
	v_pk_fma_f16 v90, v91, v153, v90 op_sel:[1,0,0]
	s_waitcnt vmcnt(36)
	v_cvt_scalef32_pk_f16_fp4 v91, v142, 1.0
	v_pk_fma_f16 v91, v92, v91, v157 op_sel_hi:[0,1,1]
	v_cvt_scalef32_pk_f16_fp4 v153, v142, 1.0 op_sel:[1,0,0]
	v_cvt_scalef32_pk_f16_fp4 v157, v142, 1.0 op_sel:[0,1,0]
	v_cvt_scalef32_pk_f16_fp4 v142, v142, 1.0 op_sel:[1,1,0]
	v_pk_fma_f16 v142, v92, v142, v150 op_sel_hi:[0,1,1]
	v_cvt_scalef32_pk_f16_fp4 v150, v143, 1.0
	v_pk_fma_f16 v150, v92, v150, v154 op_sel_hi:[0,1,1]
	v_cvt_scalef32_pk_f16_fp4 v154, v143, 1.0 op_sel:[1,0,0]
	v_pk_fma_f16 v154, v92, v154, v158 op_sel_hi:[0,1,1]
	v_cvt_scalef32_pk_f16_fp4 v158, v143, 1.0 op_sel:[0,1,0]
	v_cvt_scalef32_pk_f16_fp4 v143, v143, 1.0 op_sel:[1,1,0]
	v_pk_fma_f16 v143, v92, v143, v151 op_sel_hi:[0,1,1]
	v_cvt_scalef32_pk_f16_fp4 v151, v144, 1.0
	v_pk_fma_f16 v151, v92, v151, v155 op_sel_hi:[0,1,1]
	v_cvt_scalef32_pk_f16_fp4 v155, v144, 1.0 op_sel:[1,0,0]
	v_pk_fma_f16 v155, v92, v155, v159 op_sel_hi:[0,1,1]
	v_cvt_scalef32_pk_f16_fp4 v159, v144, 1.0 op_sel:[0,1,0]
	v_cvt_scalef32_pk_f16_fp4 v144, v144, 1.0 op_sel:[1,1,0]
	v_pk_fma_f16 v144, v92, v144, v152 op_sel_hi:[0,1,1]
	v_cvt_scalef32_pk_f16_fp4 v152, v145, 1.0
	v_pk_fma_f16 v152, v92, v152, v156 op_sel_hi:[0,1,1]
	v_cvt_scalef32_pk_f16_fp4 v156, v145, 1.0 op_sel:[1,0,0]
	v_pk_fma_f16 v156, v92, v156, v160 op_sel_hi:[0,1,1]
	v_cvt_scalef32_pk_f16_fp4 v160, v145, 1.0 op_sel:[0,1,0]
	v_cvt_scalef32_pk_f16_fp4 v145, v145, 1.0 op_sel:[1,1,0]
	v_pk_fma_f16 v90, v92, v145, v90 op_sel_hi:[0,1,1]
	s_waitcnt vmcnt(35)
	v_cvt_scalef32_pk_f16_fp4 v145, v126, 1.0
	v_pk_fma_f16 v153, v92, v153, v161 op_sel_hi:[0,1,1]
	v_pk_fma_f16 v91, v92, v145, v91 op_sel:[1,0,0]
	v_cvt_scalef32_pk_f16_fp4 v145, v126, 1.0 op_sel:[1,0,0]
	v_pk_fma_f16 v145, v92, v145, v153 op_sel:[1,0,0]
	v_cvt_scalef32_pk_f16_fp4 v153, v126, 1.0 op_sel:[0,1,0]
	v_cvt_scalef32_pk_f16_fp4 v126, v126, 1.0 op_sel:[1,1,0]
	v_pk_fma_f16 v126, v92, v126, v142 op_sel:[1,0,0]
	v_cvt_scalef32_pk_f16_fp4 v142, v127, 1.0
	v_pk_fma_f16 v142, v92, v142, v150 op_sel:[1,0,0]
	v_cvt_scalef32_pk_f16_fp4 v150, v127, 1.0 op_sel:[1,0,0]
	v_pk_fma_f16 v150, v92, v150, v154 op_sel:[1,0,0]
	v_cvt_scalef32_pk_f16_fp4 v154, v127, 1.0 op_sel:[0,1,0]
	v_cvt_scalef32_pk_f16_fp4 v127, v127, 1.0 op_sel:[1,1,0]
	v_pk_fma_f16 v127, v92, v127, v143 op_sel:[1,0,0]
	v_cvt_scalef32_pk_f16_fp4 v143, v128, 1.0
	v_pk_fma_f16 v143, v92, v143, v151 op_sel:[1,0,0]
	v_cvt_scalef32_pk_f16_fp4 v151, v128, 1.0 op_sel:[1,0,0]
	v_pk_fma_f16 v151, v92, v151, v155 op_sel:[1,0,0]
	v_cvt_scalef32_pk_f16_fp4 v155, v128, 1.0 op_sel:[0,1,0]
	v_cvt_scalef32_pk_f16_fp4 v128, v128, 1.0 op_sel:[1,1,0]
	v_pk_fma_f16 v128, v92, v128, v144 op_sel:[1,0,0]
	v_cvt_scalef32_pk_f16_fp4 v144, v129, 1.0
	v_pk_fma_f16 v144, v92, v144, v152 op_sel:[1,0,0]
	v_cvt_scalef32_pk_f16_fp4 v152, v129, 1.0 op_sel:[1,0,0]
	v_pk_fma_f16 v157, v92, v157, v165 op_sel_hi:[0,1,1]
	v_pk_fma_f16 v158, v92, v158, v162 op_sel_hi:[0,1,1]
	v_pk_fma_f16 v159, v92, v159, v163 op_sel_hi:[0,1,1]
	v_pk_fma_f16 v160, v92, v160, v164 op_sel_hi:[0,1,1]
	v_pk_fma_f16 v152, v92, v152, v156 op_sel:[1,0,0]
	v_cvt_scalef32_pk_f16_fp4 v156, v129, 1.0 op_sel:[0,1,0]
	v_cvt_scalef32_pk_f16_fp4 v129, v129, 1.0 op_sel:[1,1,0]
	v_pk_fma_f16 v153, v92, v153, v157 op_sel:[1,0,0]
	v_pk_fma_f16 v154, v92, v154, v158 op_sel:[1,0,0]
	v_pk_fma_f16 v155, v92, v155, v159 op_sel:[1,0,0]
	v_pk_fma_f16 v156, v92, v156, v160 op_sel:[1,0,0]
	v_pk_fma_f16 v90, v92, v129, v90 op_sel:[1,0,0]
	s_waitcnt vmcnt(34)
	v_cvt_scalef32_pk_f16_fp4 v92, v110, 1.0
	v_pk_fma_f16 v91, v93, v92, v91 op_sel_hi:[0,1,1]
	v_cvt_scalef32_pk_f16_fp4 v92, v110, 1.0 op_sel:[1,0,0]
	v_cvt_scalef32_pk_f16_fp4 v129, v110, 1.0 op_sel:[0,1,0]
	v_cvt_scalef32_pk_f16_fp4 v110, v110, 1.0 op_sel:[1,1,0]
	v_pk_fma_f16 v110, v93, v110, v126 op_sel_hi:[0,1,1]
	v_cvt_scalef32_pk_f16_fp4 v126, v111, 1.0
	v_pk_fma_f16 v92, v93, v92, v145 op_sel_hi:[0,1,1]
	v_pk_fma_f16 v126, v93, v126, v142 op_sel_hi:[0,1,1]
	v_cvt_scalef32_pk_f16_fp4 v142, v111, 1.0 op_sel:[1,0,0]
	v_cvt_scalef32_pk_f16_fp4 v145, v111, 1.0 op_sel:[0,1,0]
	v_cvt_scalef32_pk_f16_fp4 v111, v111, 1.0 op_sel:[1,1,0]
	v_pk_fma_f16 v111, v93, v111, v127 op_sel_hi:[0,1,1]
	v_cvt_scalef32_pk_f16_fp4 v127, v112, 1.0
	v_pk_fma_f16 v142, v93, v142, v150 op_sel_hi:[0,1,1]
	v_pk_fma_f16 v127, v93, v127, v143 op_sel_hi:[0,1,1]
	v_cvt_scalef32_pk_f16_fp4 v143, v112, 1.0 op_sel:[1,0,0]
	v_cvt_scalef32_pk_f16_fp4 v150, v112, 1.0 op_sel:[0,1,0]
	v_cvt_scalef32_pk_f16_fp4 v112, v112, 1.0 op_sel:[1,1,0]
	v_pk_fma_f16 v112, v93, v112, v128 op_sel_hi:[0,1,1]
	v_cvt_scalef32_pk_f16_fp4 v128, v113, 1.0
	v_pk_fma_f16 v143, v93, v143, v151 op_sel_hi:[0,1,1]
	v_pk_fma_f16 v128, v93, v128, v144 op_sel_hi:[0,1,1]
	v_cvt_scalef32_pk_f16_fp4 v144, v113, 1.0 op_sel:[1,0,0]
	v_cvt_scalef32_pk_f16_fp4 v151, v113, 1.0 op_sel:[0,1,0]
	v_cvt_scalef32_pk_f16_fp4 v113, v113, 1.0 op_sel:[1,1,0]
	v_pk_fma_f16 v90, v93, v113, v90 op_sel_hi:[0,1,1]
	s_waitcnt vmcnt(33)
	v_cvt_scalef32_pk_f16_fp4 v113, v102, 1.0
	v_pk_fma_f16 v91, v93, v113, v91 op_sel:[1,0,0]
	v_cvt_scalef32_pk_f16_fp4 v113, v102, 1.0 op_sel:[1,0,0]
	v_pk_fma_f16 v92, v93, v113, v92 op_sel:[1,0,0]
	v_cvt_scalef32_pk_f16_fp4 v113, v102, 1.0 op_sel:[0,1,0]
	v_cvt_scalef32_pk_f16_fp4 v102, v102, 1.0 op_sel:[1,1,0]
	v_pk_fma_f16 v129, v93, v129, v153 op_sel_hi:[0,1,1]
	v_pk_fma_f16 v102, v93, v102, v110 op_sel:[1,0,0]
	v_cvt_scalef32_pk_f16_fp4 v110, v103, 1.0
	v_pk_fma_f16 v113, v93, v113, v129 op_sel:[1,0,0]
	v_pk_fma_f16 v110, v93, v110, v126 op_sel:[1,0,0]
	v_cvt_scalef32_pk_f16_fp4 v126, v103, 1.0 op_sel:[1,0,0]
	v_cvt_scalef32_pk_f16_fp4 v129, v103, 1.0 op_sel:[0,1,0]
	v_cvt_scalef32_pk_f16_fp4 v103, v103, 1.0 op_sel:[1,1,0]
	v_pk_fma_f16 v103, v93, v103, v111 op_sel:[1,0,0]
	v_cvt_scalef32_pk_f16_fp4 v111, v104, 1.0
	v_pk_fma_f16 v126, v93, v126, v142 op_sel:[1,0,0]
	v_pk_fma_f16 v111, v93, v111, v127 op_sel:[1,0,0]
	v_cvt_scalef32_pk_f16_fp4 v127, v104, 1.0 op_sel:[1,0,0]
	v_cvt_scalef32_pk_f16_fp4 v142, v104, 1.0 op_sel:[0,1,0]
	v_cvt_scalef32_pk_f16_fp4 v104, v104, 1.0 op_sel:[1,1,0]
	v_pk_fma_f16 v104, v93, v104, v112 op_sel:[1,0,0]
	v_cvt_scalef32_pk_f16_fp4 v112, v105, 1.0
	v_pk_fma_f16 v145, v93, v145, v154 op_sel_hi:[0,1,1]
	v_pk_fma_f16 v150, v93, v150, v155 op_sel_hi:[0,1,1]
	v_pk_fma_f16 v144, v93, v144, v152 op_sel_hi:[0,1,1]
	v_pk_fma_f16 v151, v93, v151, v156 op_sel_hi:[0,1,1]
	v_pk_fma_f16 v127, v93, v127, v143 op_sel:[1,0,0]
	v_pk_fma_f16 v112, v93, v112, v128 op_sel:[1,0,0]
	v_cvt_scalef32_pk_f16_fp4 v128, v105, 1.0 op_sel:[1,0,0]
	v_cvt_scalef32_pk_f16_fp4 v143, v105, 1.0 op_sel:[0,1,0]
	v_cvt_scalef32_pk_f16_fp4 v105, v105, 1.0 op_sel:[1,1,0]
	v_pk_fma_f16 v129, v93, v129, v145 op_sel:[1,0,0]
	v_pk_fma_f16 v142, v93, v142, v150 op_sel:[1,0,0]
	v_pk_fma_f16 v128, v93, v128, v144 op_sel:[1,0,0]
	v_pk_fma_f16 v143, v93, v143, v151 op_sel:[1,0,0]
	v_pk_fma_f16 v90, v93, v105, v90 op_sel:[1,0,0]
	s_waitcnt vmcnt(32)
	v_cvt_scalef32_pk_f16_fp4 v93, v94, 1.0
	v_pk_fma_f16 v91, v18, v93, v91 op_sel_hi:[0,1,1]
	v_cvt_scalef32_pk_f16_fp4 v93, v94, 1.0 op_sel:[1,0,0]
	v_pk_fma_f16 v92, v18, v93, v92 op_sel_hi:[0,1,1]
	v_cvt_scalef32_pk_f16_fp4 v93, v94, 1.0 op_sel:[0,1,0]
	v_cvt_scalef32_pk_f16_fp4 v94, v94, 1.0 op_sel:[1,1,0]
	v_pk_fma_f16 v94, v18, v94, v102 op_sel_hi:[0,1,1]
	v_cvt_scalef32_pk_f16_fp4 v102, v95, 1.0
	v_pk_fma_f16 v102, v18, v102, v110 op_sel_hi:[0,1,1]
	v_cvt_scalef32_pk_f16_fp4 v105, v95, 1.0 op_sel:[1,0,0]
	v_cvt_scalef32_pk_f16_fp4 v110, v95, 1.0 op_sel:[0,1,0]
	v_cvt_scalef32_pk_f16_fp4 v95, v95, 1.0 op_sel:[1,1,0]
	v_pk_fma_f16 v95, v18, v95, v103 op_sel_hi:[0,1,1]
	v_cvt_scalef32_pk_f16_fp4 v103, v96, 1.0
	v_pk_fma_f16 v93, v18, v93, v113 op_sel_hi:[0,1,1]
	v_pk_fma_f16 v103, v18, v103, v111 op_sel_hi:[0,1,1]
	v_cvt_scalef32_pk_f16_fp4 v111, v96, 1.0 op_sel:[1,0,0]
	v_cvt_scalef32_pk_f16_fp4 v113, v96, 1.0 op_sel:[0,1,0]
	v_cvt_scalef32_pk_f16_fp4 v96, v96, 1.0 op_sel:[1,1,0]
	v_pk_fma_f16 v96, v18, v96, v104 op_sel_hi:[0,1,1]
	v_cvt_scalef32_pk_f16_fp4 v104, v97, 1.0
	v_pk_fma_f16 v105, v18, v105, v126 op_sel_hi:[0,1,1]
	v_pk_fma_f16 v104, v18, v104, v112 op_sel_hi:[0,1,1]
	v_cvt_scalef32_pk_f16_fp4 v112, v97, 1.0 op_sel:[1,0,0]
	v_cvt_scalef32_pk_f16_fp4 v126, v97, 1.0 op_sel:[0,1,0]
	v_cvt_scalef32_pk_f16_fp4 v97, v97, 1.0 op_sel:[1,1,0]
	v_pk_fma_f16 v90, v18, v97, v90 op_sel_hi:[0,1,1]
	s_waitcnt vmcnt(31)
	v_cvt_scalef32_pk_f16_fp4 v97, v86, 1.0
	v_pk_fma_f16 v91, v18, v97, v91 op_sel:[1,0,0]
	v_cvt_scalef32_pk_f16_fp4 v97, v86, 1.0 op_sel:[1,0,0]
	v_pk_fma_f16 v92, v18, v97, v92 op_sel:[1,0,0]
	v_cvt_scalef32_pk_f16_fp4 v97, v86, 1.0 op_sel:[0,1,0]
	v_cvt_scalef32_pk_f16_fp4 v86, v86, 1.0 op_sel:[1,1,0]
	v_pk_fma_f16 v86, v18, v86, v94 op_sel:[1,0,0]
	v_cvt_scalef32_pk_f16_fp4 v94, v87, 1.0
	v_pk_fma_f16 v93, v18, v97, v93 op_sel:[1,0,0]
	v_pk_fma_f16 v94, v18, v94, v102 op_sel:[1,0,0]
	v_cvt_scalef32_pk_f16_fp4 v97, v87, 1.0 op_sel:[1,0,0]
	v_cvt_scalef32_pk_f16_fp4 v102, v87, 1.0 op_sel:[0,1,0]
	v_cvt_scalef32_pk_f16_fp4 v87, v87, 1.0 op_sel:[1,1,0]
	v_pk_fma_f16 v87, v18, v87, v95 op_sel:[1,0,0]
	v_cvt_scalef32_pk_f16_fp4 v95, v88, 1.0
	v_pk_fma_f16 v97, v18, v97, v105 op_sel:[1,0,0]
	v_pk_fma_f16 v95, v18, v95, v103 op_sel:[1,0,0]
	v_cvt_scalef32_pk_f16_fp4 v103, v88, 1.0 op_sel:[1,0,0]
	v_cvt_scalef32_pk_f16_fp4 v105, v88, 1.0 op_sel:[0,1,0]
	v_cvt_scalef32_pk_f16_fp4 v88, v88, 1.0 op_sel:[1,1,0]
	v_pk_fma_f16 v110, v18, v110, v129 op_sel_hi:[0,1,1]
	v_pk_fma_f16 v88, v18, v88, v96 op_sel:[1,0,0]
	v_cvt_scalef32_pk_f16_fp4 v96, v89, 1.0
	v_pk_fma_f16 v111, v18, v111, v127 op_sel_hi:[0,1,1]
	v_pk_fma_f16 v113, v18, v113, v142 op_sel_hi:[0,1,1]
	v_pk_fma_f16 v112, v18, v112, v128 op_sel_hi:[0,1,1]
	v_pk_fma_f16 v126, v18, v126, v143 op_sel_hi:[0,1,1]
	v_pk_fma_f16 v102, v18, v102, v110 op_sel:[1,0,0]
	v_pk_fma_f16 v96, v18, v96, v104 op_sel:[1,0,0]
	v_cvt_scalef32_pk_f16_fp4 v104, v89, 1.0 op_sel:[1,0,0]
	v_cvt_scalef32_pk_f16_fp4 v110, v89, 1.0 op_sel:[0,1,0]
	v_cvt_scalef32_pk_f16_fp4 v89, v89, 1.0 op_sel:[1,1,0]
	v_pk_fma_f16 v103, v18, v103, v111 op_sel:[1,0,0]
	v_pk_fma_f16 v105, v18, v105, v113 op_sel:[1,0,0]
	v_pk_fma_f16 v104, v18, v104, v112 op_sel:[1,0,0]
	v_pk_fma_f16 v110, v18, v110, v126 op_sel:[1,0,0]
	v_pk_fma_f16 v18, v18, v89, v90 op_sel:[1,0,0]
	s_waitcnt vmcnt(30)
	v_cvt_scalef32_pk_f16_fp4 v89, v78, 1.0
	v_pk_fma_f16 v89, v19, v89, v91 op_sel_hi:[0,1,1]
	v_cvt_scalef32_pk_f16_fp4 v90, v78, 1.0 op_sel:[1,0,0]
	v_cvt_scalef32_pk_f16_fp4 v91, v78, 1.0 op_sel:[0,1,0]
	v_cvt_scalef32_pk_f16_fp4 v78, v78, 1.0 op_sel:[1,1,0]
	v_pk_fma_f16 v90, v19, v90, v92 op_sel_hi:[0,1,1]
	v_pk_fma_f16 v91, v19, v91, v93 op_sel_hi:[0,1,1]
	v_pk_fma_f16 v78, v19, v78, v86 op_sel_hi:[0,1,1]
	v_cvt_scalef32_pk_f16_fp4 v86, v79, 1.0
	v_cvt_scalef32_pk_f16_fp4 v92, v79, 1.0 op_sel:[1,0,0]
	v_cvt_scalef32_pk_f16_fp4 v93, v79, 1.0 op_sel:[0,1,0]
	v_cvt_scalef32_pk_f16_fp4 v79, v79, 1.0 op_sel:[1,1,0]
	v_pk_fma_f16 v79, v19, v79, v87 op_sel_hi:[0,1,1]
	v_cvt_scalef32_pk_f16_fp4 v87, v80, 1.0
	v_pk_fma_f16 v86, v19, v86, v94 op_sel_hi:[0,1,1]
	v_pk_fma_f16 v87, v19, v87, v95 op_sel_hi:[0,1,1]
	v_cvt_scalef32_pk_f16_fp4 v94, v80, 1.0 op_sel:[1,0,0]
	v_cvt_scalef32_pk_f16_fp4 v95, v80, 1.0 op_sel:[0,1,0]
	v_cvt_scalef32_pk_f16_fp4 v80, v80, 1.0 op_sel:[1,1,0]
	v_pk_fma_f16 v80, v19, v80, v88 op_sel_hi:[0,1,1]
	v_cvt_scalef32_pk_f16_fp4 v88, v81, 1.0
	v_pk_fma_f16 v92, v19, v92, v97 op_sel_hi:[0,1,1]
	v_pk_fma_f16 v88, v19, v88, v96 op_sel_hi:[0,1,1]
	v_cvt_scalef32_pk_f16_fp4 v96, v81, 1.0 op_sel:[1,0,0]
	v_cvt_scalef32_pk_f16_fp4 v97, v81, 1.0 op_sel:[0,1,0]
	v_cvt_scalef32_pk_f16_fp4 v81, v81, 1.0 op_sel:[1,1,0]
	v_pk_fma_f16 v18, v19, v81, v18 op_sel_hi:[0,1,1]
	s_waitcnt vmcnt(29)
	v_cvt_scalef32_pk_f16_fp4 v81, v70, 1.0
	v_pk_fma_f16 v81, v19, v81, v89 op_sel:[1,0,0]
	v_cvt_scalef32_pk_f16_fp4 v89, v70, 1.0 op_sel:[1,0,0]
	v_pk_fma_f16 v89, v19, v89, v90 op_sel:[1,0,0]
	v_cvt_scalef32_pk_f16_fp4 v90, v70, 1.0 op_sel:[0,1,0]
	v_cvt_scalef32_pk_f16_fp4 v70, v70, 1.0 op_sel:[1,1,0]
	v_pk_fma_f16 v70, v19, v70, v78 op_sel:[1,0,0]
	v_cvt_scalef32_pk_f16_fp4 v78, v71, 1.0
	v_pk_fma_f16 v90, v19, v90, v91 op_sel:[1,0,0]
	v_pk_fma_f16 v78, v19, v78, v86 op_sel:[1,0,0]
	v_cvt_scalef32_pk_f16_fp4 v86, v71, 1.0 op_sel:[1,0,0]
	v_cvt_scalef32_pk_f16_fp4 v91, v71, 1.0 op_sel:[0,1,0]
	v_cvt_scalef32_pk_f16_fp4 v71, v71, 1.0 op_sel:[1,1,0]
	v_pk_fma_f16 v71, v19, v71, v79 op_sel:[1,0,0]
	v_cvt_scalef32_pk_f16_fp4 v79, v72, 1.0
	v_pk_fma_f16 v86, v19, v86, v92 op_sel:[1,0,0]
	v_pk_fma_f16 v79, v19, v79, v87 op_sel:[1,0,0]
	v_cvt_scalef32_pk_f16_fp4 v87, v72, 1.0 op_sel:[1,0,0]
	v_cvt_scalef32_pk_f16_fp4 v92, v72, 1.0 op_sel:[0,1,0]
	v_cvt_scalef32_pk_f16_fp4 v72, v72, 1.0 op_sel:[1,1,0]
	v_pk_fma_f16 v93, v19, v93, v102 op_sel_hi:[0,1,1]
	v_pk_fma_f16 v72, v19, v72, v80 op_sel:[1,0,0]
	v_cvt_scalef32_pk_f16_fp4 v80, v73, 1.0
	v_pk_fma_f16 v94, v19, v94, v103 op_sel_hi:[0,1,1]
	v_pk_fma_f16 v95, v19, v95, v105 op_sel_hi:[0,1,1]
	v_pk_fma_f16 v96, v19, v96, v104 op_sel_hi:[0,1,1]
	v_pk_fma_f16 v97, v19, v97, v110 op_sel_hi:[0,1,1]
	v_pk_fma_f16 v91, v19, v91, v93 op_sel:[1,0,0]
	v_pk_fma_f16 v80, v19, v80, v88 op_sel:[1,0,0]
	v_cvt_scalef32_pk_f16_fp4 v88, v73, 1.0 op_sel:[1,0,0]
	v_cvt_scalef32_pk_f16_fp4 v93, v73, 1.0 op_sel:[0,1,0]
	v_cvt_scalef32_pk_f16_fp4 v73, v73, 1.0 op_sel:[1,1,0]
	v_pk_fma_f16 v87, v19, v87, v94 op_sel:[1,0,0]
	v_pk_fma_f16 v92, v19, v92, v95 op_sel:[1,0,0]
	v_pk_fma_f16 v88, v19, v88, v96 op_sel:[1,0,0]
	v_pk_fma_f16 v93, v19, v93, v97 op_sel:[1,0,0]
	v_pk_fma_f16 v18, v19, v73, v18 op_sel:[1,0,0]
	s_waitcnt vmcnt(28)
	v_cvt_scalef32_pk_f16_fp4 v19, v58, 1.0
	v_pk_fma_f16 v19, v20, v19, v81 op_sel_hi:[0,1,1]
	v_cvt_scalef32_pk_f16_fp4 v73, v58, 1.0 op_sel:[1,0,0]
	v_cvt_scalef32_pk_f16_fp4 v81, v58, 1.0 op_sel:[0,1,0]
	v_cvt_scalef32_pk_f16_fp4 v58, v58, 1.0 op_sel:[1,1,0]
	v_pk_fma_f16 v58, v20, v58, v70 op_sel_hi:[0,1,1]
	v_cvt_scalef32_pk_f16_fp4 v70, v59, 1.0
	v_pk_fma_f16 v70, v20, v70, v78 op_sel_hi:[0,1,1]
	v_cvt_scalef32_pk_f16_fp4 v78, v59, 1.0 op_sel:[1,0,0]
	v_pk_fma_f16 v78, v20, v78, v86 op_sel_hi:[0,1,1]
	v_cvt_scalef32_pk_f16_fp4 v86, v59, 1.0 op_sel:[0,1,0]
	v_cvt_scalef32_pk_f16_fp4 v59, v59, 1.0 op_sel:[1,1,0]
	v_pk_fma_f16 v59, v20, v59, v71 op_sel_hi:[0,1,1]
	v_cvt_scalef32_pk_f16_fp4 v71, v60, 1.0
	v_pk_fma_f16 v71, v20, v71, v79 op_sel_hi:[0,1,1]
	v_cvt_scalef32_pk_f16_fp4 v79, v60, 1.0 op_sel:[1,0,0]
	v_pk_fma_f16 v79, v20, v79, v87 op_sel_hi:[0,1,1]
	v_cvt_scalef32_pk_f16_fp4 v87, v60, 1.0 op_sel:[0,1,0]
	v_cvt_scalef32_pk_f16_fp4 v60, v60, 1.0 op_sel:[1,1,0]
	v_pk_fma_f16 v60, v20, v60, v72 op_sel_hi:[0,1,1]
	v_cvt_scalef32_pk_f16_fp4 v72, v61, 1.0
	v_pk_fma_f16 v72, v20, v72, v80 op_sel_hi:[0,1,1]
	v_cvt_scalef32_pk_f16_fp4 v80, v61, 1.0 op_sel:[1,0,0]
	v_pk_fma_f16 v80, v20, v80, v88 op_sel_hi:[0,1,1]
	v_cvt_scalef32_pk_f16_fp4 v88, v61, 1.0 op_sel:[0,1,0]
	v_cvt_scalef32_pk_f16_fp4 v61, v61, 1.0 op_sel:[1,1,0]
	v_pk_fma_f16 v18, v20, v61, v18 op_sel_hi:[0,1,1]
	s_waitcnt vmcnt(27)
	v_cvt_scalef32_pk_f16_fp4 v61, v50, 1.0
	v_pk_fma_f16 v73, v20, v73, v89 op_sel_hi:[0,1,1]
	v_pk_fma_f16 v19, v20, v61, v19 op_sel:[1,0,0]
	v_cvt_scalef32_pk_f16_fp4 v61, v50, 1.0 op_sel:[1,0,0]
	v_pk_fma_f16 v61, v20, v61, v73 op_sel:[1,0,0]
	v_cvt_scalef32_pk_f16_fp4 v73, v50, 1.0 op_sel:[0,1,0]
	v_cvt_scalef32_pk_f16_fp4 v50, v50, 1.0 op_sel:[1,1,0]
	v_pk_fma_f16 v50, v20, v50, v58 op_sel:[1,0,0]
	v_cvt_scalef32_pk_f16_fp4 v58, v51, 1.0
	v_pk_fma_f16 v58, v20, v58, v70 op_sel:[1,0,0]
	v_cvt_scalef32_pk_f16_fp4 v70, v51, 1.0 op_sel:[1,0,0]
	v_pk_fma_f16 v70, v20, v70, v78 op_sel:[1,0,0]
	v_cvt_scalef32_pk_f16_fp4 v78, v51, 1.0 op_sel:[0,1,0]
	v_cvt_scalef32_pk_f16_fp4 v51, v51, 1.0 op_sel:[1,1,0]
	v_pk_fma_f16 v51, v20, v51, v59 op_sel:[1,0,0]
	v_cvt_scalef32_pk_f16_fp4 v59, v52, 1.0
	v_pk_fma_f16 v59, v20, v59, v71 op_sel:[1,0,0]
	v_cvt_scalef32_pk_f16_fp4 v71, v52, 1.0 op_sel:[1,0,0]
	v_pk_fma_f16 v71, v20, v71, v79 op_sel:[1,0,0]
	v_cvt_scalef32_pk_f16_fp4 v79, v52, 1.0 op_sel:[0,1,0]
	v_cvt_scalef32_pk_f16_fp4 v52, v52, 1.0 op_sel:[1,1,0]
	v_pk_fma_f16 v52, v20, v52, v60 op_sel:[1,0,0]
	v_cvt_scalef32_pk_f16_fp4 v60, v53, 1.0
	v_pk_fma_f16 v60, v20, v60, v72 op_sel:[1,0,0]
	v_cvt_scalef32_pk_f16_fp4 v72, v53, 1.0 op_sel:[1,0,0]
	v_pk_fma_f16 v81, v20, v81, v90 op_sel_hi:[0,1,1]
	v_pk_fma_f16 v86, v20, v86, v91 op_sel_hi:[0,1,1]
	v_pk_fma_f16 v87, v20, v87, v92 op_sel_hi:[0,1,1]
	v_pk_fma_f16 v88, v20, v88, v93 op_sel_hi:[0,1,1]
	v_pk_fma_f16 v72, v20, v72, v80 op_sel:[1,0,0]
	v_cvt_scalef32_pk_f16_fp4 v80, v53, 1.0 op_sel:[0,1,0]
	v_cvt_scalef32_pk_f16_fp4 v53, v53, 1.0 op_sel:[1,1,0]
	v_pk_fma_f16 v73, v20, v73, v81 op_sel:[1,0,0]
	v_pk_fma_f16 v78, v20, v78, v86 op_sel:[1,0,0]
	v_pk_fma_f16 v79, v20, v79, v87 op_sel:[1,0,0]
	v_pk_fma_f16 v80, v20, v80, v88 op_sel:[1,0,0]
	v_pk_fma_f16 v18, v20, v53, v18 op_sel:[1,0,0]
	s_waitcnt vmcnt(26)
	v_cvt_scalef32_pk_f16_fp4 v20, v38, 1.0
	v_pk_fma_f16 v19, v21, v20, v19 op_sel_hi:[0,1,1]
	v_cvt_scalef32_pk_f16_fp4 v20, v38, 1.0 op_sel:[1,0,0]
	v_cvt_scalef32_pk_f16_fp4 v53, v38, 1.0 op_sel:[0,1,0]
	v_cvt_scalef32_pk_f16_fp4 v38, v38, 1.0 op_sel:[1,1,0]
	v_pk_fma_f16 v38, v21, v38, v50 op_sel_hi:[0,1,1]
	v_cvt_scalef32_pk_f16_fp4 v50, v39, 1.0
	v_pk_fma_f16 v20, v21, v20, v61 op_sel_hi:[0,1,1]
	v_pk_fma_f16 v50, v21, v50, v58 op_sel_hi:[0,1,1]
	v_cvt_scalef32_pk_f16_fp4 v58, v39, 1.0 op_sel:[1,0,0]
	v_cvt_scalef32_pk_f16_fp4 v61, v39, 1.0 op_sel:[0,1,0]
	v_cvt_scalef32_pk_f16_fp4 v39, v39, 1.0 op_sel:[1,1,0]
	v_pk_fma_f16 v39, v21, v39, v51 op_sel_hi:[0,1,1]
	v_cvt_scalef32_pk_f16_fp4 v51, v40, 1.0
	v_pk_fma_f16 v58, v21, v58, v70 op_sel_hi:[0,1,1]
	v_pk_fma_f16 v51, v21, v51, v59 op_sel_hi:[0,1,1]
	v_cvt_scalef32_pk_f16_fp4 v59, v40, 1.0 op_sel:[1,0,0]
	v_cvt_scalef32_pk_f16_fp4 v70, v40, 1.0 op_sel:[0,1,0]
	v_cvt_scalef32_pk_f16_fp4 v40, v40, 1.0 op_sel:[1,1,0]
	v_pk_fma_f16 v40, v21, v40, v52 op_sel_hi:[0,1,1]
	v_cvt_scalef32_pk_f16_fp4 v52, v41, 1.0
	v_pk_fma_f16 v59, v21, v59, v71 op_sel_hi:[0,1,1]
	v_pk_fma_f16 v52, v21, v52, v60 op_sel_hi:[0,1,1]
	v_cvt_scalef32_pk_f16_fp4 v60, v41, 1.0 op_sel:[1,0,0]
	v_cvt_scalef32_pk_f16_fp4 v71, v41, 1.0 op_sel:[0,1,0]
	v_cvt_scalef32_pk_f16_fp4 v41, v41, 1.0 op_sel:[1,1,0]
	v_pk_fma_f16 v18, v21, v41, v18 op_sel_hi:[0,1,1]
	s_waitcnt vmcnt(25)
	v_cvt_scalef32_pk_f16_fp4 v41, v30, 1.0
	v_pk_fma_f16 v19, v21, v41, v19 op_sel:[1,0,0]
	v_cvt_scalef32_pk_f16_fp4 v41, v30, 1.0 op_sel:[1,0,0]
	v_pk_fma_f16 v20, v21, v41, v20 op_sel:[1,0,0]
	v_cvt_scalef32_pk_f16_fp4 v41, v30, 1.0 op_sel:[0,1,0]
	v_cvt_scalef32_pk_f16_fp4 v30, v30, 1.0 op_sel:[1,1,0]
	v_pk_fma_f16 v53, v21, v53, v73 op_sel_hi:[0,1,1]
	v_pk_fma_f16 v30, v21, v30, v38 op_sel:[1,0,0]
	v_cvt_scalef32_pk_f16_fp4 v38, v31, 1.0
	v_pk_fma_f16 v41, v21, v41, v53 op_sel:[1,0,0]
	v_pk_fma_f16 v38, v21, v38, v50 op_sel:[1,0,0]
	v_cvt_scalef32_pk_f16_fp4 v50, v31, 1.0 op_sel:[1,0,0]
	v_cvt_scalef32_pk_f16_fp4 v53, v31, 1.0 op_sel:[0,1,0]
	v_cvt_scalef32_pk_f16_fp4 v31, v31, 1.0 op_sel:[1,1,0]
	v_pk_fma_f16 v31, v21, v31, v39 op_sel:[1,0,0]
	v_cvt_scalef32_pk_f16_fp4 v39, v32, 1.0
	v_pk_fma_f16 v50, v21, v50, v58 op_sel:[1,0,0]
	v_pk_fma_f16 v39, v21, v39, v51 op_sel:[1,0,0]
	v_cvt_scalef32_pk_f16_fp4 v51, v32, 1.0 op_sel:[1,0,0]
	v_cvt_scalef32_pk_f16_fp4 v58, v32, 1.0 op_sel:[0,1,0]
	v_cvt_scalef32_pk_f16_fp4 v32, v32, 1.0 op_sel:[1,1,0]
	v_pk_fma_f16 v61, v21, v61, v78 op_sel_hi:[0,1,1]
	v_pk_fma_f16 v70, v21, v70, v79 op_sel_hi:[0,1,1]
	v_pk_fma_f16 v71, v21, v71, v80 op_sel_hi:[0,1,1]
	v_pk_fma_f16 v51, v21, v51, v59 op_sel:[1,0,0]
	v_pk_fma_f16 v32, v21, v32, v40 op_sel:[1,0,0]
	v_cvt_scalef32_pk_f16_fp4 v40, v33, 1.0
	v_cvt_scalef32_pk_f16_fp4 v59, v33, 1.0 op_sel:[0,1,0]
	v_pk_fma_f16 v53, v21, v53, v61 op_sel:[1,0,0]
	v_pk_fma_f16 v58, v21, v58, v70 op_sel:[1,0,0]
	v_pk_fma_f16 v40, v21, v40, v52 op_sel:[1,0,0]
	v_cvt_scalef32_pk_f16_fp4 v52, v33, 1.0 op_sel:[1,0,0]
	v_pk_fma_f16 v59, v21, v59, v71 op_sel:[1,0,0]
	v_cvt_scalef32_pk_f16_fp4 v33, v33, 1.0 op_sel:[1,1,0]
	v_pk_fma_f16 v60, v21, v60, v72 op_sel_hi:[0,1,1]
	v_pk_fma_f16 v18, v21, v33, v18 op_sel:[1,0,0]
	v_permlane32_swap_b32_e32 v19, v39
	v_permlane32_swap_b32_e32 v41, v58
	v_permlane32_swap_b32_e32 v30, v32
	v_permlane32_swap_b32_e32 v38, v40
	v_permlane32_swap_b32_e32 v53, v59
	v_pk_fma_f16 v52, v21, v52, v60 op_sel:[1,0,0]
	v_pk_add_f16 v19, v19, v39
	v_pk_add_f16 v21, v41, v58
	v_pk_add_f16 v30, v30, v32
	v_pk_add_f16 v32, v38, v40
	v_pk_add_f16 v38, v53, v59
	v_permlane32_swap_b32_e32 v31, v18
	v_permlane32_swap_b32_e32 v20, v51
	v_permlane32_swap_b32_e32 v50, v52
	v_pk_add_f16 v18, v31, v18
	v_permlane16_swap_b32_e32 v19, v32
	v_permlane16_swap_b32_e32 v21, v38
	v_pk_add_f16 v20, v20, v51
	v_pk_add_f16 v33, v50, v52
	v_pk_add_f16 v19, v19, v32
	v_pk_add_f16 v21, v21, v38
	v_permlane16_swap_b32_e32 v30, v18
	v_permlane16_swap_b32_e32 v20, v33
	v_pk_add_f16 v18, v30, v18
	v_cndmask_b32_e64 v30, v21, v19, s[8:9]
	v_cndmask_b32_e64 v19, v19, v21, s[8:9]
	v_pk_add_f16 v20, v20, v33
	v_cvt_f32_f16_e32 v32, v201
	v_mov_b32_dpp v19, v19 row_ror:8 row_mask:0xf bank_mask:0xf bound_ctrl:1
	v_pk_add_f16 v21, v30, v19
	v_cndmask_b32_e64 v30, v18, v20, s[8:9]
	v_cndmask_b32_e64 v18, v20, v18, s[8:9]
	v_cvt_f32_f16_sdwa v19, v200 dst_sel:DWORD dst_unused:UNUSED_PAD src0_sel:WORD_1
	v_cvt_f32_f16_e32 v20, v21
	v_mov_b32_dpp v31, v18 row_ror:8 row_mask:0xf bank_mask:0xf bound_ctrl:1
	v_cvt_f32_f16_e32 v18, v200
	v_cvt_f32_f16_sdwa v21, v21 dst_sel:DWORD dst_unused:UNUSED_PAD src0_sel:WORD_1
	v_pk_add_f16 v39, v30, v31
	v_cvt_f32_f16_e32 v30, v198
	v_cvt_f32_f16_sdwa v31, v198 dst_sel:DWORD dst_unused:UNUSED_PAD src0_sel:WORD_1
	v_cvt_f32_f16_sdwa v33, v201 dst_sel:DWORD dst_unused:UNUSED_PAD src0_sel:WORD_1
	v_cvt_f32_f16_e32 v38, v39
	v_cvt_f32_f16_sdwa v39, v39 dst_sel:DWORD dst_unused:UNUSED_PAD src0_sel:WORD_1
	v_pk_fma_f32 v[18:19], v[2:3], v[20:21], v[18:19]
	v_cvt_f32_f16_e32 v20, v199
	v_cvt_f32_f16_sdwa v21, v199 dst_sel:DWORD dst_unused:UNUSED_PAD src0_sel:WORD_1
	v_pk_add_f32 v[18:19], v[18:19], v[30:31]
	v_pk_fma_f32 v[30:31], v[4:5], v[38:39], v[32:33]
	v_cvt_pk_f16_f32 v18, v18, v19
	v_pk_add_f32 v[20:21], v[30:31], v[20:21]
	s_nop 0
	v_cvt_pk_f16_f32 v19, v20, v21
	global_store_dwordx2 v[196:197], v[18:19], off
	s_mov_b32 s28, s17
	s_cbranch_scc0 .LBB0_2243
	s_mov_b64 s[18:19], 0

.LBB0_3098:
	s_or_b64 exec, exec, s[0:1]
	s_mov_b64 s[0:1], 0
	s_mov_b64 s[8:9], 0
	s_waitcnt lgkmcnt(0)
	s_barrier
	v_readlane_b32 s12, v250, 0
	s_mov_b64 s[8:9], 0
	v_readlane_b32 s13, v250, 1
	v_readlane_b32 s14, v250, 2
	s_mov_b64 s[18:19], 0
	s_mov_b64 s[12:13], 0
	s_mov_b64 s[8:9], 0
	v_readlane_b32 s15, v250, 3
	s_add_u32 s0, s14, s0
	s_mov_b64 s[10:11], 0
	s_addc_u32 s1, s15, s1
	s_mov_b64 s[16:17], 0
	s_mov_b64 s[8:9], 0
	s_mov_b64 s[14:15], 0
	v_mov_b32_e32 v2, v0
	s_add_u32 s0, s0, 0x6800
	s_getreg_b32 s2, hwreg(HW_REG_XCC_ID, 0, 4)
	v_and_b32_e32 v3, 63, v2
	s_addc_u32 s1, s1, 0
	s_and_b32 s26, s2, 7
	v_mov_b32_e32 v202, 0
	v_cmp_eq_u32_e64 s[8:9], 0, v3
	s_and_saveexec_b64 s[20:21], s[8:9]
	s_cbranch_execz .LBB0_3102
	s_mov_b64 s[24:25], exec
	v_mbcnt_lo_u32_b32 v4, s24, 0
	v_mbcnt_hi_u32_b32 v4, s25, v4
	v_cmp_eq_u32_e32 vcc, 0, v4
	s_and_saveexec_b64 s[22:23], vcc
	s_cbranch_execz .LBB0_3101
	s_bcnt1_i32_b64 s24, s[24:25]
	s_lshl_b32 s27, s26, 8
	s_lshl_b32 s24, s24, 3
	v_mov_b32_e32 v5, s27
	v_mov_b32_e32 v6, s24
	global_atomic_add v5, v5, v6, s[0:1] sc0
.LBB0_3101:
	s_or_b64 exec, exec, s[22:23]
	s_waitcnt vmcnt(0)
	v_readfirstlane_b32 s22, v5
	s_nop 1
	v_lshl_add_u32 v202, v4, 3, s22
.LBB0_3102:
	s_or_b64 exec, exec, s[20:21]
	v_readlane_b32 s20, v250, 0
	v_readlane_b32 s22, v250, 2
	v_readlane_b32 s23, v250, 3
	s_add_u32 s18, s22, s18
	s_addc_u32 s19, s23, s19
	v_readlane_b32 s21, v250, 1
	s_add_u32 s20, s22, s12
	s_addc_u32 s21, s23, s13
	s_add_u32 s12, s22, s16
	s_addc_u32 s13, s23, s17
	s_add_u32 s12, s12, 0x3ed06000
	s_addc_u32 s13, s13, 0
	s_add_u32 s14, s22, s14
	s_addc_u32 s15, s23, s15
	s_add_u32 s14, s14, 0x4c618000
	s_addc_u32 s15, s15, 0
	s_add_u32 s10, s22, s10
	s_addc_u32 s11, s23, s11
	v_lshlrev_b32_e32 v203, 2, v3
	v_lshlrev_b32_e32 v4, 4, v3
	v_lshlrev_b32_e32 v3, 3, v3
	s_add_u32 s16, s10, 0x50e18000
	v_and_b32_e32 v182, 0x1c0, v3
	v_mov_b32_e32 v183, 0
	v_and_b32_e32 v3, 56, v2
	s_addc_u32 s17, s11, 0
	v_and_b32_e32 v204, 0x70, v4
	v_lshl_add_u64 v[4:5], s[18:19], 0, v[182:183]
	s_mov_b64 s[10:11], 0x2ade6000
	v_lshlrev_b32_e32 v182, 2, v3
	v_lshl_add_u64 v[184:185], v[4:5], 0, s[10:11]
	v_lshl_add_u64 v[4:5], s[20:21], 0, v[182:183]
	s_mov_b64 s[10:11], 0x4c198000
	v_and_b32_e32 v2, 8, v2
	v_lshl_add_u64 v[186:187], v[4:5], 0, s[10:11]
	s_mov_b32 s29, 0
	v_cmp_eq_u32_e64 s[10:11], 0, v2
	v_mov_b32_e32 v206, s26
	v_mov_b32_e32 v205, 8
	s_mov_b32 s28, 0xa000
	s_branch .LBB0_3105

.LBB0_3109:
	s_add_i32 s24, s18, s30
	s_add_i32 s19, s24, 2
	s_add_i32 s26, s24, 1
	s_add_i32 s21, s24, 3
	s_cmp_lt_u32 s30, 6
	s_cselect_b32 s20, s19, s24
	s_cselect_b32 s22, s21, s26
	s_ashr_i32 s21, s20, 31
	s_ashr_i32 s27, s26, 31
	s_ashr_i32 s25, s24, 31
	s_lshl_b64 s[34:35], s[20:21], 9
	s_lshl_b64 s[36:37], s[26:27], 8
	s_lshl_b64 s[20:21], s[24:25], 12
	s_add_i32 s19, s30, 1
	s_cmp_lt_u32 s19, 7
	s_cselect_b64 s[38:39], -1, 0
	s_ashr_i32 s23, s22, 31
	s_lshl_b64 s[22:23], s[22:23], 9
	s_cmp_lg_u64 s[38:39], 0
	s_addc_u32 s24, s24, 1
	s_lshl_b64 s[26:27], s[26:27], 12
	v_lshl_add_u64 v[18:19], v[184:185], 0, s[34:35]
	v_lshl_add_u64 v[30:31], v[186:187], 0, s[36:37]
	global_load_dwordx4 v[166:169], v[18:19], off offset:48
	global_load_dwordx4 v[170:173], v[18:19], off offset:32
	global_load_dwordx4 v[174:177], v[18:19], off offset:16
	global_load_dwordx4 v[178:181], v[18:19], off
	s_nop 0
	global_load_dwordx4 v[18:21], v[30:31], off offset:16
	global_load_dwordx4 v[90:93], v[30:31], off
	v_lshl_add_u64 v[196:197], v[190:191], 0, s[26:27]
	v_lshl_add_u64 v[30:31], v[192:193], 0, s[26:27]
	global_load_dwordx2 v[198:199], v[196:197], off
	global_load_dwordx2 v[200:201], v[30:31], off
	s_waitcnt vmcnt(29)
	v_lshl_add_u32 v30, v138, 7, v207
	v_lshl_add_u32 v31, v139, 7, v207
	global_load_dwordx4 v[162:165], v30, s[12:13]
	global_load_dwordx4 v[158:161], v31, s[12:13]
	v_lshl_add_u32 v30, v140, 7, v207
	v_lshl_add_u32 v31, v141, 7, v207
	global_load_dwordx4 v[154:157], v30, s[12:13]
	global_load_dwordx4 v[150:153], v31, s[12:13]
	v_lshl_add_u32 v30, v130, 7, v207
	v_lshl_add_u32 v31, v131, 7, v207
	global_load_dwordx4 v[142:145], v30, s[12:13]
	global_load_dwordx4 v[126:129], v31, s[12:13]
	v_lshl_add_u32 v30, v132, 7, v207
	v_lshl_add_u32 v31, v133, 7, v207
	global_load_dwordx4 v[110:113], v30, s[12:13]
	global_load_dwordx4 v[102:105], v31, s[12:13]
	v_lshl_add_u32 v30, v122, 7, v207
	v_lshl_add_u32 v31, v123, 7, v207
	global_load_dwordx4 v[94:97], v30, s[12:13]
	global_load_dwordx4 v[86:89], v31, s[12:13]
	v_lshl_add_u32 v30, v124, 7, v207
	v_lshl_add_u32 v31, v125, 7, v207
	global_load_dwordx4 v[78:81], v30, s[12:13]
	global_load_dwordx4 v[70:73], v31, s[12:13]
	s_waitcnt vmcnt(40)
	v_lshl_add_u32 v30, v118, 7, v207
	v_lshl_add_u32 v31, v119, 7, v207
	global_load_dwordx4 v[58:61], v30, s[12:13]
	global_load_dwordx4 v[50:53], v31, s[12:13]
	v_lshl_add_u32 v30, v120, 7, v207
	v_lshl_add_u32 v31, v121, 7, v207
	global_load_dwordx4 v[38:41], v30, s[12:13]
	s_nop 0
	global_load_dwordx4 v[30:33], v31, s[12:13]
	s_ashr_i32 s25, s24, 31
	s_lshl_b64 s[26:27], s[24:25], 8
	s_lshl_b64 s[24:25], s[24:25], 12
	s_add_i32 s19, s30, 2
	s_cmp_gt_u32 s30, 5
	s_waitcnt vmcnt(36)
	v_cvt_scalef32_pk_f16_fp4 v118, v146, 1.0
	v_pk_fma_f16 v118, v42, v118, 0 op_sel_hi:[0,1,1]
	v_cvt_scalef32_pk_f16_fp4 v119, v146, 1.0 op_sel:[1,0,0]
	v_cvt_scalef32_pk_f16_fp4 v120, v146, 1.0 op_sel:[0,1,0]
	v_cvt_scalef32_pk_f16_fp4 v121, v146, 1.0 op_sel:[1,1,0]
	s_waitcnt vmcnt(35)
	v_cvt_scalef32_pk_f16_fp4 v146, v134, 1.0
	v_pk_fma_f16 v119, v42, v119, 0 op_sel_hi:[0,1,1]
	v_pk_fma_f16 v118, v42, v146, v118 op_sel:[1,0,0]
	v_cvt_scalef32_pk_f16_fp4 v146, v134, 1.0 op_sel:[1,0,0]
	v_pk_fma_f16 v121, v42, v121, 0 op_sel_hi:[0,1,1]
	v_cvt_scalef32_pk_f16_fp4 v122, v147, 1.0
	v_pk_fma_f16 v119, v42, v146, v119 op_sel:[1,0,0]
	v_cvt_scalef32_pk_f16_fp4 v146, v134, 1.0 op_sel:[0,1,0]
	v_cvt_scalef32_pk_f16_fp4 v134, v134, 1.0 op_sel:[1,1,0]
	v_pk_fma_f16 v122, v42, v122, 0 op_sel_hi:[0,1,1]
	v_cvt_scalef32_pk_f16_fp4 v123, v147, 1.0 op_sel:[1,0,0]
	v_pk_fma_f16 v121, v42, v134, v121 op_sel:[1,0,0]
	v_cvt_scalef32_pk_f16_fp4 v134, v135, 1.0
	v_pk_fma_f16 v123, v42, v123, 0 op_sel_hi:[0,1,1]
	v_cvt_scalef32_pk_f16_fp4 v124, v147, 1.0 op_sel:[0,1,0]
	v_pk_fma_f16 v122, v42, v134, v122 op_sel:[1,0,0]
	v_cvt_scalef32_pk_f16_fp4 v134, v135, 1.0 op_sel:[1,0,0]
	v_pk_fma_f16 v124, v42, v124, 0 op_sel_hi:[0,1,1]
	v_cvt_scalef32_pk_f16_fp4 v125, v147, 1.0 op_sel:[1,1,0]
	v_pk_fma_f16 v123, v42, v134, v123 op_sel:[1,0,0]
	v_cvt_scalef32_pk_f16_fp4 v134, v135, 1.0 op_sel:[0,1,0]
	v_pk_fma_f16 v125, v42, v125, 0 op_sel_hi:[0,1,1]
	v_cvt_scalef32_pk_f16_fp4 v130, v148, 1.0
	v_pk_fma_f16 v124, v42, v134, v124 op_sel:[1,0,0]
	v_cvt_scalef32_pk_f16_fp4 v134, v135, 1.0 op_sel:[1,1,0]
	v_pk_fma_f16 v130, v42, v130, 0 op_sel_hi:[0,1,1]
	v_cvt_scalef32_pk_f16_fp4 v131, v148, 1.0 op_sel:[1,0,0]
	v_pk_fma_f16 v125, v42, v134, v125 op_sel:[1,0,0]
	v_cvt_scalef32_pk_f16_fp4 v134, v136, 1.0
	v_pk_fma_f16 v131, v42, v131, 0 op_sel_hi:[0,1,1]
	v_cvt_scalef32_pk_f16_fp4 v132, v148, 1.0 op_sel:[0,1,0]
	v_pk_fma_f16 v130, v42, v134, v130 op_sel:[1,0,0]
	v_cvt_scalef32_pk_f16_fp4 v134, v136, 1.0 op_sel:[1,0,0]
	v_pk_fma_f16 v132, v42, v132, 0 op_sel_hi:[0,1,1]
	v_cvt_scalef32_pk_f16_fp4 v133, v148, 1.0 op_sel:[1,1,0]
	v_pk_fma_f16 v131, v42, v134, v131 op_sel:[1,0,0]
	v_cvt_scalef32_pk_f16_fp4 v134, v136, 1.0 op_sel:[0,1,0]
	v_pk_fma_f16 v133, v42, v133, 0 op_sel_hi:[0,1,1]
	v_cvt_scalef32_pk_f16_fp4 v138, v149, 1.0
	v_cvt_scalef32_pk_f16_fp4 v139, v149, 1.0 op_sel:[1,0,0]
	v_cvt_scalef32_pk_f16_fp4 v140, v149, 1.0 op_sel:[0,1,0]
	v_cvt_scalef32_pk_f16_fp4 v141, v149, 1.0 op_sel:[1,1,0]
	v_pk_fma_f16 v132, v42, v134, v132 op_sel:[1,0,0]
	v_cvt_scalef32_pk_f16_fp4 v134, v136, 1.0 op_sel:[1,1,0]
	v_pk_fma_f16 v120, v42, v120, 0 op_sel_hi:[0,1,1]
	v_pk_fma_f16 v138, v42, v138, 0 op_sel_hi:[0,1,1]
	v_pk_fma_f16 v139, v42, v139, 0 op_sel_hi:[0,1,1]
	v_pk_fma_f16 v140, v42, v140, 0 op_sel_hi:[0,1,1]
	v_pk_fma_f16 v141, v42, v141, 0 op_sel_hi:[0,1,1]
	v_pk_fma_f16 v133, v42, v134, v133 op_sel:[1,0,0]
	v_cvt_scalef32_pk_f16_fp4 v134, v137, 1.0
	v_cvt_scalef32_pk_f16_fp4 v135, v137, 1.0 op_sel:[1,0,0]
	v_cvt_scalef32_pk_f16_fp4 v136, v137, 1.0 op_sel:[0,1,0]
	v_cvt_scalef32_pk_f16_fp4 v137, v137, 1.0 op_sel:[1,1,0]
	v_pk_fma_f16 v120, v42, v146, v120 op_sel:[1,0,0]
	v_pk_fma_f16 v134, v42, v134, v138 op_sel:[1,0,0]
	v_pk_fma_f16 v135, v42, v135, v139 op_sel:[1,0,0]
	v_pk_fma_f16 v136, v42, v136, v140 op_sel:[1,0,0]
	v_pk_fma_f16 v42, v42, v137, v141 op_sel:[1,0,0]
	s_waitcnt vmcnt(34)
	v_cvt_scalef32_pk_f16_fp4 v137, v114, 1.0
	v_pk_fma_f16 v118, v43, v137, v118 op_sel_hi:[0,1,1]
	v_cvt_scalef32_pk_f16_fp4 v137, v114, 1.0 op_sel:[1,0,0]
	v_pk_fma_f16 v119, v43, v137, v119 op_sel_hi:[0,1,1]
	v_cvt_scalef32_pk_f16_fp4 v137, v114, 1.0 op_sel:[0,1,0]
	v_cvt_scalef32_pk_f16_fp4 v114, v114, 1.0 op_sel:[1,1,0]
	v_pk_fma_f16 v114, v43, v114, v121 op_sel_hi:[0,1,1]
	v_cvt_scalef32_pk_f16_fp4 v121, v115, 1.0
	v_pk_fma_f16 v121, v43, v121, v122 op_sel_hi:[0,1,1]
	v_cvt_scalef32_pk_f16_fp4 v122, v115, 1.0 op_sel:[1,0,0]
	v_pk_fma_f16 v122, v43, v122, v123 op_sel_hi:[0,1,1]
	v_cvt_scalef32_pk_f16_fp4 v123, v115, 1.0 op_sel:[0,1,0]
	v_pk_fma_f16 v123, v43, v123, v124 op_sel_hi:[0,1,1]
	v_cvt_scalef32_pk_f16_fp4 v115, v115, 1.0 op_sel:[1,1,0]
	v_cvt_scalef32_pk_f16_fp4 v124, v116, 1.0
	v_pk_fma_f16 v115, v43, v115, v125 op_sel_hi:[0,1,1]
	v_pk_fma_f16 v124, v43, v124, v130 op_sel_hi:[0,1,1]
	v_cvt_scalef32_pk_f16_fp4 v125, v116, 1.0 op_sel:[1,0,0]
	v_cvt_scalef32_pk_f16_fp4 v130, v116, 1.0 op_sel:[0,1,0]
	v_cvt_scalef32_pk_f16_fp4 v116, v116, 1.0 op_sel:[1,1,0]
	v_pk_fma_f16 v125, v43, v125, v131 op_sel_hi:[0,1,1]
	v_pk_fma_f16 v130, v43, v130, v132 op_sel_hi:[0,1,1]
	v_pk_fma_f16 v116, v43, v116, v133 op_sel_hi:[0,1,1]
	v_cvt_scalef32_pk_f16_fp4 v131, v117, 1.0
	v_cvt_scalef32_pk_f16_fp4 v132, v117, 1.0 op_sel:[1,0,0]
	v_cvt_scalef32_pk_f16_fp4 v133, v117, 1.0 op_sel:[0,1,0]
	v_cvt_scalef32_pk_f16_fp4 v117, v117, 1.0 op_sel:[1,1,0]
	v_pk_fma_f16 v42, v43, v117, v42 op_sel_hi:[0,1,1]
	s_waitcnt vmcnt(33)
	v_cvt_scalef32_pk_f16_fp4 v117, v106, 1.0
	v_pk_fma_f16 v117, v43, v117, v118 op_sel:[1,0,0]
	v_cvt_scalef32_pk_f16_fp4 v118, v106, 1.0 op_sel:[1,0,0]
	v_pk_fma_f16 v118, v43, v118, v119 op_sel:[1,0,0]
	v_cvt_scalef32_pk_f16_fp4 v119, v106, 1.0 op_sel:[0,1,0]
	v_cvt_scalef32_pk_f16_fp4 v106, v106, 1.0 op_sel:[1,1,0]
	v_pk_fma_f16 v120, v43, v137, v120 op_sel_hi:[0,1,1]
	v_pk_fma_f16 v106, v43, v106, v114 op_sel:[1,0,0]
	v_cvt_scalef32_pk_f16_fp4 v114, v107, 1.0
	v_pk_fma_f16 v119, v43, v119, v120 op_sel:[1,0,0]
	v_pk_fma_f16 v114, v43, v114, v121 op_sel:[1,0,0]
	v_cvt_scalef32_pk_f16_fp4 v120, v107, 1.0 op_sel:[1,0,0]
	v_cvt_scalef32_pk_f16_fp4 v121, v107, 1.0 op_sel:[0,1,0]
	v_cvt_scalef32_pk_f16_fp4 v107, v107, 1.0 op_sel:[1,1,0]
	v_pk_fma_f16 v120, v43, v120, v122 op_sel:[1,0,0]
	v_pk_fma_f16 v121, v43, v121, v123 op_sel:[1,0,0]
	v_pk_fma_f16 v107, v43, v107, v115 op_sel:[1,0,0]
	v_cvt_scalef32_pk_f16_fp4 v115, v108, 1.0
	v_cvt_scalef32_pk_f16_fp4 v122, v108, 1.0 op_sel:[1,0,0]
	v_cvt_scalef32_pk_f16_fp4 v123, v108, 1.0 op_sel:[0,1,0]
	v_cvt_scalef32_pk_f16_fp4 v108, v108, 1.0 op_sel:[1,1,0]
	v_pk_fma_f16 v131, v43, v131, v134 op_sel_hi:[0,1,1]
	v_pk_fma_f16 v132, v43, v132, v135 op_sel_hi:[0,1,1]
	v_pk_fma_f16 v133, v43, v133, v136 op_sel_hi:[0,1,1]
	v_pk_fma_f16 v115, v43, v115, v124 op_sel:[1,0,0]
	v_pk_fma_f16 v122, v43, v122, v125 op_sel:[1,0,0]
	v_pk_fma_f16 v108, v43, v108, v116 op_sel:[1,0,0]
	v_cvt_scalef32_pk_f16_fp4 v116, v109, 1.0
	v_cvt_scalef32_pk_f16_fp4 v124, v109, 1.0 op_sel:[1,0,0]
	v_cvt_scalef32_pk_f16_fp4 v125, v109, 1.0 op_sel:[0,1,0]
	v_cvt_scalef32_pk_f16_fp4 v109, v109, 1.0 op_sel:[1,1,0]
	v_pk_fma_f16 v123, v43, v123, v130 op_sel:[1,0,0]
	v_pk_fma_f16 v116, v43, v116, v131 op_sel:[1,0,0]
	v_pk_fma_f16 v124, v43, v124, v132 op_sel:[1,0,0]
	v_pk_fma_f16 v125, v43, v125, v133 op_sel:[1,0,0]
	v_pk_fma_f16 v42, v43, v109, v42 op_sel:[1,0,0]
	s_waitcnt vmcnt(32)
	v_cvt_scalef32_pk_f16_fp4 v43, v98, 1.0
	v_pk_fma_f16 v43, v44, v43, v117 op_sel_hi:[0,1,1]
	v_cvt_scalef32_pk_f16_fp4 v109, v98, 1.0 op_sel:[1,0,0]
	v_cvt_scalef32_pk_f16_fp4 v117, v98, 1.0 op_sel:[0,1,0]
	v_cvt_scalef32_pk_f16_fp4 v98, v98, 1.0 op_sel:[1,1,0]
	v_pk_fma_f16 v98, v44, v98, v106 op_sel_hi:[0,1,1]
	v_cvt_scalef32_pk_f16_fp4 v106, v99, 1.0
	v_pk_fma_f16 v109, v44, v109, v118 op_sel_hi:[0,1,1]
	v_pk_fma_f16 v106, v44, v106, v114 op_sel_hi:[0,1,1]
	v_cvt_scalef32_pk_f16_fp4 v114, v99, 1.0 op_sel:[1,0,0]
	v_cvt_scalef32_pk_f16_fp4 v118, v99, 1.0 op_sel:[0,1,0]
	v_cvt_scalef32_pk_f16_fp4 v99, v99, 1.0 op_sel:[1,1,0]
	v_pk_fma_f16 v99, v44, v99, v107 op_sel_hi:[0,1,1]
	v_cvt_scalef32_pk_f16_fp4 v107, v100, 1.0
	v_pk_fma_f16 v117, v44, v117, v119 op_sel_hi:[0,1,1]
	v_pk_fma_f16 v107, v44, v107, v115 op_sel_hi:[0,1,1]
	v_cvt_scalef32_pk_f16_fp4 v115, v100, 1.0 op_sel:[1,0,0]
	v_cvt_scalef32_pk_f16_fp4 v119, v100, 1.0 op_sel:[0,1,0]
	v_cvt_scalef32_pk_f16_fp4 v100, v100, 1.0 op_sel:[1,1,0]
	v_pk_fma_f16 v100, v44, v100, v108 op_sel_hi:[0,1,1]
	v_cvt_scalef32_pk_f16_fp4 v108, v101, 1.0
	v_pk_fma_f16 v114, v44, v114, v120 op_sel_hi:[0,1,1]
	v_pk_fma_f16 v108, v44, v108, v116 op_sel_hi:[0,1,1]
	v_cvt_scalef32_pk_f16_fp4 v116, v101, 1.0 op_sel:[1,0,0]
	v_cvt_scalef32_pk_f16_fp4 v120, v101, 1.0 op_sel:[0,1,0]
	v_cvt_scalef32_pk_f16_fp4 v101, v101, 1.0 op_sel:[1,1,0]
	v_pk_fma_f16 v42, v44, v101, v42 op_sel_hi:[0,1,1]
	v_cvt_scalef32_pk_f16_fp4 v101, v82, 1.0
	v_pk_fma_f16 v43, v44, v101, v43 op_sel:[1,0,0]
	v_cvt_scalef32_pk_f16_fp4 v101, v82, 1.0 op_sel:[1,0,0]
	v_pk_fma_f16 v101, v44, v101, v109 op_sel:[1,0,0]
	v_cvt_scalef32_pk_f16_fp4 v109, v82, 1.0 op_sel:[0,1,0]
	v_cvt_scalef32_pk_f16_fp4 v82, v82, 1.0 op_sel:[1,1,0]
	v_pk_fma_f16 v82, v44, v82, v98 op_sel:[1,0,0]
	v_cvt_scalef32_pk_f16_fp4 v98, v83, 1.0
	v_pk_fma_f16 v98, v44, v98, v106 op_sel:[1,0,0]
	v_cvt_scalef32_pk_f16_fp4 v106, v83, 1.0 op_sel:[1,0,0]
	v_pk_fma_f16 v106, v44, v106, v114 op_sel:[1,0,0]
	v_cvt_scalef32_pk_f16_fp4 v114, v83, 1.0 op_sel:[0,1,0]
	v_cvt_scalef32_pk_f16_fp4 v83, v83, 1.0 op_sel:[1,1,0]
	v_pk_fma_f16 v83, v44, v83, v99 op_sel:[1,0,0]
	v_cvt_scalef32_pk_f16_fp4 v99, v84, 1.0
	v_pk_fma_f16 v115, v44, v115, v122 op_sel_hi:[0,1,1]
	v_pk_fma_f16 v99, v44, v99, v107 op_sel:[1,0,0]
	v_cvt_scalef32_pk_f16_fp4 v107, v84, 1.0 op_sel:[1,0,0]
	v_pk_fma_f16 v107, v44, v107, v115 op_sel:[1,0,0]
	v_cvt_scalef32_pk_f16_fp4 v115, v84, 1.0 op_sel:[0,1,0]
	v_cvt_scalef32_pk_f16_fp4 v84, v84, 1.0 op_sel:[1,1,0]
	v_pk_fma_f16 v84, v44, v84, v100 op_sel:[1,0,0]
	v_cvt_scalef32_pk_f16_fp4 v100, v85, 1.0
	v_pk_fma_f16 v116, v44, v116, v124 op_sel_hi:[0,1,1]
	v_pk_fma_f16 v100, v44, v100, v108 op_sel:[1,0,0]
	v_cvt_scalef32_pk_f16_fp4 v108, v85, 1.0 op_sel:[1,0,0]
	v_pk_fma_f16 v118, v44, v118, v121 op_sel_hi:[0,1,1]
	v_pk_fma_f16 v119, v44, v119, v123 op_sel_hi:[0,1,1]
	v_pk_fma_f16 v120, v44, v120, v125 op_sel_hi:[0,1,1]
	v_pk_fma_f16 v108, v44, v108, v116 op_sel:[1,0,0]
	v_cvt_scalef32_pk_f16_fp4 v116, v85, 1.0 op_sel:[0,1,0]
	v_cvt_scalef32_pk_f16_fp4 v85, v85, 1.0 op_sel:[1,1,0]
	v_pk_fma_f16 v109, v44, v109, v117 op_sel:[1,0,0]
	v_pk_fma_f16 v114, v44, v114, v118 op_sel:[1,0,0]
	v_pk_fma_f16 v115, v44, v115, v119 op_sel:[1,0,0]
	v_pk_fma_f16 v116, v44, v116, v120 op_sel:[1,0,0]
	v_pk_fma_f16 v42, v44, v85, v42 op_sel:[1,0,0]
	v_cvt_scalef32_pk_f16_fp4 v44, v74, 1.0
	v_pk_fma_f16 v43, v45, v44, v43 op_sel_hi:[0,1,1]
	v_cvt_scalef32_pk_f16_fp4 v44, v74, 1.0 op_sel:[1,0,0]
	v_cvt_scalef32_pk_f16_fp4 v85, v74, 1.0 op_sel:[0,1,0]
	v_cvt_scalef32_pk_f16_fp4 v74, v74, 1.0 op_sel:[1,1,0]
	v_pk_fma_f16 v74, v45, v74, v82 op_sel_hi:[0,1,1]
	v_cvt_scalef32_pk_f16_fp4 v82, v75, 1.0
	v_pk_fma_f16 v44, v45, v44, v101 op_sel_hi:[0,1,1]
	v_pk_fma_f16 v82, v45, v82, v98 op_sel_hi:[0,1,1]
	v_cvt_scalef32_pk_f16_fp4 v98, v75, 1.0 op_sel:[1,0,0]
	v_cvt_scalef32_pk_f16_fp4 v101, v75, 1.0 op_sel:[0,1,0]
	v_cvt_scalef32_pk_f16_fp4 v75, v75, 1.0 op_sel:[1,1,0]
	v_pk_fma_f16 v75, v45, v75, v83 op_sel_hi:[0,1,1]
	v_cvt_scalef32_pk_f16_fp4 v83, v76, 1.0
	v_pk_fma_f16 v98, v45, v98, v106 op_sel_hi:[0,1,1]
	v_pk_fma_f16 v83, v45, v83, v99 op_sel_hi:[0,1,1]
	v_cvt_scalef32_pk_f16_fp4 v99, v76, 1.0 op_sel:[1,0,0]
	v_cvt_scalef32_pk_f16_fp4 v106, v76, 1.0 op_sel:[0,1,0]
	v_cvt_scalef32_pk_f16_fp4 v76, v76, 1.0 op_sel:[1,1,0]
	v_pk_fma_f16 v76, v45, v76, v84 op_sel_hi:[0,1,1]
	v_cvt_scalef32_pk_f16_fp4 v84, v77, 1.0
	v_pk_fma_f16 v99, v45, v99, v107 op_sel_hi:[0,1,1]
	v_pk_fma_f16 v84, v45, v84, v100 op_sel_hi:[0,1,1]
	v_cvt_scalef32_pk_f16_fp4 v100, v77, 1.0 op_sel:[1,0,0]
	v_cvt_scalef32_pk_f16_fp4 v107, v77, 1.0 op_sel:[0,1,0]
	v_cvt_scalef32_pk_f16_fp4 v77, v77, 1.0 op_sel:[1,1,0]
	v_pk_fma_f16 v42, v45, v77, v42 op_sel_hi:[0,1,1]
	v_cvt_scalef32_pk_f16_fp4 v77, v66, 1.0
	v_pk_fma_f16 v43, v45, v77, v43 op_sel:[1,0,0]
	v_cvt_scalef32_pk_f16_fp4 v77, v66, 1.0 op_sel:[1,0,0]
	v_pk_fma_f16 v44, v45, v77, v44 op_sel:[1,0,0]
	v_cvt_scalef32_pk_f16_fp4 v77, v66, 1.0 op_sel:[0,1,0]
	v_cvt_scalef32_pk_f16_fp4 v66, v66, 1.0 op_sel:[1,1,0]
	v_pk_fma_f16 v85, v45, v85, v109 op_sel_hi:[0,1,1]
	v_pk_fma_f16 v66, v45, v66, v74 op_sel:[1,0,0]
	v_cvt_scalef32_pk_f16_fp4 v74, v67, 1.0
	v_pk_fma_f16 v77, v45, v77, v85 op_sel:[1,0,0]
	v_pk_fma_f16 v74, v45, v74, v82 op_sel:[1,0,0]
	v_cvt_scalef32_pk_f16_fp4 v82, v67, 1.0 op_sel:[1,0,0]
	v_cvt_scalef32_pk_f16_fp4 v85, v67, 1.0 op_sel:[0,1,0]
	v_cvt_scalef32_pk_f16_fp4 v67, v67, 1.0 op_sel:[1,1,0]
	v_pk_fma_f16 v67, v45, v67, v75 op_sel:[1,0,0]
	v_cvt_scalef32_pk_f16_fp4 v75, v68, 1.0
	v_pk_fma_f16 v82, v45, v82, v98 op_sel:[1,0,0]
	v_pk_fma_f16 v75, v45, v75, v83 op_sel:[1,0,0]
	v_cvt_scalef32_pk_f16_fp4 v83, v68, 1.0 op_sel:[1,0,0]
	v_cvt_scalef32_pk_f16_fp4 v98, v68, 1.0 op_sel:[0,1,0]
	v_cvt_scalef32_pk_f16_fp4 v68, v68, 1.0 op_sel:[1,1,0]
	v_pk_fma_f16 v68, v45, v68, v76 op_sel:[1,0,0]
	v_cvt_scalef32_pk_f16_fp4 v76, v69, 1.0
	v_pk_fma_f16 v101, v45, v101, v114 op_sel_hi:[0,1,1]
	v_pk_fma_f16 v106, v45, v106, v115 op_sel_hi:[0,1,1]
	v_pk_fma_f16 v100, v45, v100, v108 op_sel_hi:[0,1,1]
	v_pk_fma_f16 v107, v45, v107, v116 op_sel_hi:[0,1,1]
	v_pk_fma_f16 v83, v45, v83, v99 op_sel:[1,0,0]
	v_pk_fma_f16 v76, v45, v76, v84 op_sel:[1,0,0]
	v_cvt_scalef32_pk_f16_fp4 v84, v69, 1.0 op_sel:[1,0,0]
	v_cvt_scalef32_pk_f16_fp4 v99, v69, 1.0 op_sel:[0,1,0]
	v_cvt_scalef32_pk_f16_fp4 v69, v69, 1.0 op_sel:[1,1,0]
	v_pk_fma_f16 v85, v45, v85, v101 op_sel:[1,0,0]
	v_pk_fma_f16 v98, v45, v98, v106 op_sel:[1,0,0]
	v_pk_fma_f16 v84, v45, v84, v100 op_sel:[1,0,0]
	v_pk_fma_f16 v99, v45, v99, v107 op_sel:[1,0,0]
	v_pk_fma_f16 v42, v45, v69, v42 op_sel:[1,0,0]
	s_waitcnt vmcnt(31)
	v_cvt_scalef32_pk_f16_fp4 v45, v62, 1.0
	v_pk_fma_f16 v43, v6, v45, v43 op_sel_hi:[0,1,1]
	v_cvt_scalef32_pk_f16_fp4 v45, v62, 1.0 op_sel:[1,0,0]
	v_pk_fma_f16 v44, v6, v45, v44 op_sel_hi:[0,1,1]
	v_cvt_scalef32_pk_f16_fp4 v45, v62, 1.0 op_sel:[0,1,0]
	v_cvt_scalef32_pk_f16_fp4 v62, v62, 1.0 op_sel:[1,1,0]
	v_pk_fma_f16 v62, v6, v62, v66 op_sel_hi:[0,1,1]
	v_cvt_scalef32_pk_f16_fp4 v66, v63, 1.0
	v_pk_fma_f16 v66, v6, v66, v74 op_sel_hi:[0,1,1]
	v_cvt_scalef32_pk_f16_fp4 v69, v63, 1.0 op_sel:[1,0,0]
	v_cvt_scalef32_pk_f16_fp4 v74, v63, 1.0 op_sel:[0,1,0]
	v_cvt_scalef32_pk_f16_fp4 v63, v63, 1.0 op_sel:[1,1,0]
	v_pk_fma_f16 v63, v6, v63, v67 op_sel_hi:[0,1,1]
	v_cvt_scalef32_pk_f16_fp4 v67, v64, 1.0
	v_pk_fma_f16 v45, v6, v45, v77 op_sel_hi:[0,1,1]
	v_pk_fma_f16 v67, v6, v67, v75 op_sel_hi:[0,1,1]
	v_cvt_scalef32_pk_f16_fp4 v75, v64, 1.0 op_sel:[1,0,0]
	v_cvt_scalef32_pk_f16_fp4 v77, v64, 1.0 op_sel:[0,1,0]
	v_cvt_scalef32_pk_f16_fp4 v64, v64, 1.0 op_sel:[1,1,0]
	v_pk_fma_f16 v64, v6, v64, v68 op_sel_hi:[0,1,1]
	v_cvt_scalef32_pk_f16_fp4 v68, v65, 1.0
	v_pk_fma_f16 v69, v6, v69, v82 op_sel_hi:[0,1,1]
	v_pk_fma_f16 v68, v6, v68, v76 op_sel_hi:[0,1,1]
	v_cvt_scalef32_pk_f16_fp4 v76, v65, 1.0 op_sel:[1,0,0]
	v_cvt_scalef32_pk_f16_fp4 v82, v65, 1.0 op_sel:[0,1,0]
	v_cvt_scalef32_pk_f16_fp4 v65, v65, 1.0 op_sel:[1,1,0]
	v_pk_fma_f16 v42, v6, v65, v42 op_sel_hi:[0,1,1]
	s_waitcnt vmcnt(30)
	v_cvt_scalef32_pk_f16_fp4 v65, v54, 1.0
	v_pk_fma_f16 v43, v6, v65, v43 op_sel:[1,0,0]
	v_cvt_scalef32_pk_f16_fp4 v65, v54, 1.0 op_sel:[1,0,0]
	v_pk_fma_f16 v44, v6, v65, v44 op_sel:[1,0,0]
	v_cvt_scalef32_pk_f16_fp4 v65, v54, 1.0 op_sel:[0,1,0]
	v_cvt_scalef32_pk_f16_fp4 v54, v54, 1.0 op_sel:[1,1,0]
	v_pk_fma_f16 v54, v6, v54, v62 op_sel:[1,0,0]
	v_cvt_scalef32_pk_f16_fp4 v62, v55, 1.0
	v_pk_fma_f16 v45, v6, v65, v45 op_sel:[1,0,0]
	v_pk_fma_f16 v62, v6, v62, v66 op_sel:[1,0,0]
	v_cvt_scalef32_pk_f16_fp4 v65, v55, 1.0 op_sel:[1,0,0]
	v_cvt_scalef32_pk_f16_fp4 v66, v55, 1.0 op_sel:[0,1,0]
	v_cvt_scalef32_pk_f16_fp4 v55, v55, 1.0 op_sel:[1,1,0]
	v_pk_fma_f16 v55, v6, v55, v63 op_sel:[1,0,0]
	v_cvt_scalef32_pk_f16_fp4 v63, v56, 1.0
	v_pk_fma_f16 v65, v6, v65, v69 op_sel:[1,0,0]
	v_pk_fma_f16 v63, v6, v63, v67 op_sel:[1,0,0]
	v_cvt_scalef32_pk_f16_fp4 v67, v56, 1.0 op_sel:[1,0,0]
	v_cvt_scalef32_pk_f16_fp4 v69, v56, 1.0 op_sel:[0,1,0]
	v_cvt_scalef32_pk_f16_fp4 v56, v56, 1.0 op_sel:[1,1,0]
	v_pk_fma_f16 v74, v6, v74, v85 op_sel_hi:[0,1,1]
	v_pk_fma_f16 v56, v6, v56, v64 op_sel:[1,0,0]
	v_cvt_scalef32_pk_f16_fp4 v64, v57, 1.0
	v_pk_fma_f16 v75, v6, v75, v83 op_sel_hi:[0,1,1]
	v_pk_fma_f16 v77, v6, v77, v98 op_sel_hi:[0,1,1]
	v_pk_fma_f16 v76, v6, v76, v84 op_sel_hi:[0,1,1]
	v_pk_fma_f16 v82, v6, v82, v99 op_sel_hi:[0,1,1]
	v_pk_fma_f16 v66, v6, v66, v74 op_sel:[1,0,0]
	v_pk_fma_f16 v64, v6, v64, v68 op_sel:[1,0,0]
	v_cvt_scalef32_pk_f16_fp4 v68, v57, 1.0 op_sel:[1,0,0]
	v_cvt_scalef32_pk_f16_fp4 v74, v57, 1.0 op_sel:[0,1,0]
	v_cvt_scalef32_pk_f16_fp4 v57, v57, 1.0 op_sel:[1,1,0]
	v_pk_fma_f16 v67, v6, v67, v75 op_sel:[1,0,0]
	v_pk_fma_f16 v69, v6, v69, v77 op_sel:[1,0,0]
	v_pk_fma_f16 v68, v6, v68, v76 op_sel:[1,0,0]
	v_pk_fma_f16 v74, v6, v74, v82 op_sel:[1,0,0]
	v_pk_fma_f16 v6, v6, v57, v42 op_sel:[1,0,0]
	s_waitcnt vmcnt(29)
	v_cvt_scalef32_pk_f16_fp4 v42, v46, 1.0
	v_pk_fma_f16 v42, v7, v42, v43 op_sel_hi:[0,1,1]
	v_cvt_scalef32_pk_f16_fp4 v43, v46, 1.0 op_sel:[1,0,0]
	v_pk_fma_f16 v43, v7, v43, v44 op_sel_hi:[0,1,1]
	v_cvt_scalef32_pk_f16_fp4 v44, v46, 1.0 op_sel:[0,1,0]
	v_pk_fma_f16 v44, v7, v44, v45 op_sel_hi:[0,1,1]
	v_cvt_scalef32_pk_f16_fp4 v45, v46, 1.0 op_sel:[1,1,0]
	v_pk_fma_f16 v45, v7, v45, v54 op_sel_hi:[0,1,1]
	v_cvt_scalef32_pk_f16_fp4 v46, v47, 1.0
	v_cvt_scalef32_pk_f16_fp4 v54, v47, 1.0 op_sel:[1,0,0]
	v_cvt_scalef32_pk_f16_fp4 v57, v47, 1.0 op_sel:[0,1,0]
	v_cvt_scalef32_pk_f16_fp4 v47, v47, 1.0 op_sel:[1,1,0]
	v_pk_fma_f16 v47, v7, v47, v55 op_sel_hi:[0,1,1]
	v_cvt_scalef32_pk_f16_fp4 v55, v48, 1.0
	v_pk_fma_f16 v46, v7, v46, v62 op_sel_hi:[0,1,1]
	v_pk_fma_f16 v55, v7, v55, v63 op_sel_hi:[0,1,1]
	v_cvt_scalef32_pk_f16_fp4 v62, v48, 1.0 op_sel:[1,0,0]
	v_cvt_scalef32_pk_f16_fp4 v63, v48, 1.0 op_sel:[0,1,0]
	v_cvt_scalef32_pk_f16_fp4 v48, v48, 1.0 op_sel:[1,1,0]
	v_pk_fma_f16 v48, v7, v48, v56 op_sel_hi:[0,1,1]
	v_cvt_scalef32_pk_f16_fp4 v56, v49, 1.0
	v_pk_fma_f16 v54, v7, v54, v65 op_sel_hi:[0,1,1]
	v_pk_fma_f16 v56, v7, v56, v64 op_sel_hi:[0,1,1]
	v_cvt_scalef32_pk_f16_fp4 v64, v49, 1.0 op_sel:[1,0,0]
	v_cvt_scalef32_pk_f16_fp4 v65, v49, 1.0 op_sel:[0,1,0]
	v_cvt_scalef32_pk_f16_fp4 v49, v49, 1.0 op_sel:[1,1,0]
	v_pk_fma_f16 v6, v7, v49, v6 op_sel_hi:[0,1,1]
	s_waitcnt vmcnt(28)
	v_cvt_scalef32_pk_f16_fp4 v49, v34, 1.0
	v_pk_fma_f16 v42, v7, v49, v42 op_sel:[1,0,0]
	v_cvt_scalef32_pk_f16_fp4 v49, v34, 1.0 op_sel:[1,0,0]
	v_pk_fma_f16 v43, v7, v49, v43 op_sel:[1,0,0]
	v_cvt_scalef32_pk_f16_fp4 v49, v34, 1.0 op_sel:[0,1,0]
	v_cvt_scalef32_pk_f16_fp4 v34, v34, 1.0 op_sel:[1,1,0]
	v_pk_fma_f16 v34, v7, v34, v45 op_sel:[1,0,0]
	v_cvt_scalef32_pk_f16_fp4 v45, v35, 1.0
	v_pk_fma_f16 v44, v7, v49, v44 op_sel:[1,0,0]
	v_pk_fma_f16 v45, v7, v45, v46 op_sel:[1,0,0]
	v_cvt_scalef32_pk_f16_fp4 v46, v35, 1.0 op_sel:[1,0,0]
	v_cvt_scalef32_pk_f16_fp4 v49, v35, 1.0 op_sel:[0,1,0]
	v_cvt_scalef32_pk_f16_fp4 v35, v35, 1.0 op_sel:[1,1,0]
	v_pk_fma_f16 v35, v7, v35, v47 op_sel:[1,0,0]
	v_cvt_scalef32_pk_f16_fp4 v47, v36, 1.0
	v_pk_fma_f16 v46, v7, v46, v54 op_sel:[1,0,0]
	v_pk_fma_f16 v47, v7, v47, v55 op_sel:[1,0,0]
	v_cvt_scalef32_pk_f16_fp4 v54, v36, 1.0 op_sel:[1,0,0]
	v_cvt_scalef32_pk_f16_fp4 v55, v36, 1.0 op_sel:[0,1,0]
	v_cvt_scalef32_pk_f16_fp4 v36, v36, 1.0 op_sel:[1,1,0]
	v_pk_fma_f16 v57, v7, v57, v66 op_sel_hi:[0,1,1]
	v_pk_fma_f16 v36, v7, v36, v48 op_sel:[1,0,0]
	v_cvt_scalef32_pk_f16_fp4 v48, v37, 1.0
	v_pk_fma_f16 v62, v7, v62, v67 op_sel_hi:[0,1,1]
	v_pk_fma_f16 v63, v7, v63, v69 op_sel_hi:[0,1,1]
	v_pk_fma_f16 v64, v7, v64, v68 op_sel_hi:[0,1,1]
	v_pk_fma_f16 v65, v7, v65, v74 op_sel_hi:[0,1,1]
	v_pk_fma_f16 v49, v7, v49, v57 op_sel:[1,0,0]
	v_pk_fma_f16 v48, v7, v48, v56 op_sel:[1,0,0]
	v_cvt_scalef32_pk_f16_fp4 v56, v37, 1.0 op_sel:[1,0,0]
	v_cvt_scalef32_pk_f16_fp4 v57, v37, 1.0 op_sel:[0,1,0]
	v_cvt_scalef32_pk_f16_fp4 v37, v37, 1.0 op_sel:[1,1,0]
	v_pk_fma_f16 v54, v7, v54, v62 op_sel:[1,0,0]
	v_pk_fma_f16 v55, v7, v55, v63 op_sel:[1,0,0]
	v_pk_fma_f16 v56, v7, v56, v64 op_sel:[1,0,0]
	v_pk_fma_f16 v57, v7, v57, v65 op_sel:[1,0,0]
	v_pk_fma_f16 v6, v7, v37, v6 op_sel:[1,0,0]
	s_waitcnt vmcnt(27)
	v_cvt_scalef32_pk_f16_fp4 v7, v26, 1.0
	v_pk_fma_f16 v7, v8, v7, v42 op_sel_hi:[0,1,1]
	v_cvt_scalef32_pk_f16_fp4 v37, v26, 1.0 op_sel:[1,0,0]
	v_cvt_scalef32_pk_f16_fp4 v42, v26, 1.0 op_sel:[0,1,0]
	v_cvt_scalef32_pk_f16_fp4 v26, v26, 1.0 op_sel:[1,1,0]
	v_pk_fma_f16 v37, v8, v37, v43 op_sel_hi:[0,1,1]
	v_pk_fma_f16 v42, v8, v42, v44 op_sel_hi:[0,1,1]
	v_pk_fma_f16 v26, v8, v26, v34 op_sel_hi:[0,1,1]
	v_cvt_scalef32_pk_f16_fp4 v34, v27, 1.0
	v_cvt_scalef32_pk_f16_fp4 v43, v27, 1.0 op_sel:[1,0,0]
	v_cvt_scalef32_pk_f16_fp4 v44, v27, 1.0 op_sel:[0,1,0]
	v_cvt_scalef32_pk_f16_fp4 v27, v27, 1.0 op_sel:[1,1,0]
	v_pk_fma_f16 v34, v8, v34, v45 op_sel_hi:[0,1,1]
	v_pk_fma_f16 v43, v8, v43, v46 op_sel_hi:[0,1,1]
	v_pk_fma_f16 v27, v8, v27, v35 op_sel_hi:[0,1,1]
	v_cvt_scalef32_pk_f16_fp4 v35, v28, 1.0
	v_cvt_scalef32_pk_f16_fp4 v45, v28, 1.0 op_sel:[1,0,0]
	v_cvt_scalef32_pk_f16_fp4 v46, v28, 1.0 op_sel:[0,1,0]
	v_cvt_scalef32_pk_f16_fp4 v28, v28, 1.0 op_sel:[1,1,0]
	v_pk_fma_f16 v28, v8, v28, v36 op_sel_hi:[0,1,1]
	v_cvt_scalef32_pk_f16_fp4 v36, v29, 1.0
	v_pk_fma_f16 v35, v8, v35, v47 op_sel_hi:[0,1,1]
	v_pk_fma_f16 v36, v8, v36, v48 op_sel_hi:[0,1,1]
	v_cvt_scalef32_pk_f16_fp4 v47, v29, 1.0 op_sel:[1,0,0]
	v_cvt_scalef32_pk_f16_fp4 v48, v29, 1.0 op_sel:[0,1,0]
	v_cvt_scalef32_pk_f16_fp4 v29, v29, 1.0 op_sel:[1,1,0]
	v_pk_fma_f16 v6, v8, v29, v6 op_sel_hi:[0,1,1]
	s_waitcnt vmcnt(26)
	v_cvt_scalef32_pk_f16_fp4 v29, v22, 1.0
	v_pk_fma_f16 v7, v8, v29, v7 op_sel:[1,0,0]
	v_cvt_scalef32_pk_f16_fp4 v29, v22, 1.0 op_sel:[1,0,0]
	v_pk_fma_f16 v29, v8, v29, v37 op_sel:[1,0,0]
	v_cvt_scalef32_pk_f16_fp4 v37, v22, 1.0 op_sel:[0,1,0]
	v_cvt_scalef32_pk_f16_fp4 v22, v22, 1.0 op_sel:[1,1,0]
	v_pk_fma_f16 v22, v8, v22, v26 op_sel:[1,0,0]
	v_cvt_scalef32_pk_f16_fp4 v26, v23, 1.0
	v_pk_fma_f16 v37, v8, v37, v42 op_sel:[1,0,0]
	v_pk_fma_f16 v26, v8, v26, v34 op_sel:[1,0,0]
	v_cvt_scalef32_pk_f16_fp4 v34, v23, 1.0 op_sel:[1,0,0]
	v_cvt_scalef32_pk_f16_fp4 v42, v23, 1.0 op_sel:[0,1,0]
	v_cvt_scalef32_pk_f16_fp4 v23, v23, 1.0 op_sel:[1,1,0]
	v_pk_fma_f16 v23, v8, v23, v27 op_sel:[1,0,0]
	v_cvt_scalef32_pk_f16_fp4 v27, v24, 1.0
	v_pk_fma_f16 v34, v8, v34, v43 op_sel:[1,0,0]
	v_pk_fma_f16 v27, v8, v27, v35 op_sel:[1,0,0]
	v_cvt_scalef32_pk_f16_fp4 v35, v24, 1.0 op_sel:[1,0,0]
	v_cvt_scalef32_pk_f16_fp4 v43, v24, 1.0 op_sel:[0,1,0]
	v_cvt_scalef32_pk_f16_fp4 v24, v24, 1.0 op_sel:[1,1,0]
	v_pk_fma_f16 v44, v8, v44, v49 op_sel_hi:[0,1,1]
	v_pk_fma_f16 v24, v8, v24, v28 op_sel:[1,0,0]
	v_cvt_scalef32_pk_f16_fp4 v28, v25, 1.0
	v_pk_fma_f16 v45, v8, v45, v54 op_sel_hi:[0,1,1]
	v_pk_fma_f16 v46, v8, v46, v55 op_sel_hi:[0,1,1]
	v_pk_fma_f16 v47, v8, v47, v56 op_sel_hi:[0,1,1]
	v_pk_fma_f16 v48, v8, v48, v57 op_sel_hi:[0,1,1]
	v_pk_fma_f16 v42, v8, v42, v44 op_sel:[1,0,0]
	v_pk_fma_f16 v28, v8, v28, v36 op_sel:[1,0,0]
	v_cvt_scalef32_pk_f16_fp4 v36, v25, 1.0 op_sel:[1,0,0]
	v_cvt_scalef32_pk_f16_fp4 v44, v25, 1.0 op_sel:[0,1,0]
	v_cvt_scalef32_pk_f16_fp4 v25, v25, 1.0 op_sel:[1,1,0]
	v_pk_fma_f16 v35, v8, v35, v45 op_sel:[1,0,0]
	v_pk_fma_f16 v43, v8, v43, v46 op_sel:[1,0,0]
	v_pk_fma_f16 v36, v8, v36, v47 op_sel:[1,0,0]
	v_pk_fma_f16 v44, v8, v44, v48 op_sel:[1,0,0]
	v_pk_fma_f16 v6, v8, v25, v6 op_sel:[1,0,0]
	s_waitcnt vmcnt(25)
	v_cvt_scalef32_pk_f16_fp4 v8, v14, 1.0
	v_pk_fma_f16 v7, v9, v8, v7 op_sel_hi:[0,1,1]
	v_cvt_scalef32_pk_f16_fp4 v8, v14, 1.0 op_sel:[1,0,0]
	v_cvt_scalef32_pk_f16_fp4 v25, v14, 1.0 op_sel:[0,1,0]
	v_cvt_scalef32_pk_f16_fp4 v14, v14, 1.0 op_sel:[1,1,0]
	v_pk_fma_f16 v14, v9, v14, v22 op_sel_hi:[0,1,1]
	v_cvt_scalef32_pk_f16_fp4 v22, v15, 1.0
	v_pk_fma_f16 v8, v9, v8, v29 op_sel_hi:[0,1,1]
	v_pk_fma_f16 v22, v9, v22, v26 op_sel_hi:[0,1,1]
	v_cvt_scalef32_pk_f16_fp4 v26, v15, 1.0 op_sel:[1,0,0]
	v_cvt_scalef32_pk_f16_fp4 v29, v15, 1.0 op_sel:[0,1,0]
	v_cvt_scalef32_pk_f16_fp4 v15, v15, 1.0 op_sel:[1,1,0]
	v_pk_fma_f16 v15, v9, v15, v23 op_sel_hi:[0,1,1]
	v_cvt_scalef32_pk_f16_fp4 v23, v16, 1.0
	v_pk_fma_f16 v26, v9, v26, v34 op_sel_hi:[0,1,1]
	v_pk_fma_f16 v23, v9, v23, v27 op_sel_hi:[0,1,1]
	v_cvt_scalef32_pk_f16_fp4 v27, v16, 1.0 op_sel:[1,0,0]
	v_cvt_scalef32_pk_f16_fp4 v34, v16, 1.0 op_sel:[0,1,0]
	v_cvt_scalef32_pk_f16_fp4 v16, v16, 1.0 op_sel:[1,1,0]
	v_pk_fma_f16 v16, v9, v16, v24 op_sel_hi:[0,1,1]
	v_cvt_scalef32_pk_f16_fp4 v24, v17, 1.0
	v_pk_fma_f16 v27, v9, v27, v35 op_sel_hi:[0,1,1]
	v_pk_fma_f16 v24, v9, v24, v28 op_sel_hi:[0,1,1]
	v_cvt_scalef32_pk_f16_fp4 v28, v17, 1.0 op_sel:[1,0,0]
	v_cvt_scalef32_pk_f16_fp4 v35, v17, 1.0 op_sel:[0,1,0]
	v_cvt_scalef32_pk_f16_fp4 v17, v17, 1.0 op_sel:[1,1,0]
	v_pk_fma_f16 v6, v9, v17, v6 op_sel_hi:[0,1,1]
	s_waitcnt vmcnt(24)
	v_cvt_scalef32_pk_f16_fp4 v17, v10, 1.0
	v_pk_fma_f16 v7, v9, v17, v7 op_sel:[1,0,0]
	v_cvt_scalef32_pk_f16_fp4 v17, v10, 1.0 op_sel:[1,0,0]
	v_pk_fma_f16 v8, v9, v17, v8 op_sel:[1,0,0]
	v_cvt_scalef32_pk_f16_fp4 v17, v10, 1.0 op_sel:[0,1,0]
	v_cvt_scalef32_pk_f16_fp4 v10, v10, 1.0 op_sel:[1,1,0]
	v_pk_fma_f16 v25, v9, v25, v37 op_sel_hi:[0,1,1]
	v_pk_fma_f16 v10, v9, v10, v14 op_sel:[1,0,0]
	v_cvt_scalef32_pk_f16_fp4 v14, v11, 1.0
	v_pk_fma_f16 v17, v9, v17, v25 op_sel:[1,0,0]
	v_pk_fma_f16 v14, v9, v14, v22 op_sel:[1,0,0]
	v_cvt_scalef32_pk_f16_fp4 v22, v11, 1.0 op_sel:[1,0,0]
	v_cvt_scalef32_pk_f16_fp4 v25, v11, 1.0 op_sel:[0,1,0]
	v_cvt_scalef32_pk_f16_fp4 v11, v11, 1.0 op_sel:[1,1,0]
	v_pk_fma_f16 v11, v9, v11, v15 op_sel:[1,0,0]
	v_cvt_scalef32_pk_f16_fp4 v15, v12, 1.0
	v_pk_fma_f16 v22, v9, v22, v26 op_sel:[1,0,0]
	v_pk_fma_f16 v15, v9, v15, v23 op_sel:[1,0,0]
	v_cvt_scalef32_pk_f16_fp4 v23, v12, 1.0 op_sel:[1,0,0]
	v_cvt_scalef32_pk_f16_fp4 v26, v12, 1.0 op_sel:[0,1,0]
	v_cvt_scalef32_pk_f16_fp4 v12, v12, 1.0 op_sel:[1,1,0]
	v_pk_fma_f16 v29, v9, v29, v42 op_sel_hi:[0,1,1]
	v_pk_fma_f16 v34, v9, v34, v43 op_sel_hi:[0,1,1]
	v_pk_fma_f16 v35, v9, v35, v44 op_sel_hi:[0,1,1]
	v_pk_fma_f16 v23, v9, v23, v27 op_sel:[1,0,0]
	v_pk_fma_f16 v12, v9, v12, v16 op_sel:[1,0,0]
	v_cvt_scalef32_pk_f16_fp4 v16, v13, 1.0
	v_cvt_scalef32_pk_f16_fp4 v27, v13, 1.0 op_sel:[0,1,0]
	v_pk_fma_f16 v25, v9, v25, v29 op_sel:[1,0,0]
	v_pk_fma_f16 v26, v9, v26, v34 op_sel:[1,0,0]
	v_pk_fma_f16 v16, v9, v16, v24 op_sel:[1,0,0]
	v_cvt_scalef32_pk_f16_fp4 v24, v13, 1.0 op_sel:[1,0,0]
	v_pk_fma_f16 v27, v9, v27, v35 op_sel:[1,0,0]
	v_cvt_scalef32_pk_f16_fp4 v13, v13, 1.0 op_sel:[1,1,0]
	v_pk_fma_f16 v28, v9, v28, v36 op_sel_hi:[0,1,1]
	v_pk_fma_f16 v6, v9, v13, v6 op_sel:[1,0,0]
	v_permlane32_swap_b32_e32 v7, v15
	v_permlane32_swap_b32_e32 v17, v26
	v_permlane32_swap_b32_e32 v10, v12
	v_permlane32_swap_b32_e32 v14, v16
	v_permlane32_swap_b32_e32 v25, v27
	v_pk_fma_f16 v24, v9, v24, v28 op_sel:[1,0,0]
	v_pk_add_f16 v7, v7, v15
	v_pk_add_f16 v9, v17, v26
	v_pk_add_f16 v10, v10, v12
	v_pk_add_f16 v12, v14, v16
	v_pk_add_f16 v14, v25, v27
	v_permlane32_swap_b32_e32 v11, v6
	v_permlane32_swap_b32_e32 v8, v23
	v_permlane32_swap_b32_e32 v22, v24
	v_pk_add_f16 v6, v11, v6
	v_permlane16_swap_b32_e32 v7, v12
	v_permlane16_swap_b32_e32 v9, v14
	v_pk_add_f16 v8, v8, v23
	v_pk_add_f16 v13, v22, v24
	v_pk_add_f16 v7, v7, v12
	v_pk_add_f16 v9, v9, v14
	v_permlane16_swap_b32_e32 v10, v6
	v_permlane16_swap_b32_e32 v8, v13
	v_pk_add_f16 v6, v10, v6
	v_cndmask_b32_e64 v10, v9, v7, s[10:11]
	v_cndmask_b32_e64 v7, v7, v9, s[10:11]
	v_pk_add_f16 v8, v8, v13
	v_cvt_f32_f16_sdwa v13, v189 dst_sel:DWORD dst_unused:UNUSED_PAD src0_sel:WORD_1
	v_mov_b32_dpp v7, v7 row_ror:8 row_mask:0xf bank_mask:0xf bound_ctrl:1
	v_pk_add_f16 v9, v10, v7
	v_cndmask_b32_e64 v10, v6, v8, s[10:11]
	v_cndmask_b32_e64 v6, v8, v6, s[10:11]
	v_cvt_f32_f16_sdwa v7, v188 dst_sel:DWORD dst_unused:UNUSED_PAD src0_sel:WORD_1
	v_cvt_f32_f16_e32 v8, v9
	v_mov_b32_dpp v11, v6 row_ror:8 row_mask:0xf bank_mask:0xf bound_ctrl:1
	v_cvt_f32_f16_e32 v6, v188
	v_cvt_f32_f16_sdwa v9, v9 dst_sel:DWORD dst_unused:UNUSED_PAD src0_sel:WORD_1
	v_pk_add_f16 v15, v10, v11
	v_cvt_f32_f16_sdwa v11, v194 dst_sel:DWORD dst_unused:UNUSED_PAD src0_sel:WORD_1
	v_cvt_f32_f16_e32 v10, v194
	v_cvt_f32_f16_e32 v12, v189
	v_cvt_f32_f16_e32 v14, v15
	v_cvt_f32_f16_sdwa v15, v15 dst_sel:DWORD dst_unused:UNUSED_PAD src0_sel:WORD_1
	v_pk_fma_f32 v[6:7], v[2:3], v[8:9], v[6:7]
	v_cvt_f32_f16_sdwa v9, v195 dst_sel:DWORD dst_unused:UNUSED_PAD src0_sel:WORD_1
	v_cvt_f32_f16_e32 v8, v195
	v_pk_add_f32 v[6:7], v[6:7], v[10:11]
	v_pk_fma_f32 v[10:11], v[4:5], v[14:15], v[12:13]
	v_cvt_pk_f16_f32 v6, v6, v7
	v_pk_add_f32 v[8:9], v[10:11], v[8:9]
	s_nop 0
	v_cvt_pk_f16_f32 v7, v8, v9
	v_lshl_add_u64 v[8:9], v[190:191], 0, s[20:21]
	global_store_dwordx2 v[8:9], v[6:7], off
	v_lshl_add_u64 v[6:7], v[184:185], 0, s[22:23]
	v_lshl_add_u64 v[10:11], v[186:187], 0, s[26:27]
	global_load_dwordx4 v[118:121], v[6:7], off offset:48
	global_load_dwordx4 v[122:125], v[6:7], off offset:32
	global_load_dwordx4 v[130:133], v[6:7], off offset:16
	global_load_dwordx4 v[138:141], v[6:7], off
	s_nop 0
	global_load_dwordx4 v[6:9], v[10:11], off offset:16
	global_load_dwordx4 v[42:45], v[10:11], off
	v_lshl_add_u64 v[10:11], v[190:191], 0, s[24:25]
	v_lshl_add_u64 v[12:13], v[192:193], 0, s[24:25]
	global_load_dwordx2 v[194:195], v[10:11], off
	global_load_dwordx2 v[188:189], v[12:13], off
	s_waitcnt vmcnt(29)
	v_lshl_add_u32 v10, v178, 7, v207
	v_lshl_add_u32 v11, v179, 7, v207
	global_load_dwordx4 v[146:149], v10, s[12:13]
	global_load_dwordx4 v[134:137], v11, s[12:13]
	v_lshl_add_u32 v10, v180, 7, v207
	v_lshl_add_u32 v11, v181, 7, v207
	global_load_dwordx4 v[114:117], v10, s[12:13]
	global_load_dwordx4 v[106:109], v11, s[12:13]
	v_lshl_add_u32 v10, v174, 7, v207
	v_lshl_add_u32 v11, v175, 7, v207
	global_load_dwordx4 v[98:101], v10, s[12:13]
	global_load_dwordx4 v[82:85], v11, s[12:13]
	v_lshl_add_u32 v10, v176, 7, v207
	v_lshl_add_u32 v11, v177, 7, v207
	global_load_dwordx4 v[74:77], v10, s[12:13]
	global_load_dwordx4 v[66:69], v11, s[12:13]
	v_lshl_add_u32 v10, v170, 7, v207
	v_lshl_add_u32 v11, v171, 7, v207
	global_load_dwordx4 v[62:65], v10, s[12:13]
	global_load_dwordx4 v[54:57], v11, s[12:13]
	v_lshl_add_u32 v10, v172, 7, v207
	v_lshl_add_u32 v11, v173, 7, v207
	global_load_dwordx4 v[46:49], v10, s[12:13]
	global_load_dwordx4 v[34:37], v11, s[12:13]
	v_lshl_add_u32 v10, v166, 7, v207
	v_lshl_add_u32 v11, v167, 7, v207
	global_load_dwordx4 v[26:29], v10, s[12:13]
	global_load_dwordx4 v[22:25], v11, s[12:13]
	v_lshl_add_u32 v10, v168, 7, v207
	v_lshl_add_u32 v11, v169, 7, v207
	global_load_dwordx4 v[14:17], v10, s[12:13]
	s_nop 0
	global_load_dwordx4 v[10:13], v11, s[12:13]
	s_waitcnt vmcnt(40)
	v_cvt_scalef32_pk_f16_fp4 v166, v162, 1.0
	v_pk_fma_f16 v166, v90, v166, 0 op_sel_hi:[0,1,1]
	v_cvt_scalef32_pk_f16_fp4 v167, v162, 1.0 op_sel:[1,0,0]
	s_waitcnt vmcnt(39)
	v_cvt_scalef32_pk_f16_fp4 v178, v158, 1.0
	v_pk_fma_f16 v167, v90, v167, 0 op_sel_hi:[0,1,1]
	v_cvt_scalef32_pk_f16_fp4 v168, v162, 1.0 op_sel:[0,1,0]
	v_cvt_scalef32_pk_f16_fp4 v162, v162, 1.0 op_sel:[1,1,0]
	v_pk_fma_f16 v166, v90, v178, v166 op_sel:[1,0,0]
	v_cvt_scalef32_pk_f16_fp4 v178, v158, 1.0 op_sel:[1,0,0]
	v_pk_fma_f16 v162, v90, v162, 0 op_sel_hi:[0,1,1]
	v_cvt_scalef32_pk_f16_fp4 v169, v163, 1.0
	v_pk_fma_f16 v167, v90, v178, v167 op_sel:[1,0,0]
	v_cvt_scalef32_pk_f16_fp4 v178, v158, 1.0 op_sel:[0,1,0]
	v_cvt_scalef32_pk_f16_fp4 v158, v158, 1.0 op_sel:[1,1,0]
	v_pk_fma_f16 v169, v90, v169, 0 op_sel_hi:[0,1,1]
	v_cvt_scalef32_pk_f16_fp4 v170, v163, 1.0 op_sel:[1,0,0]
	v_pk_fma_f16 v158, v90, v158, v162 op_sel:[1,0,0]
	v_cvt_scalef32_pk_f16_fp4 v162, v159, 1.0
	v_pk_fma_f16 v170, v90, v170, 0 op_sel_hi:[0,1,1]
	v_cvt_scalef32_pk_f16_fp4 v171, v163, 1.0 op_sel:[0,1,0]
	v_cvt_scalef32_pk_f16_fp4 v163, v163, 1.0 op_sel:[1,1,0]
	v_pk_fma_f16 v162, v90, v162, v169 op_sel:[1,0,0]
	v_cvt_scalef32_pk_f16_fp4 v169, v159, 1.0 op_sel:[1,0,0]
	v_pk_fma_f16 v163, v90, v163, 0 op_sel_hi:[0,1,1]
	v_cvt_scalef32_pk_f16_fp4 v172, v164, 1.0
	v_pk_fma_f16 v169, v90, v169, v170 op_sel:[1,0,0]
	v_cvt_scalef32_pk_f16_fp4 v170, v159, 1.0 op_sel:[0,1,0]
	v_cvt_scalef32_pk_f16_fp4 v159, v159, 1.0 op_sel:[1,1,0]
	v_pk_fma_f16 v171, v90, v171, 0 op_sel_hi:[0,1,1]
	v_pk_fma_f16 v172, v90, v172, 0 op_sel_hi:[0,1,1]
	v_cvt_scalef32_pk_f16_fp4 v173, v164, 1.0 op_sel:[1,0,0]
	v_cvt_scalef32_pk_f16_fp4 v174, v164, 1.0 op_sel:[0,1,0]
	v_cvt_scalef32_pk_f16_fp4 v164, v164, 1.0 op_sel:[1,1,0]
	v_pk_fma_f16 v159, v90, v159, v163 op_sel:[1,0,0]
	v_cvt_scalef32_pk_f16_fp4 v163, v160, 1.0
	v_pk_fma_f16 v173, v90, v173, 0 op_sel_hi:[0,1,1]
	v_pk_fma_f16 v174, v90, v174, 0 op_sel_hi:[0,1,1]
	v_pk_fma_f16 v164, v90, v164, 0 op_sel_hi:[0,1,1]
	v_cvt_scalef32_pk_f16_fp4 v175, v165, 1.0
	v_cvt_scalef32_pk_f16_fp4 v176, v165, 1.0 op_sel:[1,0,0]
	v_cvt_scalef32_pk_f16_fp4 v177, v165, 1.0 op_sel:[0,1,0]
	v_cvt_scalef32_pk_f16_fp4 v165, v165, 1.0 op_sel:[1,1,0]
	v_pk_fma_f16 v170, v90, v170, v171 op_sel:[1,0,0]
	v_pk_fma_f16 v163, v90, v163, v172 op_sel:[1,0,0]
	v_cvt_scalef32_pk_f16_fp4 v171, v160, 1.0 op_sel:[1,0,0]
	v_cvt_scalef32_pk_f16_fp4 v172, v160, 1.0 op_sel:[0,1,0]
	v_cvt_scalef32_pk_f16_fp4 v160, v160, 1.0 op_sel:[1,1,0]
	v_pk_fma_f16 v168, v90, v168, 0 op_sel_hi:[0,1,1]
	v_pk_fma_f16 v175, v90, v175, 0 op_sel_hi:[0,1,1]
	v_pk_fma_f16 v176, v90, v176, 0 op_sel_hi:[0,1,1]
	v_pk_fma_f16 v177, v90, v177, 0 op_sel_hi:[0,1,1]
	v_pk_fma_f16 v165, v90, v165, 0 op_sel_hi:[0,1,1]
	v_pk_fma_f16 v171, v90, v171, v173 op_sel:[1,0,0]
	v_pk_fma_f16 v172, v90, v172, v174 op_sel:[1,0,0]
	v_pk_fma_f16 v160, v90, v160, v164 op_sel:[1,0,0]
	v_cvt_scalef32_pk_f16_fp4 v164, v161, 1.0
	v_cvt_scalef32_pk_f16_fp4 v173, v161, 1.0 op_sel:[1,0,0]
	v_cvt_scalef32_pk_f16_fp4 v174, v161, 1.0 op_sel:[0,1,0]
	v_cvt_scalef32_pk_f16_fp4 v161, v161, 1.0 op_sel:[1,1,0]
	v_pk_fma_f16 v168, v90, v178, v168 op_sel:[1,0,0]
	v_pk_fma_f16 v164, v90, v164, v175 op_sel:[1,0,0]
	v_pk_fma_f16 v173, v90, v173, v176 op_sel:[1,0,0]
	v_pk_fma_f16 v174, v90, v174, v177 op_sel:[1,0,0]
	v_pk_fma_f16 v90, v90, v161, v165 op_sel:[1,0,0]
	s_waitcnt vmcnt(38)
	v_cvt_scalef32_pk_f16_fp4 v161, v154, 1.0
	v_pk_fma_f16 v161, v91, v161, v166 op_sel_hi:[0,1,1]
	v_cvt_scalef32_pk_f16_fp4 v165, v154, 1.0 op_sel:[1,0,0]
	v_cvt_scalef32_pk_f16_fp4 v166, v154, 1.0 op_sel:[0,1,0]
	v_cvt_scalef32_pk_f16_fp4 v154, v154, 1.0 op_sel:[1,1,0]
	v_pk_fma_f16 v154, v91, v154, v158 op_sel_hi:[0,1,1]
	v_cvt_scalef32_pk_f16_fp4 v158, v155, 1.0
	v_pk_fma_f16 v165, v91, v165, v167 op_sel_hi:[0,1,1]
	v_pk_fma_f16 v158, v91, v158, v162 op_sel_hi:[0,1,1]
	v_cvt_scalef32_pk_f16_fp4 v162, v155, 1.0 op_sel:[1,0,0]
	v_cvt_scalef32_pk_f16_fp4 v167, v155, 1.0 op_sel:[0,1,0]
	v_cvt_scalef32_pk_f16_fp4 v155, v155, 1.0 op_sel:[1,1,0]
	v_pk_fma_f16 v155, v91, v155, v159 op_sel_hi:[0,1,1]
	v_cvt_scalef32_pk_f16_fp4 v159, v156, 1.0
	v_pk_fma_f16 v166, v91, v166, v168 op_sel_hi:[0,1,1]
	v_pk_fma_f16 v159, v91, v159, v163 op_sel_hi:[0,1,1]
	v_cvt_scalef32_pk_f16_fp4 v163, v156, 1.0 op_sel:[1,0,0]
	v_cvt_scalef32_pk_f16_fp4 v168, v156, 1.0 op_sel:[0,1,0]
	v_cvt_scalef32_pk_f16_fp4 v156, v156, 1.0 op_sel:[1,1,0]
	v_pk_fma_f16 v156, v91, v156, v160 op_sel_hi:[0,1,1]
	v_cvt_scalef32_pk_f16_fp4 v160, v157, 1.0
	v_pk_fma_f16 v162, v91, v162, v169 op_sel_hi:[0,1,1]
	v_pk_fma_f16 v160, v91, v160, v164 op_sel_hi:[0,1,1]
	v_cvt_scalef32_pk_f16_fp4 v164, v157, 1.0 op_sel:[1,0,0]
	v_cvt_scalef32_pk_f16_fp4 v169, v157, 1.0 op_sel:[0,1,0]
	v_cvt_scalef32_pk_f16_fp4 v157, v157, 1.0 op_sel:[1,1,0]
	v_pk_fma_f16 v90, v91, v157, v90 op_sel_hi:[0,1,1]
	s_waitcnt vmcnt(37)
	v_cvt_scalef32_pk_f16_fp4 v157, v150, 1.0
	v_pk_fma_f16 v157, v91, v157, v161 op_sel:[1,0,0]
	v_cvt_scalef32_pk_f16_fp4 v161, v150, 1.0 op_sel:[1,0,0]
	v_pk_fma_f16 v161, v91, v161, v165 op_sel:[1,0,0]
	v_cvt_scalef32_pk_f16_fp4 v165, v150, 1.0 op_sel:[0,1,0]
	v_cvt_scalef32_pk_f16_fp4 v150, v150, 1.0 op_sel:[1,1,0]
	v_pk_fma_f16 v150, v91, v150, v154 op_sel:[1,0,0]
	v_cvt_scalef32_pk_f16_fp4 v154, v151, 1.0
	v_pk_fma_f16 v154, v91, v154, v158 op_sel:[1,0,0]
	v_cvt_scalef32_pk_f16_fp4 v158, v151, 1.0 op_sel:[1,0,0]
	v_pk_fma_f16 v158, v91, v158, v162 op_sel:[1,0,0]
	v_cvt_scalef32_pk_f16_fp4 v162, v151, 1.0 op_sel:[0,1,0]
	v_cvt_scalef32_pk_f16_fp4 v151, v151, 1.0 op_sel:[1,1,0]
	v_pk_fma_f16 v151, v91, v151, v155 op_sel:[1,0,0]
	v_cvt_scalef32_pk_f16_fp4 v155, v152, 1.0
	v_pk_fma_f16 v163, v91, v163, v171 op_sel_hi:[0,1,1]
	v_pk_fma_f16 v155, v91, v155, v159 op_sel:[1,0,0]
	v_cvt_scalef32_pk_f16_fp4 v159, v152, 1.0 op_sel:[1,0,0]
	v_pk_fma_f16 v159, v91, v159, v163 op_sel:[1,0,0]
	v_cvt_scalef32_pk_f16_fp4 v163, v152, 1.0 op_sel:[0,1,0]
	v_cvt_scalef32_pk_f16_fp4 v152, v152, 1.0 op_sel:[1,1,0]
	v_pk_fma_f16 v152, v91, v152, v156 op_sel:[1,0,0]
	v_cvt_scalef32_pk_f16_fp4 v156, v153, 1.0
	v_pk_fma_f16 v164, v91, v164, v173 op_sel_hi:[0,1,1]
	v_pk_fma_f16 v156, v91, v156, v160 op_sel:[1,0,0]
	v_cvt_scalef32_pk_f16_fp4 v160, v153, 1.0 op_sel:[1,0,0]
	v_pk_fma_f16 v167, v91, v167, v170 op_sel_hi:[0,1,1]
	v_pk_fma_f16 v168, v91, v168, v172 op_sel_hi:[0,1,1]
	v_pk_fma_f16 v169, v91, v169, v174 op_sel_hi:[0,1,1]
	v_pk_fma_f16 v160, v91, v160, v164 op_sel:[1,0,0]
	v_cvt_scalef32_pk_f16_fp4 v164, v153, 1.0 op_sel:[0,1,0]
	v_cvt_scalef32_pk_f16_fp4 v153, v153, 1.0 op_sel:[1,1,0]
	v_pk_fma_f16 v165, v91, v165, v166 op_sel:[1,0,0]
	v_pk_fma_f16 v162, v91, v162, v167 op_sel:[1,0,0]
	v_pk_fma_f16 v163, v91, v163, v168 op_sel:[1,0,0]
	v_pk_fma_f16 v164, v91, v164, v169 op_sel:[1,0,0]
	v_pk_fma_f16 v90, v91, v153, v90 op_sel:[1,0,0]
	s_waitcnt vmcnt(36)
	v_cvt_scalef32_pk_f16_fp4 v91, v142, 1.0
	v_pk_fma_f16 v91, v92, v91, v157 op_sel_hi:[0,1,1]
	v_cvt_scalef32_pk_f16_fp4 v153, v142, 1.0 op_sel:[1,0,0]
	v_cvt_scalef32_pk_f16_fp4 v157, v142, 1.0 op_sel:[0,1,0]
	v_cvt_scalef32_pk_f16_fp4 v142, v142, 1.0 op_sel:[1,1,0]
	v_pk_fma_f16 v142, v92, v142, v150 op_sel_hi:[0,1,1]
	v_cvt_scalef32_pk_f16_fp4 v150, v143, 1.0
	v_pk_fma_f16 v150, v92, v150, v154 op_sel_hi:[0,1,1]
	v_cvt_scalef32_pk_f16_fp4 v154, v143, 1.0 op_sel:[1,0,0]
	v_pk_fma_f16 v154, v92, v154, v158 op_sel_hi:[0,1,1]
	v_cvt_scalef32_pk_f16_fp4 v158, v143, 1.0 op_sel:[0,1,0]
	v_cvt_scalef32_pk_f16_fp4 v143, v143, 1.0 op_sel:[1,1,0]
	v_pk_fma_f16 v143, v92, v143, v151 op_sel_hi:[0,1,1]
	v_cvt_scalef32_pk_f16_fp4 v151, v144, 1.0
	v_pk_fma_f16 v151, v92, v151, v155 op_sel_hi:[0,1,1]
	v_cvt_scalef32_pk_f16_fp4 v155, v144, 1.0 op_sel:[1,0,0]
	v_pk_fma_f16 v155, v92, v155, v159 op_sel_hi:[0,1,1]
	v_cvt_scalef32_pk_f16_fp4 v159, v144, 1.0 op_sel:[0,1,0]
	v_cvt_scalef32_pk_f16_fp4 v144, v144, 1.0 op_sel:[1,1,0]
	v_pk_fma_f16 v144, v92, v144, v152 op_sel_hi:[0,1,1]
	v_cvt_scalef32_pk_f16_fp4 v152, v145, 1.0
	v_pk_fma_f16 v152, v92, v152, v156 op_sel_hi:[0,1,1]
	v_cvt_scalef32_pk_f16_fp4 v156, v145, 1.0 op_sel:[1,0,0]
	v_pk_fma_f16 v156, v92, v156, v160 op_sel_hi:[0,1,1]
	v_cvt_scalef32_pk_f16_fp4 v160, v145, 1.0 op_sel:[0,1,0]
	v_cvt_scalef32_pk_f16_fp4 v145, v145, 1.0 op_sel:[1,1,0]
	v_pk_fma_f16 v90, v92, v145, v90 op_sel_hi:[0,1,1]
	s_waitcnt vmcnt(35)
	v_cvt_scalef32_pk_f16_fp4 v145, v126, 1.0
	v_pk_fma_f16 v153, v92, v153, v161 op_sel_hi:[0,1,1]
	v_pk_fma_f16 v91, v92, v145, v91 op_sel:[1,0,0]
	v_cvt_scalef32_pk_f16_fp4 v145, v126, 1.0 op_sel:[1,0,0]
	v_pk_fma_f16 v145, v92, v145, v153 op_sel:[1,0,0]
	v_cvt_scalef32_pk_f16_fp4 v153, v126, 1.0 op_sel:[0,1,0]
	v_cvt_scalef32_pk_f16_fp4 v126, v126, 1.0 op_sel:[1,1,0]
	v_pk_fma_f16 v126, v92, v126, v142 op_sel:[1,0,0]
	v_cvt_scalef32_pk_f16_fp4 v142, v127, 1.0
	v_pk_fma_f16 v142, v92, v142, v150 op_sel:[1,0,0]
	v_cvt_scalef32_pk_f16_fp4 v150, v127, 1.0 op_sel:[1,0,0]
	v_pk_fma_f16 v150, v92, v150, v154 op_sel:[1,0,0]
	v_cvt_scalef32_pk_f16_fp4 v154, v127, 1.0 op_sel:[0,1,0]
	v_cvt_scalef32_pk_f16_fp4 v127, v127, 1.0 op_sel:[1,1,0]
	v_pk_fma_f16 v127, v92, v127, v143 op_sel:[1,0,0]
	v_cvt_scalef32_pk_f16_fp4 v143, v128, 1.0
	v_pk_fma_f16 v143, v92, v143, v151 op_sel:[1,0,0]
	v_cvt_scalef32_pk_f16_fp4 v151, v128, 1.0 op_sel:[1,0,0]
	v_pk_fma_f16 v151, v92, v151, v155 op_sel:[1,0,0]
	v_cvt_scalef32_pk_f16_fp4 v155, v128, 1.0 op_sel:[0,1,0]
	v_cvt_scalef32_pk_f16_fp4 v128, v128, 1.0 op_sel:[1,1,0]
	v_pk_fma_f16 v128, v92, v128, v144 op_sel:[1,0,0]
	v_cvt_scalef32_pk_f16_fp4 v144, v129, 1.0
	v_pk_fma_f16 v144, v92, v144, v152 op_sel:[1,0,0]
	v_cvt_scalef32_pk_f16_fp4 v152, v129, 1.0 op_sel:[1,0,0]
	v_pk_fma_f16 v157, v92, v157, v165 op_sel_hi:[0,1,1]
	v_pk_fma_f16 v158, v92, v158, v162 op_sel_hi:[0,1,1]
	v_pk_fma_f16 v159, v92, v159, v163 op_sel_hi:[0,1,1]
	v_pk_fma_f16 v160, v92, v160, v164 op_sel_hi:[0,1,1]
	v_pk_fma_f16 v152, v92, v152, v156 op_sel:[1,0,0]
	v_cvt_scalef32_pk_f16_fp4 v156, v129, 1.0 op_sel:[0,1,0]
	v_cvt_scalef32_pk_f16_fp4 v129, v129, 1.0 op_sel:[1,1,0]
	v_pk_fma_f16 v153, v92, v153, v157 op_sel:[1,0,0]
	v_pk_fma_f16 v154, v92, v154, v158 op_sel:[1,0,0]
	v_pk_fma_f16 v155, v92, v155, v159 op_sel:[1,0,0]
	v_pk_fma_f16 v156, v92, v156, v160 op_sel:[1,0,0]
	v_pk_fma_f16 v90, v92, v129, v90 op_sel:[1,0,0]
	s_waitcnt vmcnt(34)
	v_cvt_scalef32_pk_f16_fp4 v92, v110, 1.0
	v_pk_fma_f16 v91, v93, v92, v91 op_sel_hi:[0,1,1]
	v_cvt_scalef32_pk_f16_fp4 v92, v110, 1.0 op_sel:[1,0,0]
	v_cvt_scalef32_pk_f16_fp4 v129, v110, 1.0 op_sel:[0,1,0]
	v_cvt_scalef32_pk_f16_fp4 v110, v110, 1.0 op_sel:[1,1,0]
	v_pk_fma_f16 v110, v93, v110, v126 op_sel_hi:[0,1,1]
	v_cvt_scalef32_pk_f16_fp4 v126, v111, 1.0
	v_pk_fma_f16 v92, v93, v92, v145 op_sel_hi:[0,1,1]
	v_pk_fma_f16 v126, v93, v126, v142 op_sel_hi:[0,1,1]
	v_cvt_scalef32_pk_f16_fp4 v142, v111, 1.0 op_sel:[1,0,0]
	v_cvt_scalef32_pk_f16_fp4 v145, v111, 1.0 op_sel:[0,1,0]
	v_cvt_scalef32_pk_f16_fp4 v111, v111, 1.0 op_sel:[1,1,0]
	v_pk_fma_f16 v111, v93, v111, v127 op_sel_hi:[0,1,1]
	v_cvt_scalef32_pk_f16_fp4 v127, v112, 1.0
	v_pk_fma_f16 v142, v93, v142, v150 op_sel_hi:[0,1,1]
	v_pk_fma_f16 v127, v93, v127, v143 op_sel_hi:[0,1,1]
	v_cvt_scalef32_pk_f16_fp4 v143, v112, 1.0 op_sel:[1,0,0]
	v_cvt_scalef32_pk_f16_fp4 v150, v112, 1.0 op_sel:[0,1,0]
	v_cvt_scalef32_pk_f16_fp4 v112, v112, 1.0 op_sel:[1,1,0]
	v_pk_fma_f16 v112, v93, v112, v128 op_sel_hi:[0,1,1]
	v_cvt_scalef32_pk_f16_fp4 v128, v113, 1.0
	v_pk_fma_f16 v143, v93, v143, v151 op_sel_hi:[0,1,1]
	v_pk_fma_f16 v128, v93, v128, v144 op_sel_hi:[0,1,1]
	v_cvt_scalef32_pk_f16_fp4 v144, v113, 1.0 op_sel:[1,0,0]
	v_cvt_scalef32_pk_f16_fp4 v151, v113, 1.0 op_sel:[0,1,0]
	v_cvt_scalef32_pk_f16_fp4 v113, v113, 1.0 op_sel:[1,1,0]
	v_pk_fma_f16 v90, v93, v113, v90 op_sel_hi:[0,1,1]
	s_waitcnt vmcnt(33)
	v_cvt_scalef32_pk_f16_fp4 v113, v102, 1.0
	v_pk_fma_f16 v91, v93, v113, v91 op_sel:[1,0,0]
	v_cvt_scalef32_pk_f16_fp4 v113, v102, 1.0 op_sel:[1,0,0]
	v_pk_fma_f16 v92, v93, v113, v92 op_sel:[1,0,0]
	v_cvt_scalef32_pk_f16_fp4 v113, v102, 1.0 op_sel:[0,1,0]
	v_cvt_scalef32_pk_f16_fp4 v102, v102, 1.0 op_sel:[1,1,0]
	v_pk_fma_f16 v129, v93, v129, v153 op_sel_hi:[0,1,1]
	v_pk_fma_f16 v102, v93, v102, v110 op_sel:[1,0,0]
	v_cvt_scalef32_pk_f16_fp4 v110, v103, 1.0
	v_pk_fma_f16 v113, v93, v113, v129 op_sel:[1,0,0]
	v_pk_fma_f16 v110, v93, v110, v126 op_sel:[1,0,0]
	v_cvt_scalef32_pk_f16_fp4 v126, v103, 1.0 op_sel:[1,0,0]
	v_cvt_scalef32_pk_f16_fp4 v129, v103, 1.0 op_sel:[0,1,0]
	v_cvt_scalef32_pk_f16_fp4 v103, v103, 1.0 op_sel:[1,1,0]
	v_pk_fma_f16 v103, v93, v103, v111 op_sel:[1,0,0]
	v_cvt_scalef32_pk_f16_fp4 v111, v104, 1.0
	v_pk_fma_f16 v126, v93, v126, v142 op_sel:[1,0,0]
	v_pk_fma_f16 v111, v93, v111, v127 op_sel:[1,0,0]
	v_cvt_scalef32_pk_f16_fp4 v127, v104, 1.0 op_sel:[1,0,0]
	v_cvt_scalef32_pk_f16_fp4 v142, v104, 1.0 op_sel:[0,1,0]
	v_cvt_scalef32_pk_f16_fp4 v104, v104, 1.0 op_sel:[1,1,0]
	v_pk_fma_f16 v104, v93, v104, v112 op_sel:[1,0,0]
	v_cvt_scalef32_pk_f16_fp4 v112, v105, 1.0
	v_pk_fma_f16 v145, v93, v145, v154 op_sel_hi:[0,1,1]
	v_pk_fma_f16 v150, v93, v150, v155 op_sel_hi:[0,1,1]
	v_pk_fma_f16 v144, v93, v144, v152 op_sel_hi:[0,1,1]
	v_pk_fma_f16 v151, v93, v151, v156 op_sel_hi:[0,1,1]
	v_pk_fma_f16 v127, v93, v127, v143 op_sel:[1,0,0]
	v_pk_fma_f16 v112, v93, v112, v128 op_sel:[1,0,0]
	v_cvt_scalef32_pk_f16_fp4 v128, v105, 1.0 op_sel:[1,0,0]
	v_cvt_scalef32_pk_f16_fp4 v143, v105, 1.0 op_sel:[0,1,0]
	v_cvt_scalef32_pk_f16_fp4 v105, v105, 1.0 op_sel:[1,1,0]
	v_pk_fma_f16 v129, v93, v129, v145 op_sel:[1,0,0]
	v_pk_fma_f16 v142, v93, v142, v150 op_sel:[1,0,0]
	v_pk_fma_f16 v128, v93, v128, v144 op_sel:[1,0,0]
	v_pk_fma_f16 v143, v93, v143, v151 op_sel:[1,0,0]
	v_pk_fma_f16 v90, v93, v105, v90 op_sel:[1,0,0]
	s_waitcnt vmcnt(32)
	v_cvt_scalef32_pk_f16_fp4 v93, v94, 1.0
	v_pk_fma_f16 v91, v18, v93, v91 op_sel_hi:[0,1,1]
	v_cvt_scalef32_pk_f16_fp4 v93, v94, 1.0 op_sel:[1,0,0]
	v_pk_fma_f16 v92, v18, v93, v92 op_sel_hi:[0,1,1]
	v_cvt_scalef32_pk_f16_fp4 v93, v94, 1.0 op_sel:[0,1,0]
	v_cvt_scalef32_pk_f16_fp4 v94, v94, 1.0 op_sel:[1,1,0]
	v_pk_fma_f16 v94, v18, v94, v102 op_sel_hi:[0,1,1]
	v_cvt_scalef32_pk_f16_fp4 v102, v95, 1.0
	v_pk_fma_f16 v102, v18, v102, v110 op_sel_hi:[0,1,1]
	v_cvt_scalef32_pk_f16_fp4 v105, v95, 1.0 op_sel:[1,0,0]
	v_cvt_scalef32_pk_f16_fp4 v110, v95, 1.0 op_sel:[0,1,0]
	v_cvt_scalef32_pk_f16_fp4 v95, v95, 1.0 op_sel:[1,1,0]
	v_pk_fma_f16 v95, v18, v95, v103 op_sel_hi:[0,1,1]
	v_cvt_scalef32_pk_f16_fp4 v103, v96, 1.0
	v_pk_fma_f16 v93, v18, v93, v113 op_sel_hi:[0,1,1]
	v_pk_fma_f16 v103, v18, v103, v111 op_sel_hi:[0,1,1]
	v_cvt_scalef32_pk_f16_fp4 v111, v96, 1.0 op_sel:[1,0,0]
	v_cvt_scalef32_pk_f16_fp4 v113, v96, 1.0 op_sel:[0,1,0]
	v_cvt_scalef32_pk_f16_fp4 v96, v96, 1.0 op_sel:[1,1,0]
	v_pk_fma_f16 v96, v18, v96, v104 op_sel_hi:[0,1,1]
	v_cvt_scalef32_pk_f16_fp4 v104, v97, 1.0
	v_pk_fma_f16 v105, v18, v105, v126 op_sel_hi:[0,1,1]
	v_pk_fma_f16 v104, v18, v104, v112 op_sel_hi:[0,1,1]
	v_cvt_scalef32_pk_f16_fp4 v112, v97, 1.0 op_sel:[1,0,0]
	v_cvt_scalef32_pk_f16_fp4 v126, v97, 1.0 op_sel:[0,1,0]
	v_cvt_scalef32_pk_f16_fp4 v97, v97, 1.0 op_sel:[1,1,0]
	v_pk_fma_f16 v90, v18, v97, v90 op_sel_hi:[0,1,1]
	s_waitcnt vmcnt(31)
	v_cvt_scalef32_pk_f16_fp4 v97, v86, 1.0
	v_pk_fma_f16 v91, v18, v97, v91 op_sel:[1,0,0]
	v_cvt_scalef32_pk_f16_fp4 v97, v86, 1.0 op_sel:[1,0,0]
	v_pk_fma_f16 v92, v18, v97, v92 op_sel:[1,0,0]
	v_cvt_scalef32_pk_f16_fp4 v97, v86, 1.0 op_sel:[0,1,0]
	v_cvt_scalef32_pk_f16_fp4 v86, v86, 1.0 op_sel:[1,1,0]
	v_pk_fma_f16 v86, v18, v86, v94 op_sel:[1,0,0]
	v_cvt_scalef32_pk_f16_fp4 v94, v87, 1.0
	v_pk_fma_f16 v93, v18, v97, v93 op_sel:[1,0,0]
	v_pk_fma_f16 v94, v18, v94, v102 op_sel:[1,0,0]
	v_cvt_scalef32_pk_f16_fp4 v97, v87, 1.0 op_sel:[1,0,0]
	v_cvt_scalef32_pk_f16_fp4 v102, v87, 1.0 op_sel:[0,1,0]
	v_cvt_scalef32_pk_f16_fp4 v87, v87, 1.0 op_sel:[1,1,0]
	v_pk_fma_f16 v87, v18, v87, v95 op_sel:[1,0,0]
	v_cvt_scalef32_pk_f16_fp4 v95, v88, 1.0
	v_pk_fma_f16 v97, v18, v97, v105 op_sel:[1,0,0]
	v_pk_fma_f16 v95, v18, v95, v103 op_sel:[1,0,0]
	v_cvt_scalef32_pk_f16_fp4 v103, v88, 1.0 op_sel:[1,0,0]
	v_cvt_scalef32_pk_f16_fp4 v105, v88, 1.0 op_sel:[0,1,0]
	v_cvt_scalef32_pk_f16_fp4 v88, v88, 1.0 op_sel:[1,1,0]
	v_pk_fma_f16 v110, v18, v110, v129 op_sel_hi:[0,1,1]
	v_pk_fma_f16 v88, v18, v88, v96 op_sel:[1,0,0]
	v_cvt_scalef32_pk_f16_fp4 v96, v89, 1.0
	v_pk_fma_f16 v111, v18, v111, v127 op_sel_hi:[0,1,1]
	v_pk_fma_f16 v113, v18, v113, v142 op_sel_hi:[0,1,1]
	v_pk_fma_f16 v112, v18, v112, v128 op_sel_hi:[0,1,1]
	v_pk_fma_f16 v126, v18, v126, v143 op_sel_hi:[0,1,1]
	v_pk_fma_f16 v102, v18, v102, v110 op_sel:[1,0,0]
	v_pk_fma_f16 v96, v18, v96, v104 op_sel:[1,0,0]
	v_cvt_scalef32_pk_f16_fp4 v104, v89, 1.0 op_sel:[1,0,0]
	v_cvt_scalef32_pk_f16_fp4 v110, v89, 1.0 op_sel:[0,1,0]
	v_cvt_scalef32_pk_f16_fp4 v89, v89, 1.0 op_sel:[1,1,0]
	v_pk_fma_f16 v103, v18, v103, v111 op_sel:[1,0,0]
	v_pk_fma_f16 v105, v18, v105, v113 op_sel:[1,0,0]
	v_pk_fma_f16 v104, v18, v104, v112 op_sel:[1,0,0]
	v_pk_fma_f16 v110, v18, v110, v126 op_sel:[1,0,0]
	v_pk_fma_f16 v18, v18, v89, v90 op_sel:[1,0,0]
	s_waitcnt vmcnt(30)
	v_cvt_scalef32_pk_f16_fp4 v89, v78, 1.0
	v_pk_fma_f16 v89, v19, v89, v91 op_sel_hi:[0,1,1]
	v_cvt_scalef32_pk_f16_fp4 v90, v78, 1.0 op_sel:[1,0,0]
	v_cvt_scalef32_pk_f16_fp4 v91, v78, 1.0 op_sel:[0,1,0]
	v_cvt_scalef32_pk_f16_fp4 v78, v78, 1.0 op_sel:[1,1,0]
	v_pk_fma_f16 v90, v19, v90, v92 op_sel_hi:[0,1,1]
	v_pk_fma_f16 v91, v19, v91, v93 op_sel_hi:[0,1,1]
	v_pk_fma_f16 v78, v19, v78, v86 op_sel_hi:[0,1,1]
	v_cvt_scalef32_pk_f16_fp4 v86, v79, 1.0
	v_cvt_scalef32_pk_f16_fp4 v92, v79, 1.0 op_sel:[1,0,0]
	v_cvt_scalef32_pk_f16_fp4 v93, v79, 1.0 op_sel:[0,1,0]
	v_cvt_scalef32_pk_f16_fp4 v79, v79, 1.0 op_sel:[1,1,0]
	v_pk_fma_f16 v79, v19, v79, v87 op_sel_hi:[0,1,1]
	v_cvt_scalef32_pk_f16_fp4 v87, v80, 1.0
	v_pk_fma_f16 v86, v19, v86, v94 op_sel_hi:[0,1,1]
	v_pk_fma_f16 v87, v19, v87, v95 op_sel_hi:[0,1,1]
	v_cvt_scalef32_pk_f16_fp4 v94, v80, 1.0 op_sel:[1,0,0]
	v_cvt_scalef32_pk_f16_fp4 v95, v80, 1.0 op_sel:[0,1,0]
	v_cvt_scalef32_pk_f16_fp4 v80, v80, 1.0 op_sel:[1,1,0]
	v_pk_fma_f16 v80, v19, v80, v88 op_sel_hi:[0,1,1]
	v_cvt_scalef32_pk_f16_fp4 v88, v81, 1.0
	v_pk_fma_f16 v92, v19, v92, v97 op_sel_hi:[0,1,1]
	v_pk_fma_f16 v88, v19, v88, v96 op_sel_hi:[0,1,1]
	v_cvt_scalef32_pk_f16_fp4 v96, v81, 1.0 op_sel:[1,0,0]
	v_cvt_scalef32_pk_f16_fp4 v97, v81, 1.0 op_sel:[0,1,0]
	v_cvt_scalef32_pk_f16_fp4 v81, v81, 1.0 op_sel:[1,1,0]
	v_pk_fma_f16 v18, v19, v81, v18 op_sel_hi:[0,1,1]
	s_waitcnt vmcnt(29)
	v_cvt_scalef32_pk_f16_fp4 v81, v70, 1.0
	v_pk_fma_f16 v81, v19, v81, v89 op_sel:[1,0,0]
	v_cvt_scalef32_pk_f16_fp4 v89, v70, 1.0 op_sel:[1,0,0]
	v_pk_fma_f16 v89, v19, v89, v90 op_sel:[1,0,0]
	v_cvt_scalef32_pk_f16_fp4 v90, v70, 1.0 op_sel:[0,1,0]
	v_cvt_scalef32_pk_f16_fp4 v70, v70, 1.0 op_sel:[1,1,0]
	v_pk_fma_f16 v70, v19, v70, v78 op_sel:[1,0,0]
	v_cvt_scalef32_pk_f16_fp4 v78, v71, 1.0
	v_pk_fma_f16 v90, v19, v90, v91 op_sel:[1,0,0]
	v_pk_fma_f16 v78, v19, v78, v86 op_sel:[1,0,0]
	v_cvt_scalef32_pk_f16_fp4 v86, v71, 1.0 op_sel:[1,0,0]
	v_cvt_scalef32_pk_f16_fp4 v91, v71, 1.0 op_sel:[0,1,0]
	v_cvt_scalef32_pk_f16_fp4 v71, v71, 1.0 op_sel:[1,1,0]
	v_pk_fma_f16 v71, v19, v71, v79 op_sel:[1,0,0]
	v_cvt_scalef32_pk_f16_fp4 v79, v72, 1.0
	v_pk_fma_f16 v86, v19, v86, v92 op_sel:[1,0,0]
	v_pk_fma_f16 v79, v19, v79, v87 op_sel:[1,0,0]
	v_cvt_scalef32_pk_f16_fp4 v87, v72, 1.0 op_sel:[1,0,0]
	v_cvt_scalef32_pk_f16_fp4 v92, v72, 1.0 op_sel:[0,1,0]
	v_cvt_scalef32_pk_f16_fp4 v72, v72, 1.0 op_sel:[1,1,0]
	v_pk_fma_f16 v93, v19, v93, v102 op_sel_hi:[0,1,1]
	v_pk_fma_f16 v72, v19, v72, v80 op_sel:[1,0,0]
	v_cvt_scalef32_pk_f16_fp4 v80, v73, 1.0
	v_pk_fma_f16 v94, v19, v94, v103 op_sel_hi:[0,1,1]
	v_pk_fma_f16 v95, v19, v95, v105 op_sel_hi:[0,1,1]
	v_pk_fma_f16 v96, v19, v96, v104 op_sel_hi:[0,1,1]
	v_pk_fma_f16 v97, v19, v97, v110 op_sel_hi:[0,1,1]
	v_pk_fma_f16 v91, v19, v91, v93 op_sel:[1,0,0]
	v_pk_fma_f16 v80, v19, v80, v88 op_sel:[1,0,0]
	v_cvt_scalef32_pk_f16_fp4 v88, v73, 1.0 op_sel:[1,0,0]
	v_cvt_scalef32_pk_f16_fp4 v93, v73, 1.0 op_sel:[0,1,0]
	v_cvt_scalef32_pk_f16_fp4 v73, v73, 1.0 op_sel:[1,1,0]
	v_pk_fma_f16 v87, v19, v87, v94 op_sel:[1,0,0]
	v_pk_fma_f16 v92, v19, v92, v95 op_sel:[1,0,0]
	v_pk_fma_f16 v88, v19, v88, v96 op_sel:[1,0,0]
	v_pk_fma_f16 v93, v19, v93, v97 op_sel:[1,0,0]
	v_pk_fma_f16 v18, v19, v73, v18 op_sel:[1,0,0]
	s_waitcnt vmcnt(28)
	v_cvt_scalef32_pk_f16_fp4 v19, v58, 1.0
	v_pk_fma_f16 v19, v20, v19, v81 op_sel_hi:[0,1,1]
	v_cvt_scalef32_pk_f16_fp4 v73, v58, 1.0 op_sel:[1,0,0]
	v_cvt_scalef32_pk_f16_fp4 v81, v58, 1.0 op_sel:[0,1,0]
	v_cvt_scalef32_pk_f16_fp4 v58, v58, 1.0 op_sel:[1,1,0]
	v_pk_fma_f16 v58, v20, v58, v70 op_sel_hi:[0,1,1]
	v_cvt_scalef32_pk_f16_fp4 v70, v59, 1.0
	v_pk_fma_f16 v70, v20, v70, v78 op_sel_hi:[0,1,1]
	v_cvt_scalef32_pk_f16_fp4 v78, v59, 1.0 op_sel:[1,0,0]
	v_pk_fma_f16 v78, v20, v78, v86 op_sel_hi:[0,1,1]
	v_cvt_scalef32_pk_f16_fp4 v86, v59, 1.0 op_sel:[0,1,0]
	v_cvt_scalef32_pk_f16_fp4 v59, v59, 1.0 op_sel:[1,1,0]
	v_pk_fma_f16 v59, v20, v59, v71 op_sel_hi:[0,1,1]
	v_cvt_scalef32_pk_f16_fp4 v71, v60, 1.0
	v_pk_fma_f16 v71, v20, v71, v79 op_sel_hi:[0,1,1]
	v_cvt_scalef32_pk_f16_fp4 v79, v60, 1.0 op_sel:[1,0,0]
	v_pk_fma_f16 v79, v20, v79, v87 op_sel_hi:[0,1,1]
	v_cvt_scalef32_pk_f16_fp4 v87, v60, 1.0 op_sel:[0,1,0]
	v_cvt_scalef32_pk_f16_fp4 v60, v60, 1.0 op_sel:[1,1,0]
	v_pk_fma_f16 v60, v20, v60, v72 op_sel_hi:[0,1,1]
	v_cvt_scalef32_pk_f16_fp4 v72, v61, 1.0
	v_pk_fma_f16 v72, v20, v72, v80 op_sel_hi:[0,1,1]
	v_cvt_scalef32_pk_f16_fp4 v80, v61, 1.0 op_sel:[1,0,0]
	v_pk_fma_f16 v80, v20, v80, v88 op_sel_hi:[0,1,1]
	v_cvt_scalef32_pk_f16_fp4 v88, v61, 1.0 op_sel:[0,1,0]
	v_cvt_scalef32_pk_f16_fp4 v61, v61, 1.0 op_sel:[1,1,0]
	v_pk_fma_f16 v18, v20, v61, v18 op_sel_hi:[0,1,1]
	s_waitcnt vmcnt(27)
	v_cvt_scalef32_pk_f16_fp4 v61, v50, 1.0
	v_pk_fma_f16 v73, v20, v73, v89 op_sel_hi:[0,1,1]
	v_pk_fma_f16 v19, v20, v61, v19 op_sel:[1,0,0]
	v_cvt_scalef32_pk_f16_fp4 v61, v50, 1.0 op_sel:[1,0,0]
	v_pk_fma_f16 v61, v20, v61, v73 op_sel:[1,0,0]
	v_cvt_scalef32_pk_f16_fp4 v73, v50, 1.0 op_sel:[0,1,0]
	v_cvt_scalef32_pk_f16_fp4 v50, v50, 1.0 op_sel:[1,1,0]
	v_pk_fma_f16 v50, v20, v50, v58 op_sel:[1,0,0]
	v_cvt_scalef32_pk_f16_fp4 v58, v51, 1.0
	v_pk_fma_f16 v58, v20, v58, v70 op_sel:[1,0,0]
	v_cvt_scalef32_pk_f16_fp4 v70, v51, 1.0 op_sel:[1,0,0]
	v_pk_fma_f16 v70, v20, v70, v78 op_sel:[1,0,0]
	v_cvt_scalef32_pk_f16_fp4 v78, v51, 1.0 op_sel:[0,1,0]
	v_cvt_scalef32_pk_f16_fp4 v51, v51, 1.0 op_sel:[1,1,0]
	v_pk_fma_f16 v51, v20, v51, v59 op_sel:[1,0,0]
	v_cvt_scalef32_pk_f16_fp4 v59, v52, 1.0
	v_pk_fma_f16 v59, v20, v59, v71 op_sel:[1,0,0]
	v_cvt_scalef32_pk_f16_fp4 v71, v52, 1.0 op_sel:[1,0,0]
	v_pk_fma_f16 v71, v20, v71, v79 op_sel:[1,0,0]
	v_cvt_scalef32_pk_f16_fp4 v79, v52, 1.0 op_sel:[0,1,0]
	v_cvt_scalef32_pk_f16_fp4 v52, v52, 1.0 op_sel:[1,1,0]
	v_pk_fma_f16 v52, v20, v52, v60 op_sel:[1,0,0]
	v_cvt_scalef32_pk_f16_fp4 v60, v53, 1.0
	v_pk_fma_f16 v60, v20, v60, v72 op_sel:[1,0,0]
	v_cvt_scalef32_pk_f16_fp4 v72, v53, 1.0 op_sel:[1,0,0]
	v_pk_fma_f16 v81, v20, v81, v90 op_sel_hi:[0,1,1]
	v_pk_fma_f16 v86, v20, v86, v91 op_sel_hi:[0,1,1]
	v_pk_fma_f16 v87, v20, v87, v92 op_sel_hi:[0,1,1]
	v_pk_fma_f16 v88, v20, v88, v93 op_sel_hi:[0,1,1]
	v_pk_fma_f16 v72, v20, v72, v80 op_sel:[1,0,0]
	v_cvt_scalef32_pk_f16_fp4 v80, v53, 1.0 op_sel:[0,1,0]
	v_cvt_scalef32_pk_f16_fp4 v53, v53, 1.0 op_sel:[1,1,0]
	v_pk_fma_f16 v73, v20, v73, v81 op_sel:[1,0,0]
	v_pk_fma_f16 v78, v20, v78, v86 op_sel:[1,0,0]
	v_pk_fma_f16 v79, v20, v79, v87 op_sel:[1,0,0]
	v_pk_fma_f16 v80, v20, v80, v88 op_sel:[1,0,0]
	v_pk_fma_f16 v18, v20, v53, v18 op_sel:[1,0,0]
	s_waitcnt vmcnt(26)
	v_cvt_scalef32_pk_f16_fp4 v20, v38, 1.0
	v_pk_fma_f16 v19, v21, v20, v19 op_sel_hi:[0,1,1]
	v_cvt_scalef32_pk_f16_fp4 v20, v38, 1.0 op_sel:[1,0,0]
	v_cvt_scalef32_pk_f16_fp4 v53, v38, 1.0 op_sel:[0,1,0]
	v_cvt_scalef32_pk_f16_fp4 v38, v38, 1.0 op_sel:[1,1,0]
	v_pk_fma_f16 v38, v21, v38, v50 op_sel_hi:[0,1,1]
	v_cvt_scalef32_pk_f16_fp4 v50, v39, 1.0
	v_pk_fma_f16 v20, v21, v20, v61 op_sel_hi:[0,1,1]
	v_pk_fma_f16 v50, v21, v50, v58 op_sel_hi:[0,1,1]
	v_cvt_scalef32_pk_f16_fp4 v58, v39, 1.0 op_sel:[1,0,0]
	v_cvt_scalef32_pk_f16_fp4 v61, v39, 1.0 op_sel:[0,1,0]
	v_cvt_scalef32_pk_f16_fp4 v39, v39, 1.0 op_sel:[1,1,0]
	v_pk_fma_f16 v39, v21, v39, v51 op_sel_hi:[0,1,1]
	v_cvt_scalef32_pk_f16_fp4 v51, v40, 1.0
	v_pk_fma_f16 v58, v21, v58, v70 op_sel_hi:[0,1,1]
	v_pk_fma_f16 v51, v21, v51, v59 op_sel_hi:[0,1,1]
	v_cvt_scalef32_pk_f16_fp4 v59, v40, 1.0 op_sel:[1,0,0]
	v_cvt_scalef32_pk_f16_fp4 v70, v40, 1.0 op_sel:[0,1,0]
	v_cvt_scalef32_pk_f16_fp4 v40, v40, 1.0 op_sel:[1,1,0]
	v_pk_fma_f16 v40, v21, v40, v52 op_sel_hi:[0,1,1]
	v_cvt_scalef32_pk_f16_fp4 v52, v41, 1.0
	v_pk_fma_f16 v59, v21, v59, v71 op_sel_hi:[0,1,1]
	v_pk_fma_f16 v52, v21, v52, v60 op_sel_hi:[0,1,1]
	v_cvt_scalef32_pk_f16_fp4 v60, v41, 1.0 op_sel:[1,0,0]
	v_cvt_scalef32_pk_f16_fp4 v71, v41, 1.0 op_sel:[0,1,0]
	v_cvt_scalef32_pk_f16_fp4 v41, v41, 1.0 op_sel:[1,1,0]
	v_pk_fma_f16 v18, v21, v41, v18 op_sel_hi:[0,1,1]
	s_waitcnt vmcnt(25)
	v_cvt_scalef32_pk_f16_fp4 v41, v30, 1.0
	v_pk_fma_f16 v19, v21, v41, v19 op_sel:[1,0,0]
	v_cvt_scalef32_pk_f16_fp4 v41, v30, 1.0 op_sel:[1,0,0]
	v_pk_fma_f16 v20, v21, v41, v20 op_sel:[1,0,0]
	v_cvt_scalef32_pk_f16_fp4 v41, v30, 1.0 op_sel:[0,1,0]
	v_cvt_scalef32_pk_f16_fp4 v30, v30, 1.0 op_sel:[1,1,0]
	v_pk_fma_f16 v53, v21, v53, v73 op_sel_hi:[0,1,1]
	v_pk_fma_f16 v30, v21, v30, v38 op_sel:[1,0,0]
	v_cvt_scalef32_pk_f16_fp4 v38, v31, 1.0
	v_pk_fma_f16 v41, v21, v41, v53 op_sel:[1,0,0]
	v_pk_fma_f16 v38, v21, v38, v50 op_sel:[1,0,0]
	v_cvt_scalef32_pk_f16_fp4 v50, v31, 1.0 op_sel:[1,0,0]
	v_cvt_scalef32_pk_f16_fp4 v53, v31, 1.0 op_sel:[0,1,0]
	v_cvt_scalef32_pk_f16_fp4 v31, v31, 1.0 op_sel:[1,1,0]
	v_pk_fma_f16 v31, v21, v31, v39 op_sel:[1,0,0]
	v_cvt_scalef32_pk_f16_fp4 v39, v32, 1.0
	v_pk_fma_f16 v50, v21, v50, v58 op_sel:[1,0,0]
	v_pk_fma_f16 v39, v21, v39, v51 op_sel:[1,0,0]
	v_cvt_scalef32_pk_f16_fp4 v51, v32, 1.0 op_sel:[1,0,0]
	v_cvt_scalef32_pk_f16_fp4 v58, v32, 1.0 op_sel:[0,1,0]
	v_cvt_scalef32_pk_f16_fp4 v32, v32, 1.0 op_sel:[1,1,0]
	v_pk_fma_f16 v61, v21, v61, v78 op_sel_hi:[0,1,1]
	v_pk_fma_f16 v70, v21, v70, v79 op_sel_hi:[0,1,1]
	v_pk_fma_f16 v71, v21, v71, v80 op_sel_hi:[0,1,1]
	v_pk_fma_f16 v51, v21, v51, v59 op_sel:[1,0,0]
	v_pk_fma_f16 v32, v21, v32, v40 op_sel:[1,0,0]
	v_cvt_scalef32_pk_f16_fp4 v40, v33, 1.0
	v_cvt_scalef32_pk_f16_fp4 v59, v33, 1.0 op_sel:[0,1,0]
	v_pk_fma_f16 v53, v21, v53, v61 op_sel:[1,0,0]
	v_pk_fma_f16 v58, v21, v58, v70 op_sel:[1,0,0]
	v_pk_fma_f16 v40, v21, v40, v52 op_sel:[1,0,0]
	v_cvt_scalef32_pk_f16_fp4 v52, v33, 1.0 op_sel:[1,0,0]
	v_pk_fma_f16 v59, v21, v59, v71 op_sel:[1,0,0]
	v_cvt_scalef32_pk_f16_fp4 v33, v33, 1.0 op_sel:[1,1,0]
	v_pk_fma_f16 v60, v21, v60, v72 op_sel_hi:[0,1,1]
	v_pk_fma_f16 v18, v21, v33, v18 op_sel:[1,0,0]
	v_permlane32_swap_b32_e32 v19, v39
	v_permlane32_swap_b32_e32 v41, v58
	v_permlane32_swap_b32_e32 v30, v32
	v_permlane32_swap_b32_e32 v38, v40
	v_permlane32_swap_b32_e32 v53, v59
	v_pk_fma_f16 v52, v21, v52, v60 op_sel:[1,0,0]
	v_pk_add_f16 v19, v19, v39
	v_pk_add_f16 v21, v41, v58
	v_pk_add_f16 v30, v30, v32
	v_pk_add_f16 v32, v38, v40
	v_pk_add_f16 v38, v53, v59
	v_permlane32_swap_b32_e32 v31, v18
	v_permlane32_swap_b32_e32 v20, v51
	v_permlane32_swap_b32_e32 v50, v52
	v_pk_add_f16 v18, v31, v18
	v_permlane16_swap_b32_e32 v19, v32
	v_permlane16_swap_b32_e32 v21, v38
	v_pk_add_f16 v20, v20, v51
	v_pk_add_f16 v33, v50, v52
	v_pk_add_f16 v19, v19, v32
	v_pk_add_f16 v21, v21, v38
	v_permlane16_swap_b32_e32 v30, v18
	v_permlane16_swap_b32_e32 v20, v33
	v_pk_add_f16 v18, v30, v18
	v_cndmask_b32_e64 v30, v21, v19, s[10:11]
	v_cndmask_b32_e64 v19, v19, v21, s[10:11]
	v_pk_add_f16 v20, v20, v33
	v_cvt_f32_f16_e32 v32, v201
	v_mov_b32_dpp v19, v19 row_ror:8 row_mask:0xf bank_mask:0xf bound_ctrl:1
	v_pk_add_f16 v21, v30, v19
	v_cndmask_b32_e64 v30, v18, v20, s[10:11]
	v_cndmask_b32_e64 v18, v20, v18, s[10:11]
	v_cvt_f32_f16_sdwa v19, v200 dst_sel:DWORD dst_unused:UNUSED_PAD src0_sel:WORD_1
	v_cvt_f32_f16_e32 v20, v21
	v_mov_b32_dpp v31, v18 row_ror:8 row_mask:0xf bank_mask:0xf bound_ctrl:1
	v_cvt_f32_f16_e32 v18, v200
	v_cvt_f32_f16_sdwa v21, v21 dst_sel:DWORD dst_unused:UNUSED_PAD src0_sel:WORD_1
	v_pk_add_f16 v39, v30, v31
	v_cvt_f32_f16_e32 v30, v198
	v_cvt_f32_f16_sdwa v31, v198 dst_sel:DWORD dst_unused:UNUSED_PAD src0_sel:WORD_1
	v_cvt_f32_f16_sdwa v33, v201 dst_sel:DWORD dst_unused:UNUSED_PAD src0_sel:WORD_1
	v_cvt_f32_f16_e32 v38, v39
	v_cvt_f32_f16_sdwa v39, v39 dst_sel:DWORD dst_unused:UNUSED_PAD src0_sel:WORD_1
	v_pk_fma_f32 v[18:19], v[2:3], v[20:21], v[18:19]
	v_cvt_f32_f16_e32 v20, v199
	v_cvt_f32_f16_sdwa v21, v199 dst_sel:DWORD dst_unused:UNUSED_PAD src0_sel:WORD_1
	v_pk_add_f32 v[18:19], v[18:19], v[30:31]
	v_pk_fma_f32 v[30:31], v[4:5], v[38:39], v[32:33]
	v_cvt_pk_f16_f32 v18, v18, v19
	v_pk_add_f32 v[20:21], v[30:31], v[20:21]
	s_nop 0
	v_cvt_pk_f16_f32 v19, v20, v21
	global_store_dwordx2 v[196:197], v[18:19], off
	s_mov_b32 s30, s19
	s_cbranch_scc0 .LBB0_3109
	s_mov_b64 s[20:21], 0

.LBB0_4083:
	s_or_b64 exec, exec, s[0:1]
	s_mov_b64 s[0:1], 0
	s_mov_b64 s[2:3], 0
	s_waitcnt lgkmcnt(0)
	s_barrier
	s_mov_b64 s[2:3], 0
	s_mov_b64 s[12:13], 0
	s_mov_b64 s[6:7], 0
	s_mov_b64 s[2:3], 0
	s_add_u32 s0, s54, s0
	s_mov_b64 s[4:5], 0
	s_addc_u32 s1, s55, s1
	s_mov_b64 s[10:11], 0
	s_mov_b64 s[2:3], 0
	s_mov_b64 s[8:9], 0
	v_mov_b32_e32 v2, v0
	s_add_u32 s0, s0, 0x7800
	s_getreg_b32 s22, hwreg(HW_REG_XCC_ID, 0, 4)
	v_and_b32_e32 v3, 63, v2
	s_addc_u32 s1, s1, 0
	s_and_b32 s20, s22, 7
	v_mov_b32_e32 v202, 0
	v_cmp_eq_u32_e64 s[2:3], 0, v3
	s_and_saveexec_b64 s[14:15], s[2:3]
	s_cbranch_execz .LBB0_4087
	s_mov_b64 s[18:19], exec
	v_mbcnt_lo_u32_b32 v4, s18, 0
	v_mbcnt_hi_u32_b32 v4, s19, v4
	v_cmp_eq_u32_e32 vcc, 0, v4
	s_and_saveexec_b64 s[16:17], vcc
	s_cbranch_execz .LBB0_4086
	s_bcnt1_i32_b64 s18, s[18:19]
	s_lshl_b32 s21, s20, 8
	s_lshl_b32 s18, s18, 3
	v_mov_b32_e32 v5, s21
	v_mov_b32_e32 v6, s18
	global_atomic_add v5, v5, v6, s[0:1] sc0
.LBB0_4086:
	s_or_b64 exec, exec, s[16:17]
	s_waitcnt vmcnt(0)
	v_readfirstlane_b32 s16, v5
	s_nop 1
	v_lshl_add_u32 v202, v4, 3, s16
.LBB0_4087:
	s_or_b64 exec, exec, s[14:15]
	s_add_u32 s12, s54, s12
	s_addc_u32 s13, s55, s13
	s_add_u32 s14, s54, s6
	s_addc_u32 s15, s55, s7
	s_add_u32 s6, s54, s10
	s_addc_u32 s7, s55, s11
	s_add_u32 s6, s6, 0x3fd06000
	s_addc_u32 s7, s7, 0
	s_add_u32 s8, s54, s8
	s_addc_u32 s9, s55, s9
	s_add_u32 s8, s8, 0x4c618000
	s_addc_u32 s9, s9, 0
	s_add_u32 s4, s54, s4
	s_addc_u32 s5, s55, s5
	v_lshlrev_b32_e32 v203, 2, v3
	v_lshlrev_b32_e32 v4, 4, v3
	v_lshlrev_b32_e32 v3, 3, v3
	s_add_u32 s10, s4, 0x50e18000
	v_and_b32_e32 v182, 0x1c0, v3
	v_mov_b32_e32 v183, 0
	v_and_b32_e32 v3, 56, v2
	s_addc_u32 s11, s5, 0
	v_and_b32_e32 v204, 0x70, v4
	v_lshl_add_u64 v[4:5], s[12:13], 0, v[182:183]
	s_mov_b64 s[4:5], 0x2ade6000
	v_lshlrev_b32_e32 v182, 2, v3
	v_lshl_add_u64 v[184:185], v[4:5], 0, s[4:5]
	v_lshl_add_u64 v[4:5], s[14:15], 0, v[182:183]
	s_mov_b64 s[4:5], 0x4c198000
	v_and_b32_e32 v2, 8, v2
	v_lshl_add_u64 v[186:187], v[4:5], 0, s[4:5]
	s_mov_b32 s24, 0
	v_cmp_eq_u32_e64 s[4:5], 0, v2
	v_mov_b32_e32 v206, s20
	v_mov_b32_e32 v205, 8
	s_mov_b32 s23, 0xa000
	s_branch .LBB0_4090

.LBB0_4094:
	s_add_i32 s18, s12, s25
	s_add_i32 s13, s18, 2
	s_add_i32 s20, s18, 1
	s_add_i32 s15, s18, 3
	s_cmp_lt_u32 s25, 6
	s_cselect_b32 s14, s13, s18
	s_cselect_b32 s16, s15, s20
	s_ashr_i32 s15, s14, 31
	s_ashr_i32 s21, s20, 31
	s_ashr_i32 s19, s18, 31
	s_lshl_b64 s[26:27], s[14:15], 9
	s_lshl_b64 s[28:29], s[20:21], 8
	s_lshl_b64 s[14:15], s[18:19], 12
	s_add_i32 s13, s25, 1
	s_cmp_lt_u32 s13, 7
	s_cselect_b64 s[30:31], -1, 0
	s_ashr_i32 s17, s16, 31
	s_lshl_b64 s[16:17], s[16:17], 9
	s_cmp_lg_u64 s[30:31], 0
	s_addc_u32 s18, s18, 1
	s_lshl_b64 s[20:21], s[20:21], 12
	v_lshl_add_u64 v[22:23], v[184:185], 0, s[26:27]
	v_lshl_add_u64 v[30:31], v[186:187], 0, s[28:29]
	global_load_dwordx4 v[166:169], v[22:23], off offset:48
	global_load_dwordx4 v[170:173], v[22:23], off offset:32
	global_load_dwordx4 v[174:177], v[22:23], off offset:16
	global_load_dwordx4 v[178:181], v[22:23], off
	s_nop 0
	global_load_dwordx4 v[22:25], v[30:31], off offset:16
	global_load_dwordx4 v[94:97], v[30:31], off
	v_lshl_add_u64 v[196:197], v[190:191], 0, s[20:21]
	v_lshl_add_u64 v[30:31], v[192:193], 0, s[20:21]
	global_load_dwordx2 v[198:199], v[196:197], off
	global_load_dwordx2 v[200:201], v[30:31], off
	s_waitcnt vmcnt(29)
	v_lshl_add_u32 v30, v134, 7, v207
	v_lshl_add_u32 v31, v135, 7, v207
	global_load_dwordx4 v[162:165], v30, s[6:7]
	global_load_dwordx4 v[158:161], v31, s[6:7]
	v_lshl_add_u32 v30, v136, 7, v207
	v_lshl_add_u32 v31, v137, 7, v207
	global_load_dwordx4 v[154:157], v30, s[6:7]
	global_load_dwordx4 v[150:153], v31, s[6:7]
	v_lshl_add_u32 v30, v126, 7, v207
	v_lshl_add_u32 v31, v127, 7, v207
	global_load_dwordx4 v[146:149], v30, s[6:7]
	global_load_dwordx4 v[138:141], v31, s[6:7]
	v_lshl_add_u32 v30, v128, 7, v207
	v_lshl_add_u32 v31, v129, 7, v207
	global_load_dwordx4 v[122:125], v30, s[6:7]
	global_load_dwordx4 v[106:109], v31, s[6:7]
	v_lshl_add_u32 v30, v118, 7, v207
	v_lshl_add_u32 v31, v119, 7, v207
	global_load_dwordx4 v[98:101], v30, s[6:7]
	global_load_dwordx4 v[86:89], v31, s[6:7]
	v_lshl_add_u32 v30, v120, 7, v207
	v_lshl_add_u32 v31, v121, 7, v207
	global_load_dwordx4 v[78:81], v30, s[6:7]
	global_load_dwordx4 v[70:73], v31, s[6:7]
	s_waitcnt vmcnt(40)
	v_lshl_add_u32 v30, v114, 7, v207
	v_lshl_add_u32 v31, v115, 7, v207
	global_load_dwordx4 v[58:61], v30, s[6:7]
	global_load_dwordx4 v[50:53], v31, s[6:7]
	v_lshl_add_u32 v30, v116, 7, v207
	v_lshl_add_u32 v31, v117, 7, v207
	global_load_dwordx4 v[42:45], v30, s[6:7]
	s_nop 0
	global_load_dwordx4 v[30:33], v31, s[6:7]
	s_ashr_i32 s19, s18, 31
	s_lshl_b64 s[20:21], s[18:19], 8
	s_lshl_b64 s[18:19], s[18:19], 12
	s_add_i32 s13, s25, 2
	s_cmp_gt_u32 s25, 5
	s_waitcnt vmcnt(36)
	v_cvt_scalef32_pk_f16_fp4 v114, v142, 1.0
	v_pk_fma_f16 v114, v38, v114, 0 op_sel_hi:[0,1,1]
	v_cvt_scalef32_pk_f16_fp4 v115, v142, 1.0 op_sel:[1,0,0]
	v_cvt_scalef32_pk_f16_fp4 v116, v142, 1.0 op_sel:[0,1,0]
	v_cvt_scalef32_pk_f16_fp4 v117, v142, 1.0 op_sel:[1,1,0]
	s_waitcnt vmcnt(35)
	v_cvt_scalef32_pk_f16_fp4 v142, v130, 1.0
	v_pk_fma_f16 v115, v38, v115, 0 op_sel_hi:[0,1,1]
	v_pk_fma_f16 v114, v38, v142, v114 op_sel:[1,0,0]
	v_cvt_scalef32_pk_f16_fp4 v142, v130, 1.0 op_sel:[1,0,0]
	v_pk_fma_f16 v117, v38, v117, 0 op_sel_hi:[0,1,1]
	v_cvt_scalef32_pk_f16_fp4 v118, v143, 1.0
	v_pk_fma_f16 v115, v38, v142, v115 op_sel:[1,0,0]
	v_cvt_scalef32_pk_f16_fp4 v142, v130, 1.0 op_sel:[0,1,0]
	v_cvt_scalef32_pk_f16_fp4 v130, v130, 1.0 op_sel:[1,1,0]
	v_pk_fma_f16 v118, v38, v118, 0 op_sel_hi:[0,1,1]
	v_cvt_scalef32_pk_f16_fp4 v119, v143, 1.0 op_sel:[1,0,0]
	v_pk_fma_f16 v117, v38, v130, v117 op_sel:[1,0,0]
	v_cvt_scalef32_pk_f16_fp4 v130, v131, 1.0
	v_pk_fma_f16 v119, v38, v119, 0 op_sel_hi:[0,1,1]
	v_cvt_scalef32_pk_f16_fp4 v120, v143, 1.0 op_sel:[0,1,0]
	v_pk_fma_f16 v118, v38, v130, v118 op_sel:[1,0,0]
	v_cvt_scalef32_pk_f16_fp4 v130, v131, 1.0 op_sel:[1,0,0]
	v_pk_fma_f16 v120, v38, v120, 0 op_sel_hi:[0,1,1]
	v_cvt_scalef32_pk_f16_fp4 v121, v143, 1.0 op_sel:[1,1,0]
	v_pk_fma_f16 v119, v38, v130, v119 op_sel:[1,0,0]
	v_cvt_scalef32_pk_f16_fp4 v130, v131, 1.0 op_sel:[0,1,0]
	v_pk_fma_f16 v121, v38, v121, 0 op_sel_hi:[0,1,1]
	v_cvt_scalef32_pk_f16_fp4 v126, v144, 1.0
	v_pk_fma_f16 v120, v38, v130, v120 op_sel:[1,0,0]
	v_cvt_scalef32_pk_f16_fp4 v130, v131, 1.0 op_sel:[1,1,0]
	v_pk_fma_f16 v126, v38, v126, 0 op_sel_hi:[0,1,1]
	v_cvt_scalef32_pk_f16_fp4 v127, v144, 1.0 op_sel:[1,0,0]
	v_pk_fma_f16 v121, v38, v130, v121 op_sel:[1,0,0]
	v_cvt_scalef32_pk_f16_fp4 v130, v132, 1.0
	v_pk_fma_f16 v127, v38, v127, 0 op_sel_hi:[0,1,1]
	v_cvt_scalef32_pk_f16_fp4 v128, v144, 1.0 op_sel:[0,1,0]
	v_pk_fma_f16 v126, v38, v130, v126 op_sel:[1,0,0]
	v_cvt_scalef32_pk_f16_fp4 v130, v132, 1.0 op_sel:[1,0,0]
	v_pk_fma_f16 v128, v38, v128, 0 op_sel_hi:[0,1,1]
	v_cvt_scalef32_pk_f16_fp4 v129, v144, 1.0 op_sel:[1,1,0]
	v_pk_fma_f16 v127, v38, v130, v127 op_sel:[1,0,0]
	v_cvt_scalef32_pk_f16_fp4 v130, v132, 1.0 op_sel:[0,1,0]
	v_pk_fma_f16 v129, v38, v129, 0 op_sel_hi:[0,1,1]
	v_cvt_scalef32_pk_f16_fp4 v134, v145, 1.0
	v_cvt_scalef32_pk_f16_fp4 v135, v145, 1.0 op_sel:[1,0,0]
	v_cvt_scalef32_pk_f16_fp4 v136, v145, 1.0 op_sel:[0,1,0]
	v_cvt_scalef32_pk_f16_fp4 v137, v145, 1.0 op_sel:[1,1,0]
	v_pk_fma_f16 v128, v38, v130, v128 op_sel:[1,0,0]
	v_cvt_scalef32_pk_f16_fp4 v130, v132, 1.0 op_sel:[1,1,0]
	v_pk_fma_f16 v116, v38, v116, 0 op_sel_hi:[0,1,1]
	v_pk_fma_f16 v134, v38, v134, 0 op_sel_hi:[0,1,1]
	v_pk_fma_f16 v135, v38, v135, 0 op_sel_hi:[0,1,1]
	v_pk_fma_f16 v136, v38, v136, 0 op_sel_hi:[0,1,1]
	v_pk_fma_f16 v137, v38, v137, 0 op_sel_hi:[0,1,1]
	v_pk_fma_f16 v129, v38, v130, v129 op_sel:[1,0,0]
	v_cvt_scalef32_pk_f16_fp4 v130, v133, 1.0
	v_cvt_scalef32_pk_f16_fp4 v131, v133, 1.0 op_sel:[1,0,0]
	v_cvt_scalef32_pk_f16_fp4 v132, v133, 1.0 op_sel:[0,1,0]
	v_cvt_scalef32_pk_f16_fp4 v133, v133, 1.0 op_sel:[1,1,0]
	v_pk_fma_f16 v116, v38, v142, v116 op_sel:[1,0,0]
	v_pk_fma_f16 v130, v38, v130, v134 op_sel:[1,0,0]
	v_pk_fma_f16 v131, v38, v131, v135 op_sel:[1,0,0]
	v_pk_fma_f16 v132, v38, v132, v136 op_sel:[1,0,0]
	v_pk_fma_f16 v38, v38, v133, v137 op_sel:[1,0,0]
	s_waitcnt vmcnt(34)
	v_cvt_scalef32_pk_f16_fp4 v133, v110, 1.0
	v_pk_fma_f16 v114, v39, v133, v114 op_sel_hi:[0,1,1]
	v_cvt_scalef32_pk_f16_fp4 v133, v110, 1.0 op_sel:[1,0,0]
	v_pk_fma_f16 v115, v39, v133, v115 op_sel_hi:[0,1,1]
	v_cvt_scalef32_pk_f16_fp4 v133, v110, 1.0 op_sel:[0,1,0]
	v_cvt_scalef32_pk_f16_fp4 v110, v110, 1.0 op_sel:[1,1,0]
	v_pk_fma_f16 v110, v39, v110, v117 op_sel_hi:[0,1,1]
	v_cvt_scalef32_pk_f16_fp4 v117, v111, 1.0
	v_pk_fma_f16 v117, v39, v117, v118 op_sel_hi:[0,1,1]
	v_cvt_scalef32_pk_f16_fp4 v118, v111, 1.0 op_sel:[1,0,0]
	v_pk_fma_f16 v118, v39, v118, v119 op_sel_hi:[0,1,1]
	v_cvt_scalef32_pk_f16_fp4 v119, v111, 1.0 op_sel:[0,1,0]
	v_pk_fma_f16 v119, v39, v119, v120 op_sel_hi:[0,1,1]
	v_cvt_scalef32_pk_f16_fp4 v111, v111, 1.0 op_sel:[1,1,0]
	v_cvt_scalef32_pk_f16_fp4 v120, v112, 1.0
	v_pk_fma_f16 v111, v39, v111, v121 op_sel_hi:[0,1,1]
	v_pk_fma_f16 v120, v39, v120, v126 op_sel_hi:[0,1,1]
	v_cvt_scalef32_pk_f16_fp4 v121, v112, 1.0 op_sel:[1,0,0]
	v_cvt_scalef32_pk_f16_fp4 v126, v112, 1.0 op_sel:[0,1,0]
	v_cvt_scalef32_pk_f16_fp4 v112, v112, 1.0 op_sel:[1,1,0]
	v_pk_fma_f16 v121, v39, v121, v127 op_sel_hi:[0,1,1]
	v_pk_fma_f16 v126, v39, v126, v128 op_sel_hi:[0,1,1]
	v_pk_fma_f16 v112, v39, v112, v129 op_sel_hi:[0,1,1]
	v_cvt_scalef32_pk_f16_fp4 v127, v113, 1.0
	v_cvt_scalef32_pk_f16_fp4 v128, v113, 1.0 op_sel:[1,0,0]
	v_cvt_scalef32_pk_f16_fp4 v129, v113, 1.0 op_sel:[0,1,0]
	v_cvt_scalef32_pk_f16_fp4 v113, v113, 1.0 op_sel:[1,1,0]
	v_pk_fma_f16 v38, v39, v113, v38 op_sel_hi:[0,1,1]
	s_waitcnt vmcnt(33)
	v_cvt_scalef32_pk_f16_fp4 v113, v102, 1.0
	v_pk_fma_f16 v113, v39, v113, v114 op_sel:[1,0,0]
	v_cvt_scalef32_pk_f16_fp4 v114, v102, 1.0 op_sel:[1,0,0]
	v_pk_fma_f16 v114, v39, v114, v115 op_sel:[1,0,0]
	v_cvt_scalef32_pk_f16_fp4 v115, v102, 1.0 op_sel:[0,1,0]
	v_cvt_scalef32_pk_f16_fp4 v102, v102, 1.0 op_sel:[1,1,0]
	v_pk_fma_f16 v116, v39, v133, v116 op_sel_hi:[0,1,1]
	v_pk_fma_f16 v102, v39, v102, v110 op_sel:[1,0,0]
	v_cvt_scalef32_pk_f16_fp4 v110, v103, 1.0
	v_pk_fma_f16 v115, v39, v115, v116 op_sel:[1,0,0]
	v_pk_fma_f16 v110, v39, v110, v117 op_sel:[1,0,0]
	v_cvt_scalef32_pk_f16_fp4 v116, v103, 1.0 op_sel:[1,0,0]
	v_cvt_scalef32_pk_f16_fp4 v117, v103, 1.0 op_sel:[0,1,0]
	v_cvt_scalef32_pk_f16_fp4 v103, v103, 1.0 op_sel:[1,1,0]
	v_pk_fma_f16 v116, v39, v116, v118 op_sel:[1,0,0]
	v_pk_fma_f16 v117, v39, v117, v119 op_sel:[1,0,0]
	v_pk_fma_f16 v103, v39, v103, v111 op_sel:[1,0,0]
	v_cvt_scalef32_pk_f16_fp4 v111, v104, 1.0
	v_cvt_scalef32_pk_f16_fp4 v118, v104, 1.0 op_sel:[1,0,0]
	v_cvt_scalef32_pk_f16_fp4 v119, v104, 1.0 op_sel:[0,1,0]
	v_cvt_scalef32_pk_f16_fp4 v104, v104, 1.0 op_sel:[1,1,0]
	v_pk_fma_f16 v127, v39, v127, v130 op_sel_hi:[0,1,1]
	v_pk_fma_f16 v128, v39, v128, v131 op_sel_hi:[0,1,1]
	v_pk_fma_f16 v129, v39, v129, v132 op_sel_hi:[0,1,1]
	v_pk_fma_f16 v111, v39, v111, v120 op_sel:[1,0,0]
	v_pk_fma_f16 v118, v39, v118, v121 op_sel:[1,0,0]
	v_pk_fma_f16 v104, v39, v104, v112 op_sel:[1,0,0]
	v_cvt_scalef32_pk_f16_fp4 v112, v105, 1.0
	v_cvt_scalef32_pk_f16_fp4 v120, v105, 1.0 op_sel:[1,0,0]
	v_cvt_scalef32_pk_f16_fp4 v121, v105, 1.0 op_sel:[0,1,0]
	v_cvt_scalef32_pk_f16_fp4 v105, v105, 1.0 op_sel:[1,1,0]
	v_pk_fma_f16 v119, v39, v119, v126 op_sel:[1,0,0]
	v_pk_fma_f16 v112, v39, v112, v127 op_sel:[1,0,0]
	v_pk_fma_f16 v120, v39, v120, v128 op_sel:[1,0,0]
	v_pk_fma_f16 v121, v39, v121, v129 op_sel:[1,0,0]
	v_pk_fma_f16 v38, v39, v105, v38 op_sel:[1,0,0]
	s_waitcnt vmcnt(32)
	v_cvt_scalef32_pk_f16_fp4 v39, v90, 1.0
	v_pk_fma_f16 v39, v40, v39, v113 op_sel_hi:[0,1,1]
	v_cvt_scalef32_pk_f16_fp4 v105, v90, 1.0 op_sel:[1,0,0]
	v_cvt_scalef32_pk_f16_fp4 v113, v90, 1.0 op_sel:[0,1,0]
	v_cvt_scalef32_pk_f16_fp4 v90, v90, 1.0 op_sel:[1,1,0]
	v_pk_fma_f16 v90, v40, v90, v102 op_sel_hi:[0,1,1]
	v_cvt_scalef32_pk_f16_fp4 v102, v91, 1.0
	v_pk_fma_f16 v105, v40, v105, v114 op_sel_hi:[0,1,1]
	v_pk_fma_f16 v102, v40, v102, v110 op_sel_hi:[0,1,1]
	v_cvt_scalef32_pk_f16_fp4 v110, v91, 1.0 op_sel:[1,0,0]
	v_cvt_scalef32_pk_f16_fp4 v114, v91, 1.0 op_sel:[0,1,0]
	v_cvt_scalef32_pk_f16_fp4 v91, v91, 1.0 op_sel:[1,1,0]
	v_pk_fma_f16 v91, v40, v91, v103 op_sel_hi:[0,1,1]
	v_cvt_scalef32_pk_f16_fp4 v103, v92, 1.0
	v_pk_fma_f16 v113, v40, v113, v115 op_sel_hi:[0,1,1]
	v_pk_fma_f16 v103, v40, v103, v111 op_sel_hi:[0,1,1]
	v_cvt_scalef32_pk_f16_fp4 v111, v92, 1.0 op_sel:[1,0,0]
	v_cvt_scalef32_pk_f16_fp4 v115, v92, 1.0 op_sel:[0,1,0]
	v_cvt_scalef32_pk_f16_fp4 v92, v92, 1.0 op_sel:[1,1,0]
	v_pk_fma_f16 v92, v40, v92, v104 op_sel_hi:[0,1,1]
	v_cvt_scalef32_pk_f16_fp4 v104, v93, 1.0
	v_pk_fma_f16 v110, v40, v110, v116 op_sel_hi:[0,1,1]
	v_pk_fma_f16 v104, v40, v104, v112 op_sel_hi:[0,1,1]
	v_cvt_scalef32_pk_f16_fp4 v112, v93, 1.0 op_sel:[1,0,0]
	v_cvt_scalef32_pk_f16_fp4 v116, v93, 1.0 op_sel:[0,1,0]
	v_cvt_scalef32_pk_f16_fp4 v93, v93, 1.0 op_sel:[1,1,0]
	v_pk_fma_f16 v38, v40, v93, v38 op_sel_hi:[0,1,1]
	v_cvt_scalef32_pk_f16_fp4 v93, v82, 1.0
	v_pk_fma_f16 v39, v40, v93, v39 op_sel:[1,0,0]
	v_cvt_scalef32_pk_f16_fp4 v93, v82, 1.0 op_sel:[1,0,0]
	v_pk_fma_f16 v93, v40, v93, v105 op_sel:[1,0,0]
	v_cvt_scalef32_pk_f16_fp4 v105, v82, 1.0 op_sel:[0,1,0]
	v_cvt_scalef32_pk_f16_fp4 v82, v82, 1.0 op_sel:[1,1,0]
	v_pk_fma_f16 v82, v40, v82, v90 op_sel:[1,0,0]
	v_cvt_scalef32_pk_f16_fp4 v90, v83, 1.0
	v_pk_fma_f16 v90, v40, v90, v102 op_sel:[1,0,0]
	v_cvt_scalef32_pk_f16_fp4 v102, v83, 1.0 op_sel:[1,0,0]
	v_pk_fma_f16 v102, v40, v102, v110 op_sel:[1,0,0]
	v_cvt_scalef32_pk_f16_fp4 v110, v83, 1.0 op_sel:[0,1,0]
	v_cvt_scalef32_pk_f16_fp4 v83, v83, 1.0 op_sel:[1,1,0]
	v_pk_fma_f16 v83, v40, v83, v91 op_sel:[1,0,0]
	v_cvt_scalef32_pk_f16_fp4 v91, v84, 1.0
	v_pk_fma_f16 v111, v40, v111, v118 op_sel_hi:[0,1,1]
	v_pk_fma_f16 v91, v40, v91, v103 op_sel:[1,0,0]
	v_cvt_scalef32_pk_f16_fp4 v103, v84, 1.0 op_sel:[1,0,0]
	v_pk_fma_f16 v103, v40, v103, v111 op_sel:[1,0,0]
	v_cvt_scalef32_pk_f16_fp4 v111, v84, 1.0 op_sel:[0,1,0]
	v_cvt_scalef32_pk_f16_fp4 v84, v84, 1.0 op_sel:[1,1,0]
	v_pk_fma_f16 v84, v40, v84, v92 op_sel:[1,0,0]
	v_cvt_scalef32_pk_f16_fp4 v92, v85, 1.0
	v_pk_fma_f16 v112, v40, v112, v120 op_sel_hi:[0,1,1]
	v_pk_fma_f16 v92, v40, v92, v104 op_sel:[1,0,0]
	v_cvt_scalef32_pk_f16_fp4 v104, v85, 1.0 op_sel:[1,0,0]
	v_pk_fma_f16 v114, v40, v114, v117 op_sel_hi:[0,1,1]
	v_pk_fma_f16 v115, v40, v115, v119 op_sel_hi:[0,1,1]
	v_pk_fma_f16 v116, v40, v116, v121 op_sel_hi:[0,1,1]
	v_pk_fma_f16 v104, v40, v104, v112 op_sel:[1,0,0]
	v_cvt_scalef32_pk_f16_fp4 v112, v85, 1.0 op_sel:[0,1,0]
	v_cvt_scalef32_pk_f16_fp4 v85, v85, 1.0 op_sel:[1,1,0]
	v_pk_fma_f16 v105, v40, v105, v113 op_sel:[1,0,0]
	v_pk_fma_f16 v110, v40, v110, v114 op_sel:[1,0,0]
	v_pk_fma_f16 v111, v40, v111, v115 op_sel:[1,0,0]
	v_pk_fma_f16 v112, v40, v112, v116 op_sel:[1,0,0]
	v_pk_fma_f16 v38, v40, v85, v38 op_sel:[1,0,0]
	v_cvt_scalef32_pk_f16_fp4 v40, v74, 1.0
	v_pk_fma_f16 v39, v41, v40, v39 op_sel_hi:[0,1,1]
	v_cvt_scalef32_pk_f16_fp4 v40, v74, 1.0 op_sel:[1,0,0]
	v_cvt_scalef32_pk_f16_fp4 v85, v74, 1.0 op_sel:[0,1,0]
	v_cvt_scalef32_pk_f16_fp4 v74, v74, 1.0 op_sel:[1,1,0]
	v_pk_fma_f16 v74, v41, v74, v82 op_sel_hi:[0,1,1]
	v_cvt_scalef32_pk_f16_fp4 v82, v75, 1.0
	v_pk_fma_f16 v40, v41, v40, v93 op_sel_hi:[0,1,1]
	v_pk_fma_f16 v82, v41, v82, v90 op_sel_hi:[0,1,1]
	v_cvt_scalef32_pk_f16_fp4 v90, v75, 1.0 op_sel:[1,0,0]
	v_cvt_scalef32_pk_f16_fp4 v93, v75, 1.0 op_sel:[0,1,0]
	v_cvt_scalef32_pk_f16_fp4 v75, v75, 1.0 op_sel:[1,1,0]
	v_pk_fma_f16 v75, v41, v75, v83 op_sel_hi:[0,1,1]
	v_cvt_scalef32_pk_f16_fp4 v83, v76, 1.0
	v_pk_fma_f16 v90, v41, v90, v102 op_sel_hi:[0,1,1]
	v_pk_fma_f16 v83, v41, v83, v91 op_sel_hi:[0,1,1]
	v_cvt_scalef32_pk_f16_fp4 v91, v76, 1.0 op_sel:[1,0,0]
	v_cvt_scalef32_pk_f16_fp4 v102, v76, 1.0 op_sel:[0,1,0]
	v_cvt_scalef32_pk_f16_fp4 v76, v76, 1.0 op_sel:[1,1,0]
	v_pk_fma_f16 v76, v41, v76, v84 op_sel_hi:[0,1,1]
	v_cvt_scalef32_pk_f16_fp4 v84, v77, 1.0
	v_pk_fma_f16 v91, v41, v91, v103 op_sel_hi:[0,1,1]
	v_pk_fma_f16 v84, v41, v84, v92 op_sel_hi:[0,1,1]
	v_cvt_scalef32_pk_f16_fp4 v92, v77, 1.0 op_sel:[1,0,0]
	v_cvt_scalef32_pk_f16_fp4 v103, v77, 1.0 op_sel:[0,1,0]
	v_cvt_scalef32_pk_f16_fp4 v77, v77, 1.0 op_sel:[1,1,0]
	v_pk_fma_f16 v38, v41, v77, v38 op_sel_hi:[0,1,1]
	v_cvt_scalef32_pk_f16_fp4 v77, v66, 1.0
	v_pk_fma_f16 v39, v41, v77, v39 op_sel:[1,0,0]
	v_cvt_scalef32_pk_f16_fp4 v77, v66, 1.0 op_sel:[1,0,0]
	v_pk_fma_f16 v40, v41, v77, v40 op_sel:[1,0,0]
	v_cvt_scalef32_pk_f16_fp4 v77, v66, 1.0 op_sel:[0,1,0]
	v_cvt_scalef32_pk_f16_fp4 v66, v66, 1.0 op_sel:[1,1,0]
	v_pk_fma_f16 v85, v41, v85, v105 op_sel_hi:[0,1,1]
	v_pk_fma_f16 v66, v41, v66, v74 op_sel:[1,0,0]
	v_cvt_scalef32_pk_f16_fp4 v74, v67, 1.0
	v_pk_fma_f16 v77, v41, v77, v85 op_sel:[1,0,0]
	v_pk_fma_f16 v74, v41, v74, v82 op_sel:[1,0,0]
	v_cvt_scalef32_pk_f16_fp4 v82, v67, 1.0 op_sel:[1,0,0]
	v_cvt_scalef32_pk_f16_fp4 v85, v67, 1.0 op_sel:[0,1,0]
	v_cvt_scalef32_pk_f16_fp4 v67, v67, 1.0 op_sel:[1,1,0]
	v_pk_fma_f16 v67, v41, v67, v75 op_sel:[1,0,0]
	v_cvt_scalef32_pk_f16_fp4 v75, v68, 1.0
	v_pk_fma_f16 v82, v41, v82, v90 op_sel:[1,0,0]
	v_pk_fma_f16 v75, v41, v75, v83 op_sel:[1,0,0]
	v_cvt_scalef32_pk_f16_fp4 v83, v68, 1.0 op_sel:[1,0,0]
	v_cvt_scalef32_pk_f16_fp4 v90, v68, 1.0 op_sel:[0,1,0]
	v_cvt_scalef32_pk_f16_fp4 v68, v68, 1.0 op_sel:[1,1,0]
	v_pk_fma_f16 v68, v41, v68, v76 op_sel:[1,0,0]
	v_cvt_scalef32_pk_f16_fp4 v76, v69, 1.0
	v_pk_fma_f16 v93, v41, v93, v110 op_sel_hi:[0,1,1]
	v_pk_fma_f16 v102, v41, v102, v111 op_sel_hi:[0,1,1]
	v_pk_fma_f16 v92, v41, v92, v104 op_sel_hi:[0,1,1]
	v_pk_fma_f16 v103, v41, v103, v112 op_sel_hi:[0,1,1]
	v_pk_fma_f16 v83, v41, v83, v91 op_sel:[1,0,0]
	v_pk_fma_f16 v76, v41, v76, v84 op_sel:[1,0,0]
	v_cvt_scalef32_pk_f16_fp4 v84, v69, 1.0 op_sel:[1,0,0]
	v_cvt_scalef32_pk_f16_fp4 v91, v69, 1.0 op_sel:[0,1,0]
	v_cvt_scalef32_pk_f16_fp4 v69, v69, 1.0 op_sel:[1,1,0]
	v_pk_fma_f16 v85, v41, v85, v93 op_sel:[1,0,0]
	v_pk_fma_f16 v90, v41, v90, v102 op_sel:[1,0,0]
	v_pk_fma_f16 v84, v41, v84, v92 op_sel:[1,0,0]
	v_pk_fma_f16 v91, v41, v91, v103 op_sel:[1,0,0]
	v_pk_fma_f16 v38, v41, v69, v38 op_sel:[1,0,0]
	s_waitcnt vmcnt(31)
	v_cvt_scalef32_pk_f16_fp4 v41, v62, 1.0
	v_pk_fma_f16 v39, v6, v41, v39 op_sel_hi:[0,1,1]
	v_cvt_scalef32_pk_f16_fp4 v41, v62, 1.0 op_sel:[1,0,0]
	v_pk_fma_f16 v40, v6, v41, v40 op_sel_hi:[0,1,1]
	v_cvt_scalef32_pk_f16_fp4 v41, v62, 1.0 op_sel:[0,1,0]
	v_cvt_scalef32_pk_f16_fp4 v62, v62, 1.0 op_sel:[1,1,0]
	v_pk_fma_f16 v62, v6, v62, v66 op_sel_hi:[0,1,1]
	v_cvt_scalef32_pk_f16_fp4 v66, v63, 1.0
	v_pk_fma_f16 v66, v6, v66, v74 op_sel_hi:[0,1,1]
	v_cvt_scalef32_pk_f16_fp4 v69, v63, 1.0 op_sel:[1,0,0]
	v_cvt_scalef32_pk_f16_fp4 v74, v63, 1.0 op_sel:[0,1,0]
	v_cvt_scalef32_pk_f16_fp4 v63, v63, 1.0 op_sel:[1,1,0]
	v_pk_fma_f16 v63, v6, v63, v67 op_sel_hi:[0,1,1]
	v_cvt_scalef32_pk_f16_fp4 v67, v64, 1.0
	v_pk_fma_f16 v41, v6, v41, v77 op_sel_hi:[0,1,1]
	v_pk_fma_f16 v67, v6, v67, v75 op_sel_hi:[0,1,1]
	v_cvt_scalef32_pk_f16_fp4 v75, v64, 1.0 op_sel:[1,0,0]
	v_cvt_scalef32_pk_f16_fp4 v77, v64, 1.0 op_sel:[0,1,0]
	v_cvt_scalef32_pk_f16_fp4 v64, v64, 1.0 op_sel:[1,1,0]
	v_pk_fma_f16 v64, v6, v64, v68 op_sel_hi:[0,1,1]
	v_cvt_scalef32_pk_f16_fp4 v68, v65, 1.0
	v_pk_fma_f16 v69, v6, v69, v82 op_sel_hi:[0,1,1]
	v_pk_fma_f16 v68, v6, v68, v76 op_sel_hi:[0,1,1]
	v_cvt_scalef32_pk_f16_fp4 v76, v65, 1.0 op_sel:[1,0,0]
	v_cvt_scalef32_pk_f16_fp4 v82, v65, 1.0 op_sel:[0,1,0]
	v_cvt_scalef32_pk_f16_fp4 v65, v65, 1.0 op_sel:[1,1,0]
	v_pk_fma_f16 v38, v6, v65, v38 op_sel_hi:[0,1,1]
	s_waitcnt vmcnt(30)
	v_cvt_scalef32_pk_f16_fp4 v65, v54, 1.0
	v_pk_fma_f16 v39, v6, v65, v39 op_sel:[1,0,0]
	v_cvt_scalef32_pk_f16_fp4 v65, v54, 1.0 op_sel:[1,0,0]
	v_pk_fma_f16 v40, v6, v65, v40 op_sel:[1,0,0]
	v_cvt_scalef32_pk_f16_fp4 v65, v54, 1.0 op_sel:[0,1,0]
	v_cvt_scalef32_pk_f16_fp4 v54, v54, 1.0 op_sel:[1,1,0]
	v_pk_fma_f16 v54, v6, v54, v62 op_sel:[1,0,0]
	v_cvt_scalef32_pk_f16_fp4 v62, v55, 1.0
	v_pk_fma_f16 v41, v6, v65, v41 op_sel:[1,0,0]
	v_pk_fma_f16 v62, v6, v62, v66 op_sel:[1,0,0]
	v_cvt_scalef32_pk_f16_fp4 v65, v55, 1.0 op_sel:[1,0,0]
	v_cvt_scalef32_pk_f16_fp4 v66, v55, 1.0 op_sel:[0,1,0]
	v_cvt_scalef32_pk_f16_fp4 v55, v55, 1.0 op_sel:[1,1,0]
	v_pk_fma_f16 v55, v6, v55, v63 op_sel:[1,0,0]
	v_cvt_scalef32_pk_f16_fp4 v63, v56, 1.0
	v_pk_fma_f16 v65, v6, v65, v69 op_sel:[1,0,0]
	v_pk_fma_f16 v63, v6, v63, v67 op_sel:[1,0,0]
	v_cvt_scalef32_pk_f16_fp4 v67, v56, 1.0 op_sel:[1,0,0]
	v_cvt_scalef32_pk_f16_fp4 v69, v56, 1.0 op_sel:[0,1,0]
	v_cvt_scalef32_pk_f16_fp4 v56, v56, 1.0 op_sel:[1,1,0]
	v_pk_fma_f16 v74, v6, v74, v85 op_sel_hi:[0,1,1]
	v_pk_fma_f16 v56, v6, v56, v64 op_sel:[1,0,0]
	v_cvt_scalef32_pk_f16_fp4 v64, v57, 1.0
	v_pk_fma_f16 v75, v6, v75, v83 op_sel_hi:[0,1,1]
	v_pk_fma_f16 v77, v6, v77, v90 op_sel_hi:[0,1,1]
	v_pk_fma_f16 v76, v6, v76, v84 op_sel_hi:[0,1,1]
	v_pk_fma_f16 v82, v6, v82, v91 op_sel_hi:[0,1,1]
	v_pk_fma_f16 v66, v6, v66, v74 op_sel:[1,0,0]
	v_pk_fma_f16 v64, v6, v64, v68 op_sel:[1,0,0]
	v_cvt_scalef32_pk_f16_fp4 v68, v57, 1.0 op_sel:[1,0,0]
	v_cvt_scalef32_pk_f16_fp4 v74, v57, 1.0 op_sel:[0,1,0]
	v_cvt_scalef32_pk_f16_fp4 v57, v57, 1.0 op_sel:[1,1,0]
	v_pk_fma_f16 v67, v6, v67, v75 op_sel:[1,0,0]
	v_pk_fma_f16 v69, v6, v69, v77 op_sel:[1,0,0]
	v_pk_fma_f16 v68, v6, v68, v76 op_sel:[1,0,0]
	v_pk_fma_f16 v74, v6, v74, v82 op_sel:[1,0,0]
	v_pk_fma_f16 v6, v6, v57, v38 op_sel:[1,0,0]
	s_waitcnt vmcnt(29)
	v_cvt_scalef32_pk_f16_fp4 v38, v46, 1.0
	v_pk_fma_f16 v38, v7, v38, v39 op_sel_hi:[0,1,1]
	v_cvt_scalef32_pk_f16_fp4 v39, v46, 1.0 op_sel:[1,0,0]
	v_pk_fma_f16 v39, v7, v39, v40 op_sel_hi:[0,1,1]
	v_cvt_scalef32_pk_f16_fp4 v40, v46, 1.0 op_sel:[0,1,0]
	v_pk_fma_f16 v40, v7, v40, v41 op_sel_hi:[0,1,1]
	v_cvt_scalef32_pk_f16_fp4 v41, v46, 1.0 op_sel:[1,1,0]
	v_pk_fma_f16 v41, v7, v41, v54 op_sel_hi:[0,1,1]
	v_cvt_scalef32_pk_f16_fp4 v46, v47, 1.0
	v_cvt_scalef32_pk_f16_fp4 v54, v47, 1.0 op_sel:[1,0,0]
	v_cvt_scalef32_pk_f16_fp4 v57, v47, 1.0 op_sel:[0,1,0]
	v_cvt_scalef32_pk_f16_fp4 v47, v47, 1.0 op_sel:[1,1,0]
	v_pk_fma_f16 v47, v7, v47, v55 op_sel_hi:[0,1,1]
	v_cvt_scalef32_pk_f16_fp4 v55, v48, 1.0
	v_pk_fma_f16 v46, v7, v46, v62 op_sel_hi:[0,1,1]
	v_pk_fma_f16 v55, v7, v55, v63 op_sel_hi:[0,1,1]
	v_cvt_scalef32_pk_f16_fp4 v62, v48, 1.0 op_sel:[1,0,0]
	v_cvt_scalef32_pk_f16_fp4 v63, v48, 1.0 op_sel:[0,1,0]
	v_cvt_scalef32_pk_f16_fp4 v48, v48, 1.0 op_sel:[1,1,0]
	v_pk_fma_f16 v48, v7, v48, v56 op_sel_hi:[0,1,1]
	v_cvt_scalef32_pk_f16_fp4 v56, v49, 1.0
	v_pk_fma_f16 v54, v7, v54, v65 op_sel_hi:[0,1,1]
	v_pk_fma_f16 v56, v7, v56, v64 op_sel_hi:[0,1,1]
	v_cvt_scalef32_pk_f16_fp4 v64, v49, 1.0 op_sel:[1,0,0]
	v_cvt_scalef32_pk_f16_fp4 v65, v49, 1.0 op_sel:[0,1,0]
	v_cvt_scalef32_pk_f16_fp4 v49, v49, 1.0 op_sel:[1,1,0]
	v_pk_fma_f16 v6, v7, v49, v6 op_sel_hi:[0,1,1]
	s_waitcnt vmcnt(28)
	v_cvt_scalef32_pk_f16_fp4 v49, v34, 1.0
	v_pk_fma_f16 v38, v7, v49, v38 op_sel:[1,0,0]
	v_cvt_scalef32_pk_f16_fp4 v49, v34, 1.0 op_sel:[1,0,0]
	v_pk_fma_f16 v39, v7, v49, v39 op_sel:[1,0,0]
	v_cvt_scalef32_pk_f16_fp4 v49, v34, 1.0 op_sel:[0,1,0]
	v_cvt_scalef32_pk_f16_fp4 v34, v34, 1.0 op_sel:[1,1,0]
	v_pk_fma_f16 v34, v7, v34, v41 op_sel:[1,0,0]
	v_cvt_scalef32_pk_f16_fp4 v41, v35, 1.0
	v_pk_fma_f16 v40, v7, v49, v40 op_sel:[1,0,0]
	v_pk_fma_f16 v41, v7, v41, v46 op_sel:[1,0,0]
	v_cvt_scalef32_pk_f16_fp4 v46, v35, 1.0 op_sel:[1,0,0]
	v_cvt_scalef32_pk_f16_fp4 v49, v35, 1.0 op_sel:[0,1,0]
	v_cvt_scalef32_pk_f16_fp4 v35, v35, 1.0 op_sel:[1,1,0]
	v_pk_fma_f16 v35, v7, v35, v47 op_sel:[1,0,0]
	v_cvt_scalef32_pk_f16_fp4 v47, v36, 1.0
	v_pk_fma_f16 v46, v7, v46, v54 op_sel:[1,0,0]
	v_pk_fma_f16 v47, v7, v47, v55 op_sel:[1,0,0]
	v_cvt_scalef32_pk_f16_fp4 v54, v36, 1.0 op_sel:[1,0,0]
	v_cvt_scalef32_pk_f16_fp4 v55, v36, 1.0 op_sel:[0,1,0]
	v_cvt_scalef32_pk_f16_fp4 v36, v36, 1.0 op_sel:[1,1,0]
	v_pk_fma_f16 v57, v7, v57, v66 op_sel_hi:[0,1,1]
	v_pk_fma_f16 v36, v7, v36, v48 op_sel:[1,0,0]
	v_cvt_scalef32_pk_f16_fp4 v48, v37, 1.0
	v_pk_fma_f16 v62, v7, v62, v67 op_sel_hi:[0,1,1]
	v_pk_fma_f16 v63, v7, v63, v69 op_sel_hi:[0,1,1]
	v_pk_fma_f16 v64, v7, v64, v68 op_sel_hi:[0,1,1]
	v_pk_fma_f16 v65, v7, v65, v74 op_sel_hi:[0,1,1]
	v_pk_fma_f16 v49, v7, v49, v57 op_sel:[1,0,0]
	v_pk_fma_f16 v48, v7, v48, v56 op_sel:[1,0,0]
	v_cvt_scalef32_pk_f16_fp4 v56, v37, 1.0 op_sel:[1,0,0]
	v_cvt_scalef32_pk_f16_fp4 v57, v37, 1.0 op_sel:[0,1,0]
	v_cvt_scalef32_pk_f16_fp4 v37, v37, 1.0 op_sel:[1,1,0]
	v_pk_fma_f16 v54, v7, v54, v62 op_sel:[1,0,0]
	v_pk_fma_f16 v55, v7, v55, v63 op_sel:[1,0,0]
	v_pk_fma_f16 v56, v7, v56, v64 op_sel:[1,0,0]
	v_pk_fma_f16 v57, v7, v57, v65 op_sel:[1,0,0]
	v_pk_fma_f16 v6, v7, v37, v6 op_sel:[1,0,0]
	s_waitcnt vmcnt(27)
	v_cvt_scalef32_pk_f16_fp4 v7, v26, 1.0
	v_pk_fma_f16 v7, v8, v7, v38 op_sel_hi:[0,1,1]
	v_cvt_scalef32_pk_f16_fp4 v37, v26, 1.0 op_sel:[1,0,0]
	v_cvt_scalef32_pk_f16_fp4 v38, v26, 1.0 op_sel:[0,1,0]
	v_cvt_scalef32_pk_f16_fp4 v26, v26, 1.0 op_sel:[1,1,0]
	v_pk_fma_f16 v37, v8, v37, v39 op_sel_hi:[0,1,1]
	v_pk_fma_f16 v38, v8, v38, v40 op_sel_hi:[0,1,1]
	v_pk_fma_f16 v26, v8, v26, v34 op_sel_hi:[0,1,1]
	v_cvt_scalef32_pk_f16_fp4 v34, v27, 1.0
	v_cvt_scalef32_pk_f16_fp4 v39, v27, 1.0 op_sel:[1,0,0]
	v_cvt_scalef32_pk_f16_fp4 v40, v27, 1.0 op_sel:[0,1,0]
	v_cvt_scalef32_pk_f16_fp4 v27, v27, 1.0 op_sel:[1,1,0]
	v_pk_fma_f16 v34, v8, v34, v41 op_sel_hi:[0,1,1]
	v_pk_fma_f16 v39, v8, v39, v46 op_sel_hi:[0,1,1]
	v_pk_fma_f16 v27, v8, v27, v35 op_sel_hi:[0,1,1]
	v_cvt_scalef32_pk_f16_fp4 v35, v28, 1.0
	v_cvt_scalef32_pk_f16_fp4 v41, v28, 1.0 op_sel:[1,0,0]
	v_cvt_scalef32_pk_f16_fp4 v46, v28, 1.0 op_sel:[0,1,0]
	v_cvt_scalef32_pk_f16_fp4 v28, v28, 1.0 op_sel:[1,1,0]
	v_pk_fma_f16 v28, v8, v28, v36 op_sel_hi:[0,1,1]
	v_cvt_scalef32_pk_f16_fp4 v36, v29, 1.0
	v_pk_fma_f16 v35, v8, v35, v47 op_sel_hi:[0,1,1]
	v_pk_fma_f16 v36, v8, v36, v48 op_sel_hi:[0,1,1]
	v_cvt_scalef32_pk_f16_fp4 v47, v29, 1.0 op_sel:[1,0,0]
	v_cvt_scalef32_pk_f16_fp4 v48, v29, 1.0 op_sel:[0,1,0]
	v_cvt_scalef32_pk_f16_fp4 v29, v29, 1.0 op_sel:[1,1,0]
	v_pk_fma_f16 v6, v8, v29, v6 op_sel_hi:[0,1,1]
	s_waitcnt vmcnt(26)
	v_cvt_scalef32_pk_f16_fp4 v29, v18, 1.0
	v_pk_fma_f16 v7, v8, v29, v7 op_sel:[1,0,0]
	v_cvt_scalef32_pk_f16_fp4 v29, v18, 1.0 op_sel:[1,0,0]
	v_pk_fma_f16 v29, v8, v29, v37 op_sel:[1,0,0]
	v_cvt_scalef32_pk_f16_fp4 v37, v18, 1.0 op_sel:[0,1,0]
	v_cvt_scalef32_pk_f16_fp4 v18, v18, 1.0 op_sel:[1,1,0]
	v_pk_fma_f16 v18, v8, v18, v26 op_sel:[1,0,0]
	v_cvt_scalef32_pk_f16_fp4 v26, v19, 1.0
	v_pk_fma_f16 v37, v8, v37, v38 op_sel:[1,0,0]
	v_pk_fma_f16 v26, v8, v26, v34 op_sel:[1,0,0]
	v_cvt_scalef32_pk_f16_fp4 v34, v19, 1.0 op_sel:[1,0,0]
	v_cvt_scalef32_pk_f16_fp4 v38, v19, 1.0 op_sel:[0,1,0]
	v_cvt_scalef32_pk_f16_fp4 v19, v19, 1.0 op_sel:[1,1,0]
	v_pk_fma_f16 v19, v8, v19, v27 op_sel:[1,0,0]
	v_cvt_scalef32_pk_f16_fp4 v27, v20, 1.0
	v_pk_fma_f16 v34, v8, v34, v39 op_sel:[1,0,0]
	v_pk_fma_f16 v27, v8, v27, v35 op_sel:[1,0,0]
	v_cvt_scalef32_pk_f16_fp4 v35, v20, 1.0 op_sel:[1,0,0]
	v_cvt_scalef32_pk_f16_fp4 v39, v20, 1.0 op_sel:[0,1,0]
	v_cvt_scalef32_pk_f16_fp4 v20, v20, 1.0 op_sel:[1,1,0]
	v_pk_fma_f16 v40, v8, v40, v49 op_sel_hi:[0,1,1]
	v_pk_fma_f16 v20, v8, v20, v28 op_sel:[1,0,0]
	v_cvt_scalef32_pk_f16_fp4 v28, v21, 1.0
	v_pk_fma_f16 v41, v8, v41, v54 op_sel_hi:[0,1,1]
	v_pk_fma_f16 v46, v8, v46, v55 op_sel_hi:[0,1,1]
	v_pk_fma_f16 v47, v8, v47, v56 op_sel_hi:[0,1,1]
	v_pk_fma_f16 v48, v8, v48, v57 op_sel_hi:[0,1,1]
	v_pk_fma_f16 v38, v8, v38, v40 op_sel:[1,0,0]
	v_pk_fma_f16 v28, v8, v28, v36 op_sel:[1,0,0]
	v_cvt_scalef32_pk_f16_fp4 v36, v21, 1.0 op_sel:[1,0,0]
	v_cvt_scalef32_pk_f16_fp4 v40, v21, 1.0 op_sel:[0,1,0]
	v_cvt_scalef32_pk_f16_fp4 v21, v21, 1.0 op_sel:[1,1,0]
	v_pk_fma_f16 v35, v8, v35, v41 op_sel:[1,0,0]
	v_pk_fma_f16 v39, v8, v39, v46 op_sel:[1,0,0]
	v_pk_fma_f16 v36, v8, v36, v47 op_sel:[1,0,0]
	v_pk_fma_f16 v40, v8, v40, v48 op_sel:[1,0,0]
	v_pk_fma_f16 v6, v8, v21, v6 op_sel:[1,0,0]
	s_waitcnt vmcnt(25)
	v_cvt_scalef32_pk_f16_fp4 v8, v14, 1.0
	v_pk_fma_f16 v7, v9, v8, v7 op_sel_hi:[0,1,1]
	v_cvt_scalef32_pk_f16_fp4 v8, v14, 1.0 op_sel:[1,0,0]
	v_cvt_scalef32_pk_f16_fp4 v21, v14, 1.0 op_sel:[0,1,0]
	v_cvt_scalef32_pk_f16_fp4 v14, v14, 1.0 op_sel:[1,1,0]
	v_pk_fma_f16 v14, v9, v14, v18 op_sel_hi:[0,1,1]
	v_cvt_scalef32_pk_f16_fp4 v18, v15, 1.0
	v_pk_fma_f16 v8, v9, v8, v29 op_sel_hi:[0,1,1]
	v_pk_fma_f16 v18, v9, v18, v26 op_sel_hi:[0,1,1]
	v_cvt_scalef32_pk_f16_fp4 v26, v15, 1.0 op_sel:[1,0,0]
	v_cvt_scalef32_pk_f16_fp4 v29, v15, 1.0 op_sel:[0,1,0]
	v_cvt_scalef32_pk_f16_fp4 v15, v15, 1.0 op_sel:[1,1,0]
	v_pk_fma_f16 v15, v9, v15, v19 op_sel_hi:[0,1,1]
	v_cvt_scalef32_pk_f16_fp4 v19, v16, 1.0
	v_pk_fma_f16 v26, v9, v26, v34 op_sel_hi:[0,1,1]
	v_pk_fma_f16 v19, v9, v19, v27 op_sel_hi:[0,1,1]
	v_cvt_scalef32_pk_f16_fp4 v27, v16, 1.0 op_sel:[1,0,0]
	v_cvt_scalef32_pk_f16_fp4 v34, v16, 1.0 op_sel:[0,1,0]
	v_cvt_scalef32_pk_f16_fp4 v16, v16, 1.0 op_sel:[1,1,0]
	v_pk_fma_f16 v16, v9, v16, v20 op_sel_hi:[0,1,1]
	v_cvt_scalef32_pk_f16_fp4 v20, v17, 1.0
	v_pk_fma_f16 v27, v9, v27, v35 op_sel_hi:[0,1,1]
	v_pk_fma_f16 v20, v9, v20, v28 op_sel_hi:[0,1,1]
	v_cvt_scalef32_pk_f16_fp4 v28, v17, 1.0 op_sel:[1,0,0]
	v_cvt_scalef32_pk_f16_fp4 v35, v17, 1.0 op_sel:[0,1,0]
	v_cvt_scalef32_pk_f16_fp4 v17, v17, 1.0 op_sel:[1,1,0]
	v_pk_fma_f16 v6, v9, v17, v6 op_sel_hi:[0,1,1]
	s_waitcnt vmcnt(24)
	v_cvt_scalef32_pk_f16_fp4 v17, v10, 1.0
	v_pk_fma_f16 v7, v9, v17, v7 op_sel:[1,0,0]
	v_cvt_scalef32_pk_f16_fp4 v17, v10, 1.0 op_sel:[1,0,0]
	v_pk_fma_f16 v8, v9, v17, v8 op_sel:[1,0,0]
	v_cvt_scalef32_pk_f16_fp4 v17, v10, 1.0 op_sel:[0,1,0]
	v_cvt_scalef32_pk_f16_fp4 v10, v10, 1.0 op_sel:[1,1,0]
	v_pk_fma_f16 v21, v9, v21, v37 op_sel_hi:[0,1,1]
	v_pk_fma_f16 v10, v9, v10, v14 op_sel:[1,0,0]
	v_cvt_scalef32_pk_f16_fp4 v14, v11, 1.0
	v_pk_fma_f16 v17, v9, v17, v21 op_sel:[1,0,0]
	v_pk_fma_f16 v14, v9, v14, v18 op_sel:[1,0,0]
	v_cvt_scalef32_pk_f16_fp4 v18, v11, 1.0 op_sel:[1,0,0]
	v_cvt_scalef32_pk_f16_fp4 v21, v11, 1.0 op_sel:[0,1,0]
	v_cvt_scalef32_pk_f16_fp4 v11, v11, 1.0 op_sel:[1,1,0]
	v_pk_fma_f16 v11, v9, v11, v15 op_sel:[1,0,0]
	v_cvt_scalef32_pk_f16_fp4 v15, v12, 1.0
	v_pk_fma_f16 v18, v9, v18, v26 op_sel:[1,0,0]
	v_pk_fma_f16 v15, v9, v15, v19 op_sel:[1,0,0]
	v_cvt_scalef32_pk_f16_fp4 v19, v12, 1.0 op_sel:[1,0,0]
	v_cvt_scalef32_pk_f16_fp4 v26, v12, 1.0 op_sel:[0,1,0]
	v_cvt_scalef32_pk_f16_fp4 v12, v12, 1.0 op_sel:[1,1,0]
	v_pk_fma_f16 v29, v9, v29, v38 op_sel_hi:[0,1,1]
	v_pk_fma_f16 v34, v9, v34, v39 op_sel_hi:[0,1,1]
	v_pk_fma_f16 v35, v9, v35, v40 op_sel_hi:[0,1,1]
	v_pk_fma_f16 v19, v9, v19, v27 op_sel:[1,0,0]
	v_pk_fma_f16 v12, v9, v12, v16 op_sel:[1,0,0]
	v_cvt_scalef32_pk_f16_fp4 v16, v13, 1.0
	v_cvt_scalef32_pk_f16_fp4 v27, v13, 1.0 op_sel:[0,1,0]
	v_pk_fma_f16 v21, v9, v21, v29 op_sel:[1,0,0]
	v_pk_fma_f16 v26, v9, v26, v34 op_sel:[1,0,0]
	v_pk_fma_f16 v16, v9, v16, v20 op_sel:[1,0,0]
	v_cvt_scalef32_pk_f16_fp4 v20, v13, 1.0 op_sel:[1,0,0]
	v_pk_fma_f16 v27, v9, v27, v35 op_sel:[1,0,0]
	v_cvt_scalef32_pk_f16_fp4 v13, v13, 1.0 op_sel:[1,1,0]
	v_pk_fma_f16 v28, v9, v28, v36 op_sel_hi:[0,1,1]
	v_pk_fma_f16 v6, v9, v13, v6 op_sel:[1,0,0]
	v_permlane32_swap_b32_e32 v7, v15
	v_permlane32_swap_b32_e32 v17, v26
	v_permlane32_swap_b32_e32 v10, v12
	v_permlane32_swap_b32_e32 v14, v16
	v_permlane32_swap_b32_e32 v21, v27
	v_pk_fma_f16 v20, v9, v20, v28 op_sel:[1,0,0]
	v_pk_add_f16 v7, v7, v15
	v_pk_add_f16 v9, v17, v26
	v_pk_add_f16 v10, v10, v12
	v_pk_add_f16 v12, v14, v16
	v_pk_add_f16 v14, v21, v27
	v_permlane32_swap_b32_e32 v11, v6
	v_permlane32_swap_b32_e32 v8, v19
	v_permlane32_swap_b32_e32 v18, v20
	v_pk_add_f16 v6, v11, v6
	v_permlane16_swap_b32_e32 v7, v12
	v_permlane16_swap_b32_e32 v9, v14
	v_pk_add_f16 v8, v8, v19
	v_pk_add_f16 v13, v18, v20
	v_pk_add_f16 v7, v7, v12
	v_pk_add_f16 v9, v9, v14
	v_permlane16_swap_b32_e32 v10, v6
	v_permlane16_swap_b32_e32 v8, v13
	v_pk_add_f16 v6, v10, v6
	v_cndmask_b32_e64 v10, v9, v7, s[4:5]
	v_cndmask_b32_e64 v7, v7, v9, s[4:5]
	v_pk_add_f16 v8, v8, v13
	v_cvt_f32_f16_sdwa v13, v189 dst_sel:DWORD dst_unused:UNUSED_PAD src0_sel:WORD_1
	v_mov_b32_dpp v7, v7 row_ror:8 row_mask:0xf bank_mask:0xf bound_ctrl:1
	v_pk_add_f16 v9, v10, v7
	v_cndmask_b32_e64 v10, v6, v8, s[4:5]
	v_cndmask_b32_e64 v6, v8, v6, s[4:5]
	v_cvt_f32_f16_sdwa v7, v188 dst_sel:DWORD dst_unused:UNUSED_PAD src0_sel:WORD_1
	v_cvt_f32_f16_e32 v8, v9
	v_mov_b32_dpp v11, v6 row_ror:8 row_mask:0xf bank_mask:0xf bound_ctrl:1
	v_cvt_f32_f16_e32 v6, v188
	v_cvt_f32_f16_sdwa v9, v9 dst_sel:DWORD dst_unused:UNUSED_PAD src0_sel:WORD_1
	v_pk_add_f16 v15, v10, v11
	v_cvt_f32_f16_sdwa v11, v194 dst_sel:DWORD dst_unused:UNUSED_PAD src0_sel:WORD_1
	v_cvt_f32_f16_e32 v10, v194
	v_cvt_f32_f16_e32 v12, v189
	v_cvt_f32_f16_e32 v14, v15
	v_cvt_f32_f16_sdwa v15, v15 dst_sel:DWORD dst_unused:UNUSED_PAD src0_sel:WORD_1
	v_pk_fma_f32 v[6:7], v[2:3], v[8:9], v[6:7]
	v_cvt_f32_f16_sdwa v9, v195 dst_sel:DWORD dst_unused:UNUSED_PAD src0_sel:WORD_1
	v_cvt_f32_f16_e32 v8, v195
	v_pk_add_f32 v[6:7], v[6:7], v[10:11]
	v_pk_fma_f32 v[10:11], v[4:5], v[14:15], v[12:13]
	v_cvt_pk_f16_f32 v6, v6, v7
	v_pk_add_f32 v[8:9], v[10:11], v[8:9]
	s_nop 0
	v_cvt_pk_f16_f32 v7, v8, v9
	v_lshl_add_u64 v[8:9], v[190:191], 0, s[14:15]
	global_store_dwordx2 v[8:9], v[6:7], off
	v_lshl_add_u64 v[6:7], v[184:185], 0, s[16:17]
	v_lshl_add_u64 v[10:11], v[186:187], 0, s[20:21]
	global_load_dwordx4 v[114:117], v[6:7], off offset:48
	global_load_dwordx4 v[118:121], v[6:7], off offset:32
	global_load_dwordx4 v[126:129], v[6:7], off offset:16
	global_load_dwordx4 v[134:137], v[6:7], off
	s_nop 0
	global_load_dwordx4 v[6:9], v[10:11], off offset:16
	global_load_dwordx4 v[38:41], v[10:11], off
	v_lshl_add_u64 v[10:11], v[190:191], 0, s[18:19]
	v_lshl_add_u64 v[12:13], v[192:193], 0, s[18:19]
	global_load_dwordx2 v[194:195], v[10:11], off
	global_load_dwordx2 v[188:189], v[12:13], off
	s_waitcnt vmcnt(29)
	v_lshl_add_u32 v10, v178, 7, v207
	v_lshl_add_u32 v11, v179, 7, v207
	global_load_dwordx4 v[142:145], v10, s[6:7]
	global_load_dwordx4 v[130:133], v11, s[6:7]
	v_lshl_add_u32 v10, v180, 7, v207
	v_lshl_add_u32 v11, v181, 7, v207
	global_load_dwordx4 v[110:113], v10, s[6:7]
	global_load_dwordx4 v[102:105], v11, s[6:7]
	v_lshl_add_u32 v10, v174, 7, v207
	v_lshl_add_u32 v11, v175, 7, v207
	global_load_dwordx4 v[90:93], v10, s[6:7]
	global_load_dwordx4 v[82:85], v11, s[6:7]
	v_lshl_add_u32 v10, v176, 7, v207
	v_lshl_add_u32 v11, v177, 7, v207
	global_load_dwordx4 v[74:77], v10, s[6:7]
	global_load_dwordx4 v[66:69], v11, s[6:7]
	v_lshl_add_u32 v10, v170, 7, v207
	v_lshl_add_u32 v11, v171, 7, v207
	global_load_dwordx4 v[62:65], v10, s[6:7]
	global_load_dwordx4 v[54:57], v11, s[6:7]
	v_lshl_add_u32 v10, v172, 7, v207
	v_lshl_add_u32 v11, v173, 7, v207
	global_load_dwordx4 v[46:49], v10, s[6:7]
	global_load_dwordx4 v[34:37], v11, s[6:7]
	v_lshl_add_u32 v10, v166, 7, v207
	v_lshl_add_u32 v11, v167, 7, v207
	global_load_dwordx4 v[26:29], v10, s[6:7]
	global_load_dwordx4 v[18:21], v11, s[6:7]
	v_lshl_add_u32 v10, v168, 7, v207
	v_lshl_add_u32 v11, v169, 7, v207
	global_load_dwordx4 v[14:17], v10, s[6:7]
	s_nop 0
	global_load_dwordx4 v[10:13], v11, s[6:7]
	s_waitcnt vmcnt(40)
	v_cvt_scalef32_pk_f16_fp4 v166, v162, 1.0
	v_pk_fma_f16 v166, v94, v166, 0 op_sel_hi:[0,1,1]
	v_cvt_scalef32_pk_f16_fp4 v167, v162, 1.0 op_sel:[1,0,0]
	s_waitcnt vmcnt(39)
	v_cvt_scalef32_pk_f16_fp4 v178, v158, 1.0
	v_pk_fma_f16 v167, v94, v167, 0 op_sel_hi:[0,1,1]
	v_cvt_scalef32_pk_f16_fp4 v168, v162, 1.0 op_sel:[0,1,0]
	v_cvt_scalef32_pk_f16_fp4 v162, v162, 1.0 op_sel:[1,1,0]
	v_pk_fma_f16 v166, v94, v178, v166 op_sel:[1,0,0]
	v_cvt_scalef32_pk_f16_fp4 v178, v158, 1.0 op_sel:[1,0,0]
	v_pk_fma_f16 v162, v94, v162, 0 op_sel_hi:[0,1,1]
	v_cvt_scalef32_pk_f16_fp4 v169, v163, 1.0
	v_pk_fma_f16 v167, v94, v178, v167 op_sel:[1,0,0]
	v_cvt_scalef32_pk_f16_fp4 v178, v158, 1.0 op_sel:[0,1,0]
	v_cvt_scalef32_pk_f16_fp4 v158, v158, 1.0 op_sel:[1,1,0]
	v_pk_fma_f16 v169, v94, v169, 0 op_sel_hi:[0,1,1]
	v_cvt_scalef32_pk_f16_fp4 v170, v163, 1.0 op_sel:[1,0,0]
	v_pk_fma_f16 v158, v94, v158, v162 op_sel:[1,0,0]
	v_cvt_scalef32_pk_f16_fp4 v162, v159, 1.0
	v_pk_fma_f16 v170, v94, v170, 0 op_sel_hi:[0,1,1]
	v_cvt_scalef32_pk_f16_fp4 v171, v163, 1.0 op_sel:[0,1,0]
	v_cvt_scalef32_pk_f16_fp4 v163, v163, 1.0 op_sel:[1,1,0]
	v_pk_fma_f16 v162, v94, v162, v169 op_sel:[1,0,0]
	v_cvt_scalef32_pk_f16_fp4 v169, v159, 1.0 op_sel:[1,0,0]
	v_pk_fma_f16 v163, v94, v163, 0 op_sel_hi:[0,1,1]
	v_cvt_scalef32_pk_f16_fp4 v172, v164, 1.0
	v_pk_fma_f16 v169, v94, v169, v170 op_sel:[1,0,0]
	v_cvt_scalef32_pk_f16_fp4 v170, v159, 1.0 op_sel:[0,1,0]
	v_cvt_scalef32_pk_f16_fp4 v159, v159, 1.0 op_sel:[1,1,0]
	v_pk_fma_f16 v171, v94, v171, 0 op_sel_hi:[0,1,1]
	v_pk_fma_f16 v172, v94, v172, 0 op_sel_hi:[0,1,1]
	v_cvt_scalef32_pk_f16_fp4 v173, v164, 1.0 op_sel:[1,0,0]
	v_cvt_scalef32_pk_f16_fp4 v174, v164, 1.0 op_sel:[0,1,0]
	v_cvt_scalef32_pk_f16_fp4 v164, v164, 1.0 op_sel:[1,1,0]
	v_pk_fma_f16 v159, v94, v159, v163 op_sel:[1,0,0]
	v_cvt_scalef32_pk_f16_fp4 v163, v160, 1.0
	v_pk_fma_f16 v173, v94, v173, 0 op_sel_hi:[0,1,1]
	v_pk_fma_f16 v174, v94, v174, 0 op_sel_hi:[0,1,1]
	v_pk_fma_f16 v164, v94, v164, 0 op_sel_hi:[0,1,1]
	v_cvt_scalef32_pk_f16_fp4 v175, v165, 1.0
	v_cvt_scalef32_pk_f16_fp4 v176, v165, 1.0 op_sel:[1,0,0]
	v_cvt_scalef32_pk_f16_fp4 v177, v165, 1.0 op_sel:[0,1,0]
	v_cvt_scalef32_pk_f16_fp4 v165, v165, 1.0 op_sel:[1,1,0]
	v_pk_fma_f16 v170, v94, v170, v171 op_sel:[1,0,0]
	v_pk_fma_f16 v163, v94, v163, v172 op_sel:[1,0,0]
	v_cvt_scalef32_pk_f16_fp4 v171, v160, 1.0 op_sel:[1,0,0]
	v_cvt_scalef32_pk_f16_fp4 v172, v160, 1.0 op_sel:[0,1,0]
	v_cvt_scalef32_pk_f16_fp4 v160, v160, 1.0 op_sel:[1,1,0]
	v_pk_fma_f16 v168, v94, v168, 0 op_sel_hi:[0,1,1]
	v_pk_fma_f16 v175, v94, v175, 0 op_sel_hi:[0,1,1]
	v_pk_fma_f16 v176, v94, v176, 0 op_sel_hi:[0,1,1]
	v_pk_fma_f16 v177, v94, v177, 0 op_sel_hi:[0,1,1]
	v_pk_fma_f16 v165, v94, v165, 0 op_sel_hi:[0,1,1]
	v_pk_fma_f16 v171, v94, v171, v173 op_sel:[1,0,0]
	v_pk_fma_f16 v172, v94, v172, v174 op_sel:[1,0,0]
	v_pk_fma_f16 v160, v94, v160, v164 op_sel:[1,0,0]
	v_cvt_scalef32_pk_f16_fp4 v164, v161, 1.0
	v_cvt_scalef32_pk_f16_fp4 v173, v161, 1.0 op_sel:[1,0,0]
	v_cvt_scalef32_pk_f16_fp4 v174, v161, 1.0 op_sel:[0,1,0]
	v_cvt_scalef32_pk_f16_fp4 v161, v161, 1.0 op_sel:[1,1,0]
	v_pk_fma_f16 v168, v94, v178, v168 op_sel:[1,0,0]
	v_pk_fma_f16 v164, v94, v164, v175 op_sel:[1,0,0]
	v_pk_fma_f16 v173, v94, v173, v176 op_sel:[1,0,0]
	v_pk_fma_f16 v174, v94, v174, v177 op_sel:[1,0,0]
	v_pk_fma_f16 v94, v94, v161, v165 op_sel:[1,0,0]
	s_waitcnt vmcnt(38)
	v_cvt_scalef32_pk_f16_fp4 v161, v154, 1.0
	v_pk_fma_f16 v161, v95, v161, v166 op_sel_hi:[0,1,1]
	v_cvt_scalef32_pk_f16_fp4 v165, v154, 1.0 op_sel:[1,0,0]
	v_cvt_scalef32_pk_f16_fp4 v166, v154, 1.0 op_sel:[0,1,0]
	v_cvt_scalef32_pk_f16_fp4 v154, v154, 1.0 op_sel:[1,1,0]
	v_pk_fma_f16 v154, v95, v154, v158 op_sel_hi:[0,1,1]
	v_cvt_scalef32_pk_f16_fp4 v158, v155, 1.0
	v_pk_fma_f16 v165, v95, v165, v167 op_sel_hi:[0,1,1]
	v_pk_fma_f16 v158, v95, v158, v162 op_sel_hi:[0,1,1]
	v_cvt_scalef32_pk_f16_fp4 v162, v155, 1.0 op_sel:[1,0,0]
	v_cvt_scalef32_pk_f16_fp4 v167, v155, 1.0 op_sel:[0,1,0]
	v_cvt_scalef32_pk_f16_fp4 v155, v155, 1.0 op_sel:[1,1,0]
	v_pk_fma_f16 v155, v95, v155, v159 op_sel_hi:[0,1,1]
	v_cvt_scalef32_pk_f16_fp4 v159, v156, 1.0
	v_pk_fma_f16 v166, v95, v166, v168 op_sel_hi:[0,1,1]
	v_pk_fma_f16 v159, v95, v159, v163 op_sel_hi:[0,1,1]
	v_cvt_scalef32_pk_f16_fp4 v163, v156, 1.0 op_sel:[1,0,0]
	v_cvt_scalef32_pk_f16_fp4 v168, v156, 1.0 op_sel:[0,1,0]
	v_cvt_scalef32_pk_f16_fp4 v156, v156, 1.0 op_sel:[1,1,0]
	v_pk_fma_f16 v156, v95, v156, v160 op_sel_hi:[0,1,1]
	v_cvt_scalef32_pk_f16_fp4 v160, v157, 1.0
	v_pk_fma_f16 v162, v95, v162, v169 op_sel_hi:[0,1,1]
	v_pk_fma_f16 v160, v95, v160, v164 op_sel_hi:[0,1,1]
	v_cvt_scalef32_pk_f16_fp4 v164, v157, 1.0 op_sel:[1,0,0]
	v_cvt_scalef32_pk_f16_fp4 v169, v157, 1.0 op_sel:[0,1,0]
	v_cvt_scalef32_pk_f16_fp4 v157, v157, 1.0 op_sel:[1,1,0]
	v_pk_fma_f16 v94, v95, v157, v94 op_sel_hi:[0,1,1]
	s_waitcnt vmcnt(37)
	v_cvt_scalef32_pk_f16_fp4 v157, v150, 1.0
	v_pk_fma_f16 v157, v95, v157, v161 op_sel:[1,0,0]
	v_cvt_scalef32_pk_f16_fp4 v161, v150, 1.0 op_sel:[1,0,0]
	v_pk_fma_f16 v161, v95, v161, v165 op_sel:[1,0,0]
	v_cvt_scalef32_pk_f16_fp4 v165, v150, 1.0 op_sel:[0,1,0]
	v_cvt_scalef32_pk_f16_fp4 v150, v150, 1.0 op_sel:[1,1,0]
	v_pk_fma_f16 v150, v95, v150, v154 op_sel:[1,0,0]
	v_cvt_scalef32_pk_f16_fp4 v154, v151, 1.0
	v_pk_fma_f16 v154, v95, v154, v158 op_sel:[1,0,0]
	v_cvt_scalef32_pk_f16_fp4 v158, v151, 1.0 op_sel:[1,0,0]
	v_pk_fma_f16 v158, v95, v158, v162 op_sel:[1,0,0]
	v_cvt_scalef32_pk_f16_fp4 v162, v151, 1.0 op_sel:[0,1,0]
	v_cvt_scalef32_pk_f16_fp4 v151, v151, 1.0 op_sel:[1,1,0]
	v_pk_fma_f16 v151, v95, v151, v155 op_sel:[1,0,0]
	v_cvt_scalef32_pk_f16_fp4 v155, v152, 1.0
	v_pk_fma_f16 v163, v95, v163, v171 op_sel_hi:[0,1,1]
	v_pk_fma_f16 v155, v95, v155, v159 op_sel:[1,0,0]
	v_cvt_scalef32_pk_f16_fp4 v159, v152, 1.0 op_sel:[1,0,0]
	v_pk_fma_f16 v159, v95, v159, v163 op_sel:[1,0,0]
	v_cvt_scalef32_pk_f16_fp4 v163, v152, 1.0 op_sel:[0,1,0]
	v_cvt_scalef32_pk_f16_fp4 v152, v152, 1.0 op_sel:[1,1,0]
	v_pk_fma_f16 v152, v95, v152, v156 op_sel:[1,0,0]
	v_cvt_scalef32_pk_f16_fp4 v156, v153, 1.0
	v_pk_fma_f16 v164, v95, v164, v173 op_sel_hi:[0,1,1]
	v_pk_fma_f16 v156, v95, v156, v160 op_sel:[1,0,0]
	v_cvt_scalef32_pk_f16_fp4 v160, v153, 1.0 op_sel:[1,0,0]
	v_pk_fma_f16 v167, v95, v167, v170 op_sel_hi:[0,1,1]
	v_pk_fma_f16 v168, v95, v168, v172 op_sel_hi:[0,1,1]
	v_pk_fma_f16 v169, v95, v169, v174 op_sel_hi:[0,1,1]
	v_pk_fma_f16 v160, v95, v160, v164 op_sel:[1,0,0]
	v_cvt_scalef32_pk_f16_fp4 v164, v153, 1.0 op_sel:[0,1,0]
	v_cvt_scalef32_pk_f16_fp4 v153, v153, 1.0 op_sel:[1,1,0]
	v_pk_fma_f16 v165, v95, v165, v166 op_sel:[1,0,0]
	v_pk_fma_f16 v162, v95, v162, v167 op_sel:[1,0,0]
	v_pk_fma_f16 v163, v95, v163, v168 op_sel:[1,0,0]
	v_pk_fma_f16 v164, v95, v164, v169 op_sel:[1,0,0]
	v_pk_fma_f16 v94, v95, v153, v94 op_sel:[1,0,0]
	s_waitcnt vmcnt(36)
	v_cvt_scalef32_pk_f16_fp4 v95, v146, 1.0
	v_pk_fma_f16 v95, v96, v95, v157 op_sel_hi:[0,1,1]
	v_cvt_scalef32_pk_f16_fp4 v153, v146, 1.0 op_sel:[1,0,0]
	v_cvt_scalef32_pk_f16_fp4 v157, v146, 1.0 op_sel:[0,1,0]
	v_cvt_scalef32_pk_f16_fp4 v146, v146, 1.0 op_sel:[1,1,0]
	v_pk_fma_f16 v146, v96, v146, v150 op_sel_hi:[0,1,1]
	v_cvt_scalef32_pk_f16_fp4 v150, v147, 1.0
	v_pk_fma_f16 v150, v96, v150, v154 op_sel_hi:[0,1,1]
	v_cvt_scalef32_pk_f16_fp4 v154, v147, 1.0 op_sel:[1,0,0]
	v_pk_fma_f16 v154, v96, v154, v158 op_sel_hi:[0,1,1]
	v_cvt_scalef32_pk_f16_fp4 v158, v147, 1.0 op_sel:[0,1,0]
	v_cvt_scalef32_pk_f16_fp4 v147, v147, 1.0 op_sel:[1,1,0]
	v_pk_fma_f16 v147, v96, v147, v151 op_sel_hi:[0,1,1]
	v_cvt_scalef32_pk_f16_fp4 v151, v148, 1.0
	v_pk_fma_f16 v151, v96, v151, v155 op_sel_hi:[0,1,1]
	v_cvt_scalef32_pk_f16_fp4 v155, v148, 1.0 op_sel:[1,0,0]
	v_pk_fma_f16 v155, v96, v155, v159 op_sel_hi:[0,1,1]
	v_cvt_scalef32_pk_f16_fp4 v159, v148, 1.0 op_sel:[0,1,0]
	v_cvt_scalef32_pk_f16_fp4 v148, v148, 1.0 op_sel:[1,1,0]
	v_pk_fma_f16 v148, v96, v148, v152 op_sel_hi:[0,1,1]
	v_cvt_scalef32_pk_f16_fp4 v152, v149, 1.0
	v_pk_fma_f16 v152, v96, v152, v156 op_sel_hi:[0,1,1]
	v_cvt_scalef32_pk_f16_fp4 v156, v149, 1.0 op_sel:[1,0,0]
	v_pk_fma_f16 v156, v96, v156, v160 op_sel_hi:[0,1,1]
	v_cvt_scalef32_pk_f16_fp4 v160, v149, 1.0 op_sel:[0,1,0]
	v_cvt_scalef32_pk_f16_fp4 v149, v149, 1.0 op_sel:[1,1,0]
	v_pk_fma_f16 v94, v96, v149, v94 op_sel_hi:[0,1,1]
	s_waitcnt vmcnt(35)
	v_cvt_scalef32_pk_f16_fp4 v149, v138, 1.0
	v_pk_fma_f16 v153, v96, v153, v161 op_sel_hi:[0,1,1]
	v_pk_fma_f16 v95, v96, v149, v95 op_sel:[1,0,0]
	v_cvt_scalef32_pk_f16_fp4 v149, v138, 1.0 op_sel:[1,0,0]
	v_pk_fma_f16 v149, v96, v149, v153 op_sel:[1,0,0]
	v_cvt_scalef32_pk_f16_fp4 v153, v138, 1.0 op_sel:[0,1,0]
	v_cvt_scalef32_pk_f16_fp4 v138, v138, 1.0 op_sel:[1,1,0]
	v_pk_fma_f16 v138, v96, v138, v146 op_sel:[1,0,0]
	v_cvt_scalef32_pk_f16_fp4 v146, v139, 1.0
	v_pk_fma_f16 v146, v96, v146, v150 op_sel:[1,0,0]
	v_cvt_scalef32_pk_f16_fp4 v150, v139, 1.0 op_sel:[1,0,0]
	v_pk_fma_f16 v150, v96, v150, v154 op_sel:[1,0,0]
	v_cvt_scalef32_pk_f16_fp4 v154, v139, 1.0 op_sel:[0,1,0]
	v_cvt_scalef32_pk_f16_fp4 v139, v139, 1.0 op_sel:[1,1,0]
	v_pk_fma_f16 v139, v96, v139, v147 op_sel:[1,0,0]
	v_cvt_scalef32_pk_f16_fp4 v147, v140, 1.0
	v_pk_fma_f16 v147, v96, v147, v151 op_sel:[1,0,0]
	v_cvt_scalef32_pk_f16_fp4 v151, v140, 1.0 op_sel:[1,0,0]
	v_pk_fma_f16 v151, v96, v151, v155 op_sel:[1,0,0]
	v_cvt_scalef32_pk_f16_fp4 v155, v140, 1.0 op_sel:[0,1,0]
	v_cvt_scalef32_pk_f16_fp4 v140, v140, 1.0 op_sel:[1,1,0]
	v_pk_fma_f16 v140, v96, v140, v148 op_sel:[1,0,0]
	v_cvt_scalef32_pk_f16_fp4 v148, v141, 1.0
	v_pk_fma_f16 v148, v96, v148, v152 op_sel:[1,0,0]
	v_cvt_scalef32_pk_f16_fp4 v152, v141, 1.0 op_sel:[1,0,0]
	v_pk_fma_f16 v157, v96, v157, v165 op_sel_hi:[0,1,1]
	v_pk_fma_f16 v158, v96, v158, v162 op_sel_hi:[0,1,1]
	v_pk_fma_f16 v159, v96, v159, v163 op_sel_hi:[0,1,1]
	v_pk_fma_f16 v160, v96, v160, v164 op_sel_hi:[0,1,1]
	v_pk_fma_f16 v152, v96, v152, v156 op_sel:[1,0,0]
	v_cvt_scalef32_pk_f16_fp4 v156, v141, 1.0 op_sel:[0,1,0]
	v_cvt_scalef32_pk_f16_fp4 v141, v141, 1.0 op_sel:[1,1,0]
	v_pk_fma_f16 v153, v96, v153, v157 op_sel:[1,0,0]
	v_pk_fma_f16 v154, v96, v154, v158 op_sel:[1,0,0]
	v_pk_fma_f16 v155, v96, v155, v159 op_sel:[1,0,0]
	v_pk_fma_f16 v156, v96, v156, v160 op_sel:[1,0,0]
	v_pk_fma_f16 v94, v96, v141, v94 op_sel:[1,0,0]
	s_waitcnt vmcnt(34)
	v_cvt_scalef32_pk_f16_fp4 v96, v122, 1.0
	v_pk_fma_f16 v95, v97, v96, v95 op_sel_hi:[0,1,1]
	v_cvt_scalef32_pk_f16_fp4 v96, v122, 1.0 op_sel:[1,0,0]
	v_cvt_scalef32_pk_f16_fp4 v141, v122, 1.0 op_sel:[0,1,0]
	v_cvt_scalef32_pk_f16_fp4 v122, v122, 1.0 op_sel:[1,1,0]
	v_pk_fma_f16 v122, v97, v122, v138 op_sel_hi:[0,1,1]
	v_cvt_scalef32_pk_f16_fp4 v138, v123, 1.0
	v_pk_fma_f16 v96, v97, v96, v149 op_sel_hi:[0,1,1]
	v_pk_fma_f16 v138, v97, v138, v146 op_sel_hi:[0,1,1]
	v_cvt_scalef32_pk_f16_fp4 v146, v123, 1.0 op_sel:[1,0,0]
	v_cvt_scalef32_pk_f16_fp4 v149, v123, 1.0 op_sel:[0,1,0]
	v_cvt_scalef32_pk_f16_fp4 v123, v123, 1.0 op_sel:[1,1,0]
	v_pk_fma_f16 v123, v97, v123, v139 op_sel_hi:[0,1,1]
	v_cvt_scalef32_pk_f16_fp4 v139, v124, 1.0
	v_pk_fma_f16 v146, v97, v146, v150 op_sel_hi:[0,1,1]
	v_pk_fma_f16 v139, v97, v139, v147 op_sel_hi:[0,1,1]
	v_cvt_scalef32_pk_f16_fp4 v147, v124, 1.0 op_sel:[1,0,0]
	v_cvt_scalef32_pk_f16_fp4 v150, v124, 1.0 op_sel:[0,1,0]
	v_cvt_scalef32_pk_f16_fp4 v124, v124, 1.0 op_sel:[1,1,0]
	v_pk_fma_f16 v124, v97, v124, v140 op_sel_hi:[0,1,1]
	v_cvt_scalef32_pk_f16_fp4 v140, v125, 1.0
	v_pk_fma_f16 v147, v97, v147, v151 op_sel_hi:[0,1,1]
	v_pk_fma_f16 v140, v97, v140, v148 op_sel_hi:[0,1,1]
	v_cvt_scalef32_pk_f16_fp4 v148, v125, 1.0 op_sel:[1,0,0]
	v_cvt_scalef32_pk_f16_fp4 v151, v125, 1.0 op_sel:[0,1,0]
	v_cvt_scalef32_pk_f16_fp4 v125, v125, 1.0 op_sel:[1,1,0]
	v_pk_fma_f16 v94, v97, v125, v94 op_sel_hi:[0,1,1]
	s_waitcnt vmcnt(33)
	v_cvt_scalef32_pk_f16_fp4 v125, v106, 1.0
	v_pk_fma_f16 v95, v97, v125, v95 op_sel:[1,0,0]
	v_cvt_scalef32_pk_f16_fp4 v125, v106, 1.0 op_sel:[1,0,0]
	v_pk_fma_f16 v96, v97, v125, v96 op_sel:[1,0,0]
	v_cvt_scalef32_pk_f16_fp4 v125, v106, 1.0 op_sel:[0,1,0]
	v_cvt_scalef32_pk_f16_fp4 v106, v106, 1.0 op_sel:[1,1,0]
	v_pk_fma_f16 v141, v97, v141, v153 op_sel_hi:[0,1,1]
	v_pk_fma_f16 v106, v97, v106, v122 op_sel:[1,0,0]
	v_cvt_scalef32_pk_f16_fp4 v122, v107, 1.0
	v_pk_fma_f16 v125, v97, v125, v141 op_sel:[1,0,0]
	v_pk_fma_f16 v122, v97, v122, v138 op_sel:[1,0,0]
	v_cvt_scalef32_pk_f16_fp4 v138, v107, 1.0 op_sel:[1,0,0]
	v_cvt_scalef32_pk_f16_fp4 v141, v107, 1.0 op_sel:[0,1,0]
	v_cvt_scalef32_pk_f16_fp4 v107, v107, 1.0 op_sel:[1,1,0]
	v_pk_fma_f16 v107, v97, v107, v123 op_sel:[1,0,0]
	v_cvt_scalef32_pk_f16_fp4 v123, v108, 1.0
	v_pk_fma_f16 v138, v97, v138, v146 op_sel:[1,0,0]
	v_pk_fma_f16 v123, v97, v123, v139 op_sel:[1,0,0]
	v_cvt_scalef32_pk_f16_fp4 v139, v108, 1.0 op_sel:[1,0,0]
	v_cvt_scalef32_pk_f16_fp4 v146, v108, 1.0 op_sel:[0,1,0]
	v_cvt_scalef32_pk_f16_fp4 v108, v108, 1.0 op_sel:[1,1,0]
	v_pk_fma_f16 v108, v97, v108, v124 op_sel:[1,0,0]
	v_cvt_scalef32_pk_f16_fp4 v124, v109, 1.0
	v_pk_fma_f16 v149, v97, v149, v154 op_sel_hi:[0,1,1]
	v_pk_fma_f16 v150, v97, v150, v155 op_sel_hi:[0,1,1]
	v_pk_fma_f16 v148, v97, v148, v152 op_sel_hi:[0,1,1]
	v_pk_fma_f16 v151, v97, v151, v156 op_sel_hi:[0,1,1]
	v_pk_fma_f16 v139, v97, v139, v147 op_sel:[1,0,0]
	v_pk_fma_f16 v124, v97, v124, v140 op_sel:[1,0,0]
	v_cvt_scalef32_pk_f16_fp4 v140, v109, 1.0 op_sel:[1,0,0]
	v_cvt_scalef32_pk_f16_fp4 v147, v109, 1.0 op_sel:[0,1,0]
	v_cvt_scalef32_pk_f16_fp4 v109, v109, 1.0 op_sel:[1,1,0]
	v_pk_fma_f16 v141, v97, v141, v149 op_sel:[1,0,0]
	v_pk_fma_f16 v146, v97, v146, v150 op_sel:[1,0,0]
	v_pk_fma_f16 v140, v97, v140, v148 op_sel:[1,0,0]
	v_pk_fma_f16 v147, v97, v147, v151 op_sel:[1,0,0]
	v_pk_fma_f16 v94, v97, v109, v94 op_sel:[1,0,0]
	s_waitcnt vmcnt(32)
	v_cvt_scalef32_pk_f16_fp4 v97, v98, 1.0
	v_pk_fma_f16 v95, v22, v97, v95 op_sel_hi:[0,1,1]
	v_cvt_scalef32_pk_f16_fp4 v97, v98, 1.0 op_sel:[1,0,0]
	v_pk_fma_f16 v96, v22, v97, v96 op_sel_hi:[0,1,1]
	v_cvt_scalef32_pk_f16_fp4 v97, v98, 1.0 op_sel:[0,1,0]
	v_cvt_scalef32_pk_f16_fp4 v98, v98, 1.0 op_sel:[1,1,0]
	v_pk_fma_f16 v98, v22, v98, v106 op_sel_hi:[0,1,1]
	v_cvt_scalef32_pk_f16_fp4 v106, v99, 1.0
	v_pk_fma_f16 v106, v22, v106, v122 op_sel_hi:[0,1,1]
	v_cvt_scalef32_pk_f16_fp4 v109, v99, 1.0 op_sel:[1,0,0]
	v_cvt_scalef32_pk_f16_fp4 v122, v99, 1.0 op_sel:[0,1,0]
	v_cvt_scalef32_pk_f16_fp4 v99, v99, 1.0 op_sel:[1,1,0]
	v_pk_fma_f16 v99, v22, v99, v107 op_sel_hi:[0,1,1]
	v_cvt_scalef32_pk_f16_fp4 v107, v100, 1.0
	v_pk_fma_f16 v97, v22, v97, v125 op_sel_hi:[0,1,1]
	v_pk_fma_f16 v107, v22, v107, v123 op_sel_hi:[0,1,1]
	v_cvt_scalef32_pk_f16_fp4 v123, v100, 1.0 op_sel:[1,0,0]
	v_cvt_scalef32_pk_f16_fp4 v125, v100, 1.0 op_sel:[0,1,0]
	v_cvt_scalef32_pk_f16_fp4 v100, v100, 1.0 op_sel:[1,1,0]
	v_pk_fma_f16 v100, v22, v100, v108 op_sel_hi:[0,1,1]
	v_cvt_scalef32_pk_f16_fp4 v108, v101, 1.0
	v_pk_fma_f16 v109, v22, v109, v138 op_sel_hi:[0,1,1]
	v_pk_fma_f16 v108, v22, v108, v124 op_sel_hi:[0,1,1]
	v_cvt_scalef32_pk_f16_fp4 v124, v101, 1.0 op_sel:[1,0,0]
	v_cvt_scalef32_pk_f16_fp4 v138, v101, 1.0 op_sel:[0,1,0]
	v_cvt_scalef32_pk_f16_fp4 v101, v101, 1.0 op_sel:[1,1,0]
	v_pk_fma_f16 v94, v22, v101, v94 op_sel_hi:[0,1,1]
	s_waitcnt vmcnt(31)
	v_cvt_scalef32_pk_f16_fp4 v101, v86, 1.0
	v_pk_fma_f16 v95, v22, v101, v95 op_sel:[1,0,0]
	v_cvt_scalef32_pk_f16_fp4 v101, v86, 1.0 op_sel:[1,0,0]
	v_pk_fma_f16 v96, v22, v101, v96 op_sel:[1,0,0]
	v_cvt_scalef32_pk_f16_fp4 v101, v86, 1.0 op_sel:[0,1,0]
	v_cvt_scalef32_pk_f16_fp4 v86, v86, 1.0 op_sel:[1,1,0]
	v_pk_fma_f16 v86, v22, v86, v98 op_sel:[1,0,0]
	v_cvt_scalef32_pk_f16_fp4 v98, v87, 1.0
	v_pk_fma_f16 v97, v22, v101, v97 op_sel:[1,0,0]
	v_pk_fma_f16 v98, v22, v98, v106 op_sel:[1,0,0]
	v_cvt_scalef32_pk_f16_fp4 v101, v87, 1.0 op_sel:[1,0,0]
	v_cvt_scalef32_pk_f16_fp4 v106, v87, 1.0 op_sel:[0,1,0]
	v_cvt_scalef32_pk_f16_fp4 v87, v87, 1.0 op_sel:[1,1,0]
	v_pk_fma_f16 v87, v22, v87, v99 op_sel:[1,0,0]
	v_cvt_scalef32_pk_f16_fp4 v99, v88, 1.0
	v_pk_fma_f16 v101, v22, v101, v109 op_sel:[1,0,0]
	v_pk_fma_f16 v99, v22, v99, v107 op_sel:[1,0,0]
	v_cvt_scalef32_pk_f16_fp4 v107, v88, 1.0 op_sel:[1,0,0]
	v_cvt_scalef32_pk_f16_fp4 v109, v88, 1.0 op_sel:[0,1,0]
	v_cvt_scalef32_pk_f16_fp4 v88, v88, 1.0 op_sel:[1,1,0]
	v_pk_fma_f16 v122, v22, v122, v141 op_sel_hi:[0,1,1]
	v_pk_fma_f16 v88, v22, v88, v100 op_sel:[1,0,0]
	v_cvt_scalef32_pk_f16_fp4 v100, v89, 1.0
	v_pk_fma_f16 v123, v22, v123, v139 op_sel_hi:[0,1,1]
	v_pk_fma_f16 v125, v22, v125, v146 op_sel_hi:[0,1,1]
	v_pk_fma_f16 v124, v22, v124, v140 op_sel_hi:[0,1,1]
	v_pk_fma_f16 v138, v22, v138, v147 op_sel_hi:[0,1,1]
	v_pk_fma_f16 v106, v22, v106, v122 op_sel:[1,0,0]
	v_pk_fma_f16 v100, v22, v100, v108 op_sel:[1,0,0]
	v_cvt_scalef32_pk_f16_fp4 v108, v89, 1.0 op_sel:[1,0,0]
	v_cvt_scalef32_pk_f16_fp4 v122, v89, 1.0 op_sel:[0,1,0]
	v_cvt_scalef32_pk_f16_fp4 v89, v89, 1.0 op_sel:[1,1,0]
	v_pk_fma_f16 v107, v22, v107, v123 op_sel:[1,0,0]
	v_pk_fma_f16 v109, v22, v109, v125 op_sel:[1,0,0]
	v_pk_fma_f16 v108, v22, v108, v124 op_sel:[1,0,0]
	v_pk_fma_f16 v122, v22, v122, v138 op_sel:[1,0,0]
	v_pk_fma_f16 v22, v22, v89, v94 op_sel:[1,0,0]
	s_waitcnt vmcnt(30)
	v_cvt_scalef32_pk_f16_fp4 v89, v78, 1.0
	v_pk_fma_f16 v89, v23, v89, v95 op_sel_hi:[0,1,1]
	v_cvt_scalef32_pk_f16_fp4 v94, v78, 1.0 op_sel:[1,0,0]
	v_cvt_scalef32_pk_f16_fp4 v95, v78, 1.0 op_sel:[0,1,0]
	v_cvt_scalef32_pk_f16_fp4 v78, v78, 1.0 op_sel:[1,1,0]
	v_pk_fma_f16 v94, v23, v94, v96 op_sel_hi:[0,1,1]
	v_pk_fma_f16 v95, v23, v95, v97 op_sel_hi:[0,1,1]
	v_pk_fma_f16 v78, v23, v78, v86 op_sel_hi:[0,1,1]
	v_cvt_scalef32_pk_f16_fp4 v86, v79, 1.0
	v_cvt_scalef32_pk_f16_fp4 v96, v79, 1.0 op_sel:[1,0,0]
	v_cvt_scalef32_pk_f16_fp4 v97, v79, 1.0 op_sel:[0,1,0]
	v_cvt_scalef32_pk_f16_fp4 v79, v79, 1.0 op_sel:[1,1,0]
	v_pk_fma_f16 v79, v23, v79, v87 op_sel_hi:[0,1,1]
	v_cvt_scalef32_pk_f16_fp4 v87, v80, 1.0
	v_pk_fma_f16 v86, v23, v86, v98 op_sel_hi:[0,1,1]
	v_pk_fma_f16 v87, v23, v87, v99 op_sel_hi:[0,1,1]
	v_cvt_scalef32_pk_f16_fp4 v98, v80, 1.0 op_sel:[1,0,0]
	v_cvt_scalef32_pk_f16_fp4 v99, v80, 1.0 op_sel:[0,1,0]
	v_cvt_scalef32_pk_f16_fp4 v80, v80, 1.0 op_sel:[1,1,0]
	v_pk_fma_f16 v80, v23, v80, v88 op_sel_hi:[0,1,1]
	v_cvt_scalef32_pk_f16_fp4 v88, v81, 1.0
	v_pk_fma_f16 v96, v23, v96, v101 op_sel_hi:[0,1,1]
	v_pk_fma_f16 v88, v23, v88, v100 op_sel_hi:[0,1,1]
	v_cvt_scalef32_pk_f16_fp4 v100, v81, 1.0 op_sel:[1,0,0]
	v_cvt_scalef32_pk_f16_fp4 v101, v81, 1.0 op_sel:[0,1,0]
	v_cvt_scalef32_pk_f16_fp4 v81, v81, 1.0 op_sel:[1,1,0]
	v_pk_fma_f16 v22, v23, v81, v22 op_sel_hi:[0,1,1]
	s_waitcnt vmcnt(29)
	v_cvt_scalef32_pk_f16_fp4 v81, v70, 1.0
	v_pk_fma_f16 v81, v23, v81, v89 op_sel:[1,0,0]
	v_cvt_scalef32_pk_f16_fp4 v89, v70, 1.0 op_sel:[1,0,0]
	v_pk_fma_f16 v89, v23, v89, v94 op_sel:[1,0,0]
	v_cvt_scalef32_pk_f16_fp4 v94, v70, 1.0 op_sel:[0,1,0]
	v_cvt_scalef32_pk_f16_fp4 v70, v70, 1.0 op_sel:[1,1,0]
	v_pk_fma_f16 v70, v23, v70, v78 op_sel:[1,0,0]
	v_cvt_scalef32_pk_f16_fp4 v78, v71, 1.0
	v_pk_fma_f16 v94, v23, v94, v95 op_sel:[1,0,0]
	v_pk_fma_f16 v78, v23, v78, v86 op_sel:[1,0,0]
	v_cvt_scalef32_pk_f16_fp4 v86, v71, 1.0 op_sel:[1,0,0]
	v_cvt_scalef32_pk_f16_fp4 v95, v71, 1.0 op_sel:[0,1,0]
	v_cvt_scalef32_pk_f16_fp4 v71, v71, 1.0 op_sel:[1,1,0]
	v_pk_fma_f16 v71, v23, v71, v79 op_sel:[1,0,0]
	v_cvt_scalef32_pk_f16_fp4 v79, v72, 1.0
	v_pk_fma_f16 v86, v23, v86, v96 op_sel:[1,0,0]
	v_pk_fma_f16 v79, v23, v79, v87 op_sel:[1,0,0]
	v_cvt_scalef32_pk_f16_fp4 v87, v72, 1.0 op_sel:[1,0,0]
	v_cvt_scalef32_pk_f16_fp4 v96, v72, 1.0 op_sel:[0,1,0]
	v_cvt_scalef32_pk_f16_fp4 v72, v72, 1.0 op_sel:[1,1,0]
	v_pk_fma_f16 v97, v23, v97, v106 op_sel_hi:[0,1,1]
	v_pk_fma_f16 v72, v23, v72, v80 op_sel:[1,0,0]
	v_cvt_scalef32_pk_f16_fp4 v80, v73, 1.0
	v_pk_fma_f16 v98, v23, v98, v107 op_sel_hi:[0,1,1]
	v_pk_fma_f16 v99, v23, v99, v109 op_sel_hi:[0,1,1]
	v_pk_fma_f16 v100, v23, v100, v108 op_sel_hi:[0,1,1]
	v_pk_fma_f16 v101, v23, v101, v122 op_sel_hi:[0,1,1]
	v_pk_fma_f16 v95, v23, v95, v97 op_sel:[1,0,0]
	v_pk_fma_f16 v80, v23, v80, v88 op_sel:[1,0,0]
	v_cvt_scalef32_pk_f16_fp4 v88, v73, 1.0 op_sel:[1,0,0]
	v_cvt_scalef32_pk_f16_fp4 v97, v73, 1.0 op_sel:[0,1,0]
	v_cvt_scalef32_pk_f16_fp4 v73, v73, 1.0 op_sel:[1,1,0]
	v_pk_fma_f16 v87, v23, v87, v98 op_sel:[1,0,0]
	v_pk_fma_f16 v96, v23, v96, v99 op_sel:[1,0,0]
	v_pk_fma_f16 v88, v23, v88, v100 op_sel:[1,0,0]
	v_pk_fma_f16 v97, v23, v97, v101 op_sel:[1,0,0]
	v_pk_fma_f16 v22, v23, v73, v22 op_sel:[1,0,0]
	s_waitcnt vmcnt(28)
	v_cvt_scalef32_pk_f16_fp4 v23, v58, 1.0
	v_pk_fma_f16 v23, v24, v23, v81 op_sel_hi:[0,1,1]
	v_cvt_scalef32_pk_f16_fp4 v73, v58, 1.0 op_sel:[1,0,0]
	v_cvt_scalef32_pk_f16_fp4 v81, v58, 1.0 op_sel:[0,1,0]
	v_cvt_scalef32_pk_f16_fp4 v58, v58, 1.0 op_sel:[1,1,0]
	v_pk_fma_f16 v58, v24, v58, v70 op_sel_hi:[0,1,1]
	v_cvt_scalef32_pk_f16_fp4 v70, v59, 1.0
	v_pk_fma_f16 v70, v24, v70, v78 op_sel_hi:[0,1,1]
	v_cvt_scalef32_pk_f16_fp4 v78, v59, 1.0 op_sel:[1,0,0]
	v_pk_fma_f16 v78, v24, v78, v86 op_sel_hi:[0,1,1]
	v_cvt_scalef32_pk_f16_fp4 v86, v59, 1.0 op_sel:[0,1,0]
	v_cvt_scalef32_pk_f16_fp4 v59, v59, 1.0 op_sel:[1,1,0]
	v_pk_fma_f16 v59, v24, v59, v71 op_sel_hi:[0,1,1]
	v_cvt_scalef32_pk_f16_fp4 v71, v60, 1.0
	v_pk_fma_f16 v71, v24, v71, v79 op_sel_hi:[0,1,1]
	v_cvt_scalef32_pk_f16_fp4 v79, v60, 1.0 op_sel:[1,0,0]
	v_pk_fma_f16 v79, v24, v79, v87 op_sel_hi:[0,1,1]
	v_cvt_scalef32_pk_f16_fp4 v87, v60, 1.0 op_sel:[0,1,0]
	v_cvt_scalef32_pk_f16_fp4 v60, v60, 1.0 op_sel:[1,1,0]
	v_pk_fma_f16 v60, v24, v60, v72 op_sel_hi:[0,1,1]
	v_cvt_scalef32_pk_f16_fp4 v72, v61, 1.0
	v_pk_fma_f16 v72, v24, v72, v80 op_sel_hi:[0,1,1]
	v_cvt_scalef32_pk_f16_fp4 v80, v61, 1.0 op_sel:[1,0,0]
	v_pk_fma_f16 v80, v24, v80, v88 op_sel_hi:[0,1,1]
	v_cvt_scalef32_pk_f16_fp4 v88, v61, 1.0 op_sel:[0,1,0]
	v_cvt_scalef32_pk_f16_fp4 v61, v61, 1.0 op_sel:[1,1,0]
	v_pk_fma_f16 v22, v24, v61, v22 op_sel_hi:[0,1,1]
	s_waitcnt vmcnt(27)
	v_cvt_scalef32_pk_f16_fp4 v61, v50, 1.0
	v_pk_fma_f16 v73, v24, v73, v89 op_sel_hi:[0,1,1]
	v_pk_fma_f16 v23, v24, v61, v23 op_sel:[1,0,0]
	v_cvt_scalef32_pk_f16_fp4 v61, v50, 1.0 op_sel:[1,0,0]
	v_pk_fma_f16 v61, v24, v61, v73 op_sel:[1,0,0]
	v_cvt_scalef32_pk_f16_fp4 v73, v50, 1.0 op_sel:[0,1,0]
	v_cvt_scalef32_pk_f16_fp4 v50, v50, 1.0 op_sel:[1,1,0]
	v_pk_fma_f16 v50, v24, v50, v58 op_sel:[1,0,0]
	v_cvt_scalef32_pk_f16_fp4 v58, v51, 1.0
	v_pk_fma_f16 v58, v24, v58, v70 op_sel:[1,0,0]
	v_cvt_scalef32_pk_f16_fp4 v70, v51, 1.0 op_sel:[1,0,0]
	v_pk_fma_f16 v70, v24, v70, v78 op_sel:[1,0,0]
	v_cvt_scalef32_pk_f16_fp4 v78, v51, 1.0 op_sel:[0,1,0]
	v_cvt_scalef32_pk_f16_fp4 v51, v51, 1.0 op_sel:[1,1,0]
	v_pk_fma_f16 v51, v24, v51, v59 op_sel:[1,0,0]
	v_cvt_scalef32_pk_f16_fp4 v59, v52, 1.0
	v_pk_fma_f16 v59, v24, v59, v71 op_sel:[1,0,0]
	v_cvt_scalef32_pk_f16_fp4 v71, v52, 1.0 op_sel:[1,0,0]
	v_pk_fma_f16 v71, v24, v71, v79 op_sel:[1,0,0]
	v_cvt_scalef32_pk_f16_fp4 v79, v52, 1.0 op_sel:[0,1,0]
	v_cvt_scalef32_pk_f16_fp4 v52, v52, 1.0 op_sel:[1,1,0]
	v_pk_fma_f16 v52, v24, v52, v60 op_sel:[1,0,0]
	v_cvt_scalef32_pk_f16_fp4 v60, v53, 1.0
	v_pk_fma_f16 v60, v24, v60, v72 op_sel:[1,0,0]
	v_cvt_scalef32_pk_f16_fp4 v72, v53, 1.0 op_sel:[1,0,0]
	v_pk_fma_f16 v81, v24, v81, v94 op_sel_hi:[0,1,1]
	v_pk_fma_f16 v86, v24, v86, v95 op_sel_hi:[0,1,1]
	v_pk_fma_f16 v87, v24, v87, v96 op_sel_hi:[0,1,1]
	v_pk_fma_f16 v88, v24, v88, v97 op_sel_hi:[0,1,1]
	v_pk_fma_f16 v72, v24, v72, v80 op_sel:[1,0,0]
	v_cvt_scalef32_pk_f16_fp4 v80, v53, 1.0 op_sel:[0,1,0]
	v_cvt_scalef32_pk_f16_fp4 v53, v53, 1.0 op_sel:[1,1,0]
	v_pk_fma_f16 v73, v24, v73, v81 op_sel:[1,0,0]
	v_pk_fma_f16 v78, v24, v78, v86 op_sel:[1,0,0]
	v_pk_fma_f16 v79, v24, v79, v87 op_sel:[1,0,0]
	v_pk_fma_f16 v80, v24, v80, v88 op_sel:[1,0,0]
	v_pk_fma_f16 v22, v24, v53, v22 op_sel:[1,0,0]
	s_waitcnt vmcnt(26)
	v_cvt_scalef32_pk_f16_fp4 v24, v42, 1.0
	v_pk_fma_f16 v23, v25, v24, v23 op_sel_hi:[0,1,1]
	v_cvt_scalef32_pk_f16_fp4 v24, v42, 1.0 op_sel:[1,0,0]
	v_cvt_scalef32_pk_f16_fp4 v53, v42, 1.0 op_sel:[0,1,0]
	v_cvt_scalef32_pk_f16_fp4 v42, v42, 1.0 op_sel:[1,1,0]
	v_pk_fma_f16 v42, v25, v42, v50 op_sel_hi:[0,1,1]
	v_cvt_scalef32_pk_f16_fp4 v50, v43, 1.0
	v_pk_fma_f16 v24, v25, v24, v61 op_sel_hi:[0,1,1]
	v_pk_fma_f16 v50, v25, v50, v58 op_sel_hi:[0,1,1]
	v_cvt_scalef32_pk_f16_fp4 v58, v43, 1.0 op_sel:[1,0,0]
	v_cvt_scalef32_pk_f16_fp4 v61, v43, 1.0 op_sel:[0,1,0]
	v_cvt_scalef32_pk_f16_fp4 v43, v43, 1.0 op_sel:[1,1,0]
	v_pk_fma_f16 v43, v25, v43, v51 op_sel_hi:[0,1,1]
	v_cvt_scalef32_pk_f16_fp4 v51, v44, 1.0
	v_pk_fma_f16 v58, v25, v58, v70 op_sel_hi:[0,1,1]
	v_pk_fma_f16 v51, v25, v51, v59 op_sel_hi:[0,1,1]
	v_cvt_scalef32_pk_f16_fp4 v59, v44, 1.0 op_sel:[1,0,0]
	v_cvt_scalef32_pk_f16_fp4 v70, v44, 1.0 op_sel:[0,1,0]
	v_cvt_scalef32_pk_f16_fp4 v44, v44, 1.0 op_sel:[1,1,0]
	v_pk_fma_f16 v44, v25, v44, v52 op_sel_hi:[0,1,1]
	v_cvt_scalef32_pk_f16_fp4 v52, v45, 1.0
	v_pk_fma_f16 v59, v25, v59, v71 op_sel_hi:[0,1,1]
	v_pk_fma_f16 v52, v25, v52, v60 op_sel_hi:[0,1,1]
	v_cvt_scalef32_pk_f16_fp4 v60, v45, 1.0 op_sel:[1,0,0]
	v_cvt_scalef32_pk_f16_fp4 v71, v45, 1.0 op_sel:[0,1,0]
	v_cvt_scalef32_pk_f16_fp4 v45, v45, 1.0 op_sel:[1,1,0]
	v_pk_fma_f16 v22, v25, v45, v22 op_sel_hi:[0,1,1]
	s_waitcnt vmcnt(25)
	v_cvt_scalef32_pk_f16_fp4 v45, v30, 1.0
	v_pk_fma_f16 v23, v25, v45, v23 op_sel:[1,0,0]
	v_cvt_scalef32_pk_f16_fp4 v45, v30, 1.0 op_sel:[1,0,0]
	v_pk_fma_f16 v24, v25, v45, v24 op_sel:[1,0,0]
	v_cvt_scalef32_pk_f16_fp4 v45, v30, 1.0 op_sel:[0,1,0]
	v_cvt_scalef32_pk_f16_fp4 v30, v30, 1.0 op_sel:[1,1,0]
	v_pk_fma_f16 v53, v25, v53, v73 op_sel_hi:[0,1,1]
	v_pk_fma_f16 v30, v25, v30, v42 op_sel:[1,0,0]
	v_cvt_scalef32_pk_f16_fp4 v42, v31, 1.0
	v_pk_fma_f16 v45, v25, v45, v53 op_sel:[1,0,0]
	v_pk_fma_f16 v42, v25, v42, v50 op_sel:[1,0,0]
	v_cvt_scalef32_pk_f16_fp4 v50, v31, 1.0 op_sel:[1,0,0]
	v_cvt_scalef32_pk_f16_fp4 v53, v31, 1.0 op_sel:[0,1,0]
	v_cvt_scalef32_pk_f16_fp4 v31, v31, 1.0 op_sel:[1,1,0]
	v_pk_fma_f16 v31, v25, v31, v43 op_sel:[1,0,0]
	v_cvt_scalef32_pk_f16_fp4 v43, v32, 1.0
	v_pk_fma_f16 v50, v25, v50, v58 op_sel:[1,0,0]
	v_pk_fma_f16 v43, v25, v43, v51 op_sel:[1,0,0]
	v_cvt_scalef32_pk_f16_fp4 v51, v32, 1.0 op_sel:[1,0,0]
	v_cvt_scalef32_pk_f16_fp4 v58, v32, 1.0 op_sel:[0,1,0]
	v_cvt_scalef32_pk_f16_fp4 v32, v32, 1.0 op_sel:[1,1,0]
	v_pk_fma_f16 v61, v25, v61, v78 op_sel_hi:[0,1,1]
	v_pk_fma_f16 v70, v25, v70, v79 op_sel_hi:[0,1,1]
	v_pk_fma_f16 v71, v25, v71, v80 op_sel_hi:[0,1,1]
	v_pk_fma_f16 v51, v25, v51, v59 op_sel:[1,0,0]
	v_pk_fma_f16 v32, v25, v32, v44 op_sel:[1,0,0]
	v_cvt_scalef32_pk_f16_fp4 v44, v33, 1.0
	v_cvt_scalef32_pk_f16_fp4 v59, v33, 1.0 op_sel:[0,1,0]
	v_pk_fma_f16 v53, v25, v53, v61 op_sel:[1,0,0]
	v_pk_fma_f16 v58, v25, v58, v70 op_sel:[1,0,0]
	v_pk_fma_f16 v44, v25, v44, v52 op_sel:[1,0,0]
	v_cvt_scalef32_pk_f16_fp4 v52, v33, 1.0 op_sel:[1,0,0]
	v_pk_fma_f16 v59, v25, v59, v71 op_sel:[1,0,0]
	v_cvt_scalef32_pk_f16_fp4 v33, v33, 1.0 op_sel:[1,1,0]
	v_pk_fma_f16 v60, v25, v60, v72 op_sel_hi:[0,1,1]
	v_pk_fma_f16 v22, v25, v33, v22 op_sel:[1,0,0]
	v_permlane32_swap_b32_e32 v23, v43
	v_permlane32_swap_b32_e32 v45, v58
	v_permlane32_swap_b32_e32 v30, v32
	v_permlane32_swap_b32_e32 v42, v44
	v_permlane32_swap_b32_e32 v53, v59
	v_pk_fma_f16 v52, v25, v52, v60 op_sel:[1,0,0]
	v_pk_add_f16 v23, v23, v43
	v_pk_add_f16 v25, v45, v58
	v_pk_add_f16 v30, v30, v32
	v_pk_add_f16 v32, v42, v44
	v_pk_add_f16 v42, v53, v59
	v_permlane32_swap_b32_e32 v31, v22
	v_permlane32_swap_b32_e32 v24, v51
	v_permlane32_swap_b32_e32 v50, v52
	v_pk_add_f16 v22, v31, v22
	v_permlane16_swap_b32_e32 v23, v32
	v_permlane16_swap_b32_e32 v25, v42
	v_pk_add_f16 v24, v24, v51
	v_pk_add_f16 v33, v50, v52
	v_pk_add_f16 v23, v23, v32
	v_pk_add_f16 v25, v25, v42
	v_permlane16_swap_b32_e32 v30, v22
	v_permlane16_swap_b32_e32 v24, v33
	v_pk_add_f16 v22, v30, v22
	v_cndmask_b32_e64 v30, v25, v23, s[4:5]
	v_cndmask_b32_e64 v23, v23, v25, s[4:5]
	v_pk_add_f16 v24, v24, v33
	v_cvt_f32_f16_e32 v32, v201
	v_mov_b32_dpp v23, v23 row_ror:8 row_mask:0xf bank_mask:0xf bound_ctrl:1
	v_pk_add_f16 v25, v30, v23
	v_cndmask_b32_e64 v30, v22, v24, s[4:5]
	v_cndmask_b32_e64 v22, v24, v22, s[4:5]
	v_cvt_f32_f16_sdwa v23, v200 dst_sel:DWORD dst_unused:UNUSED_PAD src0_sel:WORD_1
	v_cvt_f32_f16_e32 v24, v25
	v_mov_b32_dpp v31, v22 row_ror:8 row_mask:0xf bank_mask:0xf bound_ctrl:1
	v_cvt_f32_f16_e32 v22, v200
	v_cvt_f32_f16_sdwa v25, v25 dst_sel:DWORD dst_unused:UNUSED_PAD src0_sel:WORD_1
	v_pk_add_f16 v43, v30, v31
	v_cvt_f32_f16_e32 v30, v198
	v_cvt_f32_f16_sdwa v31, v198 dst_sel:DWORD dst_unused:UNUSED_PAD src0_sel:WORD_1
	v_cvt_f32_f16_sdwa v33, v201 dst_sel:DWORD dst_unused:UNUSED_PAD src0_sel:WORD_1
	v_cvt_f32_f16_e32 v42, v43
	v_cvt_f32_f16_sdwa v43, v43 dst_sel:DWORD dst_unused:UNUSED_PAD src0_sel:WORD_1
	v_pk_fma_f32 v[22:23], v[2:3], v[24:25], v[22:23]
	v_cvt_f32_f16_e32 v24, v199
	v_cvt_f32_f16_sdwa v25, v199 dst_sel:DWORD dst_unused:UNUSED_PAD src0_sel:WORD_1
	v_pk_add_f32 v[22:23], v[22:23], v[30:31]
	v_pk_fma_f32 v[30:31], v[4:5], v[42:43], v[32:33]
	v_cvt_pk_f16_f32 v22, v22, v23
	v_pk_add_f32 v[24:25], v[30:31], v[24:25]
	s_nop 0
	v_cvt_pk_f16_f32 v23, v24, v25
	global_store_dwordx2 v[196:197], v[22:23], off
	s_mov_b32 s25, s13
	s_cbranch_scc0 .LBB0_4094
	s_mov_b64 s[14:15], 0
